# speedup vs baseline: 1.0169x; 1.0169x over previous
; __device__ __forceinline__ float sigmf(float x) { return 1.f / (1.f + __expf(-x)); }
; __device__ __forceinline__ float softplusf(float x) { return fmaxf(x, 0.f) + __logf(1.f + __expf(-fabsf(x))); }
; __device__ __forceinline__ void inproj_epilogue(const Params& p, int layer, int mt, int ntile, int tid,
;                                                 f32x16 (&acc)[2][2], unsigned char* smem) {
;     ...
;   const int m0 = mt * 128;
;   if (mode == 3) {
;     float* dt = (float*)(p.ws + OFF_DT) + (size_t)m0 * 16;
;     const float* bias = p.ssd_dt_bias + layer * 16;
;     acc_foreach(tid, acc, [&](int row, int col, float v) {
;       if (col < 16) *(dt + row * 16 + col) = softplusf(v + bias[col]);
;     });
;   } else {
;     bf16r* dstb = dst + (size_t)m0 * ld + c0;
;     bf16r* sT = (bf16r*)smem;
;     acc_foreach(tid, acc, [&](int row, int col, float v) {
;       int t = m0 + row;
;       float o = v;
;       if (mode == 1) o = (t >= NPADR) ? v : 0.f;
;       if (mode == 2) o = sigmf(v);
;       sT[row * 136 + col] = f2bf(o);
;     });
.LBB0_205:
	s_lshl_b32 s60, s6, 7
	s_ashr_i32 s61, s60, 31
	s_cmp_lg_u32 s7, 3
	s_mov_b64 s[4:5], -1
	s_cbranch_scc0 .LBB0_399
	v_mov_b32_e32 v106, v108
	s_movk_i32 s4, 0xffc0
	v_lshrrev_b32_e32 v107, 3, v106
	v_ashrrev_i32_e32 v96, 1, v106
	v_and_b32_e32 v107, 4, v107
	v_and_or_b32 v96, v96, s4, v107
	s_cmp_eq_u32 s7, 1
	s_cselect_b64 s[4:5], -1, 0
	v_add_u32_e32 v107, s60, v96
	s_cmp_eq_u32 s7, 2
	s_cselect_b64 s[12:13], -1, 0
	s_cmp_lg_u32 s7, 2
	v_cmp_lt_i32_e64 s[8:9], s43, v107
	s_cbranch_scc0 .Lsg_1

; __device__ __forceinline__ float sigmf(float x) { return 1.f / (1.f + __expf(-x)); }
; __device__ __forceinline__ void inproj_epilogue(const Params& p, int layer, int mt, int ntile, int tid,
;                                                 f32x16 (&acc)[2][2], unsigned char* smem) {
;     ...
;     acc_foreach(tid, acc, [&](int row, int col, float v) {
;       int t = m0 + row;
;       float o = v;
;       if (mode == 1) o = (t >= NPADR) ? v : 0.f;
;       if (mode == 2) o = sigmf(v);
;       sT[row * 136 + col] = f2bf(o);
;     });
.LBB0_209:
	v_bfe_u32 v110, v107, 16, 1
	v_and_b32_e32 v106, 0x5f, v106
	v_add3_u32 v111, v107, v110, s77
	v_mul_lo_u32 v110, v96, s78
	v_lshl_add_u32 v107, v106, 1, v110
	ds_write_b16_d16_hi v107, v111
	v_add3_u32 v111, s60, v96, 1
	v_cmp_lt_i32_e64 s[10:11], s43, v111
	v_cndmask_b32_e64 v111, 0, 1, s[12:13]
	v_cmp_ne_u32_e64 s[6:7], 1, v111
	s_andn2_b64 vcc, exec, s[12:13]
	s_cbranch_vccz .Lsg_2

; __device__ __forceinline__ float sigmf(float x) { return 1.f / (1.f + __expf(-x)); }
; __device__ __forceinline__ void inproj_epilogue(const Params& p, int layer, int mt, int ntile, int tid,
;                                                 f32x16 (&acc)[2][2], unsigned char* smem) {
;     ...
;     acc_foreach(tid, acc, [&](int row, int col, float v) {
;       int t = m0 + row;
;       float o = v;
;       if (mode == 1) o = (t >= NPADR) ? v : 0.f;
;       if (mode == 2) o = sigmf(v);
;       sT[row * 136 + col] = f2bf(o);
;     });
.LBB0_212:
	v_bfe_u32 v112, v111, 16, 1
	v_add3_u32 v112, v111, v112, s77
	v_add_u32_e32 v111, 0x110, v110
	v_lshl_add_u32 v110, v106, 1, v111
	ds_write_b16_d16_hi v110, v112
	v_add3_u32 v112, s60, v96, 2
	s_and_b64 vcc, exec, s[6:7]
	v_cmp_lt_i32_e64 s[12:13], s43, v112
	s_cbranch_vccz .Lsg_3

; __device__ __forceinline__ float sigmf(float x) { return 1.f / (1.f + __expf(-x)); }
; __device__ __forceinline__ void inproj_epilogue(const Params& p, int layer, int mt, int ntile, int tid,
;                                                 f32x16 (&acc)[2][2], unsigned char* smem) {
;     ...
;     acc_foreach(tid, acc, [&](int row, int col, float v) {
;       int t = m0 + row;
;       float o = v;
;       if (mode == 1) o = (t >= NPADR) ? v : 0.f;
;       if (mode == 2) o = sigmf(v);
;       sT[row * 136 + col] = f2bf(o);
;     });
.LBB0_215:
	v_bfe_u32 v113, v112, 16, 1
	v_add3_u32 v113, v112, v113, s77
	v_add_u32_e32 v112, 0x110, v111
	v_lshl_add_u32 v111, v106, 1, v112
	ds_write_b16_d16_hi v111, v113
	v_add3_u32 v113, s60, v96, 3
	s_and_b64 vcc, exec, s[6:7]
	v_cmp_lt_i32_e64 s[14:15], s43, v113
	s_cbranch_vccz .Lsg_4

; __device__ __forceinline__ float sigmf(float x) { return 1.f / (1.f + __expf(-x)); }
; __device__ __forceinline__ void inproj_epilogue(const Params& p, int layer, int mt, int ntile, int tid,
;                                                 f32x16 (&acc)[2][2], unsigned char* smem) {
;     ...
;     acc_foreach(tid, acc, [&](int row, int col, float v) {
;       int t = m0 + row;
;       float o = v;
;       if (mode == 1) o = (t >= NPADR) ? v : 0.f;
;       if (mode == 2) o = sigmf(v);
;       sT[row * 136 + col] = f2bf(o);
;     });
.LBB0_218:
	v_bfe_u32 v114, v113, 16, 1
	v_add3_u32 v114, v113, v114, s77
	v_add_u32_e32 v113, 0x110, v112
	v_lshl_add_u32 v112, v106, 1, v113
	ds_write_b16_d16_hi v112, v114
	v_add3_u32 v114, s60, v96, 8
	s_and_b64 vcc, exec, s[6:7]
	v_cmp_lt_i32_e64 s[16:17], s43, v114
	s_cbranch_vccz .Lsg_5

; __device__ __forceinline__ float sigmf(float x) { return 1.f / (1.f + __expf(-x)); }
; __device__ __forceinline__ void inproj_epilogue(const Params& p, int layer, int mt, int ntile, int tid,
;                                                 f32x16 (&acc)[2][2], unsigned char* smem) {
;     ...
;     acc_foreach(tid, acc, [&](int row, int col, float v) {
;       int t = m0 + row;
;       float o = v;
;       if (mode == 1) o = (t >= NPADR) ? v : 0.f;
;       if (mode == 2) o = sigmf(v);
;       sT[row * 136 + col] = f2bf(o);
;     });
.LBB0_221:
	v_bfe_u32 v115, v114, 16, 1
	v_add3_u32 v115, v114, v115, s77
	v_add_u32_e32 v114, 0x550, v113
	v_lshl_add_u32 v113, v106, 1, v114
	ds_write_b16_d16_hi v113, v115
	v_add3_u32 v115, s60, v96, 9
	s_and_b64 vcc, exec, s[6:7]
	v_cmp_lt_i32_e64 s[18:19], s43, v115
	s_cbranch_vccz .Lsg_6

; __device__ __forceinline__ float sigmf(float x) { return 1.f / (1.f + __expf(-x)); }
; __device__ __forceinline__ void inproj_epilogue(const Params& p, int layer, int mt, int ntile, int tid,
;                                                 f32x16 (&acc)[2][2], unsigned char* smem) {
;     ...
;     acc_foreach(tid, acc, [&](int row, int col, float v) {
;       int t = m0 + row;
;       float o = v;
;       if (mode == 1) o = (t >= NPADR) ? v : 0.f;
;       if (mode == 2) o = sigmf(v);
;       sT[row * 136 + col] = f2bf(o);
;     });
.LBB0_224:
	v_bfe_u32 v116, v115, 16, 1
	v_add3_u32 v116, v115, v116, s77
	v_add_u32_e32 v115, 0x110, v114
	v_lshl_add_u32 v114, v106, 1, v115
	ds_write_b16_d16_hi v114, v116
	v_add3_u32 v116, s60, v96, 10
	s_and_b64 vcc, exec, s[6:7]
	v_cmp_lt_i32_e64 s[20:21], s43, v116
	s_cbranch_vccz .Lsg_7

; __device__ __forceinline__ float sigmf(float x) { return 1.f / (1.f + __expf(-x)); }
; __device__ __forceinline__ void inproj_epilogue(const Params& p, int layer, int mt, int ntile, int tid,
;                                                 f32x16 (&acc)[2][2], unsigned char* smem) {
;     ...
;     acc_foreach(tid, acc, [&](int row, int col, float v) {
;       int t = m0 + row;
;       float o = v;
;       if (mode == 1) o = (t >= NPADR) ? v : 0.f;
;       if (mode == 2) o = sigmf(v);
;       sT[row * 136 + col] = f2bf(o);
;     });
.LBB0_227:
	v_bfe_u32 v117, v116, 16, 1
	v_add3_u32 v117, v116, v117, s77
	v_add_u32_e32 v116, 0x110, v115
	v_lshl_add_u32 v115, v106, 1, v116
	ds_write_b16_d16_hi v115, v117
	v_add3_u32 v117, s60, v96, 11
	s_and_b64 vcc, exec, s[6:7]
	v_cmp_lt_i32_e64 s[22:23], s43, v117
	s_cbranch_vccz .Lsg_8

; __device__ __forceinline__ float sigmf(float x) { return 1.f / (1.f + __expf(-x)); }
; __device__ __forceinline__ void inproj_epilogue(const Params& p, int layer, int mt, int ntile, int tid,
;                                                 f32x16 (&acc)[2][2], unsigned char* smem) {
;     ...
;     acc_foreach(tid, acc, [&](int row, int col, float v) {
;       int t = m0 + row;
;       float o = v;
;       if (mode == 1) o = (t >= NPADR) ? v : 0.f;
;       if (mode == 2) o = sigmf(v);
;       sT[row * 136 + col] = f2bf(o);
;     });
.LBB0_230:
	v_bfe_u32 v118, v117, 16, 1
	v_add_u32_e32 v116, 0x110, v116
	v_add3_u32 v118, v117, v118, s77
	v_lshl_add_u32 v117, v106, 1, v116
	ds_write_b16_d16_hi v117, v118
	v_add3_u32 v118, s60, v96, 16
	s_and_b64 vcc, exec, s[6:7]
	v_cmp_lt_i32_e64 s[24:25], s43, v118
	s_cbranch_vccz .Lsg_9

; __device__ __forceinline__ float sigmf(float x) { return 1.f / (1.f + __expf(-x)); }
; __device__ __forceinline__ void inproj_epilogue(const Params& p, int layer, int mt, int ntile, int tid,
;                                                 f32x16 (&acc)[2][2], unsigned char* smem) {
;     ...
;     acc_foreach(tid, acc, [&](int row, int col, float v) {
;       int t = m0 + row;
;       float o = v;
;       if (mode == 1) o = (t >= NPADR) ? v : 0.f;
;       if (mode == 2) o = sigmf(v);
;       sT[row * 136 + col] = f2bf(o);
;     });
.LBB0_233:
	v_bfe_u32 v119, v118, 16, 1
	v_add_u32_e32 v116, 0x550, v116
	v_add3_u32 v119, v118, v119, s77
	v_lshl_add_u32 v118, v106, 1, v116
	ds_write_b16_d16_hi v118, v119
	v_add3_u32 v119, s60, v96, 17
	s_and_b64 vcc, exec, s[6:7]
	v_cmp_lt_i32_e64 s[26:27], s43, v119
	s_cbranch_vccz .Lsg_10

; __device__ __forceinline__ float sigmf(float x) { return 1.f / (1.f + __expf(-x)); }
; __device__ __forceinline__ void inproj_epilogue(const Params& p, int layer, int mt, int ntile, int tid,
;                                                 f32x16 (&acc)[2][2], unsigned char* smem) {
;     ...
;     acc_foreach(tid, acc, [&](int row, int col, float v) {
;       int t = m0 + row;
;       float o = v;
;       if (mode == 1) o = (t >= NPADR) ? v : 0.f;
;       if (mode == 2) o = sigmf(v);
;       sT[row * 136 + col] = f2bf(o);
;     });
.LBB0_236:
	v_bfe_u32 v120, v119, 16, 1
	v_add_u32_e32 v116, 0x110, v116
	v_add3_u32 v120, v119, v120, s77
	v_lshl_add_u32 v119, v106, 1, v116
	ds_write_b16_d16_hi v119, v120
	v_add3_u32 v120, s60, v96, 18
	s_and_b64 vcc, exec, s[6:7]
	v_cmp_lt_i32_e64 s[28:29], s43, v120
	s_cbranch_vccz .Lsg_11

; __device__ __forceinline__ float sigmf(float x) { return 1.f / (1.f + __expf(-x)); }
; __device__ __forceinline__ void inproj_epilogue(const Params& p, int layer, int mt, int ntile, int tid,
;                                                 f32x16 (&acc)[2][2], unsigned char* smem) {
;     ...
;     acc_foreach(tid, acc, [&](int row, int col, float v) {
;       int t = m0 + row;
;       float o = v;
;       if (mode == 1) o = (t >= NPADR) ? v : 0.f;
;       if (mode == 2) o = sigmf(v);
;       sT[row * 136 + col] = f2bf(o);
;     });
.LBB0_239:
	v_bfe_u32 v121, v120, 16, 1
	v_add_u32_e32 v116, 0x110, v116
	v_add3_u32 v121, v120, v121, s77
	v_lshl_add_u32 v120, v106, 1, v116
	ds_write_b16_d16_hi v120, v121
	v_add3_u32 v121, s60, v96, 19
	s_and_b64 vcc, exec, s[6:7]
	v_cmp_lt_i32_e64 s[30:31], s43, v121
	s_cbranch_vccz .Lsg_12

; __device__ __forceinline__ float sigmf(float x) { return 1.f / (1.f + __expf(-x)); }
; __device__ __forceinline__ void inproj_epilogue(const Params& p, int layer, int mt, int ntile, int tid,
;                                                 f32x16 (&acc)[2][2], unsigned char* smem) {
;     ...
;     acc_foreach(tid, acc, [&](int row, int col, float v) {
;       int t = m0 + row;
;       float o = v;
;       if (mode == 1) o = (t >= NPADR) ? v : 0.f;
;       if (mode == 2) o = sigmf(v);
;       sT[row * 136 + col] = f2bf(o);
;     });
.LBB0_242:
	v_bfe_u32 v122, v121, 16, 1
	v_add_u32_e32 v116, 0x110, v116
	v_add3_u32 v122, v121, v122, s77
	v_lshl_add_u32 v121, v106, 1, v116
	ds_write_b16_d16_hi v121, v122
	v_add3_u32 v122, s60, v96, 24
	s_and_b64 vcc, exec, s[6:7]
	v_cmp_lt_i32_e64 s[34:35], s43, v122
	s_cbranch_vccz .Lsg_13

; __device__ __forceinline__ float sigmf(float x) { return 1.f / (1.f + __expf(-x)); }
; __device__ __forceinline__ void inproj_epilogue(const Params& p, int layer, int mt, int ntile, int tid,
;                                                 f32x16 (&acc)[2][2], unsigned char* smem) {
;     ...
;     acc_foreach(tid, acc, [&](int row, int col, float v) {
;       int t = m0 + row;
;       float o = v;
;       if (mode == 1) o = (t >= NPADR) ? v : 0.f;
;       if (mode == 2) o = sigmf(v);
;       sT[row * 136 + col] = f2bf(o);
;     });
.LBB0_245:
	v_bfe_u32 v123, v122, 16, 1
	v_add_u32_e32 v116, 0x550, v116
	v_add3_u32 v123, v122, v123, s77
	v_lshl_add_u32 v122, v106, 1, v116
	ds_write_b16_d16_hi v122, v123
	v_add3_u32 v123, s60, v96, 25
	s_and_b64 vcc, exec, s[6:7]
	v_cmp_lt_i32_e64 s[36:37], s43, v123
	s_cbranch_vccz .Lsg_14

; __device__ __forceinline__ float sigmf(float x) { return 1.f / (1.f + __expf(-x)); }
; __device__ __forceinline__ void inproj_epilogue(const Params& p, int layer, int mt, int ntile, int tid,
;                                                 f32x16 (&acc)[2][2], unsigned char* smem) {
;     ...
;     acc_foreach(tid, acc, [&](int row, int col, float v) {
;       int t = m0 + row;
;       float o = v;
;       if (mode == 1) o = (t >= NPADR) ? v : 0.f;
;       if (mode == 2) o = sigmf(v);
;       sT[row * 136 + col] = f2bf(o);
;     });
.LBB0_248:
	v_bfe_u32 v124, v123, 16, 1
	v_add_u32_e32 v116, 0x110, v116
	v_add3_u32 v124, v123, v124, s77
	v_lshl_add_u32 v123, v106, 1, v116
	ds_write_b16_d16_hi v123, v124
	v_add3_u32 v124, s60, v96, 26
	s_and_b64 vcc, exec, s[6:7]
	v_cmp_lt_i32_e64 s[38:39], s43, v124
	s_cbranch_vccz .Lsg_15

; __device__ __forceinline__ float sigmf(float x) { return 1.f / (1.f + __expf(-x)); }
; __device__ __forceinline__ void inproj_epilogue(const Params& p, int layer, int mt, int ntile, int tid,
;                                                 f32x16 (&acc)[2][2], unsigned char* smem) {
;     ...
;     acc_foreach(tid, acc, [&](int row, int col, float v) {
;       int t = m0 + row;
;       float o = v;
;       if (mode == 1) o = (t >= NPADR) ? v : 0.f;
;       if (mode == 2) o = sigmf(v);
;       sT[row * 136 + col] = f2bf(o);
;     });
.LBB0_251:
	v_bfe_u32 v125, v124, 16, 1
	v_add_u32_e32 v116, 0x110, v116
	v_add3_u32 v124, v124, v125, s77
	v_lshl_add_u32 v116, v106, 1, v116
	ds_write_b16_d16_hi v116, v124
	v_add3_u32 v124, s60, v96, 27
	s_and_b64 vcc, exec, s[6:7]
	v_cmp_lt_i32_e64 s[40:41], s43, v124
	s_cbranch_vccz .Lsg_16

; __device__ __forceinline__ float sigmf(float x) { return 1.f / (1.f + __expf(-x)); }
; template <int MT, int NT, class F>
; __device__ __forceinline__ void acc_foreach(int tid, f32x16 (&acc)[MT][NT], F f) {
;     ...
;         int row = wm * (MT * 32) + mt * 32 + (i & 3) + 8 * (i >> 2) + 4 * hi;
;         int col = wn * (NT * 32) + nt * 32 + c;
;         f(row, col, acc[mt][nt][i]);
; __device__ __forceinline__ void inproj_epilogue(const Params& p, int layer, int mt, int ntile, int tid,
;                                                 f32x16 (&acc)[2][2], unsigned char* smem) {
;     ...
;     acc_foreach(tid, acc, [&](int row, int col, float v) {
;       int t = m0 + row;
;       float o = v;
;       if (mode == 1) o = (t >= NPADR) ? v : 0.f;
;       if (mode == 2) o = sigmf(v);
;       sT[row * 136 + col] = f2bf(o);
;     });
.LBB0_254:
	v_bfe_u32 v125, v124, 16, 1
	v_add3_u32 v124, v124, v125, s77
	ds_write_b16_d16_hi v116, v124 offset:272
	s_and_b64 vcc, exec, s[6:7]
	s_cbranch_vccz .Lsg_17

; __device__ __forceinline__ float sigmf(float x) { return 1.f / (1.f + __expf(-x)); }
; template <int MT, int NT, class F>
; __device__ __forceinline__ void acc_foreach(int tid, f32x16 (&acc)[MT][NT], F f) {
;     ...
;         int row = wm * (MT * 32) + mt * 32 + (i & 3) + 8 * (i >> 2) + 4 * hi;
;         int col = wn * (NT * 32) + nt * 32 + c;
;         f(row, col, acc[mt][nt][i]);
; __device__ __forceinline__ void inproj_epilogue(const Params& p, int layer, int mt, int ntile, int tid,
;                                                 f32x16 (&acc)[2][2], unsigned char* smem) {
;     ...
;     acc_foreach(tid, acc, [&](int row, int col, float v) {
;       int t = m0 + row;
;       float o = v;
;       if (mode == 1) o = (t >= NPADR) ? v : 0.f;
;       if (mode == 2) o = sigmf(v);
;       sT[row * 136 + col] = f2bf(o);
;     });
.LBB0_257:
	v_bfe_u32 v124, v48, 16, 1
	v_add3_u32 v48, v48, v124, s77
	s_and_b64 vcc, exec, s[6:7]
	ds_write_b16_d16_hi v107, v48 offset:64
	s_cbranch_vccz .Lsg_18

; __device__ __forceinline__ float sigmf(float x) { return 1.f / (1.f + __expf(-x)); }
; __device__ __forceinline__ void inproj_epilogue(const Params& p, int layer, int mt, int ntile, int tid,
;                                                 f32x16 (&acc)[2][2], unsigned char* smem) {
;     ...
;     acc_foreach(tid, acc, [&](int row, int col, float v) {
;       int t = m0 + row;
;       float o = v;
;       if (mode == 1) o = (t >= NPADR) ? v : 0.f;
;       if (mode == 2) o = sigmf(v);
;       sT[row * 136 + col] = f2bf(o);
;     });
.LBB0_260:
	v_bfe_u32 v49, v48, 16, 1
	v_add3_u32 v48, v48, v49, s77
	s_and_b64 vcc, exec, s[6:7]
	ds_write_b16_d16_hi v110, v48 offset:64
	s_cbranch_vccz .Lsg_19

; __device__ __forceinline__ float sigmf(float x) { return 1.f / (1.f + __expf(-x)); }
; __device__ __forceinline__ void inproj_epilogue(const Params& p, int layer, int mt, int ntile, int tid,
;                                                 f32x16 (&acc)[2][2], unsigned char* smem) {
;     ...
;     acc_foreach(tid, acc, [&](int row, int col, float v) {
;       int t = m0 + row;
;       float o = v;
;       if (mode == 1) o = (t >= NPADR) ? v : 0.f;
;       if (mode == 2) o = sigmf(v);
;       sT[row * 136 + col] = f2bf(o);
;     });
.LBB0_263:
	v_bfe_u32 v49, v48, 16, 1
	v_add3_u32 v48, v48, v49, s77
	s_and_b64 vcc, exec, s[6:7]
	ds_write_b16_d16_hi v111, v48 offset:64
	s_cbranch_vccz .Lsg_20

; __device__ __forceinline__ float sigmf(float x) { return 1.f / (1.f + __expf(-x)); }
; __device__ __forceinline__ void inproj_epilogue(const Params& p, int layer, int mt, int ntile, int tid,
;                                                 f32x16 (&acc)[2][2], unsigned char* smem) {
;     ...
;     acc_foreach(tid, acc, [&](int row, int col, float v) {
;       int t = m0 + row;
;       float o = v;
;       if (mode == 1) o = (t >= NPADR) ? v : 0.f;
;       if (mode == 2) o = sigmf(v);
;       sT[row * 136 + col] = f2bf(o);
;     });
.LBB0_266:
	v_bfe_u32 v49, v48, 16, 1
	v_add3_u32 v48, v48, v49, s77
	s_and_b64 vcc, exec, s[6:7]
	ds_write_b16_d16_hi v112, v48 offset:64
	s_cbranch_vccz .Lsg_21

; __device__ __forceinline__ float sigmf(float x) { return 1.f / (1.f + __expf(-x)); }
; __device__ __forceinline__ void inproj_epilogue(const Params& p, int layer, int mt, int ntile, int tid,
;                                                 f32x16 (&acc)[2][2], unsigned char* smem) {
;     ...
;     acc_foreach(tid, acc, [&](int row, int col, float v) {
;       int t = m0 + row;
;       float o = v;
;       if (mode == 1) o = (t >= NPADR) ? v : 0.f;
;       if (mode == 2) o = sigmf(v);
;       sT[row * 136 + col] = f2bf(o);
;     });
.LBB0_269:
	v_bfe_u32 v49, v48, 16, 1
	v_add3_u32 v48, v48, v49, s77
	s_and_b64 vcc, exec, s[6:7]
	ds_write_b16_d16_hi v113, v48 offset:64
	s_cbranch_vccz .Lsg_22

; __device__ __forceinline__ float sigmf(float x) { return 1.f / (1.f + __expf(-x)); }
; __device__ __forceinline__ void inproj_epilogue(const Params& p, int layer, int mt, int ntile, int tid,
;                                                 f32x16 (&acc)[2][2], unsigned char* smem) {
;     ...
;     acc_foreach(tid, acc, [&](int row, int col, float v) {
;       int t = m0 + row;
;       float o = v;
;       if (mode == 1) o = (t >= NPADR) ? v : 0.f;
;       if (mode == 2) o = sigmf(v);
;       sT[row * 136 + col] = f2bf(o);
;     });
.LBB0_272:
	v_bfe_u32 v49, v48, 16, 1
	v_add3_u32 v48, v48, v49, s77
	s_and_b64 vcc, exec, s[6:7]
	ds_write_b16_d16_hi v114, v48 offset:64
	s_cbranch_vccz .Lsg_23

; __device__ __forceinline__ float sigmf(float x) { return 1.f / (1.f + __expf(-x)); }
; __device__ __forceinline__ void inproj_epilogue(const Params& p, int layer, int mt, int ntile, int tid,
;                                                 f32x16 (&acc)[2][2], unsigned char* smem) {
;     ...
;     acc_foreach(tid, acc, [&](int row, int col, float v) {
;       int t = m0 + row;
;       float o = v;
;       if (mode == 1) o = (t >= NPADR) ? v : 0.f;
;       if (mode == 2) o = sigmf(v);
;       sT[row * 136 + col] = f2bf(o);
;     });
.LBB0_275:
	v_bfe_u32 v49, v48, 16, 1
	v_add3_u32 v48, v48, v49, s77
	s_and_b64 vcc, exec, s[6:7]
	ds_write_b16_d16_hi v115, v48 offset:64
	s_cbranch_vccz .Lsg_24

; __device__ __forceinline__ float sigmf(float x) { return 1.f / (1.f + __expf(-x)); }
; __device__ __forceinline__ void inproj_epilogue(const Params& p, int layer, int mt, int ntile, int tid,
;                                                 f32x16 (&acc)[2][2], unsigned char* smem) {
;     ...
;     acc_foreach(tid, acc, [&](int row, int col, float v) {
;       int t = m0 + row;
;       float o = v;
;       if (mode == 1) o = (t >= NPADR) ? v : 0.f;
;       if (mode == 2) o = sigmf(v);
;       sT[row * 136 + col] = f2bf(o);
;     });
.LBB0_278:
	v_bfe_u32 v49, v48, 16, 1
	v_add3_u32 v48, v48, v49, s77
	s_and_b64 vcc, exec, s[6:7]
	ds_write_b16_d16_hi v117, v48 offset:64
	s_cbranch_vccz .Lsg_25

; __device__ __forceinline__ float sigmf(float x) { return 1.f / (1.f + __expf(-x)); }
; __device__ __forceinline__ void inproj_epilogue(const Params& p, int layer, int mt, int ntile, int tid,
;                                                 f32x16 (&acc)[2][2], unsigned char* smem) {
;     ...
;     acc_foreach(tid, acc, [&](int row, int col, float v) {
;       int t = m0 + row;
;       float o = v;
;       if (mode == 1) o = (t >= NPADR) ? v : 0.f;
;       if (mode == 2) o = sigmf(v);
;       sT[row * 136 + col] = f2bf(o);
;     });
.LBB0_281:
	v_bfe_u32 v49, v48, 16, 1
	v_add3_u32 v48, v48, v49, s77
	s_and_b64 vcc, exec, s[6:7]
	ds_write_b16_d16_hi v118, v48 offset:64
	s_cbranch_vccz .Lsg_26

; __device__ __forceinline__ float sigmf(float x) { return 1.f / (1.f + __expf(-x)); }
; __device__ __forceinline__ void inproj_epilogue(const Params& p, int layer, int mt, int ntile, int tid,
;                                                 f32x16 (&acc)[2][2], unsigned char* smem) {
;     ...
;     acc_foreach(tid, acc, [&](int row, int col, float v) {
;       int t = m0 + row;
;       float o = v;
;       if (mode == 1) o = (t >= NPADR) ? v : 0.f;
;       if (mode == 2) o = sigmf(v);
;       sT[row * 136 + col] = f2bf(o);
;     });
.LBB0_284:
	v_bfe_u32 v49, v48, 16, 1
	v_add3_u32 v48, v48, v49, s77
	s_and_b64 vcc, exec, s[6:7]
	ds_write_b16_d16_hi v119, v48 offset:64
	s_cbranch_vccz .Lsg_27

; __device__ __forceinline__ float sigmf(float x) { return 1.f / (1.f + __expf(-x)); }
; __device__ __forceinline__ void inproj_epilogue(const Params& p, int layer, int mt, int ntile, int tid,
;                                                 f32x16 (&acc)[2][2], unsigned char* smem) {
;     ...
;     acc_foreach(tid, acc, [&](int row, int col, float v) {
;       int t = m0 + row;
;       float o = v;
;       if (mode == 1) o = (t >= NPADR) ? v : 0.f;
;       if (mode == 2) o = sigmf(v);
;       sT[row * 136 + col] = f2bf(o);
;     });
.LBB0_287:
	v_bfe_u32 v49, v48, 16, 1
	v_add3_u32 v48, v48, v49, s77
	s_and_b64 vcc, exec, s[6:7]
	ds_write_b16_d16_hi v120, v48 offset:64
	s_cbranch_vccz .Lsg_28

; __device__ __forceinline__ float sigmf(float x) { return 1.f / (1.f + __expf(-x)); }
; __device__ __forceinline__ void inproj_epilogue(const Params& p, int layer, int mt, int ntile, int tid,
;                                                 f32x16 (&acc)[2][2], unsigned char* smem) {
;     ...
;     acc_foreach(tid, acc, [&](int row, int col, float v) {
;       int t = m0 + row;
;       float o = v;
;       if (mode == 1) o = (t >= NPADR) ? v : 0.f;
;       if (mode == 2) o = sigmf(v);
;       sT[row * 136 + col] = f2bf(o);
;     });
.LBB0_290:
	v_bfe_u32 v49, v48, 16, 1
	v_add3_u32 v48, v48, v49, s77
	s_and_b64 vcc, exec, s[6:7]
	ds_write_b16_d16_hi v121, v48 offset:64
	s_cbranch_vccz .Lsg_29

; __device__ __forceinline__ float sigmf(float x) { return 1.f / (1.f + __expf(-x)); }
; __device__ __forceinline__ void inproj_epilogue(const Params& p, int layer, int mt, int ntile, int tid,
;                                                 f32x16 (&acc)[2][2], unsigned char* smem) {
;     ...
;     acc_foreach(tid, acc, [&](int row, int col, float v) {
;       int t = m0 + row;
;       float o = v;
;       if (mode == 1) o = (t >= NPADR) ? v : 0.f;
;       if (mode == 2) o = sigmf(v);
;       sT[row * 136 + col] = f2bf(o);
;     });
.LBB0_293:
	v_bfe_u32 v49, v48, 16, 1
	v_add3_u32 v48, v48, v49, s77
	s_and_b64 vcc, exec, s[6:7]
	ds_write_b16_d16_hi v122, v48 offset:64
	s_cbranch_vccz .Lsg_30

; __device__ __forceinline__ float sigmf(float x) { return 1.f / (1.f + __expf(-x)); }
; __device__ __forceinline__ void inproj_epilogue(const Params& p, int layer, int mt, int ntile, int tid,
;                                                 f32x16 (&acc)[2][2], unsigned char* smem) {
;     ...
;     acc_foreach(tid, acc, [&](int row, int col, float v) {
;       int t = m0 + row;
;       float o = v;
;       if (mode == 1) o = (t >= NPADR) ? v : 0.f;
;       if (mode == 2) o = sigmf(v);
;       sT[row * 136 + col] = f2bf(o);
;     });
.LBB0_296:
	v_bfe_u32 v49, v48, 16, 1
	v_add3_u32 v48, v48, v49, s77
	s_and_b64 vcc, exec, s[6:7]
	ds_write_b16_d16_hi v123, v48 offset:64
	s_cbranch_vccz .Lsg_31

; __device__ __forceinline__ float sigmf(float x) { return 1.f / (1.f + __expf(-x)); }
; __device__ __forceinline__ void inproj_epilogue(const Params& p, int layer, int mt, int ntile, int tid,
;                                                 f32x16 (&acc)[2][2], unsigned char* smem) {
;     ...
;     acc_foreach(tid, acc, [&](int row, int col, float v) {
;       int t = m0 + row;
;       float o = v;
;       if (mode == 1) o = (t >= NPADR) ? v : 0.f;
;       if (mode == 2) o = sigmf(v);
;       sT[row * 136 + col] = f2bf(o);
;     });
.LBB0_299:
	v_bfe_u32 v49, v48, 16, 1
	v_add3_u32 v48, v48, v49, s77
	s_and_b64 vcc, exec, s[6:7]
	ds_write_b16_d16_hi v116, v48 offset:64
	s_cbranch_vccz .Lsg_32

; __device__ __forceinline__ float sigmf(float x) { return 1.f / (1.f + __expf(-x)); }
; template <int MT, int NT, class F>
; __device__ __forceinline__ void acc_foreach(int tid, f32x16 (&acc)[MT][NT], F f) {
;     ...
;         int row = wm * (MT * 32) + mt * 32 + (i & 3) + 8 * (i >> 2) + 4 * hi;
;         int col = wn * (NT * 32) + nt * 32 + c;
;         f(row, col, acc[mt][nt][i]);
; __device__ __forceinline__ void inproj_epilogue(const Params& p, int layer, int mt, int ntile, int tid,
;                                                 f32x16 (&acc)[2][2], unsigned char* smem) {
;     ...
;     acc_foreach(tid, acc, [&](int row, int col, float v) {
;       int t = m0 + row;
;       float o = v;
;       if (mode == 1) o = (t >= NPADR) ? v : 0.f;
;       if (mode == 2) o = sigmf(v);
;       sT[row * 136 + col] = f2bf(o);
;     });
.LBB0_302:
	v_bfe_u32 v50, v48, 16, 1
	v_add_u32_e32 v49, 0x110, v116
	v_add3_u32 v48, v48, v50, s77
	ds_write_b16_d16_hi v49, v48 offset:64
	v_or_b32_e32 v48, 32, v96
	v_add_u32_e32 v49, s60, v48
	s_and_b64 vcc, exec, s[6:7]
	v_cmp_lt_i32_e64 s[8:9], s43, v49
	s_cbranch_vccz .Lsg_33

; __device__ __forceinline__ float sigmf(float x) { return 1.f / (1.f + __expf(-x)); }
; __device__ __forceinline__ void inproj_epilogue(const Params& p, int layer, int mt, int ntile, int tid,
;                                                 f32x16 (&acc)[2][2], unsigned char* smem) {
;     ...
;     acc_foreach(tid, acc, [&](int row, int col, float v) {
;       int t = m0 + row;
;       float o = v;
;       if (mode == 1) o = (t >= NPADR) ? v : 0.f;
;       if (mode == 2) o = sigmf(v);
;       sT[row * 136 + col] = f2bf(o);
;     });
.LBB0_305:
	v_bfe_u32 v50, v49, 16, 1
	v_add3_u32 v50, v49, v50, s77
	v_mul_lo_u32 v49, v48, s78
	v_lshl_add_u32 v48, v106, 1, v49
	ds_write_b16_d16_hi v48, v50
	v_add3_u32 v50, s60, v96, 33
	s_and_b64 vcc, exec, s[6:7]
	v_cmp_lt_i32_e64 s[10:11], s43, v50
	s_cbranch_vccz .Lsg_34

; __device__ __forceinline__ float sigmf(float x) { return 1.f / (1.f + __expf(-x)); }
; __device__ __forceinline__ void inproj_epilogue(const Params& p, int layer, int mt, int ntile, int tid,
;                                                 f32x16 (&acc)[2][2], unsigned char* smem) {
;     ...
;     acc_foreach(tid, acc, [&](int row, int col, float v) {
;       int t = m0 + row;
;       float o = v;
;       if (mode == 1) o = (t >= NPADR) ? v : 0.f;
;       if (mode == 2) o = sigmf(v);
;       sT[row * 136 + col] = f2bf(o);
;     });
.LBB0_308:
	v_bfe_u32 v51, v50, 16, 1
	v_add3_u32 v51, v50, v51, s77
	v_add_u32_e32 v50, 0x110, v49
	v_lshl_add_u32 v49, v106, 1, v50
	ds_write_b16_d16_hi v49, v51
	v_add3_u32 v51, s60, v96, 34
	s_and_b64 vcc, exec, s[6:7]
	v_cmp_lt_i32_e64 s[12:13], s43, v51
	s_cbranch_vccz .Lsg_35

; __device__ __forceinline__ float sigmf(float x) { return 1.f / (1.f + __expf(-x)); }
; __device__ __forceinline__ void inproj_epilogue(const Params& p, int layer, int mt, int ntile, int tid,
;                                                 f32x16 (&acc)[2][2], unsigned char* smem) {
;     ...
;     acc_foreach(tid, acc, [&](int row, int col, float v) {
;       int t = m0 + row;
;       float o = v;
;       if (mode == 1) o = (t >= NPADR) ? v : 0.f;
;       if (mode == 2) o = sigmf(v);
;       sT[row * 136 + col] = f2bf(o);
;     });
.LBB0_311:
	v_bfe_u32 v52, v51, 16, 1
	v_add3_u32 v52, v51, v52, s77
	v_add_u32_e32 v51, 0x110, v50
	v_lshl_add_u32 v50, v106, 1, v51
	ds_write_b16_d16_hi v50, v52
	v_add3_u32 v52, s60, v96, 35
	s_and_b64 vcc, exec, s[6:7]
	v_cmp_lt_i32_e64 s[14:15], s43, v52
	s_cbranch_vccz .Lsg_36

; __device__ __forceinline__ float sigmf(float x) { return 1.f / (1.f + __expf(-x)); }
; __device__ __forceinline__ void inproj_epilogue(const Params& p, int layer, int mt, int ntile, int tid,
;                                                 f32x16 (&acc)[2][2], unsigned char* smem) {
;     ...
;     acc_foreach(tid, acc, [&](int row, int col, float v) {
;       int t = m0 + row;
;       float o = v;
;       if (mode == 1) o = (t >= NPADR) ? v : 0.f;
;       if (mode == 2) o = sigmf(v);
;       sT[row * 136 + col] = f2bf(o);
;     });
.LBB0_314:
	v_bfe_u32 v53, v52, 16, 1
	v_add3_u32 v53, v52, v53, s77
	v_add_u32_e32 v52, 0x110, v51
	v_lshl_add_u32 v51, v106, 1, v52
	ds_write_b16_d16_hi v51, v53
	v_add3_u32 v53, s60, v96, 40
	s_and_b64 vcc, exec, s[6:7]
	v_cmp_lt_i32_e64 s[16:17], s43, v53
	s_cbranch_vccz .Lsg_37

; __device__ __forceinline__ float sigmf(float x) { return 1.f / (1.f + __expf(-x)); }
; __device__ __forceinline__ void inproj_epilogue(const Params& p, int layer, int mt, int ntile, int tid,
;                                                 f32x16 (&acc)[2][2], unsigned char* smem) {
;     ...
;     acc_foreach(tid, acc, [&](int row, int col, float v) {
;       int t = m0 + row;
;       float o = v;
;       if (mode == 1) o = (t >= NPADR) ? v : 0.f;
;       if (mode == 2) o = sigmf(v);
;       sT[row * 136 + col] = f2bf(o);
;     });
.LBB0_317:
	v_bfe_u32 v54, v53, 16, 1
	v_add3_u32 v54, v53, v54, s77
	v_add_u32_e32 v53, 0x550, v52
	v_lshl_add_u32 v52, v106, 1, v53
	ds_write_b16_d16_hi v52, v54
	v_add3_u32 v54, s60, v96, 41
	s_and_b64 vcc, exec, s[6:7]
	v_cmp_lt_i32_e64 s[18:19], s43, v54
	s_cbranch_vccz .Lsg_38

; __device__ __forceinline__ float sigmf(float x) { return 1.f / (1.f + __expf(-x)); }
; __device__ __forceinline__ void inproj_epilogue(const Params& p, int layer, int mt, int ntile, int tid,
;                                                 f32x16 (&acc)[2][2], unsigned char* smem) {
;     ...
;     acc_foreach(tid, acc, [&](int row, int col, float v) {
;       int t = m0 + row;
;       float o = v;
;       if (mode == 1) o = (t >= NPADR) ? v : 0.f;
;       if (mode == 2) o = sigmf(v);
;       sT[row * 136 + col] = f2bf(o);
;     });
.LBB0_320:
	v_bfe_u32 v55, v54, 16, 1
	v_add3_u32 v55, v54, v55, s77
	v_add_u32_e32 v54, 0x110, v53
	v_lshl_add_u32 v53, v106, 1, v54
	ds_write_b16_d16_hi v53, v55
	v_add3_u32 v55, s60, v96, 42
	s_and_b64 vcc, exec, s[6:7]
	v_cmp_lt_i32_e64 s[20:21], s43, v55
	s_cbranch_vccz .Lsg_39

; __device__ __forceinline__ float sigmf(float x) { return 1.f / (1.f + __expf(-x)); }
; __device__ __forceinline__ void inproj_epilogue(const Params& p, int layer, int mt, int ntile, int tid,
;                                                 f32x16 (&acc)[2][2], unsigned char* smem) {
;     ...
;     acc_foreach(tid, acc, [&](int row, int col, float v) {
;       int t = m0 + row;
;       float o = v;
;       if (mode == 1) o = (t >= NPADR) ? v : 0.f;
;       if (mode == 2) o = sigmf(v);
;       sT[row * 136 + col] = f2bf(o);
;     });
.LBB0_323:
	v_bfe_u32 v56, v55, 16, 1
	v_add3_u32 v56, v55, v56, s77
	v_add_u32_e32 v55, 0x110, v54
	v_lshl_add_u32 v54, v106, 1, v55
	ds_write_b16_d16_hi v54, v56
	v_add3_u32 v56, s60, v96, 43
	s_and_b64 vcc, exec, s[6:7]
	v_cmp_lt_i32_e64 s[22:23], s43, v56
	s_cbranch_vccz .Lsg_40

; __device__ __forceinline__ float sigmf(float x) { return 1.f / (1.f + __expf(-x)); }
; __device__ __forceinline__ void inproj_epilogue(const Params& p, int layer, int mt, int ntile, int tid,
;                                                 f32x16 (&acc)[2][2], unsigned char* smem) {
;     ...
;     acc_foreach(tid, acc, [&](int row, int col, float v) {
;       int t = m0 + row;
;       float o = v;
;       if (mode == 1) o = (t >= NPADR) ? v : 0.f;
;       if (mode == 2) o = sigmf(v);
;       sT[row * 136 + col] = f2bf(o);
;     });
.LBB0_326:
	v_bfe_u32 v57, v56, 16, 1
	v_add_u32_e32 v55, 0x110, v55
	v_add3_u32 v57, v56, v57, s77
	v_lshl_add_u32 v56, v106, 1, v55
	ds_write_b16_d16_hi v56, v57
	v_add3_u32 v57, s60, v96, 48
	s_and_b64 vcc, exec, s[6:7]
	v_cmp_lt_i32_e64 s[24:25], s43, v57
	s_cbranch_vccz .Lsg_41

; __device__ __forceinline__ float sigmf(float x) { return 1.f / (1.f + __expf(-x)); }
; __device__ __forceinline__ void inproj_epilogue(const Params& p, int layer, int mt, int ntile, int tid,
;                                                 f32x16 (&acc)[2][2], unsigned char* smem) {
;     ...
;     acc_foreach(tid, acc, [&](int row, int col, float v) {
;       int t = m0 + row;
;       float o = v;
;       if (mode == 1) o = (t >= NPADR) ? v : 0.f;
;       if (mode == 2) o = sigmf(v);
;       sT[row * 136 + col] = f2bf(o);
;     });
.LBB0_329:
	v_bfe_u32 v58, v57, 16, 1
	v_add_u32_e32 v55, 0x550, v55
	v_add3_u32 v58, v57, v58, s77
	v_lshl_add_u32 v57, v106, 1, v55
	ds_write_b16_d16_hi v57, v58
	v_add3_u32 v58, s60, v96, 49
	s_and_b64 vcc, exec, s[6:7]
	v_cmp_lt_i32_e64 s[26:27], s43, v58
	s_cbranch_vccz .Lsg_42

; __device__ __forceinline__ float sigmf(float x) { return 1.f / (1.f + __expf(-x)); }
; __device__ __forceinline__ void inproj_epilogue(const Params& p, int layer, int mt, int ntile, int tid,
;                                                 f32x16 (&acc)[2][2], unsigned char* smem) {
;     ...
;     acc_foreach(tid, acc, [&](int row, int col, float v) {
;       int t = m0 + row;
;       float o = v;
;       if (mode == 1) o = (t >= NPADR) ? v : 0.f;
;       if (mode == 2) o = sigmf(v);
;       sT[row * 136 + col] = f2bf(o);
;     });
.LBB0_332:
	v_bfe_u32 v59, v58, 16, 1
	v_add_u32_e32 v55, 0x110, v55
	v_add3_u32 v59, v58, v59, s77
	v_lshl_add_u32 v58, v106, 1, v55
	ds_write_b16_d16_hi v58, v59
	v_add3_u32 v59, s60, v96, 50
	s_and_b64 vcc, exec, s[6:7]
	v_cmp_lt_i32_e64 s[28:29], s43, v59
	s_cbranch_vccz .Lsg_43

; __device__ __forceinline__ float sigmf(float x) { return 1.f / (1.f + __expf(-x)); }
; __device__ __forceinline__ void inproj_epilogue(const Params& p, int layer, int mt, int ntile, int tid,
;                                                 f32x16 (&acc)[2][2], unsigned char* smem) {
;     ...
;     acc_foreach(tid, acc, [&](int row, int col, float v) {
;       int t = m0 + row;
;       float o = v;
;       if (mode == 1) o = (t >= NPADR) ? v : 0.f;
;       if (mode == 2) o = sigmf(v);
;       sT[row * 136 + col] = f2bf(o);
;     });
.LBB0_335:
	v_bfe_u32 v60, v59, 16, 1
	v_add_u32_e32 v55, 0x110, v55
	v_add3_u32 v60, v59, v60, s77
	v_lshl_add_u32 v59, v106, 1, v55
	ds_write_b16_d16_hi v59, v60
	v_add3_u32 v60, s60, v96, 51
	s_and_b64 vcc, exec, s[6:7]
	v_cmp_lt_i32_e64 s[30:31], s43, v60
	s_cbranch_vccz .Lsg_44

; __device__ __forceinline__ float sigmf(float x) { return 1.f / (1.f + __expf(-x)); }
; __device__ __forceinline__ void inproj_epilogue(const Params& p, int layer, int mt, int ntile, int tid,
;                                                 f32x16 (&acc)[2][2], unsigned char* smem) {
;     ...
;     acc_foreach(tid, acc, [&](int row, int col, float v) {
;       int t = m0 + row;
;       float o = v;
;       if (mode == 1) o = (t >= NPADR) ? v : 0.f;
;       if (mode == 2) o = sigmf(v);
;       sT[row * 136 + col] = f2bf(o);
;     });
.LBB0_338:
	v_bfe_u32 v61, v60, 16, 1
	v_add_u32_e32 v55, 0x110, v55
	v_add3_u32 v61, v60, v61, s77
	v_lshl_add_u32 v60, v106, 1, v55
	ds_write_b16_d16_hi v60, v61
	v_add3_u32 v61, s60, v96, 56
	s_and_b64 vcc, exec, s[6:7]
	v_cmp_lt_i32_e64 s[34:35], s43, v61
	s_cbranch_vccz .Lsg_45

; __device__ __forceinline__ float sigmf(float x) { return 1.f / (1.f + __expf(-x)); }
; __device__ __forceinline__ void inproj_epilogue(const Params& p, int layer, int mt, int ntile, int tid,
;                                                 f32x16 (&acc)[2][2], unsigned char* smem) {
;     ...
;     acc_foreach(tid, acc, [&](int row, int col, float v) {
;       int t = m0 + row;
;       float o = v;
;       if (mode == 1) o = (t >= NPADR) ? v : 0.f;
;       if (mode == 2) o = sigmf(v);
;       sT[row * 136 + col] = f2bf(o);
;     });
.LBB0_341:
	v_bfe_u32 v62, v61, 16, 1
	v_add_u32_e32 v55, 0x550, v55
	v_add3_u32 v62, v61, v62, s77
	v_lshl_add_u32 v61, v106, 1, v55
	ds_write_b16_d16_hi v61, v62
	v_add3_u32 v62, s60, v96, 57
	s_and_b64 vcc, exec, s[6:7]
	v_cmp_lt_i32_e64 s[36:37], s43, v62
	s_cbranch_vccz .Lsg_46

; __device__ __forceinline__ float sigmf(float x) { return 1.f / (1.f + __expf(-x)); }
; __device__ __forceinline__ void inproj_epilogue(const Params& p, int layer, int mt, int ntile, int tid,
;                                                 f32x16 (&acc)[2][2], unsigned char* smem) {
;     ...
;     acc_foreach(tid, acc, [&](int row, int col, float v) {
;       int t = m0 + row;
;       float o = v;
;       if (mode == 1) o = (t >= NPADR) ? v : 0.f;
;       if (mode == 2) o = sigmf(v);
;       sT[row * 136 + col] = f2bf(o);
;     });
.LBB0_344:
	v_bfe_u32 v63, v62, 16, 1
	v_add_u32_e32 v55, 0x110, v55
	v_add3_u32 v63, v62, v63, s77
	v_lshl_add_u32 v62, v106, 1, v55
	ds_write_b16_d16_hi v62, v63
	v_add3_u32 v63, s60, v96, 58
	s_and_b64 vcc, exec, s[6:7]
	v_cmp_lt_i32_e64 s[38:39], s43, v63
	s_cbranch_vccz .Lsg_47

; __device__ __forceinline__ float sigmf(float x) { return 1.f / (1.f + __expf(-x)); }
; __device__ __forceinline__ void inproj_epilogue(const Params& p, int layer, int mt, int ntile, int tid,
;                                                 f32x16 (&acc)[2][2], unsigned char* smem) {
;     ...
;     acc_foreach(tid, acc, [&](int row, int col, float v) {
;       int t = m0 + row;
;       float o = v;
;       if (mode == 1) o = (t >= NPADR) ? v : 0.f;
;       if (mode == 2) o = sigmf(v);
;       sT[row * 136 + col] = f2bf(o);
;     });
.LBB0_347:
	v_bfe_u32 v107, v63, 16, 1
	v_add_u32_e32 v55, 0x110, v55
	v_add3_u32 v63, v63, v107, s77
	v_lshl_add_u32 v55, v106, 1, v55
	ds_write_b16_d16_hi v55, v63
	v_add3_u32 v63, s60, v96, 59
	s_and_b64 vcc, exec, s[6:7]
	v_cmp_lt_i32_e64 s[40:41], s43, v63
	s_cbranch_vccz .Lsg_48

; __device__ __forceinline__ float sigmf(float x) { return 1.f / (1.f + __expf(-x)); }
; template <int MT, int NT, class F>
; __device__ __forceinline__ void acc_foreach(int tid, f32x16 (&acc)[MT][NT], F f) {
;     ...
;         int row = wm * (MT * 32) + mt * 32 + (i & 3) + 8 * (i >> 2) + 4 * hi;
;         int col = wn * (NT * 32) + nt * 32 + c;
;         f(row, col, acc[mt][nt][i]);
; __device__ __forceinline__ void inproj_epilogue(const Params& p, int layer, int mt, int ntile, int tid,
;                                                 f32x16 (&acc)[2][2], unsigned char* smem) {
;     ...
;     acc_foreach(tid, acc, [&](int row, int col, float v) {
;       int t = m0 + row;
;       float o = v;
;       if (mode == 1) o = (t >= NPADR) ? v : 0.f;
;       if (mode == 2) o = sigmf(v);
;       sT[row * 136 + col] = f2bf(o);
;     });
.LBB0_350:
	v_bfe_u32 v96, v63, 16, 1
	v_add3_u32 v63, v63, v96, s77
	ds_write_b16_d16_hi v55, v63 offset:272
	s_and_b64 vcc, exec, s[6:7]
	s_cbranch_vccz .Lsg_49

; __device__ __forceinline__ float sigmf(float x) { return 1.f / (1.f + __expf(-x)); }
; __device__ __forceinline__ void inproj_epilogue(const Params& p, int layer, int mt, int ntile, int tid,
;                                                 f32x16 (&acc)[2][2], unsigned char* smem) {
;     ...
;     acc_foreach(tid, acc, [&](int row, int col, float v) {
;       int t = m0 + row;
;       float o = v;
;       if (mode == 1) o = (t >= NPADR) ? v : 0.f;
;       if (mode == 2) o = sigmf(v);
;       sT[row * 136 + col] = f2bf(o);
;     });
.LBB0_353:
	v_bfe_u32 v63, v32, 16, 1
	v_add3_u32 v32, v32, v63, s77
	s_and_b64 vcc, exec, s[6:7]
	ds_write_b16_d16_hi v48, v32 offset:64
	s_cbranch_vccz .Lsg_50

; __device__ __forceinline__ float sigmf(float x) { return 1.f / (1.f + __expf(-x)); }
; __device__ __forceinline__ void inproj_epilogue(const Params& p, int layer, int mt, int ntile, int tid,
;                                                 f32x16 (&acc)[2][2], unsigned char* smem) {
;     ...
;     acc_foreach(tid, acc, [&](int row, int col, float v) {
;       int t = m0 + row;
;       float o = v;
;       if (mode == 1) o = (t >= NPADR) ? v : 0.f;
;       if (mode == 2) o = sigmf(v);
;       sT[row * 136 + col] = f2bf(o);
;     });
.LBB0_356:
	v_bfe_u32 v33, v32, 16, 1
	v_add3_u32 v32, v32, v33, s77
	s_and_b64 vcc, exec, s[6:7]
	ds_write_b16_d16_hi v49, v32 offset:64
	s_cbranch_vccz .Lsg_51

; __device__ __forceinline__ float sigmf(float x) { return 1.f / (1.f + __expf(-x)); }
; __device__ __forceinline__ void inproj_epilogue(const Params& p, int layer, int mt, int ntile, int tid,
;                                                 f32x16 (&acc)[2][2], unsigned char* smem) {
;     ...
;     acc_foreach(tid, acc, [&](int row, int col, float v) {
;       int t = m0 + row;
;       float o = v;
;       if (mode == 1) o = (t >= NPADR) ? v : 0.f;
;       if (mode == 2) o = sigmf(v);
;       sT[row * 136 + col] = f2bf(o);
;     });
.LBB0_359:
	v_bfe_u32 v33, v32, 16, 1
	v_add3_u32 v32, v32, v33, s77
	s_and_b64 vcc, exec, s[6:7]
	ds_write_b16_d16_hi v50, v32 offset:64
	s_cbranch_vccz .Lsg_52

; __device__ __forceinline__ float sigmf(float x) { return 1.f / (1.f + __expf(-x)); }
; __device__ __forceinline__ void inproj_epilogue(const Params& p, int layer, int mt, int ntile, int tid,
;                                                 f32x16 (&acc)[2][2], unsigned char* smem) {
;     ...
;     acc_foreach(tid, acc, [&](int row, int col, float v) {
;       int t = m0 + row;
;       float o = v;
;       if (mode == 1) o = (t >= NPADR) ? v : 0.f;
;       if (mode == 2) o = sigmf(v);
;       sT[row * 136 + col] = f2bf(o);
;     });
.LBB0_362:
	v_bfe_u32 v33, v32, 16, 1
	v_add3_u32 v32, v32, v33, s77
	s_and_b64 vcc, exec, s[6:7]
	ds_write_b16_d16_hi v51, v32 offset:64
	s_cbranch_vccz .Lsg_53

; __device__ __forceinline__ float sigmf(float x) { return 1.f / (1.f + __expf(-x)); }
; __device__ __forceinline__ void inproj_epilogue(const Params& p, int layer, int mt, int ntile, int tid,
;                                                 f32x16 (&acc)[2][2], unsigned char* smem) {
;     ...
;     acc_foreach(tid, acc, [&](int row, int col, float v) {
;       int t = m0 + row;
;       float o = v;
;       if (mode == 1) o = (t >= NPADR) ? v : 0.f;
;       if (mode == 2) o = sigmf(v);
;       sT[row * 136 + col] = f2bf(o);
;     });
.LBB0_365:
	v_bfe_u32 v33, v32, 16, 1
	v_add3_u32 v32, v32, v33, s77
	s_and_b64 vcc, exec, s[6:7]
	ds_write_b16_d16_hi v52, v32 offset:64
	s_cbranch_vccz .Lsg_54

; __device__ __forceinline__ float sigmf(float x) { return 1.f / (1.f + __expf(-x)); }
; __device__ __forceinline__ void inproj_epilogue(const Params& p, int layer, int mt, int ntile, int tid,
;                                                 f32x16 (&acc)[2][2], unsigned char* smem) {
;     ...
;     acc_foreach(tid, acc, [&](int row, int col, float v) {
;       int t = m0 + row;
;       float o = v;
;       if (mode == 1) o = (t >= NPADR) ? v : 0.f;
;       if (mode == 2) o = sigmf(v);
;       sT[row * 136 + col] = f2bf(o);
;     });
.LBB0_368:
	v_bfe_u32 v33, v32, 16, 1
	v_add3_u32 v32, v32, v33, s77
	s_and_b64 vcc, exec, s[6:7]
	ds_write_b16_d16_hi v53, v32 offset:64
	s_cbranch_vccz .Lsg_55

; __device__ __forceinline__ float sigmf(float x) { return 1.f / (1.f + __expf(-x)); }
; __device__ __forceinline__ void inproj_epilogue(const Params& p, int layer, int mt, int ntile, int tid,
;                                                 f32x16 (&acc)[2][2], unsigned char* smem) {
;     ...
;     acc_foreach(tid, acc, [&](int row, int col, float v) {
;       int t = m0 + row;
;       float o = v;
;       if (mode == 1) o = (t >= NPADR) ? v : 0.f;
;       if (mode == 2) o = sigmf(v);
;       sT[row * 136 + col] = f2bf(o);
;     });
.LBB0_371:
	v_bfe_u32 v33, v32, 16, 1
	v_add3_u32 v32, v32, v33, s77
	s_and_b64 vcc, exec, s[6:7]
	ds_write_b16_d16_hi v54, v32 offset:64
	s_cbranch_vccz .Lsg_56

; __device__ __forceinline__ float sigmf(float x) { return 1.f / (1.f + __expf(-x)); }
; __device__ __forceinline__ void inproj_epilogue(const Params& p, int layer, int mt, int ntile, int tid,
;                                                 f32x16 (&acc)[2][2], unsigned char* smem) {
;     ...
;     acc_foreach(tid, acc, [&](int row, int col, float v) {
;       int t = m0 + row;
;       float o = v;
;       if (mode == 1) o = (t >= NPADR) ? v : 0.f;
;       if (mode == 2) o = sigmf(v);
;       sT[row * 136 + col] = f2bf(o);
;     });
.LBB0_374:
	v_bfe_u32 v33, v32, 16, 1
	v_add3_u32 v32, v32, v33, s77
	s_and_b64 vcc, exec, s[6:7]
	ds_write_b16_d16_hi v56, v32 offset:64
	s_cbranch_vccz .Lsg_57

; __device__ __forceinline__ float sigmf(float x) { return 1.f / (1.f + __expf(-x)); }
; __device__ __forceinline__ void inproj_epilogue(const Params& p, int layer, int mt, int ntile, int tid,
;                                                 f32x16 (&acc)[2][2], unsigned char* smem) {
;     ...
;     acc_foreach(tid, acc, [&](int row, int col, float v) {
;       int t = m0 + row;
;       float o = v;
;       if (mode == 1) o = (t >= NPADR) ? v : 0.f;
;       if (mode == 2) o = sigmf(v);
;       sT[row * 136 + col] = f2bf(o);
;     });
.LBB0_377:
	v_bfe_u32 v33, v32, 16, 1
	v_add3_u32 v32, v32, v33, s77
	s_and_b64 vcc, exec, s[6:7]
	ds_write_b16_d16_hi v57, v32 offset:64
	s_cbranch_vccz .Lsg_58

; __device__ __forceinline__ float sigmf(float x) { return 1.f / (1.f + __expf(-x)); }
; __device__ __forceinline__ void inproj_epilogue(const Params& p, int layer, int mt, int ntile, int tid,
;                                                 f32x16 (&acc)[2][2], unsigned char* smem) {
;     ...
;     acc_foreach(tid, acc, [&](int row, int col, float v) {
;       int t = m0 + row;
;       float o = v;
;       if (mode == 1) o = (t >= NPADR) ? v : 0.f;
;       if (mode == 2) o = sigmf(v);
;       sT[row * 136 + col] = f2bf(o);
;     });
.LBB0_380:
	v_bfe_u32 v33, v32, 16, 1
	v_add3_u32 v32, v32, v33, s77
	s_and_b64 vcc, exec, s[6:7]
	ds_write_b16_d16_hi v58, v32 offset:64
	s_cbranch_vccz .Lsg_59

; __device__ __forceinline__ float sigmf(float x) { return 1.f / (1.f + __expf(-x)); }
; __device__ __forceinline__ bf16r f2bf(float f) {
;   unsigned u = __float_as_uint(f);
;   u += 0x7fffu + ((u >> 16) & 1u);
;   return (bf16r)(u >> 16);
; __device__ __forceinline__ void inproj_epilogue(const Params& p, int layer, int mt, int ntile, int tid,
;                                                 f32x16 (&acc)[2][2], unsigned char* smem) {
;     ...
;       if (mode == 2) o = sigmf(v);
;       sT[row * 136 + col] = f2bf(o);
.LBB0_383:
	v_bfe_u32 v33, v32, 16, 1
	v_add3_u32 v32, v32, v33, s77
	s_and_b64 vcc, exec, s[6:7]
	ds_write_b16_d16_hi v59, v32 offset:64
	s_cbranch_vccz .Lsg_60

; __device__ __forceinline__ float sigmf(float x) { return 1.f / (1.f + __expf(-x)); }
; __device__ __forceinline__ bf16r f2bf(float f) {
;   unsigned u = __float_as_uint(f);
;   u += 0x7fffu + ((u >> 16) & 1u);
;   return (bf16r)(u >> 16);
; __device__ __forceinline__ void inproj_epilogue(const Params& p, int layer, int mt, int ntile, int tid,
;                                                 f32x16 (&acc)[2][2], unsigned char* smem) {
;     ...
;       if (mode == 2) o = sigmf(v);
;       sT[row * 136 + col] = f2bf(o);
.LBB0_386:
	v_bfe_u32 v33, v32, 16, 1
	v_add3_u32 v32, v32, v33, s77
	s_and_b64 vcc, exec, s[6:7]
	ds_write_b16_d16_hi v60, v32 offset:64
	s_cbranch_vccz .Lsg_61

; __device__ __forceinline__ float sigmf(float x) { return 1.f / (1.f + __expf(-x)); }
; __device__ __forceinline__ bf16r f2bf(float f) {
;   unsigned u = __float_as_uint(f);
;   u += 0x7fffu + ((u >> 16) & 1u);
;   return (bf16r)(u >> 16);
; __device__ __forceinline__ void inproj_epilogue(const Params& p, int layer, int mt, int ntile, int tid,
;                                                 f32x16 (&acc)[2][2], unsigned char* smem) {
;     ...
;       if (mode == 2) o = sigmf(v);
;       sT[row * 136 + col] = f2bf(o);
.LBB0_389:
	v_bfe_u32 v33, v32, 16, 1
	v_add3_u32 v32, v32, v33, s77
	s_and_b64 vcc, exec, s[6:7]
	ds_write_b16_d16_hi v61, v32 offset:64
	s_cbranch_vccz .Lsg_62

; __device__ __forceinline__ float sigmf(float x) { return 1.f / (1.f + __expf(-x)); }
; __device__ __forceinline__ bf16r f2bf(float f) {
;   unsigned u = __float_as_uint(f);
;   u += 0x7fffu + ((u >> 16) & 1u);
;   return (bf16r)(u >> 16);
; __device__ __forceinline__ void inproj_epilogue(const Params& p, int layer, int mt, int ntile, int tid,
;                                                 f32x16 (&acc)[2][2], unsigned char* smem) {
;     ...
;       if (mode == 2) o = sigmf(v);
;       sT[row * 136 + col] = f2bf(o);
.LBB0_392:
	v_bfe_u32 v33, v32, 16, 1
	v_add3_u32 v32, v32, v33, s77
	s_and_b64 vcc, exec, s[6:7]
	ds_write_b16_d16_hi v62, v32 offset:64
	s_cbranch_vccz .Lsg_63

; __device__ __forceinline__ float sigmf(float x) { return 1.f / (1.f + __expf(-x)); }
; __device__ __forceinline__ bf16r f2bf(float f) {
;   unsigned u = __float_as_uint(f);
;   u += 0x7fffu + ((u >> 16) & 1u);
;   return (bf16r)(u >> 16);
; __device__ __forceinline__ void inproj_epilogue(const Params& p, int layer, int mt, int ntile, int tid,
;                                                 f32x16 (&acc)[2][2], unsigned char* smem) {
;     ...
;       if (mode == 2) o = sigmf(v);
;       sT[row * 136 + col] = f2bf(o);
.LBB0_395:
	v_bfe_u32 v33, v32, 16, 1
	v_add3_u32 v32, v32, v33, s77
	s_and_b64 vcc, exec, s[6:7]
	ds_write_b16_d16_hi v55, v32 offset:64
	s_cbranch_vccz .Lsg_64

; __device__ __forceinline__ float siluf(float x) { return x / (1.f + __expf(-x)); }
; __device__ __forceinline__ float sigmf(float x) { return 1.f / (1.f + __expf(-x)); }
; __device__ __forceinline__ void inproj_epilogue(const Params& p, int layer, int mt, int ntile, int tid,
;                                                 f32x16 (&acc)[2][2], unsigned char* smem) {
;     ...
;       if (mode == 2) o = sigmf(v);
.Lsg_1:
	v_mul_f32_e32 v107, 0xbfb8aa3b, v16
	v_exp_f32_e32 v107, v107
	s_nop 0
	v_add_f32_e32 v107, 1.0, v107
	v_div_scale_f32 v110, s[6:7], v107, v107, 1.0
	v_rcp_f32_e32 v111, v110
	v_div_scale_f32 v112, vcc, 1.0, v107, 1.0
	v_fma_f32 v113, -v110, v111, 1.0
	v_fmac_f32_e32 v111, v113, v111
	v_mul_f32_e32 v113, v112, v111
	v_fma_f32 v114, -v110, v113, v112
	v_fmac_f32_e32 v113, v114, v111
	v_fma_f32 v110, -v110, v113, v112
	v_div_fmas_f32 v110, v110, v111, v113
	v_div_fixup_f32 v107, v110, v107, 1.0
	s_branch .LBB0_209
.Lsg_2:
	v_mul_f32_e32 v111, 0xbfb8aa3b, v17
	v_exp_f32_e32 v111, v111
	s_nop 0
	v_add_f32_e32 v111, 1.0, v111
	v_div_scale_f32 v112, s[12:13], v111, v111, 1.0
	v_rcp_f32_e32 v113, v112
	v_div_scale_f32 v114, vcc, 1.0, v111, 1.0
	v_fma_f32 v115, -v112, v113, 1.0
	v_fmac_f32_e32 v113, v115, v113
	v_mul_f32_e32 v115, v114, v113
	v_fma_f32 v116, -v112, v115, v114
	v_fmac_f32_e32 v115, v116, v113
	v_fma_f32 v112, -v112, v115, v114
	v_div_fmas_f32 v112, v112, v113, v115
	v_div_fixup_f32 v111, v112, v111, 1.0
	s_branch .LBB0_212
.Lsg_3:
	v_mul_f32_e32 v112, 0xbfb8aa3b, v18
	v_exp_f32_e32 v112, v112
	s_nop 0
	v_add_f32_e32 v112, 1.0, v112
	v_div_scale_f32 v113, s[14:15], v112, v112, 1.0
	v_rcp_f32_e32 v114, v113
	v_div_scale_f32 v115, vcc, 1.0, v112, 1.0
	v_fma_f32 v116, -v113, v114, 1.0
	v_fmac_f32_e32 v114, v116, v114
	v_mul_f32_e32 v116, v115, v114
	v_fma_f32 v117, -v113, v116, v115
	v_fmac_f32_e32 v116, v117, v114
	v_fma_f32 v113, -v113, v116, v115
	v_div_fmas_f32 v113, v113, v114, v116
	v_div_fixup_f32 v112, v113, v112, 1.0
	s_branch .LBB0_215
.Lsg_4:
	v_mul_f32_e32 v113, 0xbfb8aa3b, v19
	v_exp_f32_e32 v113, v113
	s_nop 0
	v_add_f32_e32 v113, 1.0, v113
	v_div_scale_f32 v114, s[16:17], v113, v113, 1.0
	v_rcp_f32_e32 v115, v114
	v_div_scale_f32 v116, vcc, 1.0, v113, 1.0
	v_fma_f32 v117, -v114, v115, 1.0
	v_fmac_f32_e32 v115, v117, v115
	v_mul_f32_e32 v117, v116, v115
	v_fma_f32 v118, -v114, v117, v116
	v_fmac_f32_e32 v117, v118, v115
	v_fma_f32 v114, -v114, v117, v116
	v_div_fmas_f32 v114, v114, v115, v117
	v_div_fixup_f32 v113, v114, v113, 1.0
	s_branch .LBB0_218
.Lsg_5:
	v_mul_f32_e32 v114, 0xbfb8aa3b, v20
	v_exp_f32_e32 v114, v114
	s_nop 0
	v_add_f32_e32 v114, 1.0, v114
	v_div_scale_f32 v115, s[18:19], v114, v114, 1.0
	v_rcp_f32_e32 v116, v115
	v_div_scale_f32 v117, vcc, 1.0, v114, 1.0
	v_fma_f32 v118, -v115, v116, 1.0
	v_fmac_f32_e32 v116, v118, v116
	v_mul_f32_e32 v118, v117, v116
	v_fma_f32 v119, -v115, v118, v117
	v_fmac_f32_e32 v118, v119, v116
	v_fma_f32 v115, -v115, v118, v117
	v_div_fmas_f32 v115, v115, v116, v118
	v_div_fixup_f32 v114, v115, v114, 1.0
	s_branch .LBB0_221
.Lsg_6:
	v_mul_f32_e32 v115, 0xbfb8aa3b, v21
	v_exp_f32_e32 v115, v115
	s_nop 0
	v_add_f32_e32 v115, 1.0, v115
	v_div_scale_f32 v116, s[20:21], v115, v115, 1.0
	v_rcp_f32_e32 v117, v116
	v_div_scale_f32 v118, vcc, 1.0, v115, 1.0
	v_fma_f32 v119, -v116, v117, 1.0
	v_fmac_f32_e32 v117, v119, v117
	v_mul_f32_e32 v119, v118, v117
	v_fma_f32 v120, -v116, v119, v118
	v_fmac_f32_e32 v119, v120, v117
	v_fma_f32 v116, -v116, v119, v118
	v_div_fmas_f32 v116, v116, v117, v119
	v_div_fixup_f32 v115, v116, v115, 1.0
	s_branch .LBB0_224
.Lsg_7:
	v_mul_f32_e32 v116, 0xbfb8aa3b, v22
	v_exp_f32_e32 v116, v116
	s_nop 0
	v_add_f32_e32 v116, 1.0, v116
	v_div_scale_f32 v117, s[22:23], v116, v116, 1.0
	v_rcp_f32_e32 v118, v117
	v_div_scale_f32 v119, vcc, 1.0, v116, 1.0
	v_fma_f32 v120, -v117, v118, 1.0
	v_fmac_f32_e32 v118, v120, v118
	v_mul_f32_e32 v120, v119, v118
	v_fma_f32 v121, -v117, v120, v119
	v_fmac_f32_e32 v120, v121, v118
	v_fma_f32 v117, -v117, v120, v119
	v_div_fmas_f32 v117, v117, v118, v120
	v_div_fixup_f32 v116, v117, v116, 1.0
	s_branch .LBB0_227
.Lsg_8:
	v_mul_f32_e32 v117, 0xbfb8aa3b, v23
	v_exp_f32_e32 v117, v117
	s_nop 0
	v_add_f32_e32 v117, 1.0, v117
	v_div_scale_f32 v118, s[24:25], v117, v117, 1.0
	v_rcp_f32_e32 v119, v118
	v_div_scale_f32 v120, vcc, 1.0, v117, 1.0
	v_fma_f32 v121, -v118, v119, 1.0
	v_fmac_f32_e32 v119, v121, v119
	v_mul_f32_e32 v121, v120, v119
	v_fma_f32 v122, -v118, v121, v120
	v_fmac_f32_e32 v121, v122, v119
	v_fma_f32 v118, -v118, v121, v120
	v_div_fmas_f32 v118, v118, v119, v121
	v_div_fixup_f32 v117, v118, v117, 1.0
	s_branch .LBB0_230
.Lsg_9:
	v_mul_f32_e32 v118, 0xbfb8aa3b, v24
	v_exp_f32_e32 v118, v118
	s_nop 0
	v_add_f32_e32 v118, 1.0, v118
	v_div_scale_f32 v119, s[26:27], v118, v118, 1.0
	v_rcp_f32_e32 v120, v119
	v_div_scale_f32 v121, vcc, 1.0, v118, 1.0
	v_fma_f32 v122, -v119, v120, 1.0
	v_fmac_f32_e32 v120, v122, v120
	v_mul_f32_e32 v122, v121, v120
	v_fma_f32 v123, -v119, v122, v121
	v_fmac_f32_e32 v122, v123, v120
	v_fma_f32 v119, -v119, v122, v121
	v_div_fmas_f32 v119, v119, v120, v122
	v_div_fixup_f32 v118, v119, v118, 1.0
	s_branch .LBB0_233
.Lsg_10:
	v_mul_f32_e32 v119, 0xbfb8aa3b, v25
	v_exp_f32_e32 v119, v119
	s_nop 0
	v_add_f32_e32 v119, 1.0, v119
	v_div_scale_f32 v120, s[28:29], v119, v119, 1.0
	v_rcp_f32_e32 v121, v120
	v_div_scale_f32 v122, vcc, 1.0, v119, 1.0
	v_fma_f32 v123, -v120, v121, 1.0
	v_fmac_f32_e32 v121, v123, v121
	v_mul_f32_e32 v123, v122, v121
	v_fma_f32 v124, -v120, v123, v122
	v_fmac_f32_e32 v123, v124, v121
	v_fma_f32 v120, -v120, v123, v122
	v_div_fmas_f32 v120, v120, v121, v123
	v_div_fixup_f32 v119, v120, v119, 1.0
	s_branch .LBB0_236
.Lsg_11:
	v_mul_f32_e32 v120, 0xbfb8aa3b, v26
	v_exp_f32_e32 v120, v120
	s_nop 0
	v_add_f32_e32 v120, 1.0, v120
	v_div_scale_f32 v121, s[30:31], v120, v120, 1.0
	v_rcp_f32_e32 v122, v121
	v_div_scale_f32 v123, vcc, 1.0, v120, 1.0
	v_fma_f32 v124, -v121, v122, 1.0
	v_fmac_f32_e32 v122, v124, v122
	v_mul_f32_e32 v124, v123, v122
	v_fma_f32 v125, -v121, v124, v123
	v_fmac_f32_e32 v124, v125, v122
	v_fma_f32 v121, -v121, v124, v123
	v_div_fmas_f32 v121, v121, v122, v124
	v_div_fixup_f32 v120, v121, v120, 1.0
	s_branch .LBB0_239
; __device__ __forceinline__ float siluf(float x) { return x / (1.f + __expf(-x)); }
; __device__ __forceinline__ float sigmf(float x) { return 1.f / (1.f + __expf(-x)); }
; __device__ __forceinline__ void inproj_epilogue(const Params& p, int layer, int mt, int ntile, int tid,
;                                                 f32x16 (&acc)[2][2], unsigned char* smem) {
;     ...
;       if (mode == 2) o = sigmf(v);
.Lsg_12:
	v_mul_f32_e32 v121, 0xbfb8aa3b, v27
	v_exp_f32_e32 v121, v121
	s_nop 0
	v_add_f32_e32 v121, 1.0, v121
	v_div_scale_f32 v122, s[34:35], v121, v121, 1.0
	v_rcp_f32_e32 v123, v122
	v_div_scale_f32 v124, vcc, 1.0, v121, 1.0
	v_fma_f32 v125, -v122, v123, 1.0
	v_fmac_f32_e32 v123, v125, v123
	v_mul_f32_e32 v125, v124, v123
	v_fma_f32 v126, -v122, v125, v124
	v_fmac_f32_e32 v125, v126, v123
	v_fma_f32 v122, -v122, v125, v124
	v_div_fmas_f32 v122, v122, v123, v125
	v_div_fixup_f32 v121, v122, v121, 1.0
	s_branch .LBB0_242
.Lsg_13:
	v_mul_f32_e32 v122, 0xbfb8aa3b, v28
	v_exp_f32_e32 v122, v122
	s_nop 0
	v_add_f32_e32 v122, 1.0, v122
	v_div_scale_f32 v123, s[36:37], v122, v122, 1.0
	v_rcp_f32_e32 v124, v123
	v_div_scale_f32 v125, vcc, 1.0, v122, 1.0
	v_fma_f32 v126, -v123, v124, 1.0
	v_fmac_f32_e32 v124, v126, v124
	v_mul_f32_e32 v126, v125, v124
	v_fma_f32 v127, -v123, v126, v125
	v_fmac_f32_e32 v126, v127, v124
	v_fma_f32 v123, -v123, v126, v125
	v_div_fmas_f32 v123, v123, v124, v126
	v_div_fixup_f32 v122, v123, v122, 1.0
	s_branch .LBB0_245
.Lsg_14:
	v_mul_f32_e32 v123, 0xbfb8aa3b, v29
	v_exp_f32_e32 v123, v123
	s_nop 0
	v_add_f32_e32 v123, 1.0, v123
	v_div_scale_f32 v124, s[38:39], v123, v123, 1.0
	v_rcp_f32_e32 v125, v124
	v_div_scale_f32 v126, vcc, 1.0, v123, 1.0
	v_fma_f32 v127, -v124, v125, 1.0
	v_fmac_f32_e32 v125, v127, v125
	v_mul_f32_e32 v127, v126, v125
	v_fma_f32 v128, -v124, v127, v126
	v_fmac_f32_e32 v127, v128, v125
	v_fma_f32 v124, -v124, v127, v126
	v_div_fmas_f32 v124, v124, v125, v127
	v_div_fixup_f32 v123, v124, v123, 1.0
	s_branch .LBB0_248
.Lsg_15:
	v_mul_f32_e32 v124, 0xbfb8aa3b, v30
	v_exp_f32_e32 v124, v124
	s_nop 0
	v_add_f32_e32 v124, 1.0, v124
	v_div_scale_f32 v125, s[40:41], v124, v124, 1.0
	v_rcp_f32_e32 v126, v125
	v_div_scale_f32 v127, vcc, 1.0, v124, 1.0
	v_fma_f32 v128, -v125, v126, 1.0
	v_fmac_f32_e32 v126, v128, v126
	v_mul_f32_e32 v128, v127, v126
	v_fma_f32 v129, -v125, v128, v127
	v_fmac_f32_e32 v128, v129, v126
	v_fma_f32 v125, -v125, v128, v127
	v_div_fmas_f32 v125, v125, v126, v128
	v_div_fixup_f32 v124, v125, v124, 1.0
	s_branch .LBB0_251
.Lsg_16:
	v_mul_f32_e32 v124, 0xbfb8aa3b, v31
	v_exp_f32_e32 v124, v124
	s_nop 0
	v_add_f32_e32 v124, 1.0, v124
	v_div_scale_f32 v125, vcc, v124, v124, 1.0
	v_rcp_f32_e32 v126, v125
	v_div_scale_f32 v127, vcc, 1.0, v124, 1.0
	v_fma_f32 v128, -v125, v126, 1.0
	v_fmac_f32_e32 v126, v128, v126
	v_mul_f32_e32 v128, v127, v126
	v_fma_f32 v129, -v125, v128, v127
	v_fmac_f32_e32 v128, v129, v126
	v_fma_f32 v125, -v125, v128, v127
	v_div_fmas_f32 v125, v125, v126, v128
	v_div_fixup_f32 v124, v125, v124, 1.0
	s_branch .LBB0_254
.Lsg_17:
	v_mul_f32_e32 v48, 0xbfb8aa3b, v48
	v_exp_f32_e32 v48, v48
	s_nop 0
	v_add_f32_e32 v48, 1.0, v48
	v_div_scale_f32 v124, s[8:9], v48, v48, 1.0
	v_rcp_f32_e32 v125, v124
	v_div_scale_f32 v126, vcc, 1.0, v48, 1.0
	v_fma_f32 v127, -v124, v125, 1.0
	v_fmac_f32_e32 v125, v127, v125
	v_mul_f32_e32 v127, v126, v125
	v_fma_f32 v128, -v124, v127, v126
	v_fmac_f32_e32 v127, v128, v125
	v_fma_f32 v124, -v124, v127, v126
	v_div_fmas_f32 v124, v124, v125, v127
	v_div_fixup_f32 v48, v124, v48, 1.0
	s_branch .LBB0_257
.Lsg_18:
	v_mul_f32_e32 v48, 0xbfb8aa3b, v49
	v_exp_f32_e32 v48, v48
	s_nop 0
	v_add_f32_e32 v48, 1.0, v48
	v_div_scale_f32 v49, s[8:9], v48, v48, 1.0
	v_rcp_f32_e32 v107, v49
	v_div_scale_f32 v124, vcc, 1.0, v48, 1.0
	v_fma_f32 v125, -v49, v107, 1.0
	v_fmac_f32_e32 v107, v125, v107
	v_mul_f32_e32 v125, v124, v107
	v_fma_f32 v126, -v49, v125, v124
	v_fmac_f32_e32 v125, v126, v107
	v_fma_f32 v49, -v49, v125, v124
	v_div_fmas_f32 v49, v49, v107, v125
	v_div_fixup_f32 v48, v49, v48, 1.0
	s_branch .LBB0_260
.Lsg_19:
	v_mul_f32_e32 v48, 0xbfb8aa3b, v50
	v_exp_f32_e32 v48, v48
	s_nop 0
	v_add_f32_e32 v48, 1.0, v48
	v_div_scale_f32 v49, s[8:9], v48, v48, 1.0
	v_rcp_f32_e32 v50, v49
	v_div_scale_f32 v107, vcc, 1.0, v48, 1.0
	v_fma_f32 v110, -v49, v50, 1.0
	v_fmac_f32_e32 v50, v110, v50
	v_mul_f32_e32 v110, v107, v50
	v_fma_f32 v124, -v49, v110, v107
	v_fmac_f32_e32 v110, v124, v50
	v_fma_f32 v49, -v49, v110, v107
	v_div_fmas_f32 v49, v49, v50, v110
	v_div_fixup_f32 v48, v49, v48, 1.0
	s_branch .LBB0_263
.Lsg_20:
	v_mul_f32_e32 v48, 0xbfb8aa3b, v51
	v_exp_f32_e32 v48, v48
	s_nop 0
	v_add_f32_e32 v48, 1.0, v48
	v_div_scale_f32 v49, s[8:9], v48, v48, 1.0
	v_rcp_f32_e32 v50, v49
	v_div_scale_f32 v51, vcc, 1.0, v48, 1.0
	v_fma_f32 v107, -v49, v50, 1.0
	v_fmac_f32_e32 v50, v107, v50
	v_mul_f32_e32 v107, v51, v50
	v_fma_f32 v110, -v49, v107, v51
	v_fmac_f32_e32 v107, v110, v50
	v_fma_f32 v49, -v49, v107, v51
	v_div_fmas_f32 v49, v49, v50, v107
	v_div_fixup_f32 v48, v49, v48, 1.0
	s_branch .LBB0_266
.Lsg_21:
	v_mul_f32_e32 v48, 0xbfb8aa3b, v52
	v_exp_f32_e32 v48, v48
	s_nop 0
	v_add_f32_e32 v48, 1.0, v48
	v_div_scale_f32 v49, s[8:9], v48, v48, 1.0
	v_rcp_f32_e32 v50, v49
	v_div_scale_f32 v51, vcc, 1.0, v48, 1.0
	v_fma_f32 v52, -v49, v50, 1.0
	v_fmac_f32_e32 v50, v52, v50
	v_mul_f32_e32 v52, v51, v50
	v_fma_f32 v107, -v49, v52, v51
	v_fmac_f32_e32 v52, v107, v50
	v_fma_f32 v49, -v49, v52, v51
	v_div_fmas_f32 v49, v49, v50, v52
	v_div_fixup_f32 v48, v49, v48, 1.0
	s_branch .LBB0_269
.Lsg_22:
	v_mul_f32_e32 v48, 0xbfb8aa3b, v53
	v_exp_f32_e32 v48, v48
	s_nop 0
	v_add_f32_e32 v48, 1.0, v48
	v_div_scale_f32 v49, s[8:9], v48, v48, 1.0
	v_rcp_f32_e32 v50, v49
	v_div_scale_f32 v51, vcc, 1.0, v48, 1.0
	v_fma_f32 v52, -v49, v50, 1.0
	v_fmac_f32_e32 v50, v52, v50
	v_mul_f32_e32 v52, v51, v50
	v_fma_f32 v53, -v49, v52, v51
	v_fmac_f32_e32 v52, v53, v50
	v_fma_f32 v49, -v49, v52, v51
	v_div_fmas_f32 v49, v49, v50, v52
	v_div_fixup_f32 v48, v49, v48, 1.0
	s_branch .LBB0_272
; __device__ __forceinline__ float siluf(float x) { return x / (1.f + __expf(-x)); }
; __device__ __forceinline__ float sigmf(float x) { return 1.f / (1.f + __expf(-x)); }
; __device__ __forceinline__ void inproj_epilogue(const Params& p, int layer, int mt, int ntile, int tid,
;                                                 f32x16 (&acc)[2][2], unsigned char* smem) {
;     ...
;       if (mode == 2) o = sigmf(v);
.Lsg_23:
	v_mul_f32_e32 v48, 0xbfb8aa3b, v54
	v_exp_f32_e32 v48, v48
	s_nop 0
	v_add_f32_e32 v48, 1.0, v48
	v_div_scale_f32 v49, s[8:9], v48, v48, 1.0
	v_rcp_f32_e32 v50, v49
	v_div_scale_f32 v51, vcc, 1.0, v48, 1.0
	v_fma_f32 v52, -v49, v50, 1.0
	v_fmac_f32_e32 v50, v52, v50
	v_mul_f32_e32 v52, v51, v50
	v_fma_f32 v53, -v49, v52, v51
	v_fmac_f32_e32 v52, v53, v50
	v_fma_f32 v49, -v49, v52, v51
	v_div_fmas_f32 v49, v49, v50, v52
	v_div_fixup_f32 v48, v49, v48, 1.0
	s_branch .LBB0_275
.Lsg_24:
	v_mul_f32_e32 v48, 0xbfb8aa3b, v55
	v_exp_f32_e32 v48, v48
	s_nop 0
	v_add_f32_e32 v48, 1.0, v48
	v_div_scale_f32 v49, s[8:9], v48, v48, 1.0
	v_rcp_f32_e32 v50, v49
	v_div_scale_f32 v51, vcc, 1.0, v48, 1.0
	v_fma_f32 v52, -v49, v50, 1.0
	v_fmac_f32_e32 v50, v52, v50
	v_mul_f32_e32 v52, v51, v50
	v_fma_f32 v53, -v49, v52, v51
	v_fmac_f32_e32 v52, v53, v50
	v_fma_f32 v49, -v49, v52, v51
	v_div_fmas_f32 v49, v49, v50, v52
	v_div_fixup_f32 v48, v49, v48, 1.0
	s_branch .LBB0_278
.Lsg_25:
	v_mul_f32_e32 v48, 0xbfb8aa3b, v56
	v_exp_f32_e32 v48, v48
	s_nop 0
	v_add_f32_e32 v48, 1.0, v48
	v_div_scale_f32 v49, s[8:9], v48, v48, 1.0
	v_rcp_f32_e32 v50, v49
	v_div_scale_f32 v51, vcc, 1.0, v48, 1.0
	v_fma_f32 v52, -v49, v50, 1.0
	v_fmac_f32_e32 v50, v52, v50
	v_mul_f32_e32 v52, v51, v50
	v_fma_f32 v53, -v49, v52, v51
	v_fmac_f32_e32 v52, v53, v50
	v_fma_f32 v49, -v49, v52, v51
	v_div_fmas_f32 v49, v49, v50, v52
	v_div_fixup_f32 v48, v49, v48, 1.0
	s_branch .LBB0_281
.Lsg_26:
	v_mul_f32_e32 v48, 0xbfb8aa3b, v57
	v_exp_f32_e32 v48, v48
	s_nop 0
	v_add_f32_e32 v48, 1.0, v48
	v_div_scale_f32 v49, s[8:9], v48, v48, 1.0
	v_rcp_f32_e32 v50, v49
	v_div_scale_f32 v51, vcc, 1.0, v48, 1.0
	v_fma_f32 v52, -v49, v50, 1.0
	v_fmac_f32_e32 v50, v52, v50
	v_mul_f32_e32 v52, v51, v50
	v_fma_f32 v53, -v49, v52, v51
	v_fmac_f32_e32 v52, v53, v50
	v_fma_f32 v49, -v49, v52, v51
	v_div_fmas_f32 v49, v49, v50, v52
	v_div_fixup_f32 v48, v49, v48, 1.0
	s_branch .LBB0_284
.Lsg_27:
	v_mul_f32_e32 v48, 0xbfb8aa3b, v58
	v_exp_f32_e32 v48, v48
	s_nop 0
	v_add_f32_e32 v48, 1.0, v48
	v_div_scale_f32 v49, s[8:9], v48, v48, 1.0
	v_rcp_f32_e32 v50, v49
	v_div_scale_f32 v51, vcc, 1.0, v48, 1.0
	v_fma_f32 v52, -v49, v50, 1.0
	v_fmac_f32_e32 v50, v52, v50
	v_mul_f32_e32 v52, v51, v50
	v_fma_f32 v53, -v49, v52, v51
	v_fmac_f32_e32 v52, v53, v50
	v_fma_f32 v49, -v49, v52, v51
	v_div_fmas_f32 v49, v49, v50, v52
	v_div_fixup_f32 v48, v49, v48, 1.0
	s_branch .LBB0_287
.Lsg_28:
	v_mul_f32_e32 v48, 0xbfb8aa3b, v59
	v_exp_f32_e32 v48, v48
	s_nop 0
	v_add_f32_e32 v48, 1.0, v48
	v_div_scale_f32 v49, s[8:9], v48, v48, 1.0
	v_rcp_f32_e32 v50, v49
	v_div_scale_f32 v51, vcc, 1.0, v48, 1.0
	v_fma_f32 v52, -v49, v50, 1.0
	v_fmac_f32_e32 v50, v52, v50
	v_mul_f32_e32 v52, v51, v50
	v_fma_f32 v53, -v49, v52, v51
	v_fmac_f32_e32 v52, v53, v50
	v_fma_f32 v49, -v49, v52, v51
	v_div_fmas_f32 v49, v49, v50, v52
	v_div_fixup_f32 v48, v49, v48, 1.0
	s_branch .LBB0_290
.Lsg_29:
	v_mul_f32_e32 v48, 0xbfb8aa3b, v60
	v_exp_f32_e32 v48, v48
	s_nop 0
	v_add_f32_e32 v48, 1.0, v48
	v_div_scale_f32 v49, s[8:9], v48, v48, 1.0
	v_rcp_f32_e32 v50, v49
	v_div_scale_f32 v51, vcc, 1.0, v48, 1.0
	v_fma_f32 v52, -v49, v50, 1.0
	v_fmac_f32_e32 v50, v52, v50
	v_mul_f32_e32 v52, v51, v50
	v_fma_f32 v53, -v49, v52, v51
	v_fmac_f32_e32 v52, v53, v50
	v_fma_f32 v49, -v49, v52, v51
	v_div_fmas_f32 v49, v49, v50, v52
	v_div_fixup_f32 v48, v49, v48, 1.0
	s_branch .LBB0_293
.Lsg_30:
	v_mul_f32_e32 v48, 0xbfb8aa3b, v61
	v_exp_f32_e32 v48, v48
	s_nop 0
	v_add_f32_e32 v48, 1.0, v48
	v_div_scale_f32 v49, s[8:9], v48, v48, 1.0
	v_rcp_f32_e32 v50, v49
	v_div_scale_f32 v51, vcc, 1.0, v48, 1.0
	v_fma_f32 v52, -v49, v50, 1.0
	v_fmac_f32_e32 v50, v52, v50
	v_mul_f32_e32 v52, v51, v50
	v_fma_f32 v53, -v49, v52, v51
	v_fmac_f32_e32 v52, v53, v50
	v_fma_f32 v49, -v49, v52, v51
	v_div_fmas_f32 v49, v49, v50, v52
	v_div_fixup_f32 v48, v49, v48, 1.0
	s_branch .LBB0_296
.Lsg_31:
	v_mul_f32_e32 v48, 0xbfb8aa3b, v62
	v_exp_f32_e32 v48, v48
	s_nop 0
	v_add_f32_e32 v48, 1.0, v48
	v_div_scale_f32 v49, s[8:9], v48, v48, 1.0
	v_rcp_f32_e32 v50, v49
	v_div_scale_f32 v51, vcc, 1.0, v48, 1.0
	v_fma_f32 v52, -v49, v50, 1.0
	v_fmac_f32_e32 v50, v52, v50
	v_mul_f32_e32 v52, v51, v50
	v_fma_f32 v53, -v49, v52, v51
	v_fmac_f32_e32 v52, v53, v50
	v_fma_f32 v49, -v49, v52, v51
	v_div_fmas_f32 v49, v49, v50, v52
	v_div_fixup_f32 v48, v49, v48, 1.0
	s_branch .LBB0_299
.Lsg_32:
	v_mul_f32_e32 v48, 0xbfb8aa3b, v63
	v_exp_f32_e32 v48, v48
	s_nop 0
	v_add_f32_e32 v48, 1.0, v48
	v_div_scale_f32 v49, s[8:9], v48, v48, 1.0
	v_rcp_f32_e32 v50, v49
	v_div_scale_f32 v51, vcc, 1.0, v48, 1.0
	v_fma_f32 v52, -v49, v50, 1.0
	v_fmac_f32_e32 v50, v52, v50
	v_mul_f32_e32 v52, v51, v50
	v_fma_f32 v53, -v49, v52, v51
	v_fmac_f32_e32 v52, v53, v50
	v_fma_f32 v49, -v49, v52, v51
	v_div_fmas_f32 v49, v49, v50, v52
	v_div_fixup_f32 v48, v49, v48, 1.0
	s_branch .LBB0_302
.Lsg_33:
	v_mul_f32_e32 v49, 0xbfb8aa3b, v0
	v_exp_f32_e32 v49, v49
	s_nop 0
	v_add_f32_e32 v49, 1.0, v49
	v_div_scale_f32 v50, s[10:11], v49, v49, 1.0
	v_rcp_f32_e32 v51, v50
	v_div_scale_f32 v52, vcc, 1.0, v49, 1.0
	v_fma_f32 v53, -v50, v51, 1.0
	v_fmac_f32_e32 v51, v53, v51
	v_mul_f32_e32 v53, v52, v51
	v_fma_f32 v54, -v50, v53, v52
	v_fmac_f32_e32 v53, v54, v51
	v_fma_f32 v50, -v50, v53, v52
	v_div_fmas_f32 v50, v50, v51, v53
	v_div_fixup_f32 v49, v50, v49, 1.0
	s_branch .LBB0_305
.Lsg_34:
	v_mul_f32_e32 v50, 0xbfb8aa3b, v1
	v_exp_f32_e32 v50, v50
	s_nop 0
	v_add_f32_e32 v50, 1.0, v50
	v_div_scale_f32 v51, s[12:13], v50, v50, 1.0
	v_rcp_f32_e32 v52, v51
	v_div_scale_f32 v53, vcc, 1.0, v50, 1.0
	v_fma_f32 v54, -v51, v52, 1.0
	v_fmac_f32_e32 v52, v54, v52
	v_mul_f32_e32 v54, v53, v52
	v_fma_f32 v55, -v51, v54, v53
	v_fmac_f32_e32 v54, v55, v52
	v_fma_f32 v51, -v51, v54, v53
	v_div_fmas_f32 v51, v51, v52, v54
	v_div_fixup_f32 v50, v51, v50, 1.0
	s_branch .LBB0_308
; __device__ __forceinline__ float siluf(float x) { return x / (1.f + __expf(-x)); }
; __device__ __forceinline__ float sigmf(float x) { return 1.f / (1.f + __expf(-x)); }
; __device__ __forceinline__ void inproj_epilogue(const Params& p, int layer, int mt, int ntile, int tid,
;                                                 f32x16 (&acc)[2][2], unsigned char* smem) {
;     ...
;       if (mode == 2) o = sigmf(v);
.Lsg_35:
	v_mul_f32_e32 v51, 0xbfb8aa3b, v2
	v_exp_f32_e32 v51, v51
	s_nop 0
	v_add_f32_e32 v51, 1.0, v51
	v_div_scale_f32 v52, s[14:15], v51, v51, 1.0
	v_rcp_f32_e32 v53, v52
	v_div_scale_f32 v54, vcc, 1.0, v51, 1.0
	v_fma_f32 v55, -v52, v53, 1.0
	v_fmac_f32_e32 v53, v55, v53
	v_mul_f32_e32 v55, v54, v53
	v_fma_f32 v56, -v52, v55, v54
	v_fmac_f32_e32 v55, v56, v53
	v_fma_f32 v52, -v52, v55, v54
	v_div_fmas_f32 v52, v52, v53, v55
	v_div_fixup_f32 v51, v52, v51, 1.0
	s_branch .LBB0_311
.Lsg_36:
	v_mul_f32_e32 v52, 0xbfb8aa3b, v3
	v_exp_f32_e32 v52, v52
	s_nop 0
	v_add_f32_e32 v52, 1.0, v52
	v_div_scale_f32 v53, s[16:17], v52, v52, 1.0
	v_rcp_f32_e32 v54, v53
	v_div_scale_f32 v55, vcc, 1.0, v52, 1.0
	v_fma_f32 v56, -v53, v54, 1.0
	v_fmac_f32_e32 v54, v56, v54
	v_mul_f32_e32 v56, v55, v54
	v_fma_f32 v57, -v53, v56, v55
	v_fmac_f32_e32 v56, v57, v54
	v_fma_f32 v53, -v53, v56, v55
	v_div_fmas_f32 v53, v53, v54, v56
	v_div_fixup_f32 v52, v53, v52, 1.0
	s_branch .LBB0_314
.Lsg_37:
	v_mul_f32_e32 v53, 0xbfb8aa3b, v4
	v_exp_f32_e32 v53, v53
	s_nop 0
	v_add_f32_e32 v53, 1.0, v53
	v_div_scale_f32 v54, s[18:19], v53, v53, 1.0
	v_rcp_f32_e32 v55, v54
	v_div_scale_f32 v56, vcc, 1.0, v53, 1.0
	v_fma_f32 v57, -v54, v55, 1.0
	v_fmac_f32_e32 v55, v57, v55
	v_mul_f32_e32 v57, v56, v55
	v_fma_f32 v58, -v54, v57, v56
	v_fmac_f32_e32 v57, v58, v55
	v_fma_f32 v54, -v54, v57, v56
	v_div_fmas_f32 v54, v54, v55, v57
	v_div_fixup_f32 v53, v54, v53, 1.0
	s_branch .LBB0_317
.Lsg_38:
	v_mul_f32_e32 v54, 0xbfb8aa3b, v5
	v_exp_f32_e32 v54, v54
	s_nop 0
	v_add_f32_e32 v54, 1.0, v54
	v_div_scale_f32 v55, s[20:21], v54, v54, 1.0
	v_rcp_f32_e32 v56, v55
	v_div_scale_f32 v57, vcc, 1.0, v54, 1.0
	v_fma_f32 v58, -v55, v56, 1.0
	v_fmac_f32_e32 v56, v58, v56
	v_mul_f32_e32 v58, v57, v56
	v_fma_f32 v59, -v55, v58, v57
	v_fmac_f32_e32 v58, v59, v56
	v_fma_f32 v55, -v55, v58, v57
	v_div_fmas_f32 v55, v55, v56, v58
	v_div_fixup_f32 v54, v55, v54, 1.0
	s_branch .LBB0_320
.Lsg_39:
	v_mul_f32_e32 v55, 0xbfb8aa3b, v6
	v_exp_f32_e32 v55, v55
	s_nop 0
	v_add_f32_e32 v55, 1.0, v55
	v_div_scale_f32 v56, s[22:23], v55, v55, 1.0
	v_rcp_f32_e32 v57, v56
	v_div_scale_f32 v58, vcc, 1.0, v55, 1.0
	v_fma_f32 v59, -v56, v57, 1.0
	v_fmac_f32_e32 v57, v59, v57
	v_mul_f32_e32 v59, v58, v57
	v_fma_f32 v60, -v56, v59, v58
	v_fmac_f32_e32 v59, v60, v57
	v_fma_f32 v56, -v56, v59, v58
	v_div_fmas_f32 v56, v56, v57, v59
	v_div_fixup_f32 v55, v56, v55, 1.0
	s_branch .LBB0_323
.Lsg_40:
	v_mul_f32_e32 v56, 0xbfb8aa3b, v7
	v_exp_f32_e32 v56, v56
	s_nop 0
	v_add_f32_e32 v56, 1.0, v56
	v_div_scale_f32 v57, s[24:25], v56, v56, 1.0
	v_rcp_f32_e32 v58, v57
	v_div_scale_f32 v59, vcc, 1.0, v56, 1.0
	v_fma_f32 v60, -v57, v58, 1.0
	v_fmac_f32_e32 v58, v60, v58
	v_mul_f32_e32 v60, v59, v58
	v_fma_f32 v61, -v57, v60, v59
	v_fmac_f32_e32 v60, v61, v58
	v_fma_f32 v57, -v57, v60, v59
	v_div_fmas_f32 v57, v57, v58, v60
	v_div_fixup_f32 v56, v57, v56, 1.0
	s_branch .LBB0_326
.Lsg_41:
	v_mul_f32_e32 v57, 0xbfb8aa3b, v8
	v_exp_f32_e32 v57, v57
	s_nop 0
	v_add_f32_e32 v57, 1.0, v57
	v_div_scale_f32 v58, s[26:27], v57, v57, 1.0
	v_rcp_f32_e32 v59, v58
	v_div_scale_f32 v60, vcc, 1.0, v57, 1.0
	v_fma_f32 v61, -v58, v59, 1.0
	v_fmac_f32_e32 v59, v61, v59
	v_mul_f32_e32 v61, v60, v59
	v_fma_f32 v62, -v58, v61, v60
	v_fmac_f32_e32 v61, v62, v59
	v_fma_f32 v58, -v58, v61, v60
	v_div_fmas_f32 v58, v58, v59, v61
	v_div_fixup_f32 v57, v58, v57, 1.0
	s_branch .LBB0_329
.Lsg_42:
	v_mul_f32_e32 v58, 0xbfb8aa3b, v9
	v_exp_f32_e32 v58, v58
	s_nop 0
	v_add_f32_e32 v58, 1.0, v58
	v_div_scale_f32 v59, s[28:29], v58, v58, 1.0
	v_rcp_f32_e32 v60, v59
	v_div_scale_f32 v61, vcc, 1.0, v58, 1.0
	v_fma_f32 v62, -v59, v60, 1.0
	v_fmac_f32_e32 v60, v62, v60
	v_mul_f32_e32 v62, v61, v60
	v_fma_f32 v63, -v59, v62, v61
	v_fmac_f32_e32 v62, v63, v60
	v_fma_f32 v59, -v59, v62, v61
	v_div_fmas_f32 v59, v59, v60, v62
	v_div_fixup_f32 v58, v59, v58, 1.0
	s_branch .LBB0_332
.Lsg_43:
	v_mul_f32_e32 v59, 0xbfb8aa3b, v10
	v_exp_f32_e32 v59, v59
	s_nop 0
	v_add_f32_e32 v59, 1.0, v59
	v_div_scale_f32 v60, s[30:31], v59, v59, 1.0
	v_rcp_f32_e32 v61, v60
	v_div_scale_f32 v62, vcc, 1.0, v59, 1.0
	v_fma_f32 v63, -v60, v61, 1.0
	v_fmac_f32_e32 v61, v63, v61
	v_mul_f32_e32 v63, v62, v61
	v_fma_f32 v107, -v60, v63, v62
	v_fmac_f32_e32 v63, v107, v61
	v_fma_f32 v60, -v60, v63, v62
	v_div_fmas_f32 v60, v60, v61, v63
	v_div_fixup_f32 v59, v60, v59, 1.0
	s_branch .LBB0_335
.Lsg_44:
	v_mul_f32_e32 v60, 0xbfb8aa3b, v11
	v_exp_f32_e32 v60, v60
	s_nop 0
	v_add_f32_e32 v60, 1.0, v60
	v_div_scale_f32 v61, s[34:35], v60, v60, 1.0
	v_rcp_f32_e32 v62, v61
	v_div_scale_f32 v63, vcc, 1.0, v60, 1.0
	v_fma_f32 v107, -v61, v62, 1.0
	v_fmac_f32_e32 v62, v107, v62
	v_mul_f32_e32 v107, v63, v62
	v_fma_f32 v110, -v61, v107, v63
	v_fmac_f32_e32 v107, v110, v62
	v_fma_f32 v61, -v61, v107, v63
	v_div_fmas_f32 v61, v61, v62, v107
	v_div_fixup_f32 v60, v61, v60, 1.0
	s_branch .LBB0_338
.Lsg_45:
	v_mul_f32_e32 v61, 0xbfb8aa3b, v12
	v_exp_f32_e32 v61, v61
	s_nop 0
	v_add_f32_e32 v61, 1.0, v61
	v_div_scale_f32 v62, s[36:37], v61, v61, 1.0
	v_rcp_f32_e32 v63, v62
	v_div_scale_f32 v107, vcc, 1.0, v61, 1.0
	v_fma_f32 v110, -v62, v63, 1.0
	v_fmac_f32_e32 v63, v110, v63
	v_mul_f32_e32 v110, v107, v63
	v_fma_f32 v111, -v62, v110, v107
	v_fmac_f32_e32 v110, v111, v63
	v_fma_f32 v62, -v62, v110, v107
	v_div_fmas_f32 v62, v62, v63, v110
	v_div_fixup_f32 v61, v62, v61, 1.0
	s_branch .LBB0_341
; __device__ __forceinline__ float siluf(float x) { return x / (1.f + __expf(-x)); }
; __device__ __forceinline__ float sigmf(float x) { return 1.f / (1.f + __expf(-x)); }
; __device__ __forceinline__ void inproj_epilogue(const Params& p, int layer, int mt, int ntile, int tid,
;                                                 f32x16 (&acc)[2][2], unsigned char* smem) {
;     ...
;       if (mode == 2) o = sigmf(v);
.Lsg_46:
	v_mul_f32_e32 v62, 0xbfb8aa3b, v13
	v_exp_f32_e32 v62, v62
	s_nop 0
	v_add_f32_e32 v62, 1.0, v62
	v_div_scale_f32 v63, s[38:39], v62, v62, 1.0
	v_rcp_f32_e32 v107, v63
	v_div_scale_f32 v110, vcc, 1.0, v62, 1.0
	v_fma_f32 v111, -v63, v107, 1.0
	v_fmac_f32_e32 v107, v111, v107
	v_mul_f32_e32 v111, v110, v107
	v_fma_f32 v112, -v63, v111, v110
	v_fmac_f32_e32 v111, v112, v107
	v_fma_f32 v63, -v63, v111, v110
	v_div_fmas_f32 v63, v63, v107, v111
	v_div_fixup_f32 v62, v63, v62, 1.0
	s_branch .LBB0_344
.Lsg_47:
	v_mul_f32_e32 v63, 0xbfb8aa3b, v14
	v_exp_f32_e32 v63, v63
	s_nop 0
	v_add_f32_e32 v63, 1.0, v63
	v_div_scale_f32 v107, s[40:41], v63, v63, 1.0
	v_rcp_f32_e32 v110, v107
	v_div_scale_f32 v111, vcc, 1.0, v63, 1.0
	v_fma_f32 v112, -v107, v110, 1.0
	v_fmac_f32_e32 v110, v112, v110
	v_mul_f32_e32 v112, v111, v110
	v_fma_f32 v113, -v107, v112, v111
	v_fmac_f32_e32 v112, v113, v110
	v_fma_f32 v107, -v107, v112, v111
	v_div_fmas_f32 v107, v107, v110, v112
	v_div_fixup_f32 v63, v107, v63, 1.0
	s_branch .LBB0_347
.Lsg_48:
	v_mul_f32_e32 v63, 0xbfb8aa3b, v15
	v_exp_f32_e32 v63, v63
	s_nop 0
	v_add_f32_e32 v63, 1.0, v63
	v_div_scale_f32 v96, vcc, v63, v63, 1.0
	v_rcp_f32_e32 v106, v96
	v_div_scale_f32 v107, vcc, 1.0, v63, 1.0
	v_fma_f32 v110, -v96, v106, 1.0
	v_fmac_f32_e32 v106, v110, v106
	v_mul_f32_e32 v110, v107, v106
	v_fma_f32 v111, -v96, v110, v107
	v_fmac_f32_e32 v110, v111, v106
	v_fma_f32 v96, -v96, v110, v107
	v_div_fmas_f32 v96, v96, v106, v110
	v_div_fixup_f32 v63, v96, v63, 1.0
	s_branch .LBB0_350
.Lsg_49:
	v_mul_f32_e32 v32, 0xbfb8aa3b, v32
	v_exp_f32_e32 v32, v32
	s_nop 0
	v_add_f32_e32 v32, 1.0, v32
	v_div_scale_f32 v63, s[8:9], v32, v32, 1.0
	v_rcp_f32_e32 v96, v63
	v_div_scale_f32 v106, vcc, 1.0, v32, 1.0
	v_fma_f32 v107, -v63, v96, 1.0
	v_fmac_f32_e32 v96, v107, v96
	v_mul_f32_e32 v107, v106, v96
	v_fma_f32 v110, -v63, v107, v106
	v_fmac_f32_e32 v107, v110, v96
	v_fma_f32 v63, -v63, v107, v106
	v_div_fmas_f32 v63, v63, v96, v107
	v_div_fixup_f32 v32, v63, v32, 1.0
	s_branch .LBB0_353
.Lsg_50:
	v_mul_f32_e32 v32, 0xbfb8aa3b, v33
	v_exp_f32_e32 v32, v32
	s_nop 0
	v_add_f32_e32 v32, 1.0, v32
	v_div_scale_f32 v33, s[8:9], v32, v32, 1.0
	v_rcp_f32_e32 v48, v33
	v_div_scale_f32 v63, vcc, 1.0, v32, 1.0
	v_fma_f32 v96, -v33, v48, 1.0
	v_fmac_f32_e32 v48, v96, v48
	v_mul_f32_e32 v96, v63, v48
	v_fma_f32 v106, -v33, v96, v63
	v_fmac_f32_e32 v96, v106, v48
	v_fma_f32 v33, -v33, v96, v63
	v_div_fmas_f32 v33, v33, v48, v96
	v_div_fixup_f32 v32, v33, v32, 1.0
	s_branch .LBB0_356
.Lsg_51:
	v_mul_f32_e32 v32, 0xbfb8aa3b, v34
	v_exp_f32_e32 v32, v32
	s_nop 0
	v_add_f32_e32 v32, 1.0, v32
	v_div_scale_f32 v33, s[8:9], v32, v32, 1.0
	v_rcp_f32_e32 v34, v33
	v_div_scale_f32 v48, vcc, 1.0, v32, 1.0
	v_fma_f32 v49, -v33, v34, 1.0
	v_fmac_f32_e32 v34, v49, v34
	v_mul_f32_e32 v49, v48, v34
	v_fma_f32 v63, -v33, v49, v48
	v_fmac_f32_e32 v49, v63, v34
	v_fma_f32 v33, -v33, v49, v48
	v_div_fmas_f32 v33, v33, v34, v49
	v_div_fixup_f32 v32, v33, v32, 1.0
	s_branch .LBB0_359
.Lsg_52:
	v_mul_f32_e32 v32, 0xbfb8aa3b, v35
	v_exp_f32_e32 v32, v32
	s_nop 0
	v_add_f32_e32 v32, 1.0, v32
	v_div_scale_f32 v33, s[8:9], v32, v32, 1.0
	v_rcp_f32_e32 v34, v33
	v_div_scale_f32 v35, vcc, 1.0, v32, 1.0
	v_fma_f32 v48, -v33, v34, 1.0
	v_fmac_f32_e32 v34, v48, v34
	v_mul_f32_e32 v48, v35, v34
	v_fma_f32 v49, -v33, v48, v35
	v_fmac_f32_e32 v48, v49, v34
	v_fma_f32 v33, -v33, v48, v35
	v_div_fmas_f32 v33, v33, v34, v48
	v_div_fixup_f32 v32, v33, v32, 1.0
	s_branch .LBB0_362
.Lsg_53:
	v_mul_f32_e32 v32, 0xbfb8aa3b, v36
	v_exp_f32_e32 v32, v32
	s_nop 0
	v_add_f32_e32 v32, 1.0, v32
	v_div_scale_f32 v33, s[8:9], v32, v32, 1.0
	v_rcp_f32_e32 v34, v33
	v_div_scale_f32 v35, vcc, 1.0, v32, 1.0
	v_fma_f32 v36, -v33, v34, 1.0
	v_fmac_f32_e32 v34, v36, v34
	v_mul_f32_e32 v36, v35, v34
	v_fma_f32 v48, -v33, v36, v35
	v_fmac_f32_e32 v36, v48, v34
	v_fma_f32 v33, -v33, v36, v35
	v_div_fmas_f32 v33, v33, v34, v36
	v_div_fixup_f32 v32, v33, v32, 1.0
	s_branch .LBB0_365
.Lsg_54:
	v_mul_f32_e32 v32, 0xbfb8aa3b, v37
	v_exp_f32_e32 v32, v32
	s_nop 0
	v_add_f32_e32 v32, 1.0, v32
	v_div_scale_f32 v33, s[8:9], v32, v32, 1.0
	v_rcp_f32_e32 v34, v33
	v_div_scale_f32 v35, vcc, 1.0, v32, 1.0
	v_fma_f32 v36, -v33, v34, 1.0
	v_fmac_f32_e32 v34, v36, v34
	v_mul_f32_e32 v36, v35, v34
	v_fma_f32 v37, -v33, v36, v35
	v_fmac_f32_e32 v36, v37, v34
	v_fma_f32 v33, -v33, v36, v35
	v_div_fmas_f32 v33, v33, v34, v36
	v_div_fixup_f32 v32, v33, v32, 1.0
	s_branch .LBB0_368
; __device__ __forceinline__ float siluf(float x) { return x / (1.f + __expf(-x)); }
; __device__ __forceinline__ float sigmf(float x) { return 1.f / (1.f + __expf(-x)); }
; __device__ __forceinline__ void inproj_epilogue(const Params& p, int layer, int mt, int ntile, int tid,
;                                                 f32x16 (&acc)[2][2], unsigned char* smem) {
;     ...
;       if (mode == 2) o = sigmf(v);
.Lsg_55:
	v_mul_f32_e32 v32, 0xbfb8aa3b, v38
	v_exp_f32_e32 v32, v32
	s_nop 0
	v_add_f32_e32 v32, 1.0, v32
	v_div_scale_f32 v33, s[8:9], v32, v32, 1.0
	v_rcp_f32_e32 v34, v33
	v_div_scale_f32 v35, vcc, 1.0, v32, 1.0
	v_fma_f32 v36, -v33, v34, 1.0
	v_fmac_f32_e32 v34, v36, v34
	v_mul_f32_e32 v36, v35, v34
	v_fma_f32 v37, -v33, v36, v35
	v_fmac_f32_e32 v36, v37, v34
	v_fma_f32 v33, -v33, v36, v35
	v_div_fmas_f32 v33, v33, v34, v36
	v_div_fixup_f32 v32, v33, v32, 1.0
	s_branch .LBB0_371
.Lsg_56:
	v_mul_f32_e32 v32, 0xbfb8aa3b, v39
	v_exp_f32_e32 v32, v32
	s_nop 0
	v_add_f32_e32 v32, 1.0, v32
	v_div_scale_f32 v33, s[8:9], v32, v32, 1.0
	v_rcp_f32_e32 v34, v33
	v_div_scale_f32 v35, vcc, 1.0, v32, 1.0
	v_fma_f32 v36, -v33, v34, 1.0
	v_fmac_f32_e32 v34, v36, v34
	v_mul_f32_e32 v36, v35, v34
	v_fma_f32 v37, -v33, v36, v35
	v_fmac_f32_e32 v36, v37, v34
	v_fma_f32 v33, -v33, v36, v35
	v_div_fmas_f32 v33, v33, v34, v36
	v_div_fixup_f32 v32, v33, v32, 1.0
	s_branch .LBB0_374
.Lsg_57:
	v_mul_f32_e32 v32, 0xbfb8aa3b, v40
	v_exp_f32_e32 v32, v32
	s_nop 0
	v_add_f32_e32 v32, 1.0, v32
	v_div_scale_f32 v33, s[8:9], v32, v32, 1.0
	v_rcp_f32_e32 v34, v33
	v_div_scale_f32 v35, vcc, 1.0, v32, 1.0
	v_fma_f32 v36, -v33, v34, 1.0
	v_fmac_f32_e32 v34, v36, v34
	v_mul_f32_e32 v36, v35, v34
	v_fma_f32 v37, -v33, v36, v35
	v_fmac_f32_e32 v36, v37, v34
	v_fma_f32 v33, -v33, v36, v35
	v_div_fmas_f32 v33, v33, v34, v36
	v_div_fixup_f32 v32, v33, v32, 1.0
	s_branch .LBB0_377
.Lsg_58:
	v_mul_f32_e32 v32, 0xbfb8aa3b, v41
	v_exp_f32_e32 v32, v32
	s_nop 0
	v_add_f32_e32 v32, 1.0, v32
	v_div_scale_f32 v33, s[8:9], v32, v32, 1.0
	v_rcp_f32_e32 v34, v33
	v_div_scale_f32 v35, vcc, 1.0, v32, 1.0
	v_fma_f32 v36, -v33, v34, 1.0
	v_fmac_f32_e32 v34, v36, v34
	v_mul_f32_e32 v36, v35, v34
	v_fma_f32 v37, -v33, v36, v35
	v_fmac_f32_e32 v36, v37, v34
	v_fma_f32 v33, -v33, v36, v35
	v_div_fmas_f32 v33, v33, v34, v36
	v_div_fixup_f32 v32, v33, v32, 1.0
	s_branch .LBB0_380
.Lsg_59:
	v_mul_f32_e32 v32, 0xbfb8aa3b, v42
	v_exp_f32_e32 v32, v32
	s_nop 0
	v_add_f32_e32 v32, 1.0, v32
	v_div_scale_f32 v33, s[8:9], v32, v32, 1.0
	v_rcp_f32_e32 v34, v33
	v_div_scale_f32 v35, vcc, 1.0, v32, 1.0
	v_fma_f32 v36, -v33, v34, 1.0
	v_fmac_f32_e32 v34, v36, v34
	v_mul_f32_e32 v36, v35, v34
	v_fma_f32 v37, -v33, v36, v35
	v_fmac_f32_e32 v36, v37, v34
	v_fma_f32 v33, -v33, v36, v35
	v_div_fmas_f32 v33, v33, v34, v36
	v_div_fixup_f32 v32, v33, v32, 1.0
	s_branch .LBB0_383
.Lsg_60:
	v_mul_f32_e32 v32, 0xbfb8aa3b, v43
	v_exp_f32_e32 v32, v32
	s_nop 0
	v_add_f32_e32 v32, 1.0, v32
	v_div_scale_f32 v33, s[8:9], v32, v32, 1.0
	v_rcp_f32_e32 v34, v33
	v_div_scale_f32 v35, vcc, 1.0, v32, 1.0
	v_fma_f32 v36, -v33, v34, 1.0
	v_fmac_f32_e32 v34, v36, v34
	v_mul_f32_e32 v36, v35, v34
	v_fma_f32 v37, -v33, v36, v35
	v_fmac_f32_e32 v36, v37, v34
	v_fma_f32 v33, -v33, v36, v35
	v_div_fmas_f32 v33, v33, v34, v36
	v_div_fixup_f32 v32, v33, v32, 1.0
	s_branch .LBB0_386
.Lsg_61:
	v_mul_f32_e32 v32, 0xbfb8aa3b, v44
	v_exp_f32_e32 v32, v32
	s_nop 0
	v_add_f32_e32 v32, 1.0, v32
	v_div_scale_f32 v33, s[8:9], v32, v32, 1.0
	v_rcp_f32_e32 v34, v33
	v_div_scale_f32 v35, vcc, 1.0, v32, 1.0
	v_fma_f32 v36, -v33, v34, 1.0
	v_fmac_f32_e32 v34, v36, v34
	v_mul_f32_e32 v36, v35, v34
	v_fma_f32 v37, -v33, v36, v35
	v_fmac_f32_e32 v36, v37, v34
	v_fma_f32 v33, -v33, v36, v35
	v_div_fmas_f32 v33, v33, v34, v36
	v_div_fixup_f32 v32, v33, v32, 1.0
	s_branch .LBB0_389
.Lsg_62:
	v_mul_f32_e32 v32, 0xbfb8aa3b, v45
	v_exp_f32_e32 v32, v32
	s_nop 0
	v_add_f32_e32 v32, 1.0, v32
	v_div_scale_f32 v33, s[8:9], v32, v32, 1.0
	v_rcp_f32_e32 v34, v33
	v_div_scale_f32 v35, vcc, 1.0, v32, 1.0
	v_fma_f32 v36, -v33, v34, 1.0
	v_fmac_f32_e32 v34, v36, v34
	v_mul_f32_e32 v36, v35, v34
	v_fma_f32 v37, -v33, v36, v35
	v_fmac_f32_e32 v36, v37, v34
	v_fma_f32 v33, -v33, v36, v35
	v_div_fmas_f32 v33, v33, v34, v36
	v_div_fixup_f32 v32, v33, v32, 1.0
	s_branch .LBB0_392
.Lsg_63:
	v_mul_f32_e32 v32, 0xbfb8aa3b, v46
	v_exp_f32_e32 v32, v32
	s_nop 0
	v_add_f32_e32 v32, 1.0, v32
	v_div_scale_f32 v33, s[8:9], v32, v32, 1.0
	v_rcp_f32_e32 v34, v33
	v_div_scale_f32 v35, vcc, 1.0, v32, 1.0
	v_fma_f32 v36, -v33, v34, 1.0
	v_fmac_f32_e32 v34, v36, v34
	v_mul_f32_e32 v36, v35, v34
	v_fma_f32 v37, -v33, v36, v35
	v_fmac_f32_e32 v36, v37, v34
	v_fma_f32 v33, -v33, v36, v35
	v_div_fmas_f32 v33, v33, v34, v36
	v_div_fixup_f32 v32, v33, v32, 1.0
	s_branch .LBB0_395
.Lsg_64:
	v_mul_f32_e32 v32, 0xbfb8aa3b, v47
	v_exp_f32_e32 v32, v32
	s_nop 0
	v_add_f32_e32 v32, 1.0, v32
	v_div_scale_f32 v33, s[4:5], v32, v32, 1.0
	v_rcp_f32_e32 v34, v33
	v_div_scale_f32 v35, vcc, 1.0, v32, 1.0
	v_fma_f32 v36, -v33, v34, 1.0
	v_fmac_f32_e32 v34, v36, v34
	v_mul_f32_e32 v36, v35, v34
	v_fma_f32 v37, -v33, v36, v35
	v_fmac_f32_e32 v36, v37, v34
	v_fma_f32 v33, -v33, v36, v35
	v_div_fmas_f32 v33, v33, v34, v36
	v_div_fixup_f32 v32, v33, v32, 1.0
	s_branch .LBB0_398

; __device__ __forceinline__ float sigmf(float x) { return 1.f / (1.f + __expf(-x)); }
; __device__ __forceinline__ float softplusf(float x) { return fmaxf(x, 0.f) + __logf(1.f + __expf(-fabsf(x))); }
; template <int MT, int NT, class F>
; __device__ __forceinline__ void acc_foreach(int tid, f32x16 (&acc)[MT][NT], F f) {
;     ...
;         int row = wm * (MT * 32) + mt * 32 + (i & 3) + 8 * (i >> 2) + 4 * hi;
; __device__ __forceinline__ void inproj_epilogue(const Params& p, int layer, int mt, int ntile, int tid,
;                                                 f32x16 (&acc)[2][2], unsigned char* smem) {
;     ...
;   const int m0 = mt * 128;
;   if (mode == 3) {
;     float* dt = (float*)(p.ws + OFF_DT) + (size_t)m0 * 16;
;     const float* bias = p.ssd_dt_bias + layer * 16;
;     acc_foreach(tid, acc, [&](int row, int col, float v) {
;       if (col < 16) *(dt + row * 16 + col) = softplusf(v + bias[col]);
;     });
;   } else {
;     bf16r* dstb = dst + (size_t)m0 * ld + c0;
;     bf16r* sT = (bf16r*)smem;
;     acc_foreach(tid, acc, [&](int row, int col, float v) {
;       int t = m0 + row;
;       float o = v;
;       if (mode == 1) o = (t >= NPADR) ? v : 0.f;
;       if (mode == 2) o = sigmf(v);
;       sT[row * 136 + col] = f2bf(o);
;     });
.LBB0_524:
	s_lshl_b32 s90, s6, 7
	s_ashr_i32 s91, s90, 31
	s_cmp_lg_u32 s7, 3
	s_mov_b64 s[4:5], -1
	s_cbranch_scc0 .LBB0_718
	v_mov_b32_e32 v106, v108
	s_movk_i32 s4, 0xffc0
	v_lshrrev_b32_e32 v107, 3, v106
	v_ashrrev_i32_e32 v96, 1, v106
	v_and_b32_e32 v107, 4, v107
	v_and_or_b32 v96, v96, s4, v107
	s_cmp_eq_u32 s7, 1
	s_cselect_b64 s[4:5], -1, 0
	v_add_u32_e32 v107, s90, v96
	s_cmp_eq_u32 s7, 2
	s_cselect_b64 s[12:13], -1, 0
	s_cmp_lg_u32 s7, 2
	v_cmp_lt_i32_e64 s[8:9], s76, v107
	s_cbranch_scc0 .Lsg_65

; __device__ __forceinline__ float sigmf(float x) { return 1.f / (1.f + __expf(-x)); }
; template <int MT, int NT, class F>
; __device__ __forceinline__ void acc_foreach(int tid, f32x16 (&acc)[MT][NT], F f) {
;     ...
;         int row = wm * (MT * 32) + mt * 32 + (i & 3) + 8 * (i >> 2) + 4 * hi;
;         int col = wn * (NT * 32) + nt * 32 + c;
; __device__ __forceinline__ void inproj_epilogue(const Params& p, int layer, int mt, int ntile, int tid,
;                                                 f32x16 (&acc)[2][2], unsigned char* smem) {
;     ...
;       if (mode == 2) o = sigmf(v);
;       sT[row * 136 + col] = f2bf(o);
.LBB0_528:
	v_bfe_u32 v110, v107, 16, 1
	v_and_b32_e32 v106, 0x5f, v106
	v_add3_u32 v111, v107, v110, s78
	v_mul_lo_u32 v110, v96, s79
	v_lshl_add_u32 v107, v106, 1, v110
	ds_write_b16_d16_hi v107, v111
	v_add3_u32 v111, s90, v96, 1
	v_cmp_lt_i32_e64 s[10:11], s76, v111
	v_cndmask_b32_e64 v111, 0, 1, s[12:13]
	v_cmp_ne_u32_e64 s[6:7], 1, v111
	s_andn2_b64 vcc, exec, s[12:13]
	s_cbranch_vccz .Lsg_66

; __device__ __forceinline__ float sigmf(float x) { return 1.f / (1.f + __expf(-x)); }
; template <int MT, int NT, class F>
; __device__ __forceinline__ void acc_foreach(int tid, f32x16 (&acc)[MT][NT], F f) {
;     ...
;         int row = wm * (MT * 32) + mt * 32 + (i & 3) + 8 * (i >> 2) + 4 * hi;
;         int col = wn * (NT * 32) + nt * 32 + c;
; __device__ __forceinline__ void inproj_epilogue(const Params& p, int layer, int mt, int ntile, int tid,
;                                                 f32x16 (&acc)[2][2], unsigned char* smem) {
;     ...
;       if (mode == 2) o = sigmf(v);
;       sT[row * 136 + col] = f2bf(o);
.LBB0_531:
	v_bfe_u32 v112, v111, 16, 1
	v_add3_u32 v112, v111, v112, s78
	v_add_u32_e32 v111, 0x110, v110
	v_lshl_add_u32 v110, v106, 1, v111
	ds_write_b16_d16_hi v110, v112
	v_add3_u32 v112, s90, v96, 2
	s_and_b64 vcc, exec, s[6:7]
	v_cmp_lt_i32_e64 s[12:13], s76, v112
	s_cbranch_vccz .Lsg_67

; __device__ __forceinline__ float sigmf(float x) { return 1.f / (1.f + __expf(-x)); }
; template <int MT, int NT, class F>
; __device__ __forceinline__ void acc_foreach(int tid, f32x16 (&acc)[MT][NT], F f) {
;     ...
;         int row = wm * (MT * 32) + mt * 32 + (i & 3) + 8 * (i >> 2) + 4 * hi;
;         int col = wn * (NT * 32) + nt * 32 + c;
; __device__ __forceinline__ void inproj_epilogue(const Params& p, int layer, int mt, int ntile, int tid,
;                                                 f32x16 (&acc)[2][2], unsigned char* smem) {
;     ...
;       if (mode == 2) o = sigmf(v);
;       sT[row * 136 + col] = f2bf(o);
.LBB0_534:
	v_bfe_u32 v113, v112, 16, 1
	v_add3_u32 v113, v112, v113, s78
	v_add_u32_e32 v112, 0x110, v111
	v_lshl_add_u32 v111, v106, 1, v112
	ds_write_b16_d16_hi v111, v113
	v_add3_u32 v113, s90, v96, 3
	s_and_b64 vcc, exec, s[6:7]
	v_cmp_lt_i32_e64 s[14:15], s76, v113
	s_cbranch_vccz .Lsg_68

; __device__ __forceinline__ float sigmf(float x) { return 1.f / (1.f + __expf(-x)); }
; template <int MT, int NT, class F>
; __device__ __forceinline__ void acc_foreach(int tid, f32x16 (&acc)[MT][NT], F f) {
;     ...
;         int row = wm * (MT * 32) + mt * 32 + (i & 3) + 8 * (i >> 2) + 4 * hi;
;         int col = wn * (NT * 32) + nt * 32 + c;
; __device__ __forceinline__ void inproj_epilogue(const Params& p, int layer, int mt, int ntile, int tid,
;                                                 f32x16 (&acc)[2][2], unsigned char* smem) {
;     ...
;       if (mode == 2) o = sigmf(v);
;       sT[row * 136 + col] = f2bf(o);
.LBB0_537:
	v_bfe_u32 v114, v113, 16, 1
	v_add3_u32 v114, v113, v114, s78
	v_add_u32_e32 v113, 0x110, v112
	v_lshl_add_u32 v112, v106, 1, v113
	ds_write_b16_d16_hi v112, v114
	v_add3_u32 v114, s90, v96, 8
	s_and_b64 vcc, exec, s[6:7]
	v_cmp_lt_i32_e64 s[16:17], s76, v114
	s_cbranch_vccz .Lsg_69

; __device__ __forceinline__ float sigmf(float x) { return 1.f / (1.f + __expf(-x)); }
; template <int MT, int NT, class F>
; __device__ __forceinline__ void acc_foreach(int tid, f32x16 (&acc)[MT][NT], F f) {
;     ...
;         int row = wm * (MT * 32) + mt * 32 + (i & 3) + 8 * (i >> 2) + 4 * hi;
;         int col = wn * (NT * 32) + nt * 32 + c;
; __device__ __forceinline__ void inproj_epilogue(const Params& p, int layer, int mt, int ntile, int tid,
;                                                 f32x16 (&acc)[2][2], unsigned char* smem) {
;     ...
;       if (mode == 2) o = sigmf(v);
;       sT[row * 136 + col] = f2bf(o);
.LBB0_540:
	v_bfe_u32 v115, v114, 16, 1
	v_add3_u32 v115, v114, v115, s78
	v_add_u32_e32 v114, 0x550, v113
	v_lshl_add_u32 v113, v106, 1, v114
	ds_write_b16_d16_hi v113, v115
	v_add3_u32 v115, s90, v96, 9
	s_and_b64 vcc, exec, s[6:7]
	v_cmp_lt_i32_e64 s[18:19], s76, v115
	s_cbranch_vccz .Lsg_70

; __device__ __forceinline__ float sigmf(float x) { return 1.f / (1.f + __expf(-x)); }
; template <int MT, int NT, class F>
; __device__ __forceinline__ void acc_foreach(int tid, f32x16 (&acc)[MT][NT], F f) {
;     ...
;         int row = wm * (MT * 32) + mt * 32 + (i & 3) + 8 * (i >> 2) + 4 * hi;
;         int col = wn * (NT * 32) + nt * 32 + c;
; __device__ __forceinline__ void inproj_epilogue(const Params& p, int layer, int mt, int ntile, int tid,
;                                                 f32x16 (&acc)[2][2], unsigned char* smem) {
;     ...
;       if (mode == 2) o = sigmf(v);
;       sT[row * 136 + col] = f2bf(o);
.LBB0_543:
	v_bfe_u32 v116, v115, 16, 1
	v_add3_u32 v116, v115, v116, s78
	v_add_u32_e32 v115, 0x110, v114
	v_lshl_add_u32 v114, v106, 1, v115
	ds_write_b16_d16_hi v114, v116
	v_add3_u32 v116, s90, v96, 10
	s_and_b64 vcc, exec, s[6:7]
	v_cmp_lt_i32_e64 s[20:21], s76, v116
	s_cbranch_vccz .Lsg_71

; __device__ __forceinline__ float sigmf(float x) { return 1.f / (1.f + __expf(-x)); }
; template <int MT, int NT, class F>
; __device__ __forceinline__ void acc_foreach(int tid, f32x16 (&acc)[MT][NT], F f) {
;     ...
;         int row = wm * (MT * 32) + mt * 32 + (i & 3) + 8 * (i >> 2) + 4 * hi;
;         int col = wn * (NT * 32) + nt * 32 + c;
; __device__ __forceinline__ void inproj_epilogue(const Params& p, int layer, int mt, int ntile, int tid,
;                                                 f32x16 (&acc)[2][2], unsigned char* smem) {
;     ...
;       if (mode == 2) o = sigmf(v);
;       sT[row * 136 + col] = f2bf(o);
.LBB0_546:
	v_bfe_u32 v117, v116, 16, 1
	v_add3_u32 v117, v116, v117, s78
	v_add_u32_e32 v116, 0x110, v115
	v_lshl_add_u32 v115, v106, 1, v116
	ds_write_b16_d16_hi v115, v117
	v_add3_u32 v117, s90, v96, 11
	s_and_b64 vcc, exec, s[6:7]
	v_cmp_lt_i32_e64 s[22:23], s76, v117
	s_cbranch_vccz .Lsg_72

; __device__ __forceinline__ float sigmf(float x) { return 1.f / (1.f + __expf(-x)); }
; template <int MT, int NT, class F>
; __device__ __forceinline__ void acc_foreach(int tid, f32x16 (&acc)[MT][NT], F f) {
;     ...
;         int row = wm * (MT * 32) + mt * 32 + (i & 3) + 8 * (i >> 2) + 4 * hi;
;         int col = wn * (NT * 32) + nt * 32 + c;
; __device__ __forceinline__ void inproj_epilogue(const Params& p, int layer, int mt, int ntile, int tid,
;                                                 f32x16 (&acc)[2][2], unsigned char* smem) {
;     ...
;       if (mode == 2) o = sigmf(v);
;       sT[row * 136 + col] = f2bf(o);
.LBB0_549:
	v_bfe_u32 v118, v117, 16, 1
	v_add_u32_e32 v116, 0x110, v116
	v_add3_u32 v118, v117, v118, s78
	v_lshl_add_u32 v117, v106, 1, v116
	ds_write_b16_d16_hi v117, v118
	v_add3_u32 v118, s90, v96, 16
	s_and_b64 vcc, exec, s[6:7]
	v_cmp_lt_i32_e64 s[24:25], s76, v118
	s_cbranch_vccz .Lsg_73

; __device__ __forceinline__ float sigmf(float x) { return 1.f / (1.f + __expf(-x)); }
; template <int MT, int NT, class F>
; __device__ __forceinline__ void acc_foreach(int tid, f32x16 (&acc)[MT][NT], F f) {
;     ...
;         int row = wm * (MT * 32) + mt * 32 + (i & 3) + 8 * (i >> 2) + 4 * hi;
;         int col = wn * (NT * 32) + nt * 32 + c;
; __device__ __forceinline__ void inproj_epilogue(const Params& p, int layer, int mt, int ntile, int tid,
;                                                 f32x16 (&acc)[2][2], unsigned char* smem) {
;     ...
;       if (mode == 2) o = sigmf(v);
;       sT[row * 136 + col] = f2bf(o);
.LBB0_552:
	v_bfe_u32 v119, v118, 16, 1
	v_add_u32_e32 v116, 0x550, v116
	v_add3_u32 v119, v118, v119, s78
	v_lshl_add_u32 v118, v106, 1, v116
	ds_write_b16_d16_hi v118, v119
	v_add3_u32 v119, s90, v96, 17
	s_and_b64 vcc, exec, s[6:7]
	v_cmp_lt_i32_e64 s[26:27], s76, v119
	s_cbranch_vccz .Lsg_74

; __device__ __forceinline__ float sigmf(float x) { return 1.f / (1.f + __expf(-x)); }
; template <int MT, int NT, class F>
; __device__ __forceinline__ void acc_foreach(int tid, f32x16 (&acc)[MT][NT], F f) {
;     ...
;         int row = wm * (MT * 32) + mt * 32 + (i & 3) + 8 * (i >> 2) + 4 * hi;
;         int col = wn * (NT * 32) + nt * 32 + c;
; __device__ __forceinline__ void inproj_epilogue(const Params& p, int layer, int mt, int ntile, int tid,
;                                                 f32x16 (&acc)[2][2], unsigned char* smem) {
;     ...
;       if (mode == 2) o = sigmf(v);
;       sT[row * 136 + col] = f2bf(o);
.LBB0_555:
	v_bfe_u32 v120, v119, 16, 1
	v_add_u32_e32 v116, 0x110, v116
	v_add3_u32 v120, v119, v120, s78
	v_lshl_add_u32 v119, v106, 1, v116
	ds_write_b16_d16_hi v119, v120
	v_add3_u32 v120, s90, v96, 18
	s_and_b64 vcc, exec, s[6:7]
	v_cmp_lt_i32_e64 s[28:29], s76, v120
	s_cbranch_vccz .Lsg_75

; __device__ __forceinline__ float sigmf(float x) { return 1.f / (1.f + __expf(-x)); }
; template <int MT, int NT, class F>
; __device__ __forceinline__ void acc_foreach(int tid, f32x16 (&acc)[MT][NT], F f) {
;     ...
;         int row = wm * (MT * 32) + mt * 32 + (i & 3) + 8 * (i >> 2) + 4 * hi;
;         int col = wn * (NT * 32) + nt * 32 + c;
; __device__ __forceinline__ void inproj_epilogue(const Params& p, int layer, int mt, int ntile, int tid,
;                                                 f32x16 (&acc)[2][2], unsigned char* smem) {
;     ...
;       if (mode == 2) o = sigmf(v);
;       sT[row * 136 + col] = f2bf(o);
.LBB0_558:
	v_bfe_u32 v121, v120, 16, 1
	v_add_u32_e32 v116, 0x110, v116
	v_add3_u32 v121, v120, v121, s78
	v_lshl_add_u32 v120, v106, 1, v116
	ds_write_b16_d16_hi v120, v121
	v_add3_u32 v121, s90, v96, 19
	s_and_b64 vcc, exec, s[6:7]
	v_cmp_lt_i32_e64 s[30:31], s76, v121
	s_cbranch_vccz .Lsg_76

; __device__ __forceinline__ float sigmf(float x) { return 1.f / (1.f + __expf(-x)); }
; template <int MT, int NT, class F>
; __device__ __forceinline__ void acc_foreach(int tid, f32x16 (&acc)[MT][NT], F f) {
;     ...
;         int row = wm * (MT * 32) + mt * 32 + (i & 3) + 8 * (i >> 2) + 4 * hi;
;         int col = wn * (NT * 32) + nt * 32 + c;
; __device__ __forceinline__ void inproj_epilogue(const Params& p, int layer, int mt, int ntile, int tid,
;                                                 f32x16 (&acc)[2][2], unsigned char* smem) {
;     ...
;       if (mode == 2) o = sigmf(v);
;       sT[row * 136 + col] = f2bf(o);
.LBB0_561:
	v_bfe_u32 v122, v121, 16, 1
	v_add_u32_e32 v116, 0x110, v116
	v_add3_u32 v122, v121, v122, s78
	v_lshl_add_u32 v121, v106, 1, v116
	ds_write_b16_d16_hi v121, v122
	v_add3_u32 v122, s90, v96, 24
	s_and_b64 vcc, exec, s[6:7]
	v_cmp_lt_i32_e64 s[34:35], s76, v122
	s_cbranch_vccz .Lsg_77

; __device__ __forceinline__ float sigmf(float x) { return 1.f / (1.f + __expf(-x)); }
; template <int MT, int NT, class F>
; __device__ __forceinline__ void acc_foreach(int tid, f32x16 (&acc)[MT][NT], F f) {
;     ...
;         int row = wm * (MT * 32) + mt * 32 + (i & 3) + 8 * (i >> 2) + 4 * hi;
;         int col = wn * (NT * 32) + nt * 32 + c;
; __device__ __forceinline__ void inproj_epilogue(const Params& p, int layer, int mt, int ntile, int tid,
;                                                 f32x16 (&acc)[2][2], unsigned char* smem) {
;     ...
;       if (mode == 2) o = sigmf(v);
;       sT[row * 136 + col] = f2bf(o);
.LBB0_564:
	v_bfe_u32 v123, v122, 16, 1
	v_add_u32_e32 v116, 0x550, v116
	v_add3_u32 v123, v122, v123, s78
	v_lshl_add_u32 v122, v106, 1, v116
	ds_write_b16_d16_hi v122, v123
	v_add3_u32 v123, s90, v96, 25
	s_and_b64 vcc, exec, s[6:7]
	v_cmp_lt_i32_e64 s[36:37], s76, v123
	s_cbranch_vccz .Lsg_78

; __device__ __forceinline__ float sigmf(float x) { return 1.f / (1.f + __expf(-x)); }
; template <int MT, int NT, class F>
; __device__ __forceinline__ void acc_foreach(int tid, f32x16 (&acc)[MT][NT], F f) {
;     ...
;         int row = wm * (MT * 32) + mt * 32 + (i & 3) + 8 * (i >> 2) + 4 * hi;
;         int col = wn * (NT * 32) + nt * 32 + c;
; __device__ __forceinline__ void inproj_epilogue(const Params& p, int layer, int mt, int ntile, int tid,
;                                                 f32x16 (&acc)[2][2], unsigned char* smem) {
;     ...
;       if (mode == 2) o = sigmf(v);
;       sT[row * 136 + col] = f2bf(o);
.LBB0_567:
	v_bfe_u32 v124, v123, 16, 1
	v_add_u32_e32 v116, 0x110, v116
	v_add3_u32 v124, v123, v124, s78
	v_lshl_add_u32 v123, v106, 1, v116
	ds_write_b16_d16_hi v123, v124
	v_add3_u32 v124, s90, v96, 26
	s_and_b64 vcc, exec, s[6:7]
	v_cmp_lt_i32_e64 s[38:39], s76, v124
	s_cbranch_vccz .Lsg_79

; __device__ __forceinline__ float sigmf(float x) { return 1.f / (1.f + __expf(-x)); }
; template <int MT, int NT, class F>
; __device__ __forceinline__ void acc_foreach(int tid, f32x16 (&acc)[MT][NT], F f) {
;     ...
;         int row = wm * (MT * 32) + mt * 32 + (i & 3) + 8 * (i >> 2) + 4 * hi;
;         int col = wn * (NT * 32) + nt * 32 + c;
; __device__ __forceinline__ void inproj_epilogue(const Params& p, int layer, int mt, int ntile, int tid,
;                                                 f32x16 (&acc)[2][2], unsigned char* smem) {
;     ...
;       if (mode == 2) o = sigmf(v);
;       sT[row * 136 + col] = f2bf(o);
.LBB0_570:
	v_bfe_u32 v125, v124, 16, 1
	v_add_u32_e32 v116, 0x110, v116
	v_add3_u32 v124, v124, v125, s78
	v_lshl_add_u32 v116, v106, 1, v116
	ds_write_b16_d16_hi v116, v124
	v_add3_u32 v124, s90, v96, 27
	s_and_b64 vcc, exec, s[6:7]
	v_cmp_lt_i32_e64 s[40:41], s76, v124
	s_cbranch_vccz .Lsg_80

; __device__ __forceinline__ float sigmf(float x) { return 1.f / (1.f + __expf(-x)); }
; template <int MT, int NT, class F>
; __device__ __forceinline__ void acc_foreach(int tid, f32x16 (&acc)[MT][NT], F f) {
;     ...
;         int row = wm * (MT * 32) + mt * 32 + (i & 3) + 8 * (i >> 2) + 4 * hi;
;         int col = wn * (NT * 32) + nt * 32 + c;
; __device__ __forceinline__ void inproj_epilogue(const Params& p, int layer, int mt, int ntile, int tid,
;                                                 f32x16 (&acc)[2][2], unsigned char* smem) {
;     ...
;       if (mode == 2) o = sigmf(v);
;       sT[row * 136 + col] = f2bf(o);
.LBB0_573:
	v_bfe_u32 v125, v124, 16, 1
	v_add3_u32 v124, v124, v125, s78
	ds_write_b16_d16_hi v116, v124 offset:272
	s_and_b64 vcc, exec, s[6:7]
	s_cbranch_vccz .Lsg_81

; __device__ __forceinline__ float sigmf(float x) { return 1.f / (1.f + __expf(-x)); }
; template <int MT, int NT, class F>
; __device__ __forceinline__ void acc_foreach(int tid, f32x16 (&acc)[MT][NT], F f) {
;     ...
;         int row = wm * (MT * 32) + mt * 32 + (i & 3) + 8 * (i >> 2) + 4 * hi;
;         int col = wn * (NT * 32) + nt * 32 + c;
; __device__ __forceinline__ void inproj_epilogue(const Params& p, int layer, int mt, int ntile, int tid,
;                                                 f32x16 (&acc)[2][2], unsigned char* smem) {
;     ...
;       if (mode == 2) o = sigmf(v);
;       sT[row * 136 + col] = f2bf(o);
.LBB0_576:
	v_bfe_u32 v124, v48, 16, 1
	v_add3_u32 v48, v48, v124, s78
	s_and_b64 vcc, exec, s[6:7]
	ds_write_b16_d16_hi v107, v48 offset:64
	s_cbranch_vccz .Lsg_82

; __device__ __forceinline__ float sigmf(float x) { return 1.f / (1.f + __expf(-x)); }
; template <int MT, int NT, class F>
; __device__ __forceinline__ void acc_foreach(int tid, f32x16 (&acc)[MT][NT], F f) {
;     ...
;         int row = wm * (MT * 32) + mt * 32 + (i & 3) + 8 * (i >> 2) + 4 * hi;
;         int col = wn * (NT * 32) + nt * 32 + c;
; __device__ __forceinline__ void inproj_epilogue(const Params& p, int layer, int mt, int ntile, int tid,
;                                                 f32x16 (&acc)[2][2], unsigned char* smem) {
;     ...
;       if (mode == 2) o = sigmf(v);
;       sT[row * 136 + col] = f2bf(o);
.LBB0_579:
	v_bfe_u32 v49, v48, 16, 1
	v_add3_u32 v48, v48, v49, s78
	s_and_b64 vcc, exec, s[6:7]
	ds_write_b16_d16_hi v110, v48 offset:64
	s_cbranch_vccz .Lsg_83

; __device__ __forceinline__ float sigmf(float x) { return 1.f / (1.f + __expf(-x)); }
; template <int MT, int NT, class F>
; __device__ __forceinline__ void acc_foreach(int tid, f32x16 (&acc)[MT][NT], F f) {
;     ...
;         int row = wm * (MT * 32) + mt * 32 + (i & 3) + 8 * (i >> 2) + 4 * hi;
;         int col = wn * (NT * 32) + nt * 32 + c;
; __device__ __forceinline__ void inproj_epilogue(const Params& p, int layer, int mt, int ntile, int tid,
;                                                 f32x16 (&acc)[2][2], unsigned char* smem) {
;     ...
;       if (mode == 2) o = sigmf(v);
;       sT[row * 136 + col] = f2bf(o);
.LBB0_582:
	v_bfe_u32 v49, v48, 16, 1
	v_add3_u32 v48, v48, v49, s78
	s_and_b64 vcc, exec, s[6:7]
	ds_write_b16_d16_hi v111, v48 offset:64
	s_cbranch_vccz .Lsg_84

; __device__ __forceinline__ float sigmf(float x) { return 1.f / (1.f + __expf(-x)); }
; template <int MT, int NT, class F>
; __device__ __forceinline__ void acc_foreach(int tid, f32x16 (&acc)[MT][NT], F f) {
;     ...
;         int row = wm * (MT * 32) + mt * 32 + (i & 3) + 8 * (i >> 2) + 4 * hi;
;         int col = wn * (NT * 32) + nt * 32 + c;
; __device__ __forceinline__ void inproj_epilogue(const Params& p, int layer, int mt, int ntile, int tid,
;                                                 f32x16 (&acc)[2][2], unsigned char* smem) {
;     ...
;       if (mode == 2) o = sigmf(v);
;       sT[row * 136 + col] = f2bf(o);
.LBB0_585:
	v_bfe_u32 v49, v48, 16, 1
	v_add3_u32 v48, v48, v49, s78
	s_and_b64 vcc, exec, s[6:7]
	ds_write_b16_d16_hi v112, v48 offset:64
	s_cbranch_vccz .Lsg_85

; __device__ __forceinline__ float sigmf(float x) { return 1.f / (1.f + __expf(-x)); }
; template <int MT, int NT, class F>
; __device__ __forceinline__ void acc_foreach(int tid, f32x16 (&acc)[MT][NT], F f) {
;     ...
;         int row = wm * (MT * 32) + mt * 32 + (i & 3) + 8 * (i >> 2) + 4 * hi;
;         int col = wn * (NT * 32) + nt * 32 + c;
; __device__ __forceinline__ void inproj_epilogue(const Params& p, int layer, int mt, int ntile, int tid,
;                                                 f32x16 (&acc)[2][2], unsigned char* smem) {
;     ...
;       if (mode == 2) o = sigmf(v);
;       sT[row * 136 + col] = f2bf(o);
.LBB0_588:
	v_bfe_u32 v49, v48, 16, 1
	v_add3_u32 v48, v48, v49, s78
	s_and_b64 vcc, exec, s[6:7]
	ds_write_b16_d16_hi v113, v48 offset:64
	s_cbranch_vccz .Lsg_86

; __device__ __forceinline__ float sigmf(float x) { return 1.f / (1.f + __expf(-x)); }
; template <int MT, int NT, class F>
; __device__ __forceinline__ void acc_foreach(int tid, f32x16 (&acc)[MT][NT], F f) {
;     ...
;         int row = wm * (MT * 32) + mt * 32 + (i & 3) + 8 * (i >> 2) + 4 * hi;
;         int col = wn * (NT * 32) + nt * 32 + c;
; __device__ __forceinline__ void inproj_epilogue(const Params& p, int layer, int mt, int ntile, int tid,
;                                                 f32x16 (&acc)[2][2], unsigned char* smem) {
;     ...
;       if (mode == 2) o = sigmf(v);
;       sT[row * 136 + col] = f2bf(o);
.LBB0_591:
	v_bfe_u32 v49, v48, 16, 1
	v_add3_u32 v48, v48, v49, s78
	s_and_b64 vcc, exec, s[6:7]
	ds_write_b16_d16_hi v114, v48 offset:64
	s_cbranch_vccz .Lsg_87

; __device__ __forceinline__ float sigmf(float x) { return 1.f / (1.f + __expf(-x)); }
; template <int MT, int NT, class F>
; __device__ __forceinline__ void acc_foreach(int tid, f32x16 (&acc)[MT][NT], F f) {
;     ...
;         int row = wm * (MT * 32) + mt * 32 + (i & 3) + 8 * (i >> 2) + 4 * hi;
;         int col = wn * (NT * 32) + nt * 32 + c;
; __device__ __forceinline__ void inproj_epilogue(const Params& p, int layer, int mt, int ntile, int tid,
;                                                 f32x16 (&acc)[2][2], unsigned char* smem) {
;     ...
;       if (mode == 2) o = sigmf(v);
;       sT[row * 136 + col] = f2bf(o);
.LBB0_594:
	v_bfe_u32 v49, v48, 16, 1
	v_add3_u32 v48, v48, v49, s78
	s_and_b64 vcc, exec, s[6:7]
	ds_write_b16_d16_hi v115, v48 offset:64
	s_cbranch_vccz .Lsg_88

; __device__ __forceinline__ float sigmf(float x) { return 1.f / (1.f + __expf(-x)); }
; template <int MT, int NT, class F>
; __device__ __forceinline__ void acc_foreach(int tid, f32x16 (&acc)[MT][NT], F f) {
;     ...
;         int row = wm * (MT * 32) + mt * 32 + (i & 3) + 8 * (i >> 2) + 4 * hi;
;         int col = wn * (NT * 32) + nt * 32 + c;
; __device__ __forceinline__ void inproj_epilogue(const Params& p, int layer, int mt, int ntile, int tid,
;                                                 f32x16 (&acc)[2][2], unsigned char* smem) {
;     ...
;       if (mode == 2) o = sigmf(v);
;       sT[row * 136 + col] = f2bf(o);
.LBB0_597:
	v_bfe_u32 v49, v48, 16, 1
	v_add3_u32 v48, v48, v49, s78
	s_and_b64 vcc, exec, s[6:7]
	ds_write_b16_d16_hi v117, v48 offset:64
	s_cbranch_vccz .Lsg_89

; __device__ __forceinline__ float sigmf(float x) { return 1.f / (1.f + __expf(-x)); }
; template <int MT, int NT, class F>
; __device__ __forceinline__ void acc_foreach(int tid, f32x16 (&acc)[MT][NT], F f) {
;     ...
;         int row = wm * (MT * 32) + mt * 32 + (i & 3) + 8 * (i >> 2) + 4 * hi;
;         int col = wn * (NT * 32) + nt * 32 + c;
; __device__ __forceinline__ void inproj_epilogue(const Params& p, int layer, int mt, int ntile, int tid,
;                                                 f32x16 (&acc)[2][2], unsigned char* smem) {
;     ...
;       if (mode == 2) o = sigmf(v);
;       sT[row * 136 + col] = f2bf(o);
.LBB0_600:
	v_bfe_u32 v49, v48, 16, 1
	v_add3_u32 v48, v48, v49, s78
	s_and_b64 vcc, exec, s[6:7]
	ds_write_b16_d16_hi v118, v48 offset:64
	s_cbranch_vccz .Lsg_90

; __device__ __forceinline__ float sigmf(float x) { return 1.f / (1.f + __expf(-x)); }
; template <int MT, int NT, class F>
; __device__ __forceinline__ void acc_foreach(int tid, f32x16 (&acc)[MT][NT], F f) {
;     ...
;         int row = wm * (MT * 32) + mt * 32 + (i & 3) + 8 * (i >> 2) + 4 * hi;
;         int col = wn * (NT * 32) + nt * 32 + c;
; __device__ __forceinline__ void inproj_epilogue(const Params& p, int layer, int mt, int ntile, int tid,
;                                                 f32x16 (&acc)[2][2], unsigned char* smem) {
;     ...
;       if (mode == 2) o = sigmf(v);
;       sT[row * 136 + col] = f2bf(o);
.LBB0_603:
	v_bfe_u32 v49, v48, 16, 1
	v_add3_u32 v48, v48, v49, s78
	s_and_b64 vcc, exec, s[6:7]
	ds_write_b16_d16_hi v119, v48 offset:64
	s_cbranch_vccz .Lsg_91

; __device__ __forceinline__ float sigmf(float x) { return 1.f / (1.f + __expf(-x)); }
; template <int MT, int NT, class F>
; __device__ __forceinline__ void acc_foreach(int tid, f32x16 (&acc)[MT][NT], F f) {
;     ...
;         int row = wm * (MT * 32) + mt * 32 + (i & 3) + 8 * (i >> 2) + 4 * hi;
;         int col = wn * (NT * 32) + nt * 32 + c;
; __device__ __forceinline__ void inproj_epilogue(const Params& p, int layer, int mt, int ntile, int tid,
;                                                 f32x16 (&acc)[2][2], unsigned char* smem) {
;     ...
;       if (mode == 2) o = sigmf(v);
;       sT[row * 136 + col] = f2bf(o);
.LBB0_606:
	v_bfe_u32 v49, v48, 16, 1
	v_add3_u32 v48, v48, v49, s78
	s_and_b64 vcc, exec, s[6:7]
	ds_write_b16_d16_hi v120, v48 offset:64
	s_cbranch_vccz .Lsg_92

; __device__ __forceinline__ float sigmf(float x) { return 1.f / (1.f + __expf(-x)); }
; template <int MT, int NT, class F>
; __device__ __forceinline__ void acc_foreach(int tid, f32x16 (&acc)[MT][NT], F f) {
;     ...
;         int row = wm * (MT * 32) + mt * 32 + (i & 3) + 8 * (i >> 2) + 4 * hi;
;         int col = wn * (NT * 32) + nt * 32 + c;
; __device__ __forceinline__ void inproj_epilogue(const Params& p, int layer, int mt, int ntile, int tid,
;                                                 f32x16 (&acc)[2][2], unsigned char* smem) {
;     ...
;       if (mode == 2) o = sigmf(v);
;       sT[row * 136 + col] = f2bf(o);
.LBB0_609:
	v_bfe_u32 v49, v48, 16, 1
	v_add3_u32 v48, v48, v49, s78
	s_and_b64 vcc, exec, s[6:7]
	ds_write_b16_d16_hi v121, v48 offset:64
	s_cbranch_vccz .Lsg_93

; __device__ __forceinline__ float sigmf(float x) { return 1.f / (1.f + __expf(-x)); }
; template <int MT, int NT, class F>
; __device__ __forceinline__ void acc_foreach(int tid, f32x16 (&acc)[MT][NT], F f) {
;     ...
;         int row = wm * (MT * 32) + mt * 32 + (i & 3) + 8 * (i >> 2) + 4 * hi;
;         int col = wn * (NT * 32) + nt * 32 + c;
; __device__ __forceinline__ void inproj_epilogue(const Params& p, int layer, int mt, int ntile, int tid,
;                                                 f32x16 (&acc)[2][2], unsigned char* smem) {
;     ...
;       if (mode == 2) o = sigmf(v);
;       sT[row * 136 + col] = f2bf(o);
.LBB0_612:
	v_bfe_u32 v49, v48, 16, 1
	v_add3_u32 v48, v48, v49, s78
	s_and_b64 vcc, exec, s[6:7]
	ds_write_b16_d16_hi v122, v48 offset:64
	s_cbranch_vccz .Lsg_94

; __device__ __forceinline__ float sigmf(float x) { return 1.f / (1.f + __expf(-x)); }
; template <int MT, int NT, class F>
; __device__ __forceinline__ void acc_foreach(int tid, f32x16 (&acc)[MT][NT], F f) {
;     ...
;         int row = wm * (MT * 32) + mt * 32 + (i & 3) + 8 * (i >> 2) + 4 * hi;
;         int col = wn * (NT * 32) + nt * 32 + c;
; __device__ __forceinline__ void inproj_epilogue(const Params& p, int layer, int mt, int ntile, int tid,
;                                                 f32x16 (&acc)[2][2], unsigned char* smem) {
;     ...
;       if (mode == 2) o = sigmf(v);
;       sT[row * 136 + col] = f2bf(o);
.LBB0_615:
	v_bfe_u32 v49, v48, 16, 1
	v_add3_u32 v48, v48, v49, s78
	s_and_b64 vcc, exec, s[6:7]
	ds_write_b16_d16_hi v123, v48 offset:64
	s_cbranch_vccz .Lsg_95

; __device__ __forceinline__ float sigmf(float x) { return 1.f / (1.f + __expf(-x)); }
; template <int MT, int NT, class F>
; __device__ __forceinline__ void acc_foreach(int tid, f32x16 (&acc)[MT][NT], F f) {
;     ...
;         int row = wm * (MT * 32) + mt * 32 + (i & 3) + 8 * (i >> 2) + 4 * hi;
;         int col = wn * (NT * 32) + nt * 32 + c;
; __device__ __forceinline__ void inproj_epilogue(const Params& p, int layer, int mt, int ntile, int tid,
;                                                 f32x16 (&acc)[2][2], unsigned char* smem) {
;     ...
;       if (mode == 2) o = sigmf(v);
;       sT[row * 136 + col] = f2bf(o);
.LBB0_618:
	v_bfe_u32 v49, v48, 16, 1
	v_add3_u32 v48, v48, v49, s78
	s_and_b64 vcc, exec, s[6:7]
	ds_write_b16_d16_hi v116, v48 offset:64
	s_cbranch_vccz .Lsg_96

; __device__ __forceinline__ float sigmf(float x) { return 1.f / (1.f + __expf(-x)); }
; template <int MT, int NT, class F>
; __device__ __forceinline__ void acc_foreach(int tid, f32x16 (&acc)[MT][NT], F f) {
;     ...
;         int row = wm * (MT * 32) + mt * 32 + (i & 3) + 8 * (i >> 2) + 4 * hi;
;         int col = wn * (NT * 32) + nt * 32 + c;
; __device__ __forceinline__ void inproj_epilogue(const Params& p, int layer, int mt, int ntile, int tid,
;                                                 f32x16 (&acc)[2][2], unsigned char* smem) {
;     ...
;       if (mode == 2) o = sigmf(v);
;       sT[row * 136 + col] = f2bf(o);
.LBB0_621:
	v_bfe_u32 v50, v48, 16, 1
	v_add_u32_e32 v49, 0x110, v116
	v_add3_u32 v48, v48, v50, s78
	ds_write_b16_d16_hi v49, v48 offset:64
	v_or_b32_e32 v48, 32, v96
	v_add_u32_e32 v49, s90, v48
	s_and_b64 vcc, exec, s[6:7]
	v_cmp_lt_i32_e64 s[8:9], s76, v49
	s_cbranch_vccz .Lsg_97

; __device__ __forceinline__ float sigmf(float x) { return 1.f / (1.f + __expf(-x)); }
; template <int MT, int NT, class F>
; __device__ __forceinline__ void acc_foreach(int tid, f32x16 (&acc)[MT][NT], F f) {
;     ...
;         int row = wm * (MT * 32) + mt * 32 + (i & 3) + 8 * (i >> 2) + 4 * hi;
;         int col = wn * (NT * 32) + nt * 32 + c;
; __device__ __forceinline__ void inproj_epilogue(const Params& p, int layer, int mt, int ntile, int tid,
;                                                 f32x16 (&acc)[2][2], unsigned char* smem) {
;     ...
;       if (mode == 2) o = sigmf(v);
;       sT[row * 136 + col] = f2bf(o);
.LBB0_624:
	v_bfe_u32 v50, v49, 16, 1
	v_add3_u32 v50, v49, v50, s78
	v_mul_lo_u32 v49, v48, s79
	v_lshl_add_u32 v48, v106, 1, v49
	ds_write_b16_d16_hi v48, v50
	v_add3_u32 v50, s90, v96, 33
	s_and_b64 vcc, exec, s[6:7]
	v_cmp_lt_i32_e64 s[10:11], s76, v50
	s_cbranch_vccz .Lsg_98

; __device__ __forceinline__ float sigmf(float x) { return 1.f / (1.f + __expf(-x)); }
; template <int MT, int NT, class F>
; __device__ __forceinline__ void acc_foreach(int tid, f32x16 (&acc)[MT][NT], F f) {
;     ...
;         int row = wm * (MT * 32) + mt * 32 + (i & 3) + 8 * (i >> 2) + 4 * hi;
;         int col = wn * (NT * 32) + nt * 32 + c;
; __device__ __forceinline__ void inproj_epilogue(const Params& p, int layer, int mt, int ntile, int tid,
;                                                 f32x16 (&acc)[2][2], unsigned char* smem) {
;     ...
;       if (mode == 2) o = sigmf(v);
;       sT[row * 136 + col] = f2bf(o);
.LBB0_627:
	v_bfe_u32 v51, v50, 16, 1
	v_add3_u32 v51, v50, v51, s78
	v_add_u32_e32 v50, 0x110, v49
	v_lshl_add_u32 v49, v106, 1, v50
	ds_write_b16_d16_hi v49, v51
	v_add3_u32 v51, s90, v96, 34
	s_and_b64 vcc, exec, s[6:7]
	v_cmp_lt_i32_e64 s[12:13], s76, v51
	s_cbranch_vccz .Lsg_99

; __device__ __forceinline__ float sigmf(float x) { return 1.f / (1.f + __expf(-x)); }
; template <int MT, int NT, class F>
; __device__ __forceinline__ void acc_foreach(int tid, f32x16 (&acc)[MT][NT], F f) {
;     ...
;         int row = wm * (MT * 32) + mt * 32 + (i & 3) + 8 * (i >> 2) + 4 * hi;
;         int col = wn * (NT * 32) + nt * 32 + c;
; __device__ __forceinline__ void inproj_epilogue(const Params& p, int layer, int mt, int ntile, int tid,
;                                                 f32x16 (&acc)[2][2], unsigned char* smem) {
;     ...
;       if (mode == 2) o = sigmf(v);
;       sT[row * 136 + col] = f2bf(o);
.LBB0_630:
	v_bfe_u32 v52, v51, 16, 1
	v_add3_u32 v52, v51, v52, s78
	v_add_u32_e32 v51, 0x110, v50
	v_lshl_add_u32 v50, v106, 1, v51
	ds_write_b16_d16_hi v50, v52
	v_add3_u32 v52, s90, v96, 35
	s_and_b64 vcc, exec, s[6:7]
	v_cmp_lt_i32_e64 s[14:15], s76, v52
	s_cbranch_vccz .Lsg_100

; __device__ __forceinline__ float sigmf(float x) { return 1.f / (1.f + __expf(-x)); }
; template <int MT, int NT, class F>
; __device__ __forceinline__ void acc_foreach(int tid, f32x16 (&acc)[MT][NT], F f) {
;     ...
;         int row = wm * (MT * 32) + mt * 32 + (i & 3) + 8 * (i >> 2) + 4 * hi;
;         int col = wn * (NT * 32) + nt * 32 + c;
; __device__ __forceinline__ void inproj_epilogue(const Params& p, int layer, int mt, int ntile, int tid,
;                                                 f32x16 (&acc)[2][2], unsigned char* smem) {
;     ...
;       if (mode == 2) o = sigmf(v);
;       sT[row * 136 + col] = f2bf(o);
.LBB0_633:
	v_bfe_u32 v53, v52, 16, 1
	v_add3_u32 v53, v52, v53, s78
	v_add_u32_e32 v52, 0x110, v51
	v_lshl_add_u32 v51, v106, 1, v52
	ds_write_b16_d16_hi v51, v53
	v_add3_u32 v53, s90, v96, 40
	s_and_b64 vcc, exec, s[6:7]
	v_cmp_lt_i32_e64 s[16:17], s76, v53
	s_cbranch_vccz .Lsg_101

; __device__ __forceinline__ float sigmf(float x) { return 1.f / (1.f + __expf(-x)); }
; template <int MT, int NT, class F>
; __device__ __forceinline__ void acc_foreach(int tid, f32x16 (&acc)[MT][NT], F f) {
;     ...
;         int row = wm * (MT * 32) + mt * 32 + (i & 3) + 8 * (i >> 2) + 4 * hi;
;         int col = wn * (NT * 32) + nt * 32 + c;
; __device__ __forceinline__ void inproj_epilogue(const Params& p, int layer, int mt, int ntile, int tid,
;                                                 f32x16 (&acc)[2][2], unsigned char* smem) {
;     ...
;       if (mode == 2) o = sigmf(v);
;       sT[row * 136 + col] = f2bf(o);
.LBB0_636:
	v_bfe_u32 v54, v53, 16, 1
	v_add3_u32 v54, v53, v54, s78
	v_add_u32_e32 v53, 0x550, v52
	v_lshl_add_u32 v52, v106, 1, v53
	ds_write_b16_d16_hi v52, v54
	v_add3_u32 v54, s90, v96, 41
	s_and_b64 vcc, exec, s[6:7]
	v_cmp_lt_i32_e64 s[18:19], s76, v54
	s_cbranch_vccz .Lsg_102

; __device__ __forceinline__ float sigmf(float x) { return 1.f / (1.f + __expf(-x)); }
; template <int MT, int NT, class F>
; __device__ __forceinline__ void acc_foreach(int tid, f32x16 (&acc)[MT][NT], F f) {
;     ...
;         int row = wm * (MT * 32) + mt * 32 + (i & 3) + 8 * (i >> 2) + 4 * hi;
;         int col = wn * (NT * 32) + nt * 32 + c;
; __device__ __forceinline__ void inproj_epilogue(const Params& p, int layer, int mt, int ntile, int tid,
;                                                 f32x16 (&acc)[2][2], unsigned char* smem) {
;     ...
;       if (mode == 2) o = sigmf(v);
;       sT[row * 136 + col] = f2bf(o);
.LBB0_639:
	v_bfe_u32 v55, v54, 16, 1
	v_add3_u32 v55, v54, v55, s78
	v_add_u32_e32 v54, 0x110, v53
	v_lshl_add_u32 v53, v106, 1, v54
	ds_write_b16_d16_hi v53, v55
	v_add3_u32 v55, s90, v96, 42
	s_and_b64 vcc, exec, s[6:7]
	v_cmp_lt_i32_e64 s[20:21], s76, v55
	s_cbranch_vccz .Lsg_103

; __device__ __forceinline__ float sigmf(float x) { return 1.f / (1.f + __expf(-x)); }
; template <int MT, int NT, class F>
; __device__ __forceinline__ void acc_foreach(int tid, f32x16 (&acc)[MT][NT], F f) {
;     ...
;         int row = wm * (MT * 32) + mt * 32 + (i & 3) + 8 * (i >> 2) + 4 * hi;
;         int col = wn * (NT * 32) + nt * 32 + c;
; __device__ __forceinline__ void inproj_epilogue(const Params& p, int layer, int mt, int ntile, int tid,
;                                                 f32x16 (&acc)[2][2], unsigned char* smem) {
;     ...
;       if (mode == 2) o = sigmf(v);
;       sT[row * 136 + col] = f2bf(o);
.LBB0_642:
	v_bfe_u32 v56, v55, 16, 1
	v_add3_u32 v56, v55, v56, s78
	v_add_u32_e32 v55, 0x110, v54
	v_lshl_add_u32 v54, v106, 1, v55
	ds_write_b16_d16_hi v54, v56
	v_add3_u32 v56, s90, v96, 43
	s_and_b64 vcc, exec, s[6:7]
	v_cmp_lt_i32_e64 s[22:23], s76, v56
	s_cbranch_vccz .Lsg_104

; __device__ __forceinline__ float sigmf(float x) { return 1.f / (1.f + __expf(-x)); }
; template <int MT, int NT, class F>
; __device__ __forceinline__ void acc_foreach(int tid, f32x16 (&acc)[MT][NT], F f) {
;     ...
;         int row = wm * (MT * 32) + mt * 32 + (i & 3) + 8 * (i >> 2) + 4 * hi;
;         int col = wn * (NT * 32) + nt * 32 + c;
; __device__ __forceinline__ void inproj_epilogue(const Params& p, int layer, int mt, int ntile, int tid,
;                                                 f32x16 (&acc)[2][2], unsigned char* smem) {
;     ...
;       if (mode == 2) o = sigmf(v);
;       sT[row * 136 + col] = f2bf(o);
.LBB0_645:
	v_bfe_u32 v57, v56, 16, 1
	v_add_u32_e32 v55, 0x110, v55
	v_add3_u32 v57, v56, v57, s78
	v_lshl_add_u32 v56, v106, 1, v55
	ds_write_b16_d16_hi v56, v57
	v_add3_u32 v57, s90, v96, 48
	s_and_b64 vcc, exec, s[6:7]
	v_cmp_lt_i32_e64 s[24:25], s76, v57
	s_cbranch_vccz .Lsg_105

; __device__ __forceinline__ float sigmf(float x) { return 1.f / (1.f + __expf(-x)); }
; template <int MT, int NT, class F>
; __device__ __forceinline__ void acc_foreach(int tid, f32x16 (&acc)[MT][NT], F f) {
;     ...
;         int row = wm * (MT * 32) + mt * 32 + (i & 3) + 8 * (i >> 2) + 4 * hi;
;         int col = wn * (NT * 32) + nt * 32 + c;
; __device__ __forceinline__ void inproj_epilogue(const Params& p, int layer, int mt, int ntile, int tid,
;                                                 f32x16 (&acc)[2][2], unsigned char* smem) {
;     ...
;       if (mode == 2) o = sigmf(v);
;       sT[row * 136 + col] = f2bf(o);
.LBB0_648:
	v_bfe_u32 v58, v57, 16, 1
	v_add_u32_e32 v55, 0x550, v55
	v_add3_u32 v58, v57, v58, s78
	v_lshl_add_u32 v57, v106, 1, v55
	ds_write_b16_d16_hi v57, v58
	v_add3_u32 v58, s90, v96, 49
	s_and_b64 vcc, exec, s[6:7]
	v_cmp_lt_i32_e64 s[26:27], s76, v58
	s_cbranch_vccz .Lsg_106

; __device__ __forceinline__ float sigmf(float x) { return 1.f / (1.f + __expf(-x)); }
; template <int MT, int NT, class F>
; __device__ __forceinline__ void acc_foreach(int tid, f32x16 (&acc)[MT][NT], F f) {
;     ...
;         int row = wm * (MT * 32) + mt * 32 + (i & 3) + 8 * (i >> 2) + 4 * hi;
;         int col = wn * (NT * 32) + nt * 32 + c;
; __device__ __forceinline__ void inproj_epilogue(const Params& p, int layer, int mt, int ntile, int tid,
;                                                 f32x16 (&acc)[2][2], unsigned char* smem) {
;     ...
;       if (mode == 2) o = sigmf(v);
;       sT[row * 136 + col] = f2bf(o);
.LBB0_651:
	v_bfe_u32 v59, v58, 16, 1
	v_add_u32_e32 v55, 0x110, v55
	v_add3_u32 v59, v58, v59, s78
	v_lshl_add_u32 v58, v106, 1, v55
	ds_write_b16_d16_hi v58, v59
	v_add3_u32 v59, s90, v96, 50
	s_and_b64 vcc, exec, s[6:7]
	v_cmp_lt_i32_e64 s[28:29], s76, v59
	s_cbranch_vccz .Lsg_107

; __device__ __forceinline__ float sigmf(float x) { return 1.f / (1.f + __expf(-x)); }
; template <int MT, int NT, class F>
; __device__ __forceinline__ void acc_foreach(int tid, f32x16 (&acc)[MT][NT], F f) {
;     ...
;         int row = wm * (MT * 32) + mt * 32 + (i & 3) + 8 * (i >> 2) + 4 * hi;
;         int col = wn * (NT * 32) + nt * 32 + c;
; __device__ __forceinline__ void inproj_epilogue(const Params& p, int layer, int mt, int ntile, int tid,
;                                                 f32x16 (&acc)[2][2], unsigned char* smem) {
;     ...
;       if (mode == 2) o = sigmf(v);
;       sT[row * 136 + col] = f2bf(o);
.LBB0_654:
	v_bfe_u32 v60, v59, 16, 1
	v_add_u32_e32 v55, 0x110, v55
	v_add3_u32 v60, v59, v60, s78
	v_lshl_add_u32 v59, v106, 1, v55
	ds_write_b16_d16_hi v59, v60
	v_add3_u32 v60, s90, v96, 51
	s_and_b64 vcc, exec, s[6:7]
	v_cmp_lt_i32_e64 s[30:31], s76, v60
	s_cbranch_vccz .Lsg_108

; __device__ __forceinline__ float sigmf(float x) { return 1.f / (1.f + __expf(-x)); }
; template <int MT, int NT, class F>
; __device__ __forceinline__ void acc_foreach(int tid, f32x16 (&acc)[MT][NT], F f) {
;     ...
;         int row = wm * (MT * 32) + mt * 32 + (i & 3) + 8 * (i >> 2) + 4 * hi;
;         int col = wn * (NT * 32) + nt * 32 + c;
; __device__ __forceinline__ void inproj_epilogue(const Params& p, int layer, int mt, int ntile, int tid,
;                                                 f32x16 (&acc)[2][2], unsigned char* smem) {
;     ...
;       if (mode == 2) o = sigmf(v);
;       sT[row * 136 + col] = f2bf(o);
.LBB0_657:
	v_bfe_u32 v61, v60, 16, 1
	v_add_u32_e32 v55, 0x110, v55
	v_add3_u32 v61, v60, v61, s78
	v_lshl_add_u32 v60, v106, 1, v55
	ds_write_b16_d16_hi v60, v61
	v_add3_u32 v61, s90, v96, 56
	s_and_b64 vcc, exec, s[6:7]
	v_cmp_lt_i32_e64 s[34:35], s76, v61
	s_cbranch_vccz .Lsg_109

; __device__ __forceinline__ float sigmf(float x) { return 1.f / (1.f + __expf(-x)); }
; template <int MT, int NT, class F>
; __device__ __forceinline__ void acc_foreach(int tid, f32x16 (&acc)[MT][NT], F f) {
;     ...
;         int row = wm * (MT * 32) + mt * 32 + (i & 3) + 8 * (i >> 2) + 4 * hi;
;         int col = wn * (NT * 32) + nt * 32 + c;
; __device__ __forceinline__ void inproj_epilogue(const Params& p, int layer, int mt, int ntile, int tid,
;                                                 f32x16 (&acc)[2][2], unsigned char* smem) {
;     ...
;       if (mode == 2) o = sigmf(v);
;       sT[row * 136 + col] = f2bf(o);
.LBB0_660:
	v_bfe_u32 v62, v61, 16, 1
	v_add_u32_e32 v55, 0x550, v55
	v_add3_u32 v62, v61, v62, s78
	v_lshl_add_u32 v61, v106, 1, v55
	ds_write_b16_d16_hi v61, v62
	v_add3_u32 v62, s90, v96, 57
	s_and_b64 vcc, exec, s[6:7]
	v_cmp_lt_i32_e64 s[36:37], s76, v62
	s_cbranch_vccz .Lsg_110

; __device__ __forceinline__ float sigmf(float x) { return 1.f / (1.f + __expf(-x)); }
; template <int MT, int NT, class F>
; __device__ __forceinline__ void acc_foreach(int tid, f32x16 (&acc)[MT][NT], F f) {
;     ...
;         int row = wm * (MT * 32) + mt * 32 + (i & 3) + 8 * (i >> 2) + 4 * hi;
;         int col = wn * (NT * 32) + nt * 32 + c;
; __device__ __forceinline__ void inproj_epilogue(const Params& p, int layer, int mt, int ntile, int tid,
;                                                 f32x16 (&acc)[2][2], unsigned char* smem) {
;     ...
;       if (mode == 2) o = sigmf(v);
;       sT[row * 136 + col] = f2bf(o);
.LBB0_663:
	v_bfe_u32 v63, v62, 16, 1
	v_add_u32_e32 v55, 0x110, v55
	v_add3_u32 v63, v62, v63, s78
	v_lshl_add_u32 v62, v106, 1, v55
	ds_write_b16_d16_hi v62, v63
	v_add3_u32 v63, s90, v96, 58
	s_and_b64 vcc, exec, s[6:7]
	v_cmp_lt_i32_e64 s[38:39], s76, v63
	s_cbranch_vccz .Lsg_111

; __device__ __forceinline__ float sigmf(float x) { return 1.f / (1.f + __expf(-x)); }
; template <int MT, int NT, class F>
; __device__ __forceinline__ void acc_foreach(int tid, f32x16 (&acc)[MT][NT], F f) {
;     ...
;         int row = wm * (MT * 32) + mt * 32 + (i & 3) + 8 * (i >> 2) + 4 * hi;
;         int col = wn * (NT * 32) + nt * 32 + c;
; __device__ __forceinline__ void inproj_epilogue(const Params& p, int layer, int mt, int ntile, int tid,
;                                                 f32x16 (&acc)[2][2], unsigned char* smem) {
;     ...
;       if (mode == 2) o = sigmf(v);
;       sT[row * 136 + col] = f2bf(o);
.LBB0_666:
	v_bfe_u32 v107, v63, 16, 1
	v_add_u32_e32 v55, 0x110, v55
	v_add3_u32 v63, v63, v107, s78
	v_lshl_add_u32 v55, v106, 1, v55
	ds_write_b16_d16_hi v55, v63
	v_add3_u32 v63, s90, v96, 59
	s_and_b64 vcc, exec, s[6:7]
	v_cmp_lt_i32_e64 s[40:41], s76, v63
	s_cbranch_vccz .Lsg_112

; __device__ __forceinline__ float sigmf(float x) { return 1.f / (1.f + __expf(-x)); }
; template <int MT, int NT, class F>
; __device__ __forceinline__ void acc_foreach(int tid, f32x16 (&acc)[MT][NT], F f) {
;     ...
;         int row = wm * (MT * 32) + mt * 32 + (i & 3) + 8 * (i >> 2) + 4 * hi;
;         int col = wn * (NT * 32) + nt * 32 + c;
; __device__ __forceinline__ void inproj_epilogue(const Params& p, int layer, int mt, int ntile, int tid,
;                                                 f32x16 (&acc)[2][2], unsigned char* smem) {
;     ...
;       if (mode == 2) o = sigmf(v);
;       sT[row * 136 + col] = f2bf(o);
.LBB0_669:
	v_bfe_u32 v96, v63, 16, 1
	v_add3_u32 v63, v63, v96, s78
	ds_write_b16_d16_hi v55, v63 offset:272
	s_and_b64 vcc, exec, s[6:7]
	s_cbranch_vccz .Lsg_113

; __device__ __forceinline__ float sigmf(float x) { return 1.f / (1.f + __expf(-x)); }
; __device__ __forceinline__ void inproj_epilogue(const Params& p, int layer, int mt, int ntile, int tid,
;                                                 f32x16 (&acc)[2][2], unsigned char* smem) {
;     ...
;     acc_foreach(tid, acc, [&](int row, int col, float v) {
;       int t = m0 + row;
;       float o = v;
;       if (mode == 1) o = (t >= NPADR) ? v : 0.f;
;       if (mode == 2) o = sigmf(v);
;       sT[row * 136 + col] = f2bf(o);
;     });
.LBB0_672:
	v_bfe_u32 v63, v32, 16, 1
	v_add3_u32 v32, v32, v63, s78
	s_and_b64 vcc, exec, s[6:7]
	ds_write_b16_d16_hi v48, v32 offset:64
	s_cbranch_vccz .Lsg_114

; __device__ __forceinline__ float sigmf(float x) { return 1.f / (1.f + __expf(-x)); }
; __device__ __forceinline__ void inproj_epilogue(const Params& p, int layer, int mt, int ntile, int tid,
;                                                 f32x16 (&acc)[2][2], unsigned char* smem) {
;     ...
;     acc_foreach(tid, acc, [&](int row, int col, float v) {
;       int t = m0 + row;
;       float o = v;
;       if (mode == 1) o = (t >= NPADR) ? v : 0.f;
;       if (mode == 2) o = sigmf(v);
;       sT[row * 136 + col] = f2bf(o);
;     });
.LBB0_675:
	v_bfe_u32 v33, v32, 16, 1
	v_add3_u32 v32, v32, v33, s78
	s_and_b64 vcc, exec, s[6:7]
	ds_write_b16_d16_hi v49, v32 offset:64
	s_cbranch_vccz .Lsg_115

; __device__ __forceinline__ float sigmf(float x) { return 1.f / (1.f + __expf(-x)); }
; __device__ __forceinline__ void inproj_epilogue(const Params& p, int layer, int mt, int ntile, int tid,
;                                                 f32x16 (&acc)[2][2], unsigned char* smem) {
;     ...
;     acc_foreach(tid, acc, [&](int row, int col, float v) {
;       int t = m0 + row;
;       float o = v;
;       if (mode == 1) o = (t >= NPADR) ? v : 0.f;
;       if (mode == 2) o = sigmf(v);
;       sT[row * 136 + col] = f2bf(o);
;     });
.LBB0_678:
	v_bfe_u32 v33, v32, 16, 1
	v_add3_u32 v32, v32, v33, s78
	s_and_b64 vcc, exec, s[6:7]
	ds_write_b16_d16_hi v50, v32 offset:64
	s_cbranch_vccz .Lsg_116

; __device__ __forceinline__ float sigmf(float x) { return 1.f / (1.f + __expf(-x)); }
; __device__ __forceinline__ void inproj_epilogue(const Params& p, int layer, int mt, int ntile, int tid,
;                                                 f32x16 (&acc)[2][2], unsigned char* smem) {
;     ...
;     acc_foreach(tid, acc, [&](int row, int col, float v) {
;       int t = m0 + row;
;       float o = v;
;       if (mode == 1) o = (t >= NPADR) ? v : 0.f;
;       if (mode == 2) o = sigmf(v);
;       sT[row * 136 + col] = f2bf(o);
;     });
.LBB0_681:
	v_bfe_u32 v33, v32, 16, 1
	v_add3_u32 v32, v32, v33, s78
	s_and_b64 vcc, exec, s[6:7]
	ds_write_b16_d16_hi v51, v32 offset:64
	s_cbranch_vccz .Lsg_117

; __device__ __forceinline__ float sigmf(float x) { return 1.f / (1.f + __expf(-x)); }
; __device__ __forceinline__ void inproj_epilogue(const Params& p, int layer, int mt, int ntile, int tid,
;                                                 f32x16 (&acc)[2][2], unsigned char* smem) {
;     ...
;     acc_foreach(tid, acc, [&](int row, int col, float v) {
;       int t = m0 + row;
;       float o = v;
;       if (mode == 1) o = (t >= NPADR) ? v : 0.f;
;       if (mode == 2) o = sigmf(v);
;       sT[row * 136 + col] = f2bf(o);
;     });
.LBB0_684:
	v_bfe_u32 v33, v32, 16, 1
	v_add3_u32 v32, v32, v33, s78
	s_and_b64 vcc, exec, s[6:7]
	ds_write_b16_d16_hi v52, v32 offset:64
	s_cbranch_vccz .Lsg_118

; __device__ __forceinline__ float sigmf(float x) { return 1.f / (1.f + __expf(-x)); }
; __device__ __forceinline__ void inproj_epilogue(const Params& p, int layer, int mt, int ntile, int tid,
;                                                 f32x16 (&acc)[2][2], unsigned char* smem) {
;     ...
;     acc_foreach(tid, acc, [&](int row, int col, float v) {
;       int t = m0 + row;
;       float o = v;
;       if (mode == 1) o = (t >= NPADR) ? v : 0.f;
;       if (mode == 2) o = sigmf(v);
;       sT[row * 136 + col] = f2bf(o);
;     });
.LBB0_687:
	v_bfe_u32 v33, v32, 16, 1
	v_add3_u32 v32, v32, v33, s78
	s_and_b64 vcc, exec, s[6:7]
	ds_write_b16_d16_hi v53, v32 offset:64
	s_cbranch_vccz .Lsg_119

; __device__ __forceinline__ float sigmf(float x) { return 1.f / (1.f + __expf(-x)); }
; __device__ __forceinline__ void inproj_epilogue(const Params& p, int layer, int mt, int ntile, int tid,
;                                                 f32x16 (&acc)[2][2], unsigned char* smem) {
;     ...
;     acc_foreach(tid, acc, [&](int row, int col, float v) {
;       int t = m0 + row;
;       float o = v;
;       if (mode == 1) o = (t >= NPADR) ? v : 0.f;
;       if (mode == 2) o = sigmf(v);
;       sT[row * 136 + col] = f2bf(o);
;     });
.LBB0_690:
	v_bfe_u32 v33, v32, 16, 1
	v_add3_u32 v32, v32, v33, s78
	s_and_b64 vcc, exec, s[6:7]
	ds_write_b16_d16_hi v54, v32 offset:64
	s_cbranch_vccz .Lsg_120

; __device__ __forceinline__ float sigmf(float x) { return 1.f / (1.f + __expf(-x)); }
; __device__ __forceinline__ void inproj_epilogue(const Params& p, int layer, int mt, int ntile, int tid,
;                                                 f32x16 (&acc)[2][2], unsigned char* smem) {
;     ...
;     acc_foreach(tid, acc, [&](int row, int col, float v) {
;       int t = m0 + row;
;       float o = v;
;       if (mode == 1) o = (t >= NPADR) ? v : 0.f;
;       if (mode == 2) o = sigmf(v);
;       sT[row * 136 + col] = f2bf(o);
;     });
.LBB0_693:
	v_bfe_u32 v33, v32, 16, 1
	v_add3_u32 v32, v32, v33, s78
	s_and_b64 vcc, exec, s[6:7]
	ds_write_b16_d16_hi v56, v32 offset:64
	s_cbranch_vccz .Lsg_121

; __device__ __forceinline__ float sigmf(float x) { return 1.f / (1.f + __expf(-x)); }
; __device__ __forceinline__ void inproj_epilogue(const Params& p, int layer, int mt, int ntile, int tid,
;                                                 f32x16 (&acc)[2][2], unsigned char* smem) {
;     ...
;     acc_foreach(tid, acc, [&](int row, int col, float v) {
;       int t = m0 + row;
;       float o = v;
;       if (mode == 1) o = (t >= NPADR) ? v : 0.f;
;       if (mode == 2) o = sigmf(v);
;       sT[row * 136 + col] = f2bf(o);
;     });
.LBB0_696:
	v_bfe_u32 v33, v32, 16, 1
	v_add3_u32 v32, v32, v33, s78
	s_and_b64 vcc, exec, s[6:7]
	ds_write_b16_d16_hi v57, v32 offset:64
	s_cbranch_vccz .Lsg_122

; __device__ __forceinline__ float sigmf(float x) { return 1.f / (1.f + __expf(-x)); }
; __device__ __forceinline__ void inproj_epilogue(const Params& p, int layer, int mt, int ntile, int tid,
;                                                 f32x16 (&acc)[2][2], unsigned char* smem) {
;     ...
;     acc_foreach(tid, acc, [&](int row, int col, float v) {
;       int t = m0 + row;
;       float o = v;
;       if (mode == 1) o = (t >= NPADR) ? v : 0.f;
;       if (mode == 2) o = sigmf(v);
;       sT[row * 136 + col] = f2bf(o);
;     });
.LBB0_699:
	v_bfe_u32 v33, v32, 16, 1
	v_add3_u32 v32, v32, v33, s78
	s_and_b64 vcc, exec, s[6:7]
	ds_write_b16_d16_hi v58, v32 offset:64
	s_cbranch_vccz .Lsg_123

; __device__ __forceinline__ float sigmf(float x) { return 1.f / (1.f + __expf(-x)); }
; __device__ __forceinline__ void inproj_epilogue(const Params& p, int layer, int mt, int ntile, int tid,
;                                                 f32x16 (&acc)[2][2], unsigned char* smem) {
;     ...
;     acc_foreach(tid, acc, [&](int row, int col, float v) {
;       int t = m0 + row;
;       float o = v;
;       if (mode == 1) o = (t >= NPADR) ? v : 0.f;
;       if (mode == 2) o = sigmf(v);
;       sT[row * 136 + col] = f2bf(o);
;     });
.LBB0_702:
	v_bfe_u32 v33, v32, 16, 1
	v_add3_u32 v32, v32, v33, s78
	s_and_b64 vcc, exec, s[6:7]
	ds_write_b16_d16_hi v59, v32 offset:64
	s_cbranch_vccz .Lsg_124

; __device__ __forceinline__ float sigmf(float x) { return 1.f / (1.f + __expf(-x)); }
; __device__ __forceinline__ void inproj_epilogue(const Params& p, int layer, int mt, int ntile, int tid,
;                                                 f32x16 (&acc)[2][2], unsigned char* smem) {
;     ...
;     acc_foreach(tid, acc, [&](int row, int col, float v) {
;       int t = m0 + row;
;       float o = v;
;       if (mode == 1) o = (t >= NPADR) ? v : 0.f;
;       if (mode == 2) o = sigmf(v);
;       sT[row * 136 + col] = f2bf(o);
;     });
.LBB0_705:
	v_bfe_u32 v33, v32, 16, 1
	v_add3_u32 v32, v32, v33, s78
	s_and_b64 vcc, exec, s[6:7]
	ds_write_b16_d16_hi v60, v32 offset:64
	s_cbranch_vccz .Lsg_125

; __device__ __forceinline__ float sigmf(float x) { return 1.f / (1.f + __expf(-x)); }
; __device__ __forceinline__ void inproj_epilogue(const Params& p, int layer, int mt, int ntile, int tid,
;                                                 f32x16 (&acc)[2][2], unsigned char* smem) {
;     ...
;     acc_foreach(tid, acc, [&](int row, int col, float v) {
;       int t = m0 + row;
;       float o = v;
;       if (mode == 1) o = (t >= NPADR) ? v : 0.f;
;       if (mode == 2) o = sigmf(v);
;       sT[row * 136 + col] = f2bf(o);
;     });
.LBB0_708:
	v_bfe_u32 v33, v32, 16, 1
	v_add3_u32 v32, v32, v33, s78
	s_and_b64 vcc, exec, s[6:7]
	ds_write_b16_d16_hi v61, v32 offset:64
	s_cbranch_vccz .Lsg_126

; __device__ __forceinline__ float sigmf(float x) { return 1.f / (1.f + __expf(-x)); }
; __device__ __forceinline__ void inproj_epilogue(const Params& p, int layer, int mt, int ntile, int tid,
;                                                 f32x16 (&acc)[2][2], unsigned char* smem) {
;     ...
;     acc_foreach(tid, acc, [&](int row, int col, float v) {
;       int t = m0 + row;
;       float o = v;
;       if (mode == 1) o = (t >= NPADR) ? v : 0.f;
;       if (mode == 2) o = sigmf(v);
;       sT[row * 136 + col] = f2bf(o);
;     });
.LBB0_711:
	v_bfe_u32 v33, v32, 16, 1
	v_add3_u32 v32, v32, v33, s78
	s_and_b64 vcc, exec, s[6:7]
	ds_write_b16_d16_hi v62, v32 offset:64
	s_cbranch_vccz .Lsg_127

; __device__ __forceinline__ float sigmf(float x) { return 1.f / (1.f + __expf(-x)); }
; __device__ __forceinline__ void inproj_epilogue(const Params& p, int layer, int mt, int ntile, int tid,
;                                                 f32x16 (&acc)[2][2], unsigned char* smem) {
;     ...
;     acc_foreach(tid, acc, [&](int row, int col, float v) {
;       int t = m0 + row;
;       float o = v;
;       if (mode == 1) o = (t >= NPADR) ? v : 0.f;
;       if (mode == 2) o = sigmf(v);
;       sT[row * 136 + col] = f2bf(o);
;     });
.LBB0_714:
	v_bfe_u32 v33, v32, 16, 1
	v_add3_u32 v32, v32, v33, s78
	s_and_b64 vcc, exec, s[6:7]
	ds_write_b16_d16_hi v55, v32 offset:64
	s_cbranch_vccz .Lsg_128

; __device__ __forceinline__ float sigmf(float x) { return 1.f / (1.f + __expf(-x)); }
; __device__ __forceinline__ float softplusf(float x) { return fmaxf(x, 0.f) + __logf(1.f + __expf(-fabsf(x))); }
; __device__ __forceinline__ void inproj_epilogue(const Params& p, int layer, int mt, int ntile, int tid,
;                                                 f32x16 (&acc)[2][2], unsigned char* smem) {
;     ...
;   const int m0 = mt * 128;
;   if (mode == 3) {
;     float* dt = (float*)(p.ws + OFF_DT) + (size_t)m0 * 16;
;     const float* bias = p.ssd_dt_bias + layer * 16;
;     acc_foreach(tid, acc, [&](int row, int col, float v) {
;       if (col < 16) *(dt + row * 16 + col) = softplusf(v + bias[col]);
;     });
;   } else {
;     bf16r* dstb = dst + (size_t)m0 * ld + c0;
;     bf16r* sT = (bf16r*)smem;
;     acc_foreach(tid, acc, [&](int row, int col, float v) {
;       int t = m0 + row;
;       float o = v;
;       if (mode == 1) o = (t >= NPADR) ? v : 0.f;
;       if (mode == 2) o = sigmf(v);
;       sT[row * 136 + col] = f2bf(o);
.LBB0_858:
	s_lshl_b32 s0, s6, 7
	s_ashr_i32 s1, s0, 31
	s_cmp_lg_u32 s7, 3
	s_mov_b64 s[4:5], -1
	s_cbranch_scc0 .LBB0_1052
	v_mov_b32_e32 v106, v108
	s_movk_i32 s4, 0xffc0
	v_lshrrev_b32_e32 v107, 3, v106
	v_ashrrev_i32_e32 v96, 1, v106
	v_and_b32_e32 v107, 4, v107
	v_and_or_b32 v96, v96, s4, v107
	s_cmp_eq_u32 s7, 1
	s_cselect_b64 s[4:5], -1, 0
	v_add_u32_e32 v107, s0, v96
	s_cmp_eq_u32 s7, 2
	s_cselect_b64 s[12:13], -1, 0
	s_cmp_lg_u32 s7, 2
	v_cmp_lt_i32_e64 s[8:9], s77, v107
	s_cbranch_scc0 .Lsg_129

; __device__ __forceinline__ float sigmf(float x) { return 1.f / (1.f + __expf(-x)); }
; __device__ __forceinline__ void inproj_epilogue(const Params& p, int layer, int mt, int ntile, int tid,
;                                                 f32x16 (&acc)[2][2], unsigned char* smem) {
;     ...
;     acc_foreach(tid, acc, [&](int row, int col, float v) {
;       int t = m0 + row;
;       float o = v;
;       if (mode == 1) o = (t >= NPADR) ? v : 0.f;
;       if (mode == 2) o = sigmf(v);
;       sT[row * 136 + col] = f2bf(o);
;     });
.LBB0_862:
	v_bfe_u32 v110, v107, 16, 1
	v_and_b32_e32 v106, 0x5f, v106
	v_add3_u32 v111, v107, v110, s79
	v_mul_lo_u32 v110, v96, s80
	v_lshl_add_u32 v107, v106, 1, v110
	ds_write_b16_d16_hi v107, v111
	v_add3_u32 v111, s0, v96, 1
	v_cmp_lt_i32_e64 s[10:11], s77, v111
	v_cndmask_b32_e64 v111, 0, 1, s[12:13]
	v_cmp_ne_u32_e64 s[6:7], 1, v111
	s_andn2_b64 vcc, exec, s[12:13]
	s_cbranch_vccz .Lsg_130

; __device__ __forceinline__ float sigmf(float x) { return 1.f / (1.f + __expf(-x)); }
; __device__ __forceinline__ void inproj_epilogue(const Params& p, int layer, int mt, int ntile, int tid,
;                                                 f32x16 (&acc)[2][2], unsigned char* smem) {
;     ...
;     acc_foreach(tid, acc, [&](int row, int col, float v) {
;       int t = m0 + row;
;       float o = v;
;       if (mode == 1) o = (t >= NPADR) ? v : 0.f;
;       if (mode == 2) o = sigmf(v);
;       sT[row * 136 + col] = f2bf(o);
;     });
.LBB0_865:
	v_bfe_u32 v112, v111, 16, 1
	v_add3_u32 v112, v111, v112, s79
	v_add_u32_e32 v111, 0x110, v110
	v_lshl_add_u32 v110, v106, 1, v111
	ds_write_b16_d16_hi v110, v112
	v_add3_u32 v112, s0, v96, 2
	s_and_b64 vcc, exec, s[6:7]
	v_cmp_lt_i32_e64 s[12:13], s77, v112
	s_cbranch_vccz .Lsg_131

; __device__ __forceinline__ float sigmf(float x) { return 1.f / (1.f + __expf(-x)); }
; __device__ __forceinline__ void inproj_epilogue(const Params& p, int layer, int mt, int ntile, int tid,
;                                                 f32x16 (&acc)[2][2], unsigned char* smem) {
;     ...
;     acc_foreach(tid, acc, [&](int row, int col, float v) {
;       int t = m0 + row;
;       float o = v;
;       if (mode == 1) o = (t >= NPADR) ? v : 0.f;
;       if (mode == 2) o = sigmf(v);
;       sT[row * 136 + col] = f2bf(o);
;     });
.LBB0_868:
	v_bfe_u32 v113, v112, 16, 1
	v_add3_u32 v113, v112, v113, s79
	v_add_u32_e32 v112, 0x110, v111
	v_lshl_add_u32 v111, v106, 1, v112
	ds_write_b16_d16_hi v111, v113
	v_add3_u32 v113, s0, v96, 3
	s_and_b64 vcc, exec, s[6:7]
	v_cmp_lt_i32_e64 s[14:15], s77, v113
	s_cbranch_vccz .Lsg_132

; __device__ __forceinline__ float sigmf(float x) { return 1.f / (1.f + __expf(-x)); }
; __device__ __forceinline__ void inproj_epilogue(const Params& p, int layer, int mt, int ntile, int tid,
;                                                 f32x16 (&acc)[2][2], unsigned char* smem) {
;     ...
;     acc_foreach(tid, acc, [&](int row, int col, float v) {
;       int t = m0 + row;
;       float o = v;
;       if (mode == 1) o = (t >= NPADR) ? v : 0.f;
;       if (mode == 2) o = sigmf(v);
;       sT[row * 136 + col] = f2bf(o);
;     });
.LBB0_871:
	v_bfe_u32 v114, v113, 16, 1
	v_add3_u32 v114, v113, v114, s79
	v_add_u32_e32 v113, 0x110, v112
	v_lshl_add_u32 v112, v106, 1, v113
	ds_write_b16_d16_hi v112, v114
	v_add3_u32 v114, s0, v96, 8
	s_and_b64 vcc, exec, s[6:7]
	v_cmp_lt_i32_e64 s[16:17], s77, v114
	s_cbranch_vccz .Lsg_133

; __device__ __forceinline__ float sigmf(float x) { return 1.f / (1.f + __expf(-x)); }
; __device__ __forceinline__ void inproj_epilogue(const Params& p, int layer, int mt, int ntile, int tid,
;                                                 f32x16 (&acc)[2][2], unsigned char* smem) {
;     ...
;     acc_foreach(tid, acc, [&](int row, int col, float v) {
;       int t = m0 + row;
;       float o = v;
;       if (mode == 1) o = (t >= NPADR) ? v : 0.f;
;       if (mode == 2) o = sigmf(v);
;       sT[row * 136 + col] = f2bf(o);
;     });
.LBB0_874:
	v_bfe_u32 v115, v114, 16, 1
	v_add3_u32 v115, v114, v115, s79
	v_add_u32_e32 v114, 0x550, v113
	v_lshl_add_u32 v113, v106, 1, v114
	ds_write_b16_d16_hi v113, v115
	v_add3_u32 v115, s0, v96, 9
	s_and_b64 vcc, exec, s[6:7]
	v_cmp_lt_i32_e64 s[18:19], s77, v115
	s_cbranch_vccz .Lsg_134

; __device__ __forceinline__ float sigmf(float x) { return 1.f / (1.f + __expf(-x)); }
; __device__ __forceinline__ void inproj_epilogue(const Params& p, int layer, int mt, int ntile, int tid,
;                                                 f32x16 (&acc)[2][2], unsigned char* smem) {
;     ...
;     acc_foreach(tid, acc, [&](int row, int col, float v) {
;       int t = m0 + row;
;       float o = v;
;       if (mode == 1) o = (t >= NPADR) ? v : 0.f;
;       if (mode == 2) o = sigmf(v);
;       sT[row * 136 + col] = f2bf(o);
;     });
.LBB0_877:
	v_bfe_u32 v116, v115, 16, 1
	v_add3_u32 v116, v115, v116, s79
	v_add_u32_e32 v115, 0x110, v114
	v_lshl_add_u32 v114, v106, 1, v115
	ds_write_b16_d16_hi v114, v116
	v_add3_u32 v116, s0, v96, 10
	s_and_b64 vcc, exec, s[6:7]
	v_cmp_lt_i32_e64 s[20:21], s77, v116
	s_cbranch_vccz .Lsg_135

; __device__ __forceinline__ float sigmf(float x) { return 1.f / (1.f + __expf(-x)); }
; __device__ __forceinline__ void inproj_epilogue(const Params& p, int layer, int mt, int ntile, int tid,
;                                                 f32x16 (&acc)[2][2], unsigned char* smem) {
;     ...
;     acc_foreach(tid, acc, [&](int row, int col, float v) {
;       int t = m0 + row;
;       float o = v;
;       if (mode == 1) o = (t >= NPADR) ? v : 0.f;
;       if (mode == 2) o = sigmf(v);
;       sT[row * 136 + col] = f2bf(o);
;     });
.LBB0_880:
	v_bfe_u32 v117, v116, 16, 1
	v_add3_u32 v117, v116, v117, s79
	v_add_u32_e32 v116, 0x110, v115
	v_lshl_add_u32 v115, v106, 1, v116
	ds_write_b16_d16_hi v115, v117
	v_add3_u32 v117, s0, v96, 11
	s_and_b64 vcc, exec, s[6:7]
	v_cmp_lt_i32_e64 s[22:23], s77, v117
	s_cbranch_vccz .Lsg_136

; __device__ __forceinline__ float sigmf(float x) { return 1.f / (1.f + __expf(-x)); }
; __device__ __forceinline__ void inproj_epilogue(const Params& p, int layer, int mt, int ntile, int tid,
;                                                 f32x16 (&acc)[2][2], unsigned char* smem) {
;     ...
;     acc_foreach(tid, acc, [&](int row, int col, float v) {
;       int t = m0 + row;
;       float o = v;
;       if (mode == 1) o = (t >= NPADR) ? v : 0.f;
;       if (mode == 2) o = sigmf(v);
;       sT[row * 136 + col] = f2bf(o);
;     });
.LBB0_883:
	v_bfe_u32 v118, v117, 16, 1
	v_add_u32_e32 v116, 0x110, v116
	v_add3_u32 v118, v117, v118, s79
	v_lshl_add_u32 v117, v106, 1, v116
	ds_write_b16_d16_hi v117, v118
	v_add3_u32 v118, s0, v96, 16
	s_and_b64 vcc, exec, s[6:7]
	v_cmp_lt_i32_e64 s[24:25], s77, v118
	s_cbranch_vccz .Lsg_137

; __device__ __forceinline__ float sigmf(float x) { return 1.f / (1.f + __expf(-x)); }
; __device__ __forceinline__ void inproj_epilogue(const Params& p, int layer, int mt, int ntile, int tid,
;                                                 f32x16 (&acc)[2][2], unsigned char* smem) {
;     ...
;     acc_foreach(tid, acc, [&](int row, int col, float v) {
;       int t = m0 + row;
;       float o = v;
;       if (mode == 1) o = (t >= NPADR) ? v : 0.f;
;       if (mode == 2) o = sigmf(v);
;       sT[row * 136 + col] = f2bf(o);
;     });
.LBB0_886:
	v_bfe_u32 v119, v118, 16, 1
	v_add_u32_e32 v116, 0x550, v116
	v_add3_u32 v119, v118, v119, s79
	v_lshl_add_u32 v118, v106, 1, v116
	ds_write_b16_d16_hi v118, v119
	v_add3_u32 v119, s0, v96, 17
	s_and_b64 vcc, exec, s[6:7]
	v_cmp_lt_i32_e64 s[26:27], s77, v119
	s_cbranch_vccz .Lsg_138

; __device__ __forceinline__ float sigmf(float x) { return 1.f / (1.f + __expf(-x)); }
; __device__ __forceinline__ void inproj_epilogue(const Params& p, int layer, int mt, int ntile, int tid,
;                                                 f32x16 (&acc)[2][2], unsigned char* smem) {
;     ...
;     acc_foreach(tid, acc, [&](int row, int col, float v) {
;       int t = m0 + row;
;       float o = v;
;       if (mode == 1) o = (t >= NPADR) ? v : 0.f;
;       if (mode == 2) o = sigmf(v);
;       sT[row * 136 + col] = f2bf(o);
;     });
.LBB0_889:
	v_bfe_u32 v120, v119, 16, 1
	v_add_u32_e32 v116, 0x110, v116
	v_add3_u32 v120, v119, v120, s79
	v_lshl_add_u32 v119, v106, 1, v116
	ds_write_b16_d16_hi v119, v120
	v_add3_u32 v120, s0, v96, 18
	s_and_b64 vcc, exec, s[6:7]
	v_cmp_lt_i32_e64 s[28:29], s77, v120
	s_cbranch_vccz .Lsg_139

; __device__ __forceinline__ float sigmf(float x) { return 1.f / (1.f + __expf(-x)); }
; __device__ __forceinline__ void inproj_epilogue(const Params& p, int layer, int mt, int ntile, int tid,
;                                                 f32x16 (&acc)[2][2], unsigned char* smem) {
;     ...
;     acc_foreach(tid, acc, [&](int row, int col, float v) {
;       int t = m0 + row;
;       float o = v;
;       if (mode == 1) o = (t >= NPADR) ? v : 0.f;
;       if (mode == 2) o = sigmf(v);
;       sT[row * 136 + col] = f2bf(o);
;     });
.LBB0_892:
	v_bfe_u32 v121, v120, 16, 1
	v_add_u32_e32 v116, 0x110, v116
	v_add3_u32 v121, v120, v121, s79
	v_lshl_add_u32 v120, v106, 1, v116
	ds_write_b16_d16_hi v120, v121
	v_add3_u32 v121, s0, v96, 19
	s_and_b64 vcc, exec, s[6:7]
	v_cmp_lt_i32_e64 s[30:31], s77, v121
	s_cbranch_vccz .Lsg_140

; __device__ __forceinline__ float sigmf(float x) { return 1.f / (1.f + __expf(-x)); }
; __device__ __forceinline__ void inproj_epilogue(const Params& p, int layer, int mt, int ntile, int tid,
;                                                 f32x16 (&acc)[2][2], unsigned char* smem) {
;     ...
;     acc_foreach(tid, acc, [&](int row, int col, float v) {
;       int t = m0 + row;
;       float o = v;
;       if (mode == 1) o = (t >= NPADR) ? v : 0.f;
;       if (mode == 2) o = sigmf(v);
;       sT[row * 136 + col] = f2bf(o);
;     });
.LBB0_895:
	v_bfe_u32 v122, v121, 16, 1
	v_add_u32_e32 v116, 0x110, v116
	v_add3_u32 v122, v121, v122, s79
	v_lshl_add_u32 v121, v106, 1, v116
	ds_write_b16_d16_hi v121, v122
	v_add3_u32 v122, s0, v96, 24
	s_and_b64 vcc, exec, s[6:7]
	v_cmp_lt_i32_e64 s[34:35], s77, v122
	s_cbranch_vccz .Lsg_141

; __device__ __forceinline__ float sigmf(float x) { return 1.f / (1.f + __expf(-x)); }
; __device__ __forceinline__ void inproj_epilogue(const Params& p, int layer, int mt, int ntile, int tid,
;                                                 f32x16 (&acc)[2][2], unsigned char* smem) {
;     ...
;     acc_foreach(tid, acc, [&](int row, int col, float v) {
;       int t = m0 + row;
;       float o = v;
;       if (mode == 1) o = (t >= NPADR) ? v : 0.f;
;       if (mode == 2) o = sigmf(v);
;       sT[row * 136 + col] = f2bf(o);
;     });
.LBB0_898:
	v_bfe_u32 v123, v122, 16, 1
	v_add_u32_e32 v116, 0x550, v116
	v_add3_u32 v123, v122, v123, s79
	v_lshl_add_u32 v122, v106, 1, v116
	ds_write_b16_d16_hi v122, v123
	v_add3_u32 v123, s0, v96, 25
	s_and_b64 vcc, exec, s[6:7]
	v_cmp_lt_i32_e64 s[36:37], s77, v123
	s_cbranch_vccz .Lsg_142

; __device__ __forceinline__ float sigmf(float x) { return 1.f / (1.f + __expf(-x)); }
; __device__ __forceinline__ void inproj_epilogue(const Params& p, int layer, int mt, int ntile, int tid,
;                                                 f32x16 (&acc)[2][2], unsigned char* smem) {
;     ...
;     acc_foreach(tid, acc, [&](int row, int col, float v) {
;       int t = m0 + row;
;       float o = v;
;       if (mode == 1) o = (t >= NPADR) ? v : 0.f;
;       if (mode == 2) o = sigmf(v);
;       sT[row * 136 + col] = f2bf(o);
;     });
.LBB0_901:
	v_bfe_u32 v124, v123, 16, 1
	v_add_u32_e32 v116, 0x110, v116
	v_add3_u32 v124, v123, v124, s79
	v_lshl_add_u32 v123, v106, 1, v116
	ds_write_b16_d16_hi v123, v124
	v_add3_u32 v124, s0, v96, 26
	s_and_b64 vcc, exec, s[6:7]
	v_cmp_lt_i32_e64 s[38:39], s77, v124
	s_cbranch_vccz .Lsg_143

; __device__ __forceinline__ float sigmf(float x) { return 1.f / (1.f + __expf(-x)); }
; __device__ __forceinline__ void inproj_epilogue(const Params& p, int layer, int mt, int ntile, int tid,
;                                                 f32x16 (&acc)[2][2], unsigned char* smem) {
;     ...
;     acc_foreach(tid, acc, [&](int row, int col, float v) {
;       int t = m0 + row;
;       float o = v;
;       if (mode == 1) o = (t >= NPADR) ? v : 0.f;
;       if (mode == 2) o = sigmf(v);
;       sT[row * 136 + col] = f2bf(o);
;     });
.LBB0_904:
	v_bfe_u32 v125, v124, 16, 1
	v_add_u32_e32 v116, 0x110, v116
	v_add3_u32 v124, v124, v125, s79
	v_lshl_add_u32 v116, v106, 1, v116
	ds_write_b16_d16_hi v116, v124
	v_add3_u32 v124, s0, v96, 27
	s_and_b64 vcc, exec, s[6:7]
	v_cmp_lt_i32_e64 s[40:41], s77, v124
	s_cbranch_vccz .Lsg_144

; __device__ __forceinline__ float sigmf(float x) { return 1.f / (1.f + __expf(-x)); }
; __device__ __forceinline__ void inproj_epilogue(const Params& p, int layer, int mt, int ntile, int tid,
;                                                 f32x16 (&acc)[2][2], unsigned char* smem) {
;     ...
;     acc_foreach(tid, acc, [&](int row, int col, float v) {
;       int t = m0 + row;
;       float o = v;
;       if (mode == 1) o = (t >= NPADR) ? v : 0.f;
;       if (mode == 2) o = sigmf(v);
;       sT[row * 136 + col] = f2bf(o);
;     });
.LBB0_907:
	v_bfe_u32 v125, v124, 16, 1
	v_add3_u32 v124, v124, v125, s79
	ds_write_b16_d16_hi v116, v124 offset:272
	s_and_b64 vcc, exec, s[6:7]
	s_cbranch_vccz .Lsg_145

; __device__ __forceinline__ float sigmf(float x) { return 1.f / (1.f + __expf(-x)); }
; __device__ __forceinline__ void inproj_epilogue(const Params& p, int layer, int mt, int ntile, int tid,
;                                                 f32x16 (&acc)[2][2], unsigned char* smem) {
;     ...
;     acc_foreach(tid, acc, [&](int row, int col, float v) {
;       int t = m0 + row;
;       float o = v;
;       if (mode == 1) o = (t >= NPADR) ? v : 0.f;
;       if (mode == 2) o = sigmf(v);
;       sT[row * 136 + col] = f2bf(o);
;     });
.LBB0_910:
	v_bfe_u32 v124, v48, 16, 1
	v_add3_u32 v48, v48, v124, s79
	s_and_b64 vcc, exec, s[6:7]
	ds_write_b16_d16_hi v107, v48 offset:64
	s_cbranch_vccz .Lsg_146

; __device__ __forceinline__ float sigmf(float x) { return 1.f / (1.f + __expf(-x)); }
; __device__ __forceinline__ void inproj_epilogue(const Params& p, int layer, int mt, int ntile, int tid,
;                                                 f32x16 (&acc)[2][2], unsigned char* smem) {
;     ...
;     acc_foreach(tid, acc, [&](int row, int col, float v) {
;       int t = m0 + row;
;       float o = v;
;       if (mode == 1) o = (t >= NPADR) ? v : 0.f;
;       if (mode == 2) o = sigmf(v);
;       sT[row * 136 + col] = f2bf(o);
;     });
.LBB0_913:
	v_bfe_u32 v49, v48, 16, 1
	v_add3_u32 v48, v48, v49, s79
	s_and_b64 vcc, exec, s[6:7]
	ds_write_b16_d16_hi v110, v48 offset:64
	s_cbranch_vccz .Lsg_147

; __device__ __forceinline__ float sigmf(float x) { return 1.f / (1.f + __expf(-x)); }
; __device__ __forceinline__ void inproj_epilogue(const Params& p, int layer, int mt, int ntile, int tid,
;                                                 f32x16 (&acc)[2][2], unsigned char* smem) {
;     ...
;     acc_foreach(tid, acc, [&](int row, int col, float v) {
;       int t = m0 + row;
;       float o = v;
;       if (mode == 1) o = (t >= NPADR) ? v : 0.f;
;       if (mode == 2) o = sigmf(v);
;       sT[row * 136 + col] = f2bf(o);
;     });
.LBB0_916:
	v_bfe_u32 v49, v48, 16, 1
	v_add3_u32 v48, v48, v49, s79
	s_and_b64 vcc, exec, s[6:7]
	ds_write_b16_d16_hi v111, v48 offset:64
	s_cbranch_vccz .Lsg_148

; __device__ __forceinline__ float sigmf(float x) { return 1.f / (1.f + __expf(-x)); }
; __device__ __forceinline__ void inproj_epilogue(const Params& p, int layer, int mt, int ntile, int tid,
;                                                 f32x16 (&acc)[2][2], unsigned char* smem) {
;     ...
;     acc_foreach(tid, acc, [&](int row, int col, float v) {
;       int t = m0 + row;
;       float o = v;
;       if (mode == 1) o = (t >= NPADR) ? v : 0.f;
;       if (mode == 2) o = sigmf(v);
;       sT[row * 136 + col] = f2bf(o);
;     });
.LBB0_919:
	v_bfe_u32 v49, v48, 16, 1
	v_add3_u32 v48, v48, v49, s79
	s_and_b64 vcc, exec, s[6:7]
	ds_write_b16_d16_hi v112, v48 offset:64
	s_cbranch_vccz .Lsg_149

; __device__ __forceinline__ float sigmf(float x) { return 1.f / (1.f + __expf(-x)); }
; __device__ __forceinline__ void inproj_epilogue(const Params& p, int layer, int mt, int ntile, int tid,
;                                                 f32x16 (&acc)[2][2], unsigned char* smem) {
;     ...
;     acc_foreach(tid, acc, [&](int row, int col, float v) {
;       int t = m0 + row;
;       float o = v;
;       if (mode == 1) o = (t >= NPADR) ? v : 0.f;
;       if (mode == 2) o = sigmf(v);
;       sT[row * 136 + col] = f2bf(o);
;     });
.LBB0_922:
	v_bfe_u32 v49, v48, 16, 1
	v_add3_u32 v48, v48, v49, s79
	s_and_b64 vcc, exec, s[6:7]
	ds_write_b16_d16_hi v113, v48 offset:64
	s_cbranch_vccz .Lsg_150

; __device__ __forceinline__ float sigmf(float x) { return 1.f / (1.f + __expf(-x)); }
; __device__ __forceinline__ void inproj_epilogue(const Params& p, int layer, int mt, int ntile, int tid,
;                                                 f32x16 (&acc)[2][2], unsigned char* smem) {
;     ...
;     acc_foreach(tid, acc, [&](int row, int col, float v) {
;       int t = m0 + row;
;       float o = v;
;       if (mode == 1) o = (t >= NPADR) ? v : 0.f;
;       if (mode == 2) o = sigmf(v);
;       sT[row * 136 + col] = f2bf(o);
;     });
.LBB0_925:
	v_bfe_u32 v49, v48, 16, 1
	v_add3_u32 v48, v48, v49, s79
	s_and_b64 vcc, exec, s[6:7]
	ds_write_b16_d16_hi v114, v48 offset:64
	s_cbranch_vccz .Lsg_151

; __device__ __forceinline__ float sigmf(float x) { return 1.f / (1.f + __expf(-x)); }
; __device__ __forceinline__ void inproj_epilogue(const Params& p, int layer, int mt, int ntile, int tid,
;                                                 f32x16 (&acc)[2][2], unsigned char* smem) {
;     ...
;     acc_foreach(tid, acc, [&](int row, int col, float v) {
;       int t = m0 + row;
;       float o = v;
;       if (mode == 1) o = (t >= NPADR) ? v : 0.f;
;       if (mode == 2) o = sigmf(v);
;       sT[row * 136 + col] = f2bf(o);
;     });
.LBB0_928:
	v_bfe_u32 v49, v48, 16, 1
	v_add3_u32 v48, v48, v49, s79
	s_and_b64 vcc, exec, s[6:7]
	ds_write_b16_d16_hi v115, v48 offset:64
	s_cbranch_vccz .Lsg_152

; __device__ __forceinline__ float sigmf(float x) { return 1.f / (1.f + __expf(-x)); }
; __device__ __forceinline__ void inproj_epilogue(const Params& p, int layer, int mt, int ntile, int tid,
;                                                 f32x16 (&acc)[2][2], unsigned char* smem) {
;     ...
;     acc_foreach(tid, acc, [&](int row, int col, float v) {
;       int t = m0 + row;
;       float o = v;
;       if (mode == 1) o = (t >= NPADR) ? v : 0.f;
;       if (mode == 2) o = sigmf(v);
;       sT[row * 136 + col] = f2bf(o);
;     });
.LBB0_931:
	v_bfe_u32 v49, v48, 16, 1
	v_add3_u32 v48, v48, v49, s79
	s_and_b64 vcc, exec, s[6:7]
	ds_write_b16_d16_hi v117, v48 offset:64
	s_cbranch_vccz .Lsg_153

; __device__ __forceinline__ float sigmf(float x) { return 1.f / (1.f + __expf(-x)); }
; __device__ __forceinline__ void inproj_epilogue(const Params& p, int layer, int mt, int ntile, int tid,
;                                                 f32x16 (&acc)[2][2], unsigned char* smem) {
;     ...
;     acc_foreach(tid, acc, [&](int row, int col, float v) {
;       int t = m0 + row;
;       float o = v;
;       if (mode == 1) o = (t >= NPADR) ? v : 0.f;
;       if (mode == 2) o = sigmf(v);
;       sT[row * 136 + col] = f2bf(o);
;     });
.LBB0_934:
	v_bfe_u32 v49, v48, 16, 1
	v_add3_u32 v48, v48, v49, s79
	s_and_b64 vcc, exec, s[6:7]
	ds_write_b16_d16_hi v118, v48 offset:64
	s_cbranch_vccz .Lsg_154

; __device__ __forceinline__ float sigmf(float x) { return 1.f / (1.f + __expf(-x)); }
; __device__ __forceinline__ void inproj_epilogue(const Params& p, int layer, int mt, int ntile, int tid,
;                                                 f32x16 (&acc)[2][2], unsigned char* smem) {
;     ...
;     acc_foreach(tid, acc, [&](int row, int col, float v) {
;       int t = m0 + row;
;       float o = v;
;       if (mode == 1) o = (t >= NPADR) ? v : 0.f;
;       if (mode == 2) o = sigmf(v);
;       sT[row * 136 + col] = f2bf(o);
;     });
.LBB0_937:
	v_bfe_u32 v49, v48, 16, 1
	v_add3_u32 v48, v48, v49, s79
	s_and_b64 vcc, exec, s[6:7]
	ds_write_b16_d16_hi v119, v48 offset:64
	s_cbranch_vccz .Lsg_155

; __device__ __forceinline__ float sigmf(float x) { return 1.f / (1.f + __expf(-x)); }
; __device__ __forceinline__ void inproj_epilogue(const Params& p, int layer, int mt, int ntile, int tid,
;                                                 f32x16 (&acc)[2][2], unsigned char* smem) {
;     ...
;     acc_foreach(tid, acc, [&](int row, int col, float v) {
;       int t = m0 + row;
;       float o = v;
;       if (mode == 1) o = (t >= NPADR) ? v : 0.f;
;       if (mode == 2) o = sigmf(v);
;       sT[row * 136 + col] = f2bf(o);
;     });
.LBB0_940:
	v_bfe_u32 v49, v48, 16, 1
	v_add3_u32 v48, v48, v49, s79
	s_and_b64 vcc, exec, s[6:7]
	ds_write_b16_d16_hi v120, v48 offset:64
	s_cbranch_vccz .Lsg_156

; __device__ __forceinline__ float sigmf(float x) { return 1.f / (1.f + __expf(-x)); }
; __device__ __forceinline__ void inproj_epilogue(const Params& p, int layer, int mt, int ntile, int tid,
;                                                 f32x16 (&acc)[2][2], unsigned char* smem) {
;     ...
;     acc_foreach(tid, acc, [&](int row, int col, float v) {
;       int t = m0 + row;
;       float o = v;
;       if (mode == 1) o = (t >= NPADR) ? v : 0.f;
;       if (mode == 2) o = sigmf(v);
;       sT[row * 136 + col] = f2bf(o);
;     });
.LBB0_943:
	v_bfe_u32 v49, v48, 16, 1
	v_add3_u32 v48, v48, v49, s79
	s_and_b64 vcc, exec, s[6:7]
	ds_write_b16_d16_hi v121, v48 offset:64
	s_cbranch_vccz .Lsg_157

; __device__ __forceinline__ float sigmf(float x) { return 1.f / (1.f + __expf(-x)); }
; __device__ __forceinline__ void inproj_epilogue(const Params& p, int layer, int mt, int ntile, int tid,
;                                                 f32x16 (&acc)[2][2], unsigned char* smem) {
;     ...
;     acc_foreach(tid, acc, [&](int row, int col, float v) {
;       int t = m0 + row;
;       float o = v;
;       if (mode == 1) o = (t >= NPADR) ? v : 0.f;
;       if (mode == 2) o = sigmf(v);
;       sT[row * 136 + col] = f2bf(o);
;     });
.LBB0_946:
	v_bfe_u32 v49, v48, 16, 1
	v_add3_u32 v48, v48, v49, s79
	s_and_b64 vcc, exec, s[6:7]
	ds_write_b16_d16_hi v122, v48 offset:64
	s_cbranch_vccz .Lsg_158

; __device__ __forceinline__ float sigmf(float x) { return 1.f / (1.f + __expf(-x)); }
; __device__ __forceinline__ void inproj_epilogue(const Params& p, int layer, int mt, int ntile, int tid,
;                                                 f32x16 (&acc)[2][2], unsigned char* smem) {
;     ...
;     acc_foreach(tid, acc, [&](int row, int col, float v) {
;       int t = m0 + row;
;       float o = v;
;       if (mode == 1) o = (t >= NPADR) ? v : 0.f;
;       if (mode == 2) o = sigmf(v);
;       sT[row * 136 + col] = f2bf(o);
;     });
.LBB0_949:
	v_bfe_u32 v49, v48, 16, 1
	v_add3_u32 v48, v48, v49, s79
	s_and_b64 vcc, exec, s[6:7]
	ds_write_b16_d16_hi v123, v48 offset:64
	s_cbranch_vccz .Lsg_159

; __device__ __forceinline__ float sigmf(float x) { return 1.f / (1.f + __expf(-x)); }
; __device__ __forceinline__ void inproj_epilogue(const Params& p, int layer, int mt, int ntile, int tid,
;                                                 f32x16 (&acc)[2][2], unsigned char* smem) {
;     ...
;     acc_foreach(tid, acc, [&](int row, int col, float v) {
;       int t = m0 + row;
;       float o = v;
;       if (mode == 1) o = (t >= NPADR) ? v : 0.f;
;       if (mode == 2) o = sigmf(v);
;       sT[row * 136 + col] = f2bf(o);
;     });
.LBB0_952:
	v_bfe_u32 v49, v48, 16, 1
	v_add3_u32 v48, v48, v49, s79
	s_and_b64 vcc, exec, s[6:7]
	ds_write_b16_d16_hi v116, v48 offset:64
	s_cbranch_vccz .Lsg_160

; __device__ __forceinline__ float sigmf(float x) { return 1.f / (1.f + __expf(-x)); }
; __device__ __forceinline__ void inproj_epilogue(const Params& p, int layer, int mt, int ntile, int tid,
;                                                 f32x16 (&acc)[2][2], unsigned char* smem) {
;     ...
;     acc_foreach(tid, acc, [&](int row, int col, float v) {
;       int t = m0 + row;
;       float o = v;
;       if (mode == 1) o = (t >= NPADR) ? v : 0.f;
;       if (mode == 2) o = sigmf(v);
;       sT[row * 136 + col] = f2bf(o);
;     });
.LBB0_955:
	v_bfe_u32 v50, v48, 16, 1
	v_add_u32_e32 v49, 0x110, v116
	v_add3_u32 v48, v48, v50, s79
	ds_write_b16_d16_hi v49, v48 offset:64
	v_or_b32_e32 v48, 32, v96
	v_add_u32_e32 v49, s0, v48
	s_and_b64 vcc, exec, s[6:7]
	v_cmp_lt_i32_e64 s[8:9], s77, v49
	s_cbranch_vccz .Lsg_161

; __device__ __forceinline__ float sigmf(float x) { return 1.f / (1.f + __expf(-x)); }
; __device__ __forceinline__ void inproj_epilogue(const Params& p, int layer, int mt, int ntile, int tid,
;                                                 f32x16 (&acc)[2][2], unsigned char* smem) {
;     ...
;     acc_foreach(tid, acc, [&](int row, int col, float v) {
;       int t = m0 + row;
;       float o = v;
;       if (mode == 1) o = (t >= NPADR) ? v : 0.f;
;       if (mode == 2) o = sigmf(v);
;       sT[row * 136 + col] = f2bf(o);
;     });
.LBB0_958:
	v_bfe_u32 v50, v49, 16, 1
	v_add3_u32 v50, v49, v50, s79
	v_mul_lo_u32 v49, v48, s80
	v_lshl_add_u32 v48, v106, 1, v49
	ds_write_b16_d16_hi v48, v50
	v_add3_u32 v50, s0, v96, 33
	s_and_b64 vcc, exec, s[6:7]
	v_cmp_lt_i32_e64 s[10:11], s77, v50
	s_cbranch_vccz .Lsg_162

; __device__ __forceinline__ float sigmf(float x) { return 1.f / (1.f + __expf(-x)); }
; __device__ __forceinline__ void inproj_epilogue(const Params& p, int layer, int mt, int ntile, int tid,
;                                                 f32x16 (&acc)[2][2], unsigned char* smem) {
;     ...
;     acc_foreach(tid, acc, [&](int row, int col, float v) {
;       int t = m0 + row;
;       float o = v;
;       if (mode == 1) o = (t >= NPADR) ? v : 0.f;
;       if (mode == 2) o = sigmf(v);
;       sT[row * 136 + col] = f2bf(o);
;     });
.LBB0_961:
	v_bfe_u32 v51, v50, 16, 1
	v_add3_u32 v51, v50, v51, s79
	v_add_u32_e32 v50, 0x110, v49
	v_lshl_add_u32 v49, v106, 1, v50
	ds_write_b16_d16_hi v49, v51
	v_add3_u32 v51, s0, v96, 34
	s_and_b64 vcc, exec, s[6:7]
	v_cmp_lt_i32_e64 s[12:13], s77, v51
	s_cbranch_vccz .Lsg_163

; __device__ __forceinline__ float sigmf(float x) { return 1.f / (1.f + __expf(-x)); }
; __device__ __forceinline__ void inproj_epilogue(const Params& p, int layer, int mt, int ntile, int tid,
;                                                 f32x16 (&acc)[2][2], unsigned char* smem) {
;     ...
;     acc_foreach(tid, acc, [&](int row, int col, float v) {
;       int t = m0 + row;
;       float o = v;
;       if (mode == 1) o = (t >= NPADR) ? v : 0.f;
;       if (mode == 2) o = sigmf(v);
;       sT[row * 136 + col] = f2bf(o);
;     });
.LBB0_964:
	v_bfe_u32 v52, v51, 16, 1
	v_add3_u32 v52, v51, v52, s79
	v_add_u32_e32 v51, 0x110, v50
	v_lshl_add_u32 v50, v106, 1, v51
	ds_write_b16_d16_hi v50, v52
	v_add3_u32 v52, s0, v96, 35
	s_and_b64 vcc, exec, s[6:7]
	v_cmp_lt_i32_e64 s[14:15], s77, v52
	s_cbranch_vccz .Lsg_164

; __device__ __forceinline__ float sigmf(float x) { return 1.f / (1.f + __expf(-x)); }
; __device__ __forceinline__ void inproj_epilogue(const Params& p, int layer, int mt, int ntile, int tid,
;                                                 f32x16 (&acc)[2][2], unsigned char* smem) {
;     ...
;     acc_foreach(tid, acc, [&](int row, int col, float v) {
;       int t = m0 + row;
;       float o = v;
;       if (mode == 1) o = (t >= NPADR) ? v : 0.f;
;       if (mode == 2) o = sigmf(v);
;       sT[row * 136 + col] = f2bf(o);
;     });
.LBB0_967:
	v_bfe_u32 v53, v52, 16, 1
	v_add3_u32 v53, v52, v53, s79
	v_add_u32_e32 v52, 0x110, v51
	v_lshl_add_u32 v51, v106, 1, v52
	ds_write_b16_d16_hi v51, v53
	v_add3_u32 v53, s0, v96, 40
	s_and_b64 vcc, exec, s[6:7]
	v_cmp_lt_i32_e64 s[16:17], s77, v53
	s_cbranch_vccz .Lsg_165

; __device__ __forceinline__ float sigmf(float x) { return 1.f / (1.f + __expf(-x)); }
; __device__ __forceinline__ void inproj_epilogue(const Params& p, int layer, int mt, int ntile, int tid,
;                                                 f32x16 (&acc)[2][2], unsigned char* smem) {
;     ...
;     acc_foreach(tid, acc, [&](int row, int col, float v) {
;       int t = m0 + row;
;       float o = v;
;       if (mode == 1) o = (t >= NPADR) ? v : 0.f;
;       if (mode == 2) o = sigmf(v);
;       sT[row * 136 + col] = f2bf(o);
;     });
.LBB0_970:
	v_bfe_u32 v54, v53, 16, 1
	v_add3_u32 v54, v53, v54, s79
	v_add_u32_e32 v53, 0x550, v52
	v_lshl_add_u32 v52, v106, 1, v53
	ds_write_b16_d16_hi v52, v54
	v_add3_u32 v54, s0, v96, 41
	s_and_b64 vcc, exec, s[6:7]
	v_cmp_lt_i32_e64 s[18:19], s77, v54
	s_cbranch_vccz .Lsg_166

; __device__ __forceinline__ float sigmf(float x) { return 1.f / (1.f + __expf(-x)); }
; __device__ __forceinline__ void inproj_epilogue(const Params& p, int layer, int mt, int ntile, int tid,
;                                                 f32x16 (&acc)[2][2], unsigned char* smem) {
;     ...
;     acc_foreach(tid, acc, [&](int row, int col, float v) {
;       int t = m0 + row;
;       float o = v;
;       if (mode == 1) o = (t >= NPADR) ? v : 0.f;
;       if (mode == 2) o = sigmf(v);
;       sT[row * 136 + col] = f2bf(o);
;     });
.LBB0_973:
	v_bfe_u32 v55, v54, 16, 1
	v_add3_u32 v55, v54, v55, s79
	v_add_u32_e32 v54, 0x110, v53
	v_lshl_add_u32 v53, v106, 1, v54
	ds_write_b16_d16_hi v53, v55
	v_add3_u32 v55, s0, v96, 42
	s_and_b64 vcc, exec, s[6:7]
	v_cmp_lt_i32_e64 s[20:21], s77, v55
	s_cbranch_vccz .Lsg_167

; __device__ __forceinline__ float sigmf(float x) { return 1.f / (1.f + __expf(-x)); }
; __device__ __forceinline__ void inproj_epilogue(const Params& p, int layer, int mt, int ntile, int tid,
;                                                 f32x16 (&acc)[2][2], unsigned char* smem) {
;     ...
;     acc_foreach(tid, acc, [&](int row, int col, float v) {
;       int t = m0 + row;
;       float o = v;
;       if (mode == 1) o = (t >= NPADR) ? v : 0.f;
;       if (mode == 2) o = sigmf(v);
;       sT[row * 136 + col] = f2bf(o);
;     });
.LBB0_976:
	v_bfe_u32 v56, v55, 16, 1
	v_add3_u32 v56, v55, v56, s79
	v_add_u32_e32 v55, 0x110, v54
	v_lshl_add_u32 v54, v106, 1, v55
	ds_write_b16_d16_hi v54, v56
	v_add3_u32 v56, s0, v96, 43
	s_and_b64 vcc, exec, s[6:7]
	v_cmp_lt_i32_e64 s[22:23], s77, v56
	s_cbranch_vccz .Lsg_168

; __device__ __forceinline__ float sigmf(float x) { return 1.f / (1.f + __expf(-x)); }
; __device__ __forceinline__ void inproj_epilogue(const Params& p, int layer, int mt, int ntile, int tid,
;                                                 f32x16 (&acc)[2][2], unsigned char* smem) {
;     ...
;     acc_foreach(tid, acc, [&](int row, int col, float v) {
;       int t = m0 + row;
;       float o = v;
;       if (mode == 1) o = (t >= NPADR) ? v : 0.f;
;       if (mode == 2) o = sigmf(v);
;       sT[row * 136 + col] = f2bf(o);
;     });
.LBB0_979:
	v_bfe_u32 v57, v56, 16, 1
	v_add_u32_e32 v55, 0x110, v55
	v_add3_u32 v57, v56, v57, s79
	v_lshl_add_u32 v56, v106, 1, v55
	ds_write_b16_d16_hi v56, v57
	v_add3_u32 v57, s0, v96, 48
	s_and_b64 vcc, exec, s[6:7]
	v_cmp_lt_i32_e64 s[24:25], s77, v57
	s_cbranch_vccz .Lsg_169

; __device__ __forceinline__ float sigmf(float x) { return 1.f / (1.f + __expf(-x)); }
; __device__ __forceinline__ void inproj_epilogue(const Params& p, int layer, int mt, int ntile, int tid,
;                                                 f32x16 (&acc)[2][2], unsigned char* smem) {
;     ...
;     acc_foreach(tid, acc, [&](int row, int col, float v) {
;       int t = m0 + row;
;       float o = v;
;       if (mode == 1) o = (t >= NPADR) ? v : 0.f;
;       if (mode == 2) o = sigmf(v);
;       sT[row * 136 + col] = f2bf(o);
;     });
.LBB0_982:
	v_bfe_u32 v58, v57, 16, 1
	v_add_u32_e32 v55, 0x550, v55
	v_add3_u32 v58, v57, v58, s79
	v_lshl_add_u32 v57, v106, 1, v55
	ds_write_b16_d16_hi v57, v58
	v_add3_u32 v58, s0, v96, 49
	s_and_b64 vcc, exec, s[6:7]
	v_cmp_lt_i32_e64 s[26:27], s77, v58
	s_cbranch_vccz .Lsg_170

; __device__ __forceinline__ float sigmf(float x) { return 1.f / (1.f + __expf(-x)); }
; __device__ __forceinline__ void inproj_epilogue(const Params& p, int layer, int mt, int ntile, int tid,
;                                                 f32x16 (&acc)[2][2], unsigned char* smem) {
;     ...
;     acc_foreach(tid, acc, [&](int row, int col, float v) {
;       int t = m0 + row;
;       float o = v;
;       if (mode == 1) o = (t >= NPADR) ? v : 0.f;
;       if (mode == 2) o = sigmf(v);
;       sT[row * 136 + col] = f2bf(o);
;     });
.LBB0_985:
	v_bfe_u32 v59, v58, 16, 1
	v_add_u32_e32 v55, 0x110, v55
	v_add3_u32 v59, v58, v59, s79
	v_lshl_add_u32 v58, v106, 1, v55
	ds_write_b16_d16_hi v58, v59
	v_add3_u32 v59, s0, v96, 50
	s_and_b64 vcc, exec, s[6:7]
	v_cmp_lt_i32_e64 s[28:29], s77, v59
	s_cbranch_vccz .Lsg_171

; __device__ __forceinline__ float sigmf(float x) { return 1.f / (1.f + __expf(-x)); }
; __device__ __forceinline__ void inproj_epilogue(const Params& p, int layer, int mt, int ntile, int tid,
;                                                 f32x16 (&acc)[2][2], unsigned char* smem) {
;     ...
;     acc_foreach(tid, acc, [&](int row, int col, float v) {
;       int t = m0 + row;
;       float o = v;
;       if (mode == 1) o = (t >= NPADR) ? v : 0.f;
;       if (mode == 2) o = sigmf(v);
;       sT[row * 136 + col] = f2bf(o);
;     });
.LBB0_988:
	v_bfe_u32 v60, v59, 16, 1
	v_add_u32_e32 v55, 0x110, v55
	v_add3_u32 v60, v59, v60, s79
	v_lshl_add_u32 v59, v106, 1, v55
	ds_write_b16_d16_hi v59, v60
	v_add3_u32 v60, s0, v96, 51
	s_and_b64 vcc, exec, s[6:7]
	v_cmp_lt_i32_e64 s[30:31], s77, v60
	s_cbranch_vccz .Lsg_172

; __device__ __forceinline__ float sigmf(float x) { return 1.f / (1.f + __expf(-x)); }
; __device__ __forceinline__ void inproj_epilogue(const Params& p, int layer, int mt, int ntile, int tid,
;                                                 f32x16 (&acc)[2][2], unsigned char* smem) {
;     ...
;     acc_foreach(tid, acc, [&](int row, int col, float v) {
;       int t = m0 + row;
;       float o = v;
;       if (mode == 1) o = (t >= NPADR) ? v : 0.f;
;       if (mode == 2) o = sigmf(v);
;       sT[row * 136 + col] = f2bf(o);
;     });
.LBB0_991:
	v_bfe_u32 v61, v60, 16, 1
	v_add_u32_e32 v55, 0x110, v55
	v_add3_u32 v61, v60, v61, s79
	v_lshl_add_u32 v60, v106, 1, v55
	ds_write_b16_d16_hi v60, v61
	v_add3_u32 v61, s0, v96, 56
	s_and_b64 vcc, exec, s[6:7]
	v_cmp_lt_i32_e64 s[34:35], s77, v61
	s_cbranch_vccz .Lsg_173

; __device__ __forceinline__ float sigmf(float x) { return 1.f / (1.f + __expf(-x)); }
; __device__ __forceinline__ void inproj_epilogue(const Params& p, int layer, int mt, int ntile, int tid,
;                                                 f32x16 (&acc)[2][2], unsigned char* smem) {
;     ...
;     acc_foreach(tid, acc, [&](int row, int col, float v) {
;       int t = m0 + row;
;       float o = v;
;       if (mode == 1) o = (t >= NPADR) ? v : 0.f;
;       if (mode == 2) o = sigmf(v);
;       sT[row * 136 + col] = f2bf(o);
;     });
.LBB0_994:
	v_bfe_u32 v62, v61, 16, 1
	v_add_u32_e32 v55, 0x550, v55
	v_add3_u32 v62, v61, v62, s79
	v_lshl_add_u32 v61, v106, 1, v55
	ds_write_b16_d16_hi v61, v62
	v_add3_u32 v62, s0, v96, 57
	s_and_b64 vcc, exec, s[6:7]
	v_cmp_lt_i32_e64 s[36:37], s77, v62
	s_cbranch_vccz .Lsg_174

; __device__ __forceinline__ float sigmf(float x) { return 1.f / (1.f + __expf(-x)); }
; __device__ __forceinline__ void inproj_epilogue(const Params& p, int layer, int mt, int ntile, int tid,
;                                                 f32x16 (&acc)[2][2], unsigned char* smem) {
;     ...
;     acc_foreach(tid, acc, [&](int row, int col, float v) {
;       int t = m0 + row;
;       float o = v;
;       if (mode == 1) o = (t >= NPADR) ? v : 0.f;
;       if (mode == 2) o = sigmf(v);
;       sT[row * 136 + col] = f2bf(o);
;     });
.LBB0_997:
	v_bfe_u32 v63, v62, 16, 1
	v_add_u32_e32 v55, 0x110, v55
	v_add3_u32 v63, v62, v63, s79
	v_lshl_add_u32 v62, v106, 1, v55
	ds_write_b16_d16_hi v62, v63
	v_add3_u32 v63, s0, v96, 58
	s_and_b64 vcc, exec, s[6:7]
	v_cmp_lt_i32_e64 s[38:39], s77, v63
	s_cbranch_vccz .Lsg_175

; __device__ __forceinline__ float sigmf(float x) { return 1.f / (1.f + __expf(-x)); }
; __device__ __forceinline__ void inproj_epilogue(const Params& p, int layer, int mt, int ntile, int tid,
;                                                 f32x16 (&acc)[2][2], unsigned char* smem) {
;     ...
;     acc_foreach(tid, acc, [&](int row, int col, float v) {
;       int t = m0 + row;
;       float o = v;
;       if (mode == 1) o = (t >= NPADR) ? v : 0.f;
;       if (mode == 2) o = sigmf(v);
;       sT[row * 136 + col] = f2bf(o);
;     });
.LBB0_1000:
	v_bfe_u32 v107, v63, 16, 1
	v_add_u32_e32 v55, 0x110, v55
	v_add3_u32 v63, v63, v107, s79
	v_lshl_add_u32 v55, v106, 1, v55
	ds_write_b16_d16_hi v55, v63
	v_add3_u32 v63, s0, v96, 59
	s_and_b64 vcc, exec, s[6:7]
	v_cmp_lt_i32_e64 s[40:41], s77, v63
	s_cbranch_vccz .Lsg_176

; __device__ __forceinline__ float sigmf(float x) { return 1.f / (1.f + __expf(-x)); }
; __device__ __forceinline__ void inproj_epilogue(const Params& p, int layer, int mt, int ntile, int tid,
;                                                 f32x16 (&acc)[2][2], unsigned char* smem) {
;     ...
;     acc_foreach(tid, acc, [&](int row, int col, float v) {
;       int t = m0 + row;
;       float o = v;
;       if (mode == 1) o = (t >= NPADR) ? v : 0.f;
;       if (mode == 2) o = sigmf(v);
;       sT[row * 136 + col] = f2bf(o);
;     });
.LBB0_1003:
	v_bfe_u32 v96, v63, 16, 1
	v_add3_u32 v63, v63, v96, s79
	ds_write_b16_d16_hi v55, v63 offset:272
	s_and_b64 vcc, exec, s[6:7]
	s_cbranch_vccz .Lsg_177

; __device__ __forceinline__ float sigmf(float x) { return 1.f / (1.f + __expf(-x)); }
; __device__ __forceinline__ void inproj_epilogue(const Params& p, int layer, int mt, int ntile, int tid,
;                                                 f32x16 (&acc)[2][2], unsigned char* smem) {
;     ...
;     acc_foreach(tid, acc, [&](int row, int col, float v) {
;       int t = m0 + row;
;       float o = v;
;       if (mode == 1) o = (t >= NPADR) ? v : 0.f;
;       if (mode == 2) o = sigmf(v);
;       sT[row * 136 + col] = f2bf(o);
;     });
.LBB0_1006:
	v_bfe_u32 v63, v32, 16, 1
	v_add3_u32 v32, v32, v63, s79
	s_and_b64 vcc, exec, s[6:7]
	ds_write_b16_d16_hi v48, v32 offset:64
	s_cbranch_vccz .Lsg_178

; __device__ __forceinline__ float sigmf(float x) { return 1.f / (1.f + __expf(-x)); }
; __device__ __forceinline__ void inproj_epilogue(const Params& p, int layer, int mt, int ntile, int tid,
;                                                 f32x16 (&acc)[2][2], unsigned char* smem) {
;     ...
;     acc_foreach(tid, acc, [&](int row, int col, float v) {
;       int t = m0 + row;
;       float o = v;
;       if (mode == 1) o = (t >= NPADR) ? v : 0.f;
;       if (mode == 2) o = sigmf(v);
;       sT[row * 136 + col] = f2bf(o);
;     });
.LBB0_1009:
	v_bfe_u32 v33, v32, 16, 1
	v_add3_u32 v32, v32, v33, s79
	s_and_b64 vcc, exec, s[6:7]
	ds_write_b16_d16_hi v49, v32 offset:64
	s_cbranch_vccz .Lsg_179

; __device__ __forceinline__ float sigmf(float x) { return 1.f / (1.f + __expf(-x)); }
; __device__ __forceinline__ void inproj_epilogue(const Params& p, int layer, int mt, int ntile, int tid,
;                                                 f32x16 (&acc)[2][2], unsigned char* smem) {
;     ...
;     acc_foreach(tid, acc, [&](int row, int col, float v) {
;       int t = m0 + row;
;       float o = v;
;       if (mode == 1) o = (t >= NPADR) ? v : 0.f;
;       if (mode == 2) o = sigmf(v);
;       sT[row * 136 + col] = f2bf(o);
;     });
.LBB0_1012:
	v_bfe_u32 v33, v32, 16, 1
	v_add3_u32 v32, v32, v33, s79
	s_and_b64 vcc, exec, s[6:7]
	ds_write_b16_d16_hi v50, v32 offset:64
	s_cbranch_vccz .Lsg_180

; __device__ __forceinline__ float sigmf(float x) { return 1.f / (1.f + __expf(-x)); }
; __device__ __forceinline__ void inproj_epilogue(const Params& p, int layer, int mt, int ntile, int tid,
;                                                 f32x16 (&acc)[2][2], unsigned char* smem) {
;     ...
;     acc_foreach(tid, acc, [&](int row, int col, float v) {
;       int t = m0 + row;
;       float o = v;
;       if (mode == 1) o = (t >= NPADR) ? v : 0.f;
;       if (mode == 2) o = sigmf(v);
;       sT[row * 136 + col] = f2bf(o);
;     });
.LBB0_1015:
	v_bfe_u32 v33, v32, 16, 1
	v_add3_u32 v32, v32, v33, s79
	s_and_b64 vcc, exec, s[6:7]
	ds_write_b16_d16_hi v51, v32 offset:64
	s_cbranch_vccz .Lsg_181

; __device__ __forceinline__ float sigmf(float x) { return 1.f / (1.f + __expf(-x)); }
; __device__ __forceinline__ void inproj_epilogue(const Params& p, int layer, int mt, int ntile, int tid,
;                                                 f32x16 (&acc)[2][2], unsigned char* smem) {
;     ...
;     acc_foreach(tid, acc, [&](int row, int col, float v) {
;       int t = m0 + row;
;       float o = v;
;       if (mode == 1) o = (t >= NPADR) ? v : 0.f;
;       if (mode == 2) o = sigmf(v);
;       sT[row * 136 + col] = f2bf(o);
;     });
.LBB0_1018:
	v_bfe_u32 v33, v32, 16, 1
	v_add3_u32 v32, v32, v33, s79
	s_and_b64 vcc, exec, s[6:7]
	ds_write_b16_d16_hi v52, v32 offset:64
	s_cbranch_vccz .Lsg_182

; __device__ __forceinline__ float sigmf(float x) { return 1.f / (1.f + __expf(-x)); }
; __device__ __forceinline__ void inproj_epilogue(const Params& p, int layer, int mt, int ntile, int tid,
;                                                 f32x16 (&acc)[2][2], unsigned char* smem) {
;     ...
;     acc_foreach(tid, acc, [&](int row, int col, float v) {
;       int t = m0 + row;
;       float o = v;
;       if (mode == 1) o = (t >= NPADR) ? v : 0.f;
;       if (mode == 2) o = sigmf(v);
;       sT[row * 136 + col] = f2bf(o);
;     });
.LBB0_1021:
	v_bfe_u32 v33, v32, 16, 1
	v_add3_u32 v32, v32, v33, s79
	s_and_b64 vcc, exec, s[6:7]
	ds_write_b16_d16_hi v53, v32 offset:64
	s_cbranch_vccz .Lsg_183

; __device__ __forceinline__ float sigmf(float x) { return 1.f / (1.f + __expf(-x)); }
; __device__ __forceinline__ void inproj_epilogue(const Params& p, int layer, int mt, int ntile, int tid,
;                                                 f32x16 (&acc)[2][2], unsigned char* smem) {
;     ...
;     acc_foreach(tid, acc, [&](int row, int col, float v) {
;       int t = m0 + row;
;       float o = v;
;       if (mode == 1) o = (t >= NPADR) ? v : 0.f;
;       if (mode == 2) o = sigmf(v);
;       sT[row * 136 + col] = f2bf(o);
;     });
.LBB0_1024:
	v_bfe_u32 v33, v32, 16, 1
	v_add3_u32 v32, v32, v33, s79
	s_and_b64 vcc, exec, s[6:7]
	ds_write_b16_d16_hi v54, v32 offset:64
	s_cbranch_vccz .Lsg_184

; __device__ __forceinline__ float sigmf(float x) { return 1.f / (1.f + __expf(-x)); }
; __device__ __forceinline__ void inproj_epilogue(const Params& p, int layer, int mt, int ntile, int tid,
;                                                 f32x16 (&acc)[2][2], unsigned char* smem) {
;     ...
;     acc_foreach(tid, acc, [&](int row, int col, float v) {
;       int t = m0 + row;
;       float o = v;
;       if (mode == 1) o = (t >= NPADR) ? v : 0.f;
;       if (mode == 2) o = sigmf(v);
;       sT[row * 136 + col] = f2bf(o);
;     });
.LBB0_1027:
	v_bfe_u32 v33, v32, 16, 1
	v_add3_u32 v32, v32, v33, s79
	s_and_b64 vcc, exec, s[6:7]
	ds_write_b16_d16_hi v56, v32 offset:64
	s_cbranch_vccz .Lsg_185

; __device__ __forceinline__ float sigmf(float x) { return 1.f / (1.f + __expf(-x)); }
; __device__ __forceinline__ void inproj_epilogue(const Params& p, int layer, int mt, int ntile, int tid,
;                                                 f32x16 (&acc)[2][2], unsigned char* smem) {
;     ...
;     acc_foreach(tid, acc, [&](int row, int col, float v) {
;       int t = m0 + row;
;       float o = v;
;       if (mode == 1) o = (t >= NPADR) ? v : 0.f;
;       if (mode == 2) o = sigmf(v);
;       sT[row * 136 + col] = f2bf(o);
;     });
.LBB0_1030:
	v_bfe_u32 v33, v32, 16, 1
	v_add3_u32 v32, v32, v33, s79
	s_and_b64 vcc, exec, s[6:7]
	ds_write_b16_d16_hi v57, v32 offset:64
	s_cbranch_vccz .Lsg_186

; __device__ __forceinline__ float sigmf(float x) { return 1.f / (1.f + __expf(-x)); }
; __device__ __forceinline__ void inproj_epilogue(const Params& p, int layer, int mt, int ntile, int tid,
;                                                 f32x16 (&acc)[2][2], unsigned char* smem) {
;     ...
;     acc_foreach(tid, acc, [&](int row, int col, float v) {
;       int t = m0 + row;
;       float o = v;
;       if (mode == 1) o = (t >= NPADR) ? v : 0.f;
;       if (mode == 2) o = sigmf(v);
;       sT[row * 136 + col] = f2bf(o);
;     });
.LBB0_1033:
	v_bfe_u32 v33, v32, 16, 1
	v_add3_u32 v32, v32, v33, s79
	s_and_b64 vcc, exec, s[6:7]
	ds_write_b16_d16_hi v58, v32 offset:64
	s_cbranch_vccz .Lsg_187

; __device__ __forceinline__ float sigmf(float x) { return 1.f / (1.f + __expf(-x)); }
; __device__ __forceinline__ void inproj_epilogue(const Params& p, int layer, int mt, int ntile, int tid,
;                                                 f32x16 (&acc)[2][2], unsigned char* smem) {
;     ...
;     acc_foreach(tid, acc, [&](int row, int col, float v) {
;       int t = m0 + row;
;       float o = v;
;       if (mode == 1) o = (t >= NPADR) ? v : 0.f;
;       if (mode == 2) o = sigmf(v);
;       sT[row * 136 + col] = f2bf(o);
;     });
.LBB0_1036:
	v_bfe_u32 v33, v32, 16, 1
	v_add3_u32 v32, v32, v33, s79
	s_and_b64 vcc, exec, s[6:7]
	ds_write_b16_d16_hi v59, v32 offset:64
	s_cbranch_vccz .Lsg_188

; __device__ __forceinline__ float sigmf(float x) { return 1.f / (1.f + __expf(-x)); }
; __device__ __forceinline__ void inproj_epilogue(const Params& p, int layer, int mt, int ntile, int tid,
;                                                 f32x16 (&acc)[2][2], unsigned char* smem) {
;     ...
;     acc_foreach(tid, acc, [&](int row, int col, float v) {
;       int t = m0 + row;
;       float o = v;
;       if (mode == 1) o = (t >= NPADR) ? v : 0.f;
;       if (mode == 2) o = sigmf(v);
;       sT[row * 136 + col] = f2bf(o);
;     });
.LBB0_1039:
	v_bfe_u32 v33, v32, 16, 1
	v_add3_u32 v32, v32, v33, s79
	s_and_b64 vcc, exec, s[6:7]
	ds_write_b16_d16_hi v60, v32 offset:64
	s_cbranch_vccz .Lsg_189

; __device__ __forceinline__ float sigmf(float x) { return 1.f / (1.f + __expf(-x)); }
; __device__ __forceinline__ void inproj_epilogue(const Params& p, int layer, int mt, int ntile, int tid,
;                                                 f32x16 (&acc)[2][2], unsigned char* smem) {
;     ...
;     acc_foreach(tid, acc, [&](int row, int col, float v) {
;       int t = m0 + row;
;       float o = v;
;       if (mode == 1) o = (t >= NPADR) ? v : 0.f;
;       if (mode == 2) o = sigmf(v);
;       sT[row * 136 + col] = f2bf(o);
;     });
.LBB0_1042:
	v_bfe_u32 v33, v32, 16, 1
	v_add3_u32 v32, v32, v33, s79
	s_and_b64 vcc, exec, s[6:7]
	ds_write_b16_d16_hi v61, v32 offset:64
	s_cbranch_vccz .Lsg_190

; __device__ __forceinline__ float sigmf(float x) { return 1.f / (1.f + __expf(-x)); }
; __device__ __forceinline__ void inproj_epilogue(const Params& p, int layer, int mt, int ntile, int tid,
;                                                 f32x16 (&acc)[2][2], unsigned char* smem) {
;     ...
;     acc_foreach(tid, acc, [&](int row, int col, float v) {
;       int t = m0 + row;
;       float o = v;
;       if (mode == 1) o = (t >= NPADR) ? v : 0.f;
;       if (mode == 2) o = sigmf(v);
;       sT[row * 136 + col] = f2bf(o);
;     });
.LBB0_1045:
	v_bfe_u32 v33, v32, 16, 1
	v_add3_u32 v32, v32, v33, s79
	s_and_b64 vcc, exec, s[6:7]
	ds_write_b16_d16_hi v62, v32 offset:64
	s_cbranch_vccz .Lsg_191

; __device__ __forceinline__ float sigmf(float x) { return 1.f / (1.f + __expf(-x)); }
; __device__ __forceinline__ void inproj_epilogue(const Params& p, int layer, int mt, int ntile, int tid,
;                                                 f32x16 (&acc)[2][2], unsigned char* smem) {
;     ...
;     acc_foreach(tid, acc, [&](int row, int col, float v) {
;       int t = m0 + row;
;       float o = v;
;       if (mode == 1) o = (t >= NPADR) ? v : 0.f;
;       if (mode == 2) o = sigmf(v);
;       sT[row * 136 + col] = f2bf(o);
;     });
.LBB0_1048:
	v_bfe_u32 v33, v32, 16, 1
	v_add3_u32 v32, v32, v33, s79
	s_and_b64 vcc, exec, s[6:7]
	ds_write_b16_d16_hi v55, v32 offset:64
	s_cbranch_vccz .Lsg_192

; __device__ __forceinline__ float softplusf(float x) { return fmaxf(x, 0.f) + __logf(1.f + __expf(-fabsf(x))); }
; __device__ __forceinline__ float sigmf(float x) { return 1.f / (1.f + __expf(-x)); }
; __device__ __forceinline__ void inproj_epilogue(const Params& p, int layer, int mt, int ntile, int tid,
;                                                 f32x16 (&acc)[2][2], unsigned char* smem) {
;     ...
;   const int m0 = mt * 128;
;   if (mode == 3) {
;     float* dt = (float*)(p.ws + OFF_DT) + (size_t)m0 * 16;
;     const float* bias = p.ssd_dt_bias + layer * 16;
;     acc_foreach(tid, acc, [&](int row, int col, float v) {
;       if (col < 16) *(dt + row * 16 + col) = softplusf(v + bias[col]);
;     });
;   } else {
;     bf16r* dstb = dst + (size_t)m0 * ld + c0;
;     bf16r* sT = (bf16r*)smem;
;     acc_foreach(tid, acc, [&](int row, int col, float v) {
;       int t = m0 + row;
;       float o = v;
;       if (mode == 1) o = (t >= NPADR) ? v : 0.f;
;       if (mode == 2) o = sigmf(v);
;       sT[row * 136 + col] = f2bf(o);
.LBB0_1642:
	s_lshl_b32 s96, s6, 7
	s_ashr_i32 s97, s96, 31
	s_cmp_lg_u32 s7, 3
	s_mov_b64 s[4:5], -1
	s_cbranch_scc0 .LBB0_1836
	v_mov_b32_e32 v106, v108
	s_movk_i32 s4, 0xffc0
	v_lshrrev_b32_e32 v107, 3, v106
	v_ashrrev_i32_e32 v96, 1, v106
	v_and_b32_e32 v107, 4, v107
	v_and_or_b32 v96, v96, s4, v107
	s_cmp_eq_u32 s7, 1
	s_cselect_b64 s[4:5], -1, 0
	v_add_u32_e32 v107, s96, v96
	s_cmp_eq_u32 s7, 2
	s_cselect_b64 s[12:13], -1, 0
	s_cmp_lg_u32 s7, 2
	v_cmp_lt_i32_e64 s[8:9], s76, v107
	s_cbranch_scc0 .Lsg_193

; __device__ __forceinline__ float sigmf(float x) { return 1.f / (1.f + __expf(-x)); }
; __device__ __forceinline__ void inproj_epilogue(const Params& p, int layer, int mt, int ntile, int tid,
;                                                 f32x16 (&acc)[2][2], unsigned char* smem) {
;     ...
;     acc_foreach(tid, acc, [&](int row, int col, float v) {
;       int t = m0 + row;
;       float o = v;
;       if (mode == 1) o = (t >= NPADR) ? v : 0.f;
;       if (mode == 2) o = sigmf(v);
;       sT[row * 136 + col] = f2bf(o);
;     });
.LBB0_1646:
	v_bfe_u32 v110, v107, 16, 1
	v_and_b32_e32 v106, 0x5f, v106
	v_add3_u32 v111, v107, v110, s78
	v_mul_lo_u32 v110, v96, s79
	v_lshl_add_u32 v107, v106, 1, v110
	ds_write_b16_d16_hi v107, v111
	v_add3_u32 v111, s96, v96, 1
	v_cmp_lt_i32_e64 s[10:11], s76, v111
	v_cndmask_b32_e64 v111, 0, 1, s[12:13]
	v_cmp_ne_u32_e64 s[6:7], 1, v111
	s_andn2_b64 vcc, exec, s[12:13]
	s_cbranch_vccz .Lsg_194

; __device__ __forceinline__ float sigmf(float x) { return 1.f / (1.f + __expf(-x)); }
; __device__ __forceinline__ void inproj_epilogue(const Params& p, int layer, int mt, int ntile, int tid,
;                                                 f32x16 (&acc)[2][2], unsigned char* smem) {
;     ...
;     acc_foreach(tid, acc, [&](int row, int col, float v) {
;       int t = m0 + row;
;       float o = v;
;       if (mode == 1) o = (t >= NPADR) ? v : 0.f;
;       if (mode == 2) o = sigmf(v);
;       sT[row * 136 + col] = f2bf(o);
;     });
.LBB0_1649:
	v_bfe_u32 v112, v111, 16, 1
	v_add3_u32 v112, v111, v112, s78
	v_add_u32_e32 v111, 0x110, v110
	v_lshl_add_u32 v110, v106, 1, v111
	ds_write_b16_d16_hi v110, v112
	v_add3_u32 v112, s96, v96, 2
	s_and_b64 vcc, exec, s[6:7]
	v_cmp_lt_i32_e64 s[12:13], s76, v112
	s_cbranch_vccz .Lsg_195

; __device__ __forceinline__ float sigmf(float x) { return 1.f / (1.f + __expf(-x)); }
; __device__ __forceinline__ void inproj_epilogue(const Params& p, int layer, int mt, int ntile, int tid,
;                                                 f32x16 (&acc)[2][2], unsigned char* smem) {
;     ...
;     acc_foreach(tid, acc, [&](int row, int col, float v) {
;       int t = m0 + row;
;       float o = v;
;       if (mode == 1) o = (t >= NPADR) ? v : 0.f;
;       if (mode == 2) o = sigmf(v);
;       sT[row * 136 + col] = f2bf(o);
;     });
.LBB0_1652:
	v_bfe_u32 v113, v112, 16, 1
	v_add3_u32 v113, v112, v113, s78
	v_add_u32_e32 v112, 0x110, v111
	v_lshl_add_u32 v111, v106, 1, v112
	ds_write_b16_d16_hi v111, v113
	v_add3_u32 v113, s96, v96, 3
	s_and_b64 vcc, exec, s[6:7]
	v_cmp_lt_i32_e64 s[14:15], s76, v113
	s_cbranch_vccz .Lsg_196

; __device__ __forceinline__ float sigmf(float x) { return 1.f / (1.f + __expf(-x)); }
; __device__ __forceinline__ void inproj_epilogue(const Params& p, int layer, int mt, int ntile, int tid,
;                                                 f32x16 (&acc)[2][2], unsigned char* smem) {
;     ...
;     acc_foreach(tid, acc, [&](int row, int col, float v) {
;       int t = m0 + row;
;       float o = v;
;       if (mode == 1) o = (t >= NPADR) ? v : 0.f;
;       if (mode == 2) o = sigmf(v);
;       sT[row * 136 + col] = f2bf(o);
;     });
.LBB0_1655:
	v_bfe_u32 v114, v113, 16, 1
	v_add3_u32 v114, v113, v114, s78
	v_add_u32_e32 v113, 0x110, v112
	v_lshl_add_u32 v112, v106, 1, v113
	ds_write_b16_d16_hi v112, v114
	v_add3_u32 v114, s96, v96, 8
	s_and_b64 vcc, exec, s[6:7]
	v_cmp_lt_i32_e64 s[16:17], s76, v114
	s_cbranch_vccz .Lsg_197

; __device__ __forceinline__ float sigmf(float x) { return 1.f / (1.f + __expf(-x)); }
; __device__ __forceinline__ void inproj_epilogue(const Params& p, int layer, int mt, int ntile, int tid,
;                                                 f32x16 (&acc)[2][2], unsigned char* smem) {
;     ...
;     acc_foreach(tid, acc, [&](int row, int col, float v) {
;       int t = m0 + row;
;       float o = v;
;       if (mode == 1) o = (t >= NPADR) ? v : 0.f;
;       if (mode == 2) o = sigmf(v);
;       sT[row * 136 + col] = f2bf(o);
;     });
.LBB0_1658:
	v_bfe_u32 v115, v114, 16, 1
	v_add3_u32 v115, v114, v115, s78
	v_add_u32_e32 v114, 0x550, v113
	v_lshl_add_u32 v113, v106, 1, v114
	ds_write_b16_d16_hi v113, v115
	v_add3_u32 v115, s96, v96, 9
	s_and_b64 vcc, exec, s[6:7]
	v_cmp_lt_i32_e64 s[18:19], s76, v115
	s_cbranch_vccz .Lsg_198

; __device__ __forceinline__ float sigmf(float x) { return 1.f / (1.f + __expf(-x)); }
; __device__ __forceinline__ void inproj_epilogue(const Params& p, int layer, int mt, int ntile, int tid,
;                                                 f32x16 (&acc)[2][2], unsigned char* smem) {
;     ...
;     acc_foreach(tid, acc, [&](int row, int col, float v) {
;       int t = m0 + row;
;       float o = v;
;       if (mode == 1) o = (t >= NPADR) ? v : 0.f;
;       if (mode == 2) o = sigmf(v);
;       sT[row * 136 + col] = f2bf(o);
;     });
.LBB0_1661:
	v_bfe_u32 v116, v115, 16, 1
	v_add3_u32 v116, v115, v116, s78
	v_add_u32_e32 v115, 0x110, v114
	v_lshl_add_u32 v114, v106, 1, v115
	ds_write_b16_d16_hi v114, v116
	v_add3_u32 v116, s96, v96, 10
	s_and_b64 vcc, exec, s[6:7]
	v_cmp_lt_i32_e64 s[20:21], s76, v116
	s_cbranch_vccz .Lsg_199

; __device__ __forceinline__ float sigmf(float x) { return 1.f / (1.f + __expf(-x)); }
; __device__ __forceinline__ void inproj_epilogue(const Params& p, int layer, int mt, int ntile, int tid,
;                                                 f32x16 (&acc)[2][2], unsigned char* smem) {
;     ...
;     acc_foreach(tid, acc, [&](int row, int col, float v) {
;       int t = m0 + row;
;       float o = v;
;       if (mode == 1) o = (t >= NPADR) ? v : 0.f;
;       if (mode == 2) o = sigmf(v);
;       sT[row * 136 + col] = f2bf(o);
;     });
.LBB0_1664:
	v_bfe_u32 v117, v116, 16, 1
	v_add3_u32 v117, v116, v117, s78
	v_add_u32_e32 v116, 0x110, v115
	v_lshl_add_u32 v115, v106, 1, v116
	ds_write_b16_d16_hi v115, v117
	v_add3_u32 v117, s96, v96, 11
	s_and_b64 vcc, exec, s[6:7]
	v_cmp_lt_i32_e64 s[22:23], s76, v117
	s_cbranch_vccz .Lsg_200

; __device__ __forceinline__ float sigmf(float x) { return 1.f / (1.f + __expf(-x)); }
; __device__ __forceinline__ void inproj_epilogue(const Params& p, int layer, int mt, int ntile, int tid,
;                                                 f32x16 (&acc)[2][2], unsigned char* smem) {
;     ...
;     acc_foreach(tid, acc, [&](int row, int col, float v) {
;       int t = m0 + row;
;       float o = v;
;       if (mode == 1) o = (t >= NPADR) ? v : 0.f;
;       if (mode == 2) o = sigmf(v);
;       sT[row * 136 + col] = f2bf(o);
;     });
.LBB0_1667:
	v_bfe_u32 v118, v117, 16, 1
	v_add_u32_e32 v116, 0x110, v116
	v_add3_u32 v118, v117, v118, s78
	v_lshl_add_u32 v117, v106, 1, v116
	ds_write_b16_d16_hi v117, v118
	v_add3_u32 v118, s96, v96, 16
	s_and_b64 vcc, exec, s[6:7]
	v_cmp_lt_i32_e64 s[24:25], s76, v118
	s_cbranch_vccz .Lsg_201

; __device__ __forceinline__ float sigmf(float x) { return 1.f / (1.f + __expf(-x)); }
; __device__ __forceinline__ void inproj_epilogue(const Params& p, int layer, int mt, int ntile, int tid,
;                                                 f32x16 (&acc)[2][2], unsigned char* smem) {
;     ...
;     acc_foreach(tid, acc, [&](int row, int col, float v) {
;       int t = m0 + row;
;       float o = v;
;       if (mode == 1) o = (t >= NPADR) ? v : 0.f;
;       if (mode == 2) o = sigmf(v);
;       sT[row * 136 + col] = f2bf(o);
;     });
.LBB0_1670:
	v_bfe_u32 v119, v118, 16, 1
	v_add_u32_e32 v116, 0x550, v116
	v_add3_u32 v119, v118, v119, s78
	v_lshl_add_u32 v118, v106, 1, v116
	ds_write_b16_d16_hi v118, v119
	v_add3_u32 v119, s96, v96, 17
	s_and_b64 vcc, exec, s[6:7]
	v_cmp_lt_i32_e64 s[26:27], s76, v119
	s_cbranch_vccz .Lsg_202

; __device__ __forceinline__ float sigmf(float x) { return 1.f / (1.f + __expf(-x)); }
; __device__ __forceinline__ void inproj_epilogue(const Params& p, int layer, int mt, int ntile, int tid,
;                                                 f32x16 (&acc)[2][2], unsigned char* smem) {
;     ...
;     acc_foreach(tid, acc, [&](int row, int col, float v) {
;       int t = m0 + row;
;       float o = v;
;       if (mode == 1) o = (t >= NPADR) ? v : 0.f;
;       if (mode == 2) o = sigmf(v);
;       sT[row * 136 + col] = f2bf(o);
;     });
.LBB0_1673:
	v_bfe_u32 v120, v119, 16, 1
	v_add_u32_e32 v116, 0x110, v116
	v_add3_u32 v120, v119, v120, s78
	v_lshl_add_u32 v119, v106, 1, v116
	ds_write_b16_d16_hi v119, v120
	v_add3_u32 v120, s96, v96, 18
	s_and_b64 vcc, exec, s[6:7]
	v_cmp_lt_i32_e64 s[28:29], s76, v120
	s_cbranch_vccz .Lsg_203

; __device__ __forceinline__ float sigmf(float x) { return 1.f / (1.f + __expf(-x)); }
; __device__ __forceinline__ void inproj_epilogue(const Params& p, int layer, int mt, int ntile, int tid,
;                                                 f32x16 (&acc)[2][2], unsigned char* smem) {
;     ...
;     acc_foreach(tid, acc, [&](int row, int col, float v) {
;       int t = m0 + row;
;       float o = v;
;       if (mode == 1) o = (t >= NPADR) ? v : 0.f;
;       if (mode == 2) o = sigmf(v);
;       sT[row * 136 + col] = f2bf(o);
;     });
.LBB0_1676:
	v_bfe_u32 v121, v120, 16, 1
	v_add_u32_e32 v116, 0x110, v116
	v_add3_u32 v121, v120, v121, s78
	v_lshl_add_u32 v120, v106, 1, v116
	ds_write_b16_d16_hi v120, v121
	v_add3_u32 v121, s96, v96, 19
	s_and_b64 vcc, exec, s[6:7]
	v_cmp_lt_i32_e64 s[30:31], s76, v121
	s_cbranch_vccz .Lsg_204

; __device__ __forceinline__ float sigmf(float x) { return 1.f / (1.f + __expf(-x)); }
; __device__ __forceinline__ void inproj_epilogue(const Params& p, int layer, int mt, int ntile, int tid,
;                                                 f32x16 (&acc)[2][2], unsigned char* smem) {
;     ...
;     acc_foreach(tid, acc, [&](int row, int col, float v) {
;       int t = m0 + row;
;       float o = v;
;       if (mode == 1) o = (t >= NPADR) ? v : 0.f;
;       if (mode == 2) o = sigmf(v);
;       sT[row * 136 + col] = f2bf(o);
;     });
.LBB0_1679:
	v_bfe_u32 v122, v121, 16, 1
	v_add_u32_e32 v116, 0x110, v116
	v_add3_u32 v122, v121, v122, s78
	v_lshl_add_u32 v121, v106, 1, v116
	ds_write_b16_d16_hi v121, v122
	v_add3_u32 v122, s96, v96, 24
	s_and_b64 vcc, exec, s[6:7]
	v_cmp_lt_i32_e64 s[34:35], s76, v122
	s_cbranch_vccz .Lsg_205

; __device__ __forceinline__ float sigmf(float x) { return 1.f / (1.f + __expf(-x)); }
; __device__ __forceinline__ void inproj_epilogue(const Params& p, int layer, int mt, int ntile, int tid,
;                                                 f32x16 (&acc)[2][2], unsigned char* smem) {
;     ...
;     acc_foreach(tid, acc, [&](int row, int col, float v) {
;       int t = m0 + row;
;       float o = v;
;       if (mode == 1) o = (t >= NPADR) ? v : 0.f;
;       if (mode == 2) o = sigmf(v);
;       sT[row * 136 + col] = f2bf(o);
;     });
.LBB0_1682:
	v_bfe_u32 v123, v122, 16, 1
	v_add_u32_e32 v116, 0x550, v116
	v_add3_u32 v123, v122, v123, s78
	v_lshl_add_u32 v122, v106, 1, v116
	ds_write_b16_d16_hi v122, v123
	v_add3_u32 v123, s96, v96, 25
	s_and_b64 vcc, exec, s[6:7]
	v_cmp_lt_i32_e64 s[36:37], s76, v123
	s_cbranch_vccz .Lsg_206

; __device__ __forceinline__ float sigmf(float x) { return 1.f / (1.f + __expf(-x)); }
; __device__ __forceinline__ void inproj_epilogue(const Params& p, int layer, int mt, int ntile, int tid,
;                                                 f32x16 (&acc)[2][2], unsigned char* smem) {
;     ...
;     acc_foreach(tid, acc, [&](int row, int col, float v) {
;       int t = m0 + row;
;       float o = v;
;       if (mode == 1) o = (t >= NPADR) ? v : 0.f;
;       if (mode == 2) o = sigmf(v);
;       sT[row * 136 + col] = f2bf(o);
;     });
.LBB0_1685:
	v_bfe_u32 v124, v123, 16, 1
	v_add_u32_e32 v116, 0x110, v116
	v_add3_u32 v124, v123, v124, s78
	v_lshl_add_u32 v123, v106, 1, v116
	ds_write_b16_d16_hi v123, v124
	v_add3_u32 v124, s96, v96, 26
	s_and_b64 vcc, exec, s[6:7]
	v_cmp_lt_i32_e64 s[38:39], s76, v124
	s_cbranch_vccz .Lsg_207

; __device__ __forceinline__ float sigmf(float x) { return 1.f / (1.f + __expf(-x)); }
; __device__ __forceinline__ void inproj_epilogue(const Params& p, int layer, int mt, int ntile, int tid,
;                                                 f32x16 (&acc)[2][2], unsigned char* smem) {
;     ...
;     acc_foreach(tid, acc, [&](int row, int col, float v) {
;       int t = m0 + row;
;       float o = v;
;       if (mode == 1) o = (t >= NPADR) ? v : 0.f;
;       if (mode == 2) o = sigmf(v);
;       sT[row * 136 + col] = f2bf(o);
;     });
.LBB0_1688:
	v_bfe_u32 v125, v124, 16, 1
	v_add_u32_e32 v116, 0x110, v116
	v_add3_u32 v124, v124, v125, s78
	v_lshl_add_u32 v116, v106, 1, v116
	ds_write_b16_d16_hi v116, v124
	v_add3_u32 v124, s96, v96, 27
	s_and_b64 vcc, exec, s[6:7]
	v_cmp_lt_i32_e64 s[40:41], s76, v124
	s_cbranch_vccz .Lsg_208

; __device__ __forceinline__ float sigmf(float x) { return 1.f / (1.f + __expf(-x)); }
; __device__ __forceinline__ void inproj_epilogue(const Params& p, int layer, int mt, int ntile, int tid,
;                                                 f32x16 (&acc)[2][2], unsigned char* smem) {
;     ...
;     acc_foreach(tid, acc, [&](int row, int col, float v) {
;       int t = m0 + row;
;       float o = v;
;       if (mode == 1) o = (t >= NPADR) ? v : 0.f;
;       if (mode == 2) o = sigmf(v);
;       sT[row * 136 + col] = f2bf(o);
;     });
.LBB0_1739:
	v_bfe_u32 v50, v48, 16, 1
	v_add_u32_e32 v49, 0x110, v116
	v_add3_u32 v48, v48, v50, s78
	ds_write_b16_d16_hi v49, v48 offset:64
	v_or_b32_e32 v48, 32, v96
	v_add_u32_e32 v49, s96, v48
	s_and_b64 vcc, exec, s[6:7]
	v_cmp_lt_i32_e64 s[8:9], s76, v49
	s_cbranch_vccz .Lsg_225

; __device__ __forceinline__ float sigmf(float x) { return 1.f / (1.f + __expf(-x)); }
; __device__ __forceinline__ void inproj_epilogue(const Params& p, int layer, int mt, int ntile, int tid,
;                                                 f32x16 (&acc)[2][2], unsigned char* smem) {
;     ...
;     acc_foreach(tid, acc, [&](int row, int col, float v) {
;       int t = m0 + row;
;       float o = v;
;       if (mode == 1) o = (t >= NPADR) ? v : 0.f;
;       if (mode == 2) o = sigmf(v);
;       sT[row * 136 + col] = f2bf(o);
;     });
.LBB0_1742:
	v_bfe_u32 v50, v49, 16, 1
	v_add3_u32 v50, v49, v50, s78
	v_mul_lo_u32 v49, v48, s79
	v_lshl_add_u32 v48, v106, 1, v49
	ds_write_b16_d16_hi v48, v50
	v_add3_u32 v50, s96, v96, 33
	s_and_b64 vcc, exec, s[6:7]
	v_cmp_lt_i32_e64 s[10:11], s76, v50
	s_cbranch_vccz .Lsg_226

; __device__ __forceinline__ float sigmf(float x) { return 1.f / (1.f + __expf(-x)); }
; __device__ __forceinline__ void inproj_epilogue(const Params& p, int layer, int mt, int ntile, int tid,
;                                                 f32x16 (&acc)[2][2], unsigned char* smem) {
;     ...
;     acc_foreach(tid, acc, [&](int row, int col, float v) {
;       int t = m0 + row;
;       float o = v;
;       if (mode == 1) o = (t >= NPADR) ? v : 0.f;
;       if (mode == 2) o = sigmf(v);
;       sT[row * 136 + col] = f2bf(o);
;     });
.LBB0_1745:
	v_bfe_u32 v51, v50, 16, 1
	v_add3_u32 v51, v50, v51, s78
	v_add_u32_e32 v50, 0x110, v49
	v_lshl_add_u32 v49, v106, 1, v50
	ds_write_b16_d16_hi v49, v51
	v_add3_u32 v51, s96, v96, 34
	s_and_b64 vcc, exec, s[6:7]
	v_cmp_lt_i32_e64 s[12:13], s76, v51
	s_cbranch_vccz .Lsg_227

; __device__ __forceinline__ float sigmf(float x) { return 1.f / (1.f + __expf(-x)); }
; __device__ __forceinline__ void inproj_epilogue(const Params& p, int layer, int mt, int ntile, int tid,
;                                                 f32x16 (&acc)[2][2], unsigned char* smem) {
;     ...
;     acc_foreach(tid, acc, [&](int row, int col, float v) {
;       int t = m0 + row;
;       float o = v;
;       if (mode == 1) o = (t >= NPADR) ? v : 0.f;
;       if (mode == 2) o = sigmf(v);
;       sT[row * 136 + col] = f2bf(o);
;     });
.LBB0_1748:
	v_bfe_u32 v52, v51, 16, 1
	v_add3_u32 v52, v51, v52, s78
	v_add_u32_e32 v51, 0x110, v50
	v_lshl_add_u32 v50, v106, 1, v51
	ds_write_b16_d16_hi v50, v52
	v_add3_u32 v52, s96, v96, 35
	s_and_b64 vcc, exec, s[6:7]
	v_cmp_lt_i32_e64 s[14:15], s76, v52
	s_cbranch_vccz .Lsg_228

; __device__ __forceinline__ float sigmf(float x) { return 1.f / (1.f + __expf(-x)); }
; __device__ __forceinline__ void inproj_epilogue(const Params& p, int layer, int mt, int ntile, int tid,
;                                                 f32x16 (&acc)[2][2], unsigned char* smem) {
;     ...
;     acc_foreach(tid, acc, [&](int row, int col, float v) {
;       int t = m0 + row;
;       float o = v;
;       if (mode == 1) o = (t >= NPADR) ? v : 0.f;
;       if (mode == 2) o = sigmf(v);
;       sT[row * 136 + col] = f2bf(o);
;     });
.LBB0_1751:
	v_bfe_u32 v53, v52, 16, 1
	v_add3_u32 v53, v52, v53, s78
	v_add_u32_e32 v52, 0x110, v51
	v_lshl_add_u32 v51, v106, 1, v52
	ds_write_b16_d16_hi v51, v53
	v_add3_u32 v53, s96, v96, 40
	s_and_b64 vcc, exec, s[6:7]
	v_cmp_lt_i32_e64 s[16:17], s76, v53
	s_cbranch_vccz .Lsg_229

; __device__ __forceinline__ float sigmf(float x) { return 1.f / (1.f + __expf(-x)); }
; __device__ __forceinline__ void inproj_epilogue(const Params& p, int layer, int mt, int ntile, int tid,
;                                                 f32x16 (&acc)[2][2], unsigned char* smem) {
;     ...
;     acc_foreach(tid, acc, [&](int row, int col, float v) {
;       int t = m0 + row;
;       float o = v;
;       if (mode == 1) o = (t >= NPADR) ? v : 0.f;
;       if (mode == 2) o = sigmf(v);
;       sT[row * 136 + col] = f2bf(o);
;     });
.LBB0_1754:
	v_bfe_u32 v54, v53, 16, 1
	v_add3_u32 v54, v53, v54, s78
	v_add_u32_e32 v53, 0x550, v52
	v_lshl_add_u32 v52, v106, 1, v53
	ds_write_b16_d16_hi v52, v54
	v_add3_u32 v54, s96, v96, 41
	s_and_b64 vcc, exec, s[6:7]
	v_cmp_lt_i32_e64 s[18:19], s76, v54
	s_cbranch_vccz .Lsg_230

; __device__ __forceinline__ float sigmf(float x) { return 1.f / (1.f + __expf(-x)); }
; __device__ __forceinline__ void inproj_epilogue(const Params& p, int layer, int mt, int ntile, int tid,
;                                                 f32x16 (&acc)[2][2], unsigned char* smem) {
;     ...
;     acc_foreach(tid, acc, [&](int row, int col, float v) {
;       int t = m0 + row;
;       float o = v;
;       if (mode == 1) o = (t >= NPADR) ? v : 0.f;
;       if (mode == 2) o = sigmf(v);
;       sT[row * 136 + col] = f2bf(o);
;     });
.LBB0_1757:
	v_bfe_u32 v55, v54, 16, 1
	v_add3_u32 v55, v54, v55, s78
	v_add_u32_e32 v54, 0x110, v53
	v_lshl_add_u32 v53, v106, 1, v54
	ds_write_b16_d16_hi v53, v55
	v_add3_u32 v55, s96, v96, 42
	s_and_b64 vcc, exec, s[6:7]
	v_cmp_lt_i32_e64 s[20:21], s76, v55
	s_cbranch_vccz .Lsg_231

; __device__ __forceinline__ float sigmf(float x) { return 1.f / (1.f + __expf(-x)); }
; __device__ __forceinline__ void inproj_epilogue(const Params& p, int layer, int mt, int ntile, int tid,
;                                                 f32x16 (&acc)[2][2], unsigned char* smem) {
;     ...
;     acc_foreach(tid, acc, [&](int row, int col, float v) {
;       int t = m0 + row;
;       float o = v;
;       if (mode == 1) o = (t >= NPADR) ? v : 0.f;
;       if (mode == 2) o = sigmf(v);
;       sT[row * 136 + col] = f2bf(o);
;     });
.LBB0_1760:
	v_bfe_u32 v56, v55, 16, 1
	v_add3_u32 v56, v55, v56, s78
	v_add_u32_e32 v55, 0x110, v54
	v_lshl_add_u32 v54, v106, 1, v55
	ds_write_b16_d16_hi v54, v56
	v_add3_u32 v56, s96, v96, 43
	s_and_b64 vcc, exec, s[6:7]
	v_cmp_lt_i32_e64 s[22:23], s76, v56
	s_cbranch_vccz .Lsg_232

; __device__ __forceinline__ float sigmf(float x) { return 1.f / (1.f + __expf(-x)); }
; __device__ __forceinline__ void inproj_epilogue(const Params& p, int layer, int mt, int ntile, int tid,
;                                                 f32x16 (&acc)[2][2], unsigned char* smem) {
;     ...
;     acc_foreach(tid, acc, [&](int row, int col, float v) {
;       int t = m0 + row;
;       float o = v;
;       if (mode == 1) o = (t >= NPADR) ? v : 0.f;
;       if (mode == 2) o = sigmf(v);
;       sT[row * 136 + col] = f2bf(o);
;     });
.LBB0_1763:
	v_bfe_u32 v57, v56, 16, 1
	v_add_u32_e32 v55, 0x110, v55
	v_add3_u32 v57, v56, v57, s78
	v_lshl_add_u32 v56, v106, 1, v55
	ds_write_b16_d16_hi v56, v57
	v_add3_u32 v57, s96, v96, 48
	s_and_b64 vcc, exec, s[6:7]
	v_cmp_lt_i32_e64 s[24:25], s76, v57
	s_cbranch_vccz .Lsg_233

; __device__ __forceinline__ float sigmf(float x) { return 1.f / (1.f + __expf(-x)); }
; __device__ __forceinline__ void inproj_epilogue(const Params& p, int layer, int mt, int ntile, int tid,
;                                                 f32x16 (&acc)[2][2], unsigned char* smem) {
;     ...
;     acc_foreach(tid, acc, [&](int row, int col, float v) {
;       int t = m0 + row;
;       float o = v;
;       if (mode == 1) o = (t >= NPADR) ? v : 0.f;
;       if (mode == 2) o = sigmf(v);
;       sT[row * 136 + col] = f2bf(o);
;     });
.LBB0_1766:
	v_bfe_u32 v58, v57, 16, 1
	v_add_u32_e32 v55, 0x550, v55
	v_add3_u32 v58, v57, v58, s78
	v_lshl_add_u32 v57, v106, 1, v55
	ds_write_b16_d16_hi v57, v58
	v_add3_u32 v58, s96, v96, 49
	s_and_b64 vcc, exec, s[6:7]
	v_cmp_lt_i32_e64 s[26:27], s76, v58
	s_cbranch_vccz .Lsg_234

; __device__ __forceinline__ float sigmf(float x) { return 1.f / (1.f + __expf(-x)); }
; __device__ __forceinline__ void inproj_epilogue(const Params& p, int layer, int mt, int ntile, int tid,
;                                                 f32x16 (&acc)[2][2], unsigned char* smem) {
;     ...
;     acc_foreach(tid, acc, [&](int row, int col, float v) {
;       int t = m0 + row;
;       float o = v;
;       if (mode == 1) o = (t >= NPADR) ? v : 0.f;
;       if (mode == 2) o = sigmf(v);
;       sT[row * 136 + col] = f2bf(o);
;     });
.LBB0_1769:
	v_bfe_u32 v59, v58, 16, 1
	v_add_u32_e32 v55, 0x110, v55
	v_add3_u32 v59, v58, v59, s78
	v_lshl_add_u32 v58, v106, 1, v55
	ds_write_b16_d16_hi v58, v59
	v_add3_u32 v59, s96, v96, 50
	s_and_b64 vcc, exec, s[6:7]
	v_cmp_lt_i32_e64 s[28:29], s76, v59
	s_cbranch_vccz .Lsg_235

; __device__ __forceinline__ float sigmf(float x) { return 1.f / (1.f + __expf(-x)); }
; __device__ __forceinline__ void inproj_epilogue(const Params& p, int layer, int mt, int ntile, int tid,
;                                                 f32x16 (&acc)[2][2], unsigned char* smem) {
;     ...
;     acc_foreach(tid, acc, [&](int row, int col, float v) {
;       int t = m0 + row;
;       float o = v;
;       if (mode == 1) o = (t >= NPADR) ? v : 0.f;
;       if (mode == 2) o = sigmf(v);
;       sT[row * 136 + col] = f2bf(o);
;     });
.LBB0_1772:
	v_bfe_u32 v60, v59, 16, 1
	v_add_u32_e32 v55, 0x110, v55
	v_add3_u32 v60, v59, v60, s78
	v_lshl_add_u32 v59, v106, 1, v55
	ds_write_b16_d16_hi v59, v60
	v_add3_u32 v60, s96, v96, 51
	s_and_b64 vcc, exec, s[6:7]
	v_cmp_lt_i32_e64 s[30:31], s76, v60
	s_cbranch_vccz .Lsg_236

; __device__ __forceinline__ float sigmf(float x) { return 1.f / (1.f + __expf(-x)); }
; __device__ __forceinline__ void inproj_epilogue(const Params& p, int layer, int mt, int ntile, int tid,
;                                                 f32x16 (&acc)[2][2], unsigned char* smem) {
;     ...
;     acc_foreach(tid, acc, [&](int row, int col, float v) {
;       int t = m0 + row;
;       float o = v;
;       if (mode == 1) o = (t >= NPADR) ? v : 0.f;
;       if (mode == 2) o = sigmf(v);
;       sT[row * 136 + col] = f2bf(o);
;     });
.LBB0_1775:
	v_bfe_u32 v61, v60, 16, 1
	v_add_u32_e32 v55, 0x110, v55
	v_add3_u32 v61, v60, v61, s78
	v_lshl_add_u32 v60, v106, 1, v55
	ds_write_b16_d16_hi v60, v61
	v_add3_u32 v61, s96, v96, 56
	s_and_b64 vcc, exec, s[6:7]
	v_cmp_lt_i32_e64 s[34:35], s76, v61
	s_cbranch_vccz .Lsg_237

; __device__ __forceinline__ float sigmf(float x) { return 1.f / (1.f + __expf(-x)); }
; __device__ __forceinline__ void inproj_epilogue(const Params& p, int layer, int mt, int ntile, int tid,
;                                                 f32x16 (&acc)[2][2], unsigned char* smem) {
;     ...
;     acc_foreach(tid, acc, [&](int row, int col, float v) {
;       int t = m0 + row;
;       float o = v;
;       if (mode == 1) o = (t >= NPADR) ? v : 0.f;
;       if (mode == 2) o = sigmf(v);
;       sT[row * 136 + col] = f2bf(o);
;     });
.LBB0_1778:
	v_bfe_u32 v62, v61, 16, 1
	v_add_u32_e32 v55, 0x550, v55
	v_add3_u32 v62, v61, v62, s78
	v_lshl_add_u32 v61, v106, 1, v55
	ds_write_b16_d16_hi v61, v62
	v_add3_u32 v62, s96, v96, 57
	s_and_b64 vcc, exec, s[6:7]
	v_cmp_lt_i32_e64 s[36:37], s76, v62
	s_cbranch_vccz .Lsg_238

; __device__ __forceinline__ float sigmf(float x) { return 1.f / (1.f + __expf(-x)); }
; __device__ __forceinline__ void inproj_epilogue(const Params& p, int layer, int mt, int ntile, int tid,
;                                                 f32x16 (&acc)[2][2], unsigned char* smem) {
;     ...
;     acc_foreach(tid, acc, [&](int row, int col, float v) {
;       int t = m0 + row;
;       float o = v;
;       if (mode == 1) o = (t >= NPADR) ? v : 0.f;
;       if (mode == 2) o = sigmf(v);
;       sT[row * 136 + col] = f2bf(o);
;     });
.LBB0_1781:
	v_bfe_u32 v63, v62, 16, 1
	v_add_u32_e32 v55, 0x110, v55
	v_add3_u32 v63, v62, v63, s78
	v_lshl_add_u32 v62, v106, 1, v55
	ds_write_b16_d16_hi v62, v63
	v_add3_u32 v63, s96, v96, 58
	s_and_b64 vcc, exec, s[6:7]
	v_cmp_lt_i32_e64 s[38:39], s76, v63
	s_cbranch_vccz .Lsg_239

; __device__ __forceinline__ float sigmf(float x) { return 1.f / (1.f + __expf(-x)); }
; __device__ __forceinline__ void inproj_epilogue(const Params& p, int layer, int mt, int ntile, int tid,
;                                                 f32x16 (&acc)[2][2], unsigned char* smem) {
;     ...
;     acc_foreach(tid, acc, [&](int row, int col, float v) {
;       int t = m0 + row;
;       float o = v;
;       if (mode == 1) o = (t >= NPADR) ? v : 0.f;
;       if (mode == 2) o = sigmf(v);
;       sT[row * 136 + col] = f2bf(o);
;     });
.LBB0_1784:
	v_bfe_u32 v107, v63, 16, 1
	v_add_u32_e32 v55, 0x110, v55
	v_add3_u32 v63, v63, v107, s78
	v_lshl_add_u32 v55, v106, 1, v55
	ds_write_b16_d16_hi v55, v63
	v_add3_u32 v63, s96, v96, 59
	s_and_b64 vcc, exec, s[6:7]
	v_cmp_lt_i32_e64 s[40:41], s76, v63
	s_cbranch_vccz .Lsg_240

; __device__ __forceinline__ float softplusf(float x) { return fmaxf(x, 0.f) + __logf(1.f + __expf(-fabsf(x))); }
; __device__ __forceinline__ float sigmf(float x) { return 1.f / (1.f + __expf(-x)); }
; __device__ __forceinline__ void inproj_epilogue(const Params& p, int layer, int mt, int ntile, int tid,
;                                                 f32x16 (&acc)[2][2], unsigned char* smem) {
;     ...
;   const int m0 = mt * 128;
;   if (mode == 3) {
;     float* dt = (float*)(p.ws + OFF_DT) + (size_t)m0 * 16;
;     const float* bias = p.ssd_dt_bias + layer * 16;
;     acc_foreach(tid, acc, [&](int row, int col, float v) {
;       if (col < 16) *(dt + row * 16 + col) = softplusf(v + bias[col]);
;     });
;   } else {
;     bf16r* dstb = dst + (size_t)m0 * ld + c0;
;     bf16r* sT = (bf16r*)smem;
;     acc_foreach(tid, acc, [&](int row, int col, float v) {
;       int t = m0 + row;
;       float o = v;
;       if (mode == 1) o = (t >= NPADR) ? v : 0.f;
;       if (mode == 2) o = sigmf(v);
;       sT[row * 136 + col] = f2bf(o);
.LBB0_2033:
	s_lshl_b32 s84, s6, 7
	s_ashr_i32 s85, s84, 31
	s_cmp_lg_u32 s7, 3
	s_mov_b64 s[4:5], -1
	s_cbranch_scc0 .LBB0_2227
	v_mov_b32_e32 v106, v108
	s_movk_i32 s4, 0xffc0
	v_lshrrev_b32_e32 v107, 3, v106
	v_ashrrev_i32_e32 v96, 1, v106
	v_and_b32_e32 v107, 4, v107
	v_and_or_b32 v96, v96, s4, v107
	s_cmp_eq_u32 s7, 1
	s_cselect_b64 s[4:5], -1, 0
	v_add_u32_e32 v107, s84, v96
	s_cmp_eq_u32 s7, 2
	s_cselect_b64 s[12:13], -1, 0
	s_cmp_lg_u32 s7, 2
	v_cmp_lt_i32_e64 s[8:9], s76, v107
	s_cbranch_scc0 .Lsg_257

; __device__ __forceinline__ float sigmf(float x) { return 1.f / (1.f + __expf(-x)); }
; __device__ __forceinline__ void inproj_epilogue(const Params& p, int layer, int mt, int ntile, int tid,
;                                                 f32x16 (&acc)[2][2], unsigned char* smem) {
;     ...
;     acc_foreach(tid, acc, [&](int row, int col, float v) {
;       int t = m0 + row;
;       float o = v;
;       if (mode == 1) o = (t >= NPADR) ? v : 0.f;
;       if (mode == 2) o = sigmf(v);
;       sT[row * 136 + col] = f2bf(o);
;     });
.LBB0_2037:
	v_bfe_u32 v110, v107, 16, 1
	v_and_b32_e32 v106, 0x5f, v106
	v_add3_u32 v111, v107, v110, s78
	v_mul_lo_u32 v110, v96, s79
	v_lshl_add_u32 v107, v106, 1, v110
	ds_write_b16_d16_hi v107, v111
	v_add3_u32 v111, s84, v96, 1
	v_cmp_lt_i32_e64 s[10:11], s76, v111
	v_cndmask_b32_e64 v111, 0, 1, s[12:13]
	v_cmp_ne_u32_e64 s[6:7], 1, v111
	s_andn2_b64 vcc, exec, s[12:13]
	s_cbranch_vccz .Lsg_258

; __device__ __forceinline__ float sigmf(float x) { return 1.f / (1.f + __expf(-x)); }
; __device__ __forceinline__ void inproj_epilogue(const Params& p, int layer, int mt, int ntile, int tid,
;                                                 f32x16 (&acc)[2][2], unsigned char* smem) {
;     ...
;     acc_foreach(tid, acc, [&](int row, int col, float v) {
;       int t = m0 + row;
;       float o = v;
;       if (mode == 1) o = (t >= NPADR) ? v : 0.f;
;       if (mode == 2) o = sigmf(v);
;       sT[row * 136 + col] = f2bf(o);
;     });
.LBB0_2040:
	v_bfe_u32 v112, v111, 16, 1
	v_add3_u32 v112, v111, v112, s78
	v_add_u32_e32 v111, 0x110, v110
	v_lshl_add_u32 v110, v106, 1, v111
	ds_write_b16_d16_hi v110, v112
	v_add3_u32 v112, s84, v96, 2
	s_and_b64 vcc, exec, s[6:7]
	v_cmp_lt_i32_e64 s[12:13], s76, v112
	s_cbranch_vccz .Lsg_259

; __device__ __forceinline__ float sigmf(float x) { return 1.f / (1.f + __expf(-x)); }
; __device__ __forceinline__ void inproj_epilogue(const Params& p, int layer, int mt, int ntile, int tid,
;                                                 f32x16 (&acc)[2][2], unsigned char* smem) {
;     ...
;     acc_foreach(tid, acc, [&](int row, int col, float v) {
;       int t = m0 + row;
;       float o = v;
;       if (mode == 1) o = (t >= NPADR) ? v : 0.f;
;       if (mode == 2) o = sigmf(v);
;       sT[row * 136 + col] = f2bf(o);
;     });
.LBB0_2043:
	v_bfe_u32 v113, v112, 16, 1
	v_add3_u32 v113, v112, v113, s78
	v_add_u32_e32 v112, 0x110, v111
	v_lshl_add_u32 v111, v106, 1, v112
	ds_write_b16_d16_hi v111, v113
	v_add3_u32 v113, s84, v96, 3
	s_and_b64 vcc, exec, s[6:7]
	v_cmp_lt_i32_e64 s[14:15], s76, v113
	s_cbranch_vccz .Lsg_260

; __device__ __forceinline__ float sigmf(float x) { return 1.f / (1.f + __expf(-x)); }
; __device__ __forceinline__ void inproj_epilogue(const Params& p, int layer, int mt, int ntile, int tid,
;                                                 f32x16 (&acc)[2][2], unsigned char* smem) {
;     ...
;     acc_foreach(tid, acc, [&](int row, int col, float v) {
;       int t = m0 + row;
;       float o = v;
;       if (mode == 1) o = (t >= NPADR) ? v : 0.f;
;       if (mode == 2) o = sigmf(v);
;       sT[row * 136 + col] = f2bf(o);
;     });
.LBB0_2046:
	v_bfe_u32 v114, v113, 16, 1
	v_add3_u32 v114, v113, v114, s78
	v_add_u32_e32 v113, 0x110, v112
	v_lshl_add_u32 v112, v106, 1, v113
	ds_write_b16_d16_hi v112, v114
	v_add3_u32 v114, s84, v96, 8
	s_and_b64 vcc, exec, s[6:7]
	v_cmp_lt_i32_e64 s[16:17], s76, v114
	s_cbranch_vccz .Lsg_261

; __device__ __forceinline__ float sigmf(float x) { return 1.f / (1.f + __expf(-x)); }
; __device__ __forceinline__ void inproj_epilogue(const Params& p, int layer, int mt, int ntile, int tid,
;                                                 f32x16 (&acc)[2][2], unsigned char* smem) {
;     ...
;     acc_foreach(tid, acc, [&](int row, int col, float v) {
;       int t = m0 + row;
;       float o = v;
;       if (mode == 1) o = (t >= NPADR) ? v : 0.f;
;       if (mode == 2) o = sigmf(v);
;       sT[row * 136 + col] = f2bf(o);
;     });
.LBB0_2049:
	v_bfe_u32 v115, v114, 16, 1
	v_add3_u32 v115, v114, v115, s78
	v_add_u32_e32 v114, 0x550, v113
	v_lshl_add_u32 v113, v106, 1, v114
	ds_write_b16_d16_hi v113, v115
	v_add3_u32 v115, s84, v96, 9
	s_and_b64 vcc, exec, s[6:7]
	v_cmp_lt_i32_e64 s[18:19], s76, v115
	s_cbranch_vccz .Lsg_262

; __device__ __forceinline__ float sigmf(float x) { return 1.f / (1.f + __expf(-x)); }
; __device__ __forceinline__ void inproj_epilogue(const Params& p, int layer, int mt, int ntile, int tid,
;                                                 f32x16 (&acc)[2][2], unsigned char* smem) {
;     ...
;     acc_foreach(tid, acc, [&](int row, int col, float v) {
;       int t = m0 + row;
;       float o = v;
;       if (mode == 1) o = (t >= NPADR) ? v : 0.f;
;       if (mode == 2) o = sigmf(v);
;       sT[row * 136 + col] = f2bf(o);
;     });
.LBB0_2052:
	v_bfe_u32 v116, v115, 16, 1
	v_add3_u32 v116, v115, v116, s78
	v_add_u32_e32 v115, 0x110, v114
	v_lshl_add_u32 v114, v106, 1, v115
	ds_write_b16_d16_hi v114, v116
	v_add3_u32 v116, s84, v96, 10
	s_and_b64 vcc, exec, s[6:7]
	v_cmp_lt_i32_e64 s[20:21], s76, v116
	s_cbranch_vccz .Lsg_263

; __device__ __forceinline__ float sigmf(float x) { return 1.f / (1.f + __expf(-x)); }
; __device__ __forceinline__ void inproj_epilogue(const Params& p, int layer, int mt, int ntile, int tid,
;                                                 f32x16 (&acc)[2][2], unsigned char* smem) {
;     ...
;     acc_foreach(tid, acc, [&](int row, int col, float v) {
;       int t = m0 + row;
;       float o = v;
;       if (mode == 1) o = (t >= NPADR) ? v : 0.f;
;       if (mode == 2) o = sigmf(v);
;       sT[row * 136 + col] = f2bf(o);
;     });
.LBB0_2055:
	v_bfe_u32 v117, v116, 16, 1
	v_add3_u32 v117, v116, v117, s78
	v_add_u32_e32 v116, 0x110, v115
	v_lshl_add_u32 v115, v106, 1, v116
	ds_write_b16_d16_hi v115, v117
	v_add3_u32 v117, s84, v96, 11
	s_and_b64 vcc, exec, s[6:7]
	v_cmp_lt_i32_e64 s[22:23], s76, v117
	s_cbranch_vccz .Lsg_264

; __device__ __forceinline__ float sigmf(float x) { return 1.f / (1.f + __expf(-x)); }
; __device__ __forceinline__ void inproj_epilogue(const Params& p, int layer, int mt, int ntile, int tid,
;                                                 f32x16 (&acc)[2][2], unsigned char* smem) {
;     ...
;     acc_foreach(tid, acc, [&](int row, int col, float v) {
;       int t = m0 + row;
;       float o = v;
;       if (mode == 1) o = (t >= NPADR) ? v : 0.f;
;       if (mode == 2) o = sigmf(v);
;       sT[row * 136 + col] = f2bf(o);
;     });
.LBB0_2058:
	v_bfe_u32 v118, v117, 16, 1
	v_add_u32_e32 v116, 0x110, v116
	v_add3_u32 v118, v117, v118, s78
	v_lshl_add_u32 v117, v106, 1, v116
	ds_write_b16_d16_hi v117, v118
	v_add3_u32 v118, s84, v96, 16
	s_and_b64 vcc, exec, s[6:7]
	v_cmp_lt_i32_e64 s[24:25], s76, v118
	s_cbranch_vccz .Lsg_265

; __device__ __forceinline__ bf16r f2bf(float f) {
;   unsigned u = __float_as_uint(f);
;   u += 0x7fffu + ((u >> 16) & 1u);
;   return (bf16r)(u >> 16);
; }
; __device__ __forceinline__ unsigned pack2(float a, float b) { return (unsigned)f2bf(a) | ((unsigned)f2bf(b) << 16); }
; __device__ __forceinline__ float lo16(unsigned v) { return __uint_as_float(v << 16); }
; __device__ __forceinline__ float hi16(unsigned v) { return __uint_as_float(v & 0xffff0000u); }
; __device__ __forceinline__ float siluf(float x) { return x / (1.f + __expf(-x)); }
; __device__ __forceinline__ float sigmf(float x) { return 1.f / (1.f + __expf(-x)); }
; __device__ __forceinline__ void inproj_epilogue(const Params& p, int layer, int mt, int ntile, int tid,
;                                                 f32x16 (&acc)[2][2], unsigned char* smem) {
;     ...
;     acc_foreach(tid, acc, [&](int row, int col, float v) {
;       int t = m0 + row;
;       float o = v;
;       if (mode == 1) o = (t >= NPADR) ? v : 0.f;
;       if (mode == 2) o = sigmf(v);
;       sT[row * 136 + col] = f2bf(o);
;     });
.LBB0_2061:
	v_bfe_u32 v119, v118, 16, 1
	v_add_u32_e32 v116, 0x550, v116
	v_add3_u32 v119, v118, v119, s78
	v_lshl_add_u32 v118, v106, 1, v116
	ds_write_b16_d16_hi v118, v119
	v_add3_u32 v119, s84, v96, 17
	s_and_b64 vcc, exec, s[6:7]
	v_cmp_lt_i32_e64 s[26:27], s76, v119
	s_cbranch_vccz .Lsg_266

; __device__ __forceinline__ bf16r f2bf(float f) {
;   unsigned u = __float_as_uint(f);
;   u += 0x7fffu + ((u >> 16) & 1u);
;   return (bf16r)(u >> 16);
; }
; __device__ __forceinline__ unsigned pack2(float a, float b) { return (unsigned)f2bf(a) | ((unsigned)f2bf(b) << 16); }
; __device__ __forceinline__ float lo16(unsigned v) { return __uint_as_float(v << 16); }
; __device__ __forceinline__ float hi16(unsigned v) { return __uint_as_float(v & 0xffff0000u); }
; __device__ __forceinline__ float siluf(float x) { return x / (1.f + __expf(-x)); }
; __device__ __forceinline__ float sigmf(float x) { return 1.f / (1.f + __expf(-x)); }
; __device__ __forceinline__ void inproj_epilogue(const Params& p, int layer, int mt, int ntile, int tid,
;                                                 f32x16 (&acc)[2][2], unsigned char* smem) {
;     ...
;     acc_foreach(tid, acc, [&](int row, int col, float v) {
;       int t = m0 + row;
;       float o = v;
;       if (mode == 1) o = (t >= NPADR) ? v : 0.f;
;       if (mode == 2) o = sigmf(v);
;       sT[row * 136 + col] = f2bf(o);
;     });
.LBB0_2064:
	v_bfe_u32 v120, v119, 16, 1
	v_add_u32_e32 v116, 0x110, v116
	v_add3_u32 v120, v119, v120, s78
	v_lshl_add_u32 v119, v106, 1, v116
	ds_write_b16_d16_hi v119, v120
	v_add3_u32 v120, s84, v96, 18
	s_and_b64 vcc, exec, s[6:7]
	v_cmp_lt_i32_e64 s[28:29], s76, v120
	s_cbranch_vccz .Lsg_267

; __device__ __forceinline__ bf16r f2bf(float f) {
;   unsigned u = __float_as_uint(f);
;   u += 0x7fffu + ((u >> 16) & 1u);
;   return (bf16r)(u >> 16);
; }
; __device__ __forceinline__ unsigned pack2(float a, float b) { return (unsigned)f2bf(a) | ((unsigned)f2bf(b) << 16); }
; __device__ __forceinline__ float lo16(unsigned v) { return __uint_as_float(v << 16); }
; __device__ __forceinline__ float hi16(unsigned v) { return __uint_as_float(v & 0xffff0000u); }
; __device__ __forceinline__ float siluf(float x) { return x / (1.f + __expf(-x)); }
; __device__ __forceinline__ float sigmf(float x) { return 1.f / (1.f + __expf(-x)); }
; __device__ __forceinline__ void inproj_epilogue(const Params& p, int layer, int mt, int ntile, int tid,
;                                                 f32x16 (&acc)[2][2], unsigned char* smem) {
;     ...
;     acc_foreach(tid, acc, [&](int row, int col, float v) {
;       int t = m0 + row;
;       float o = v;
;       if (mode == 1) o = (t >= NPADR) ? v : 0.f;
;       if (mode == 2) o = sigmf(v);
;       sT[row * 136 + col] = f2bf(o);
;     });
.LBB0_2067:
	v_bfe_u32 v121, v120, 16, 1
	v_add_u32_e32 v116, 0x110, v116
	v_add3_u32 v121, v120, v121, s78
	v_lshl_add_u32 v120, v106, 1, v116
	ds_write_b16_d16_hi v120, v121
	v_add3_u32 v121, s84, v96, 19
	s_and_b64 vcc, exec, s[6:7]
	v_cmp_lt_i32_e64 s[30:31], s76, v121
	s_cbranch_vccz .Lsg_268

; __device__ __forceinline__ bf16r f2bf(float f) {
;   unsigned u = __float_as_uint(f);
;   u += 0x7fffu + ((u >> 16) & 1u);
;   return (bf16r)(u >> 16);
; }
; __device__ __forceinline__ unsigned pack2(float a, float b) { return (unsigned)f2bf(a) | ((unsigned)f2bf(b) << 16); }
; __device__ __forceinline__ float lo16(unsigned v) { return __uint_as_float(v << 16); }
; __device__ __forceinline__ float hi16(unsigned v) { return __uint_as_float(v & 0xffff0000u); }
; __device__ __forceinline__ float siluf(float x) { return x / (1.f + __expf(-x)); }
; __device__ __forceinline__ float sigmf(float x) { return 1.f / (1.f + __expf(-x)); }
; __device__ __forceinline__ void inproj_epilogue(const Params& p, int layer, int mt, int ntile, int tid,
;                                                 f32x16 (&acc)[2][2], unsigned char* smem) {
;     ...
;     acc_foreach(tid, acc, [&](int row, int col, float v) {
;       int t = m0 + row;
;       float o = v;
;       if (mode == 1) o = (t >= NPADR) ? v : 0.f;
;       if (mode == 2) o = sigmf(v);
;       sT[row * 136 + col] = f2bf(o);
;     });
.LBB0_2070:
	v_bfe_u32 v122, v121, 16, 1
	v_add_u32_e32 v116, 0x110, v116
	v_add3_u32 v122, v121, v122, s78
	v_lshl_add_u32 v121, v106, 1, v116
	ds_write_b16_d16_hi v121, v122
	v_add3_u32 v122, s84, v96, 24
	s_and_b64 vcc, exec, s[6:7]
	v_cmp_lt_i32_e64 s[34:35], s76, v122
	s_cbranch_vccz .Lsg_269

; __device__ __forceinline__ bf16r f2bf(float f) {
;   unsigned u = __float_as_uint(f);
;   u += 0x7fffu + ((u >> 16) & 1u);
;   return (bf16r)(u >> 16);
; }
; __device__ __forceinline__ unsigned pack2(float a, float b) { return (unsigned)f2bf(a) | ((unsigned)f2bf(b) << 16); }
; __device__ __forceinline__ float lo16(unsigned v) { return __uint_as_float(v << 16); }
; __device__ __forceinline__ float hi16(unsigned v) { return __uint_as_float(v & 0xffff0000u); }
; __device__ __forceinline__ float siluf(float x) { return x / (1.f + __expf(-x)); }
; __device__ __forceinline__ float sigmf(float x) { return 1.f / (1.f + __expf(-x)); }
; __device__ __forceinline__ void inproj_epilogue(const Params& p, int layer, int mt, int ntile, int tid,
;                                                 f32x16 (&acc)[2][2], unsigned char* smem) {
;     ...
;     acc_foreach(tid, acc, [&](int row, int col, float v) {
;       int t = m0 + row;
;       float o = v;
;       if (mode == 1) o = (t >= NPADR) ? v : 0.f;
;       if (mode == 2) o = sigmf(v);
;       sT[row * 136 + col] = f2bf(o);
;     });
.LBB0_2073:
	v_bfe_u32 v123, v122, 16, 1
	v_add_u32_e32 v116, 0x550, v116
	v_add3_u32 v123, v122, v123, s78
	v_lshl_add_u32 v122, v106, 1, v116
	ds_write_b16_d16_hi v122, v123
	v_add3_u32 v123, s84, v96, 25
	s_and_b64 vcc, exec, s[6:7]
	v_cmp_lt_i32_e64 s[36:37], s76, v123
	s_cbranch_vccz .Lsg_270

; __device__ __forceinline__ bf16r f2bf(float f) {
;   unsigned u = __float_as_uint(f);
;   u += 0x7fffu + ((u >> 16) & 1u);
;   return (bf16r)(u >> 16);
; }
; __device__ __forceinline__ unsigned pack2(float a, float b) { return (unsigned)f2bf(a) | ((unsigned)f2bf(b) << 16); }
; __device__ __forceinline__ float lo16(unsigned v) { return __uint_as_float(v << 16); }
; __device__ __forceinline__ float hi16(unsigned v) { return __uint_as_float(v & 0xffff0000u); }
; __device__ __forceinline__ float siluf(float x) { return x / (1.f + __expf(-x)); }
; __device__ __forceinline__ float sigmf(float x) { return 1.f / (1.f + __expf(-x)); }
; __device__ __forceinline__ void inproj_epilogue(const Params& p, int layer, int mt, int ntile, int tid,
;                                                 f32x16 (&acc)[2][2], unsigned char* smem) {
;     ...
;     acc_foreach(tid, acc, [&](int row, int col, float v) {
;       int t = m0 + row;
;       float o = v;
;       if (mode == 1) o = (t >= NPADR) ? v : 0.f;
;       if (mode == 2) o = sigmf(v);
;       sT[row * 136 + col] = f2bf(o);
;     });
.LBB0_2076:
	v_bfe_u32 v124, v123, 16, 1
	v_add_u32_e32 v116, 0x110, v116
	v_add3_u32 v124, v123, v124, s78
	v_lshl_add_u32 v123, v106, 1, v116
	ds_write_b16_d16_hi v123, v124
	v_add3_u32 v124, s84, v96, 26
	s_and_b64 vcc, exec, s[6:7]
	v_cmp_lt_i32_e64 s[38:39], s76, v124
	s_cbranch_vccz .Lsg_271

; __device__ __forceinline__ bf16r f2bf(float f) {
;   unsigned u = __float_as_uint(f);
;   u += 0x7fffu + ((u >> 16) & 1u);
;   return (bf16r)(u >> 16);
; }
; __device__ __forceinline__ unsigned pack2(float a, float b) { return (unsigned)f2bf(a) | ((unsigned)f2bf(b) << 16); }
; __device__ __forceinline__ float lo16(unsigned v) { return __uint_as_float(v << 16); }
; __device__ __forceinline__ float hi16(unsigned v) { return __uint_as_float(v & 0xffff0000u); }
; __device__ __forceinline__ float siluf(float x) { return x / (1.f + __expf(-x)); }
; __device__ __forceinline__ float sigmf(float x) { return 1.f / (1.f + __expf(-x)); }
; __device__ __forceinline__ void inproj_epilogue(const Params& p, int layer, int mt, int ntile, int tid,
;                                                 f32x16 (&acc)[2][2], unsigned char* smem) {
;     ...
;     acc_foreach(tid, acc, [&](int row, int col, float v) {
;       int t = m0 + row;
;       float o = v;
;       if (mode == 1) o = (t >= NPADR) ? v : 0.f;
;       if (mode == 2) o = sigmf(v);
;       sT[row * 136 + col] = f2bf(o);
;     });
.LBB0_2079:
	v_bfe_u32 v125, v124, 16, 1
	v_add_u32_e32 v116, 0x110, v116
	v_add3_u32 v124, v124, v125, s78
	v_lshl_add_u32 v116, v106, 1, v116
	ds_write_b16_d16_hi v116, v124
	v_add3_u32 v124, s84, v96, 27
	s_and_b64 vcc, exec, s[6:7]
	v_cmp_lt_i32_e64 s[40:41], s76, v124
	s_cbranch_vccz .Lsg_272

; __device__ __forceinline__ bf16r f2bf(float f) {
;   unsigned u = __float_as_uint(f);
;   u += 0x7fffu + ((u >> 16) & 1u);
;   return (bf16r)(u >> 16);
; }
; __device__ __forceinline__ unsigned pack2(float a, float b) { return (unsigned)f2bf(a) | ((unsigned)f2bf(b) << 16); }
; __device__ __forceinline__ float lo16(unsigned v) { return __uint_as_float(v << 16); }
; __device__ __forceinline__ float hi16(unsigned v) { return __uint_as_float(v & 0xffff0000u); }
; __device__ __forceinline__ float siluf(float x) { return x / (1.f + __expf(-x)); }
; __device__ __forceinline__ float sigmf(float x) { return 1.f / (1.f + __expf(-x)); }
; __device__ __forceinline__ void inproj_epilogue(const Params& p, int layer, int mt, int ntile, int tid,
;                                                 f32x16 (&acc)[2][2], unsigned char* smem) {
;     ...
;     acc_foreach(tid, acc, [&](int row, int col, float v) {
;       int t = m0 + row;
;       float o = v;
;       if (mode == 1) o = (t >= NPADR) ? v : 0.f;
;       if (mode == 2) o = sigmf(v);
;       sT[row * 136 + col] = f2bf(o);
;     });
.LBB0_2130:
	v_bfe_u32 v50, v48, 16, 1
	v_add_u32_e32 v49, 0x110, v116
	v_add3_u32 v48, v48, v50, s78
	ds_write_b16_d16_hi v49, v48 offset:64
	v_or_b32_e32 v48, 32, v96
	v_add_u32_e32 v49, s84, v48
	s_and_b64 vcc, exec, s[6:7]
	v_cmp_lt_i32_e64 s[8:9], s76, v49
	s_cbranch_vccz .Lsg_289

; __device__ __forceinline__ bf16r f2bf(float f) {
;   unsigned u = __float_as_uint(f);
;   u += 0x7fffu + ((u >> 16) & 1u);
;   return (bf16r)(u >> 16);
; }
; __device__ __forceinline__ unsigned pack2(float a, float b) { return (unsigned)f2bf(a) | ((unsigned)f2bf(b) << 16); }
; __device__ __forceinline__ float lo16(unsigned v) { return __uint_as_float(v << 16); }
; __device__ __forceinline__ float hi16(unsigned v) { return __uint_as_float(v & 0xffff0000u); }
; __device__ __forceinline__ float siluf(float x) { return x / (1.f + __expf(-x)); }
; __device__ __forceinline__ float sigmf(float x) { return 1.f / (1.f + __expf(-x)); }
; __device__ __forceinline__ void inproj_epilogue(const Params& p, int layer, int mt, int ntile, int tid,
;                                                 f32x16 (&acc)[2][2], unsigned char* smem) {
;     ...
;     acc_foreach(tid, acc, [&](int row, int col, float v) {
;       int t = m0 + row;
;       float o = v;
;       if (mode == 1) o = (t >= NPADR) ? v : 0.f;
;       if (mode == 2) o = sigmf(v);
;       sT[row * 136 + col] = f2bf(o);
;     });
.LBB0_2133:
	v_bfe_u32 v50, v49, 16, 1
	v_add3_u32 v50, v49, v50, s78
	v_mul_lo_u32 v49, v48, s79
	v_lshl_add_u32 v48, v106, 1, v49
	ds_write_b16_d16_hi v48, v50
	v_add3_u32 v50, s84, v96, 33
	s_and_b64 vcc, exec, s[6:7]
	v_cmp_lt_i32_e64 s[10:11], s76, v50
	s_cbranch_vccz .Lsg_290

; __device__ __forceinline__ bf16r f2bf(float f) {
;   unsigned u = __float_as_uint(f);
;   u += 0x7fffu + ((u >> 16) & 1u);
;   return (bf16r)(u >> 16);
; }
; __device__ __forceinline__ unsigned pack2(float a, float b) { return (unsigned)f2bf(a) | ((unsigned)f2bf(b) << 16); }
; __device__ __forceinline__ float lo16(unsigned v) { return __uint_as_float(v << 16); }
; __device__ __forceinline__ float hi16(unsigned v) { return __uint_as_float(v & 0xffff0000u); }
; __device__ __forceinline__ float siluf(float x) { return x / (1.f + __expf(-x)); }
; __device__ __forceinline__ float sigmf(float x) { return 1.f / (1.f + __expf(-x)); }
; __device__ __forceinline__ void inproj_epilogue(const Params& p, int layer, int mt, int ntile, int tid,
;                                                 f32x16 (&acc)[2][2], unsigned char* smem) {
;     ...
;     acc_foreach(tid, acc, [&](int row, int col, float v) {
;       int t = m0 + row;
;       float o = v;
;       if (mode == 1) o = (t >= NPADR) ? v : 0.f;
;       if (mode == 2) o = sigmf(v);
;       sT[row * 136 + col] = f2bf(o);
;     });
.LBB0_2136:
	v_bfe_u32 v51, v50, 16, 1
	v_add3_u32 v51, v50, v51, s78
	v_add_u32_e32 v50, 0x110, v49
	v_lshl_add_u32 v49, v106, 1, v50
	ds_write_b16_d16_hi v49, v51
	v_add3_u32 v51, s84, v96, 34
	s_and_b64 vcc, exec, s[6:7]
	v_cmp_lt_i32_e64 s[12:13], s76, v51
	s_cbranch_vccz .Lsg_291

; __device__ __forceinline__ bf16r f2bf(float f) {
;   unsigned u = __float_as_uint(f);
;   u += 0x7fffu + ((u >> 16) & 1u);
;   return (bf16r)(u >> 16);
; }
; __device__ __forceinline__ unsigned pack2(float a, float b) { return (unsigned)f2bf(a) | ((unsigned)f2bf(b) << 16); }
; __device__ __forceinline__ float lo16(unsigned v) { return __uint_as_float(v << 16); }
; __device__ __forceinline__ float hi16(unsigned v) { return __uint_as_float(v & 0xffff0000u); }
; __device__ __forceinline__ float siluf(float x) { return x / (1.f + __expf(-x)); }
; __device__ __forceinline__ float sigmf(float x) { return 1.f / (1.f + __expf(-x)); }
; __device__ __forceinline__ void inproj_epilogue(const Params& p, int layer, int mt, int ntile, int tid,
;                                                 f32x16 (&acc)[2][2], unsigned char* smem) {
;     ...
;     acc_foreach(tid, acc, [&](int row, int col, float v) {
;       int t = m0 + row;
;       float o = v;
;       if (mode == 1) o = (t >= NPADR) ? v : 0.f;
;       if (mode == 2) o = sigmf(v);
;       sT[row * 136 + col] = f2bf(o);
;     });
.LBB0_2139:
	v_bfe_u32 v52, v51, 16, 1
	v_add3_u32 v52, v51, v52, s78
	v_add_u32_e32 v51, 0x110, v50
	v_lshl_add_u32 v50, v106, 1, v51
	ds_write_b16_d16_hi v50, v52
	v_add3_u32 v52, s84, v96, 35
	s_and_b64 vcc, exec, s[6:7]
	v_cmp_lt_i32_e64 s[14:15], s76, v52
	s_cbranch_vccz .Lsg_292

; __device__ __forceinline__ bf16r f2bf(float f) {
;   unsigned u = __float_as_uint(f);
;   u += 0x7fffu + ((u >> 16) & 1u);
;   return (bf16r)(u >> 16);
; }
; __device__ __forceinline__ unsigned pack2(float a, float b) { return (unsigned)f2bf(a) | ((unsigned)f2bf(b) << 16); }
; __device__ __forceinline__ float lo16(unsigned v) { return __uint_as_float(v << 16); }
; __device__ __forceinline__ float hi16(unsigned v) { return __uint_as_float(v & 0xffff0000u); }
; __device__ __forceinline__ float siluf(float x) { return x / (1.f + __expf(-x)); }
; __device__ __forceinline__ float sigmf(float x) { return 1.f / (1.f + __expf(-x)); }
; __device__ __forceinline__ void inproj_epilogue(const Params& p, int layer, int mt, int ntile, int tid,
;                                                 f32x16 (&acc)[2][2], unsigned char* smem) {
;     ...
;     acc_foreach(tid, acc, [&](int row, int col, float v) {
;       int t = m0 + row;
;       float o = v;
;       if (mode == 1) o = (t >= NPADR) ? v : 0.f;
;       if (mode == 2) o = sigmf(v);
;       sT[row * 136 + col] = f2bf(o);
;     });
.LBB0_2142:
	v_bfe_u32 v53, v52, 16, 1
	v_add3_u32 v53, v52, v53, s78
	v_add_u32_e32 v52, 0x110, v51
	v_lshl_add_u32 v51, v106, 1, v52
	ds_write_b16_d16_hi v51, v53
	v_add3_u32 v53, s84, v96, 40
	s_and_b64 vcc, exec, s[6:7]
	v_cmp_lt_i32_e64 s[16:17], s76, v53
	s_cbranch_vccz .Lsg_293

; __device__ __forceinline__ bf16r f2bf(float f) {
;   unsigned u = __float_as_uint(f);
;   u += 0x7fffu + ((u >> 16) & 1u);
;   return (bf16r)(u >> 16);
; }
; __device__ __forceinline__ unsigned pack2(float a, float b) { return (unsigned)f2bf(a) | ((unsigned)f2bf(b) << 16); }
; __device__ __forceinline__ float lo16(unsigned v) { return __uint_as_float(v << 16); }
; __device__ __forceinline__ float hi16(unsigned v) { return __uint_as_float(v & 0xffff0000u); }
; __device__ __forceinline__ float siluf(float x) { return x / (1.f + __expf(-x)); }
; __device__ __forceinline__ float sigmf(float x) { return 1.f / (1.f + __expf(-x)); }
; __device__ __forceinline__ void inproj_epilogue(const Params& p, int layer, int mt, int ntile, int tid,
;                                                 f32x16 (&acc)[2][2], unsigned char* smem) {
;     ...
;     acc_foreach(tid, acc, [&](int row, int col, float v) {
;       int t = m0 + row;
;       float o = v;
;       if (mode == 1) o = (t >= NPADR) ? v : 0.f;
;       if (mode == 2) o = sigmf(v);
;       sT[row * 136 + col] = f2bf(o);
;     });
.LBB0_2145:
	v_bfe_u32 v54, v53, 16, 1
	v_add3_u32 v54, v53, v54, s78
	v_add_u32_e32 v53, 0x550, v52
	v_lshl_add_u32 v52, v106, 1, v53
	ds_write_b16_d16_hi v52, v54
	v_add3_u32 v54, s84, v96, 41
	s_and_b64 vcc, exec, s[6:7]
	v_cmp_lt_i32_e64 s[18:19], s76, v54
	s_cbranch_vccz .Lsg_294

; __device__ __forceinline__ bf16r f2bf(float f) {
;   unsigned u = __float_as_uint(f);
;   u += 0x7fffu + ((u >> 16) & 1u);
;   return (bf16r)(u >> 16);
; }
; __device__ __forceinline__ unsigned pack2(float a, float b) { return (unsigned)f2bf(a) | ((unsigned)f2bf(b) << 16); }
; __device__ __forceinline__ float lo16(unsigned v) { return __uint_as_float(v << 16); }
; __device__ __forceinline__ float hi16(unsigned v) { return __uint_as_float(v & 0xffff0000u); }
; __device__ __forceinline__ float siluf(float x) { return x / (1.f + __expf(-x)); }
; __device__ __forceinline__ float sigmf(float x) { return 1.f / (1.f + __expf(-x)); }
; __device__ __forceinline__ void inproj_epilogue(const Params& p, int layer, int mt, int ntile, int tid,
;                                                 f32x16 (&acc)[2][2], unsigned char* smem) {
;     ...
;     acc_foreach(tid, acc, [&](int row, int col, float v) {
;       int t = m0 + row;
;       float o = v;
;       if (mode == 1) o = (t >= NPADR) ? v : 0.f;
;       if (mode == 2) o = sigmf(v);
;       sT[row * 136 + col] = f2bf(o);
;     });
.LBB0_2148:
	v_bfe_u32 v55, v54, 16, 1
	v_add3_u32 v55, v54, v55, s78
	v_add_u32_e32 v54, 0x110, v53
	v_lshl_add_u32 v53, v106, 1, v54
	ds_write_b16_d16_hi v53, v55
	v_add3_u32 v55, s84, v96, 42
	s_and_b64 vcc, exec, s[6:7]
	v_cmp_lt_i32_e64 s[20:21], s76, v55
	s_cbranch_vccz .Lsg_295

; __device__ __forceinline__ bf16r f2bf(float f) {
;   unsigned u = __float_as_uint(f);
;   u += 0x7fffu + ((u >> 16) & 1u);
;   return (bf16r)(u >> 16);
; }
; __device__ __forceinline__ unsigned pack2(float a, float b) { return (unsigned)f2bf(a) | ((unsigned)f2bf(b) << 16); }
; __device__ __forceinline__ float lo16(unsigned v) { return __uint_as_float(v << 16); }
; __device__ __forceinline__ float hi16(unsigned v) { return __uint_as_float(v & 0xffff0000u); }
; __device__ __forceinline__ float siluf(float x) { return x / (1.f + __expf(-x)); }
; __device__ __forceinline__ float sigmf(float x) { return 1.f / (1.f + __expf(-x)); }
; __device__ __forceinline__ void inproj_epilogue(const Params& p, int layer, int mt, int ntile, int tid,
;                                                 f32x16 (&acc)[2][2], unsigned char* smem) {
;     ...
;     acc_foreach(tid, acc, [&](int row, int col, float v) {
;       int t = m0 + row;
;       float o = v;
;       if (mode == 1) o = (t >= NPADR) ? v : 0.f;
;       if (mode == 2) o = sigmf(v);
;       sT[row * 136 + col] = f2bf(o);
;     });
.LBB0_2151:
	v_bfe_u32 v56, v55, 16, 1
	v_add3_u32 v56, v55, v56, s78
	v_add_u32_e32 v55, 0x110, v54
	v_lshl_add_u32 v54, v106, 1, v55
	ds_write_b16_d16_hi v54, v56
	v_add3_u32 v56, s84, v96, 43
	s_and_b64 vcc, exec, s[6:7]
	v_cmp_lt_i32_e64 s[22:23], s76, v56
	s_cbranch_vccz .Lsg_296

; __device__ __forceinline__ bf16r f2bf(float f) {
;   unsigned u = __float_as_uint(f);
;   u += 0x7fffu + ((u >> 16) & 1u);
;   return (bf16r)(u >> 16);
; }
; __device__ __forceinline__ unsigned pack2(float a, float b) { return (unsigned)f2bf(a) | ((unsigned)f2bf(b) << 16); }
; __device__ __forceinline__ float lo16(unsigned v) { return __uint_as_float(v << 16); }
; __device__ __forceinline__ float hi16(unsigned v) { return __uint_as_float(v & 0xffff0000u); }
; __device__ __forceinline__ float siluf(float x) { return x / (1.f + __expf(-x)); }
; __device__ __forceinline__ float sigmf(float x) { return 1.f / (1.f + __expf(-x)); }
; __device__ __forceinline__ void inproj_epilogue(const Params& p, int layer, int mt, int ntile, int tid,
;                                                 f32x16 (&acc)[2][2], unsigned char* smem) {
;     ...
;     acc_foreach(tid, acc, [&](int row, int col, float v) {
;       int t = m0 + row;
;       float o = v;
;       if (mode == 1) o = (t >= NPADR) ? v : 0.f;
;       if (mode == 2) o = sigmf(v);
;       sT[row * 136 + col] = f2bf(o);
;     });
.LBB0_2154:
	v_bfe_u32 v57, v56, 16, 1
	v_add_u32_e32 v55, 0x110, v55
	v_add3_u32 v57, v56, v57, s78
	v_lshl_add_u32 v56, v106, 1, v55
	ds_write_b16_d16_hi v56, v57
	v_add3_u32 v57, s84, v96, 48
	s_and_b64 vcc, exec, s[6:7]
	v_cmp_lt_i32_e64 s[24:25], s76, v57
	s_cbranch_vccz .Lsg_297

; __device__ __forceinline__ bf16r f2bf(float f) {
;   unsigned u = __float_as_uint(f);
;   u += 0x7fffu + ((u >> 16) & 1u);
;   return (bf16r)(u >> 16);
; }
; __device__ __forceinline__ unsigned pack2(float a, float b) { return (unsigned)f2bf(a) | ((unsigned)f2bf(b) << 16); }
; __device__ __forceinline__ float lo16(unsigned v) { return __uint_as_float(v << 16); }
; __device__ __forceinline__ float hi16(unsigned v) { return __uint_as_float(v & 0xffff0000u); }
; __device__ __forceinline__ float siluf(float x) { return x / (1.f + __expf(-x)); }
; __device__ __forceinline__ float sigmf(float x) { return 1.f / (1.f + __expf(-x)); }
; __device__ __forceinline__ void inproj_epilogue(const Params& p, int layer, int mt, int ntile, int tid,
;                                                 f32x16 (&acc)[2][2], unsigned char* smem) {
;     ...
;     acc_foreach(tid, acc, [&](int row, int col, float v) {
;       int t = m0 + row;
;       float o = v;
;       if (mode == 1) o = (t >= NPADR) ? v : 0.f;
;       if (mode == 2) o = sigmf(v);
;       sT[row * 136 + col] = f2bf(o);
;     });
.LBB0_2157:
	v_bfe_u32 v58, v57, 16, 1
	v_add_u32_e32 v55, 0x550, v55
	v_add3_u32 v58, v57, v58, s78
	v_lshl_add_u32 v57, v106, 1, v55
	ds_write_b16_d16_hi v57, v58
	v_add3_u32 v58, s84, v96, 49
	s_and_b64 vcc, exec, s[6:7]
	v_cmp_lt_i32_e64 s[26:27], s76, v58
	s_cbranch_vccz .Lsg_298

; __device__ __forceinline__ bf16r f2bf(float f) {
;   unsigned u = __float_as_uint(f);
;   u += 0x7fffu + ((u >> 16) & 1u);
;   return (bf16r)(u >> 16);
; }
; __device__ __forceinline__ unsigned pack2(float a, float b) { return (unsigned)f2bf(a) | ((unsigned)f2bf(b) << 16); }
; __device__ __forceinline__ float lo16(unsigned v) { return __uint_as_float(v << 16); }
; __device__ __forceinline__ float hi16(unsigned v) { return __uint_as_float(v & 0xffff0000u); }
; __device__ __forceinline__ float siluf(float x) { return x / (1.f + __expf(-x)); }
; __device__ __forceinline__ float sigmf(float x) { return 1.f / (1.f + __expf(-x)); }
; __device__ __forceinline__ void inproj_epilogue(const Params& p, int layer, int mt, int ntile, int tid,
;                                                 f32x16 (&acc)[2][2], unsigned char* smem) {
;     ...
;     acc_foreach(tid, acc, [&](int row, int col, float v) {
;       int t = m0 + row;
;       float o = v;
;       if (mode == 1) o = (t >= NPADR) ? v : 0.f;
;       if (mode == 2) o = sigmf(v);
;       sT[row * 136 + col] = f2bf(o);
;     });
.LBB0_2160:
	v_bfe_u32 v59, v58, 16, 1
	v_add_u32_e32 v55, 0x110, v55
	v_add3_u32 v59, v58, v59, s78
	v_lshl_add_u32 v58, v106, 1, v55
	ds_write_b16_d16_hi v58, v59
	v_add3_u32 v59, s84, v96, 50
	s_and_b64 vcc, exec, s[6:7]
	v_cmp_lt_i32_e64 s[28:29], s76, v59
	s_cbranch_vccz .Lsg_299

; __device__ __forceinline__ bf16r f2bf(float f) {
;   unsigned u = __float_as_uint(f);
;   u += 0x7fffu + ((u >> 16) & 1u);
;   return (bf16r)(u >> 16);
; }
; __device__ __forceinline__ unsigned pack2(float a, float b) { return (unsigned)f2bf(a) | ((unsigned)f2bf(b) << 16); }
; __device__ __forceinline__ float lo16(unsigned v) { return __uint_as_float(v << 16); }
; __device__ __forceinline__ float hi16(unsigned v) { return __uint_as_float(v & 0xffff0000u); }
; __device__ __forceinline__ float siluf(float x) { return x / (1.f + __expf(-x)); }
; __device__ __forceinline__ float sigmf(float x) { return 1.f / (1.f + __expf(-x)); }
; __device__ __forceinline__ void inproj_epilogue(const Params& p, int layer, int mt, int ntile, int tid,
;                                                 f32x16 (&acc)[2][2], unsigned char* smem) {
;     ...
;     acc_foreach(tid, acc, [&](int row, int col, float v) {
;       int t = m0 + row;
;       float o = v;
;       if (mode == 1) o = (t >= NPADR) ? v : 0.f;
;       if (mode == 2) o = sigmf(v);
;       sT[row * 136 + col] = f2bf(o);
;     });
.LBB0_2163:
	v_bfe_u32 v60, v59, 16, 1
	v_add_u32_e32 v55, 0x110, v55
	v_add3_u32 v60, v59, v60, s78
	v_lshl_add_u32 v59, v106, 1, v55
	ds_write_b16_d16_hi v59, v60
	v_add3_u32 v60, s84, v96, 51
	s_and_b64 vcc, exec, s[6:7]
	v_cmp_lt_i32_e64 s[30:31], s76, v60
	s_cbranch_vccz .Lsg_300

; __device__ __forceinline__ bf16r f2bf(float f) {
;   unsigned u = __float_as_uint(f);
;   u += 0x7fffu + ((u >> 16) & 1u);
;   return (bf16r)(u >> 16);
; }
; __device__ __forceinline__ unsigned pack2(float a, float b) { return (unsigned)f2bf(a) | ((unsigned)f2bf(b) << 16); }
; __device__ __forceinline__ float lo16(unsigned v) { return __uint_as_float(v << 16); }
; __device__ __forceinline__ float hi16(unsigned v) { return __uint_as_float(v & 0xffff0000u); }
; __device__ __forceinline__ float siluf(float x) { return x / (1.f + __expf(-x)); }
; __device__ __forceinline__ float sigmf(float x) { return 1.f / (1.f + __expf(-x)); }
; __device__ __forceinline__ void inproj_epilogue(const Params& p, int layer, int mt, int ntile, int tid,
;                                                 f32x16 (&acc)[2][2], unsigned char* smem) {
;     ...
;     acc_foreach(tid, acc, [&](int row, int col, float v) {
;       int t = m0 + row;
;       float o = v;
;       if (mode == 1) o = (t >= NPADR) ? v : 0.f;
;       if (mode == 2) o = sigmf(v);
;       sT[row * 136 + col] = f2bf(o);
;     });
.LBB0_2166:
	v_bfe_u32 v61, v60, 16, 1
	v_add_u32_e32 v55, 0x110, v55
	v_add3_u32 v61, v60, v61, s78
	v_lshl_add_u32 v60, v106, 1, v55
	ds_write_b16_d16_hi v60, v61
	v_add3_u32 v61, s84, v96, 56
	s_and_b64 vcc, exec, s[6:7]
	v_cmp_lt_i32_e64 s[34:35], s76, v61
	s_cbranch_vccz .Lsg_301

; __device__ __forceinline__ bf16r f2bf(float f) {
;   unsigned u = __float_as_uint(f);
;   u += 0x7fffu + ((u >> 16) & 1u);
;   return (bf16r)(u >> 16);
; }
; __device__ __forceinline__ unsigned pack2(float a, float b) { return (unsigned)f2bf(a) | ((unsigned)f2bf(b) << 16); }
; __device__ __forceinline__ float lo16(unsigned v) { return __uint_as_float(v << 16); }
; __device__ __forceinline__ float hi16(unsigned v) { return __uint_as_float(v & 0xffff0000u); }
; __device__ __forceinline__ float siluf(float x) { return x / (1.f + __expf(-x)); }
; __device__ __forceinline__ float sigmf(float x) { return 1.f / (1.f + __expf(-x)); }
; __device__ __forceinline__ void inproj_epilogue(const Params& p, int layer, int mt, int ntile, int tid,
;                                                 f32x16 (&acc)[2][2], unsigned char* smem) {
;     ...
;     acc_foreach(tid, acc, [&](int row, int col, float v) {
;       int t = m0 + row;
;       float o = v;
;       if (mode == 1) o = (t >= NPADR) ? v : 0.f;
;       if (mode == 2) o = sigmf(v);
;       sT[row * 136 + col] = f2bf(o);
;     });
.LBB0_2169:
	v_bfe_u32 v62, v61, 16, 1
	v_add_u32_e32 v55, 0x550, v55
	v_add3_u32 v62, v61, v62, s78
	v_lshl_add_u32 v61, v106, 1, v55
	ds_write_b16_d16_hi v61, v62
	v_add3_u32 v62, s84, v96, 57
	s_and_b64 vcc, exec, s[6:7]
	v_cmp_lt_i32_e64 s[36:37], s76, v62
	s_cbranch_vccz .Lsg_302

; __device__ __forceinline__ bf16r f2bf(float f) {
;   unsigned u = __float_as_uint(f);
;   u += 0x7fffu + ((u >> 16) & 1u);
;   return (bf16r)(u >> 16);
; }
; __device__ __forceinline__ unsigned pack2(float a, float b) { return (unsigned)f2bf(a) | ((unsigned)f2bf(b) << 16); }
; __device__ __forceinline__ float lo16(unsigned v) { return __uint_as_float(v << 16); }
; __device__ __forceinline__ float hi16(unsigned v) { return __uint_as_float(v & 0xffff0000u); }
; __device__ __forceinline__ float siluf(float x) { return x / (1.f + __expf(-x)); }
; __device__ __forceinline__ float sigmf(float x) { return 1.f / (1.f + __expf(-x)); }
; __device__ __forceinline__ void inproj_epilogue(const Params& p, int layer, int mt, int ntile, int tid,
;                                                 f32x16 (&acc)[2][2], unsigned char* smem) {
;     ...
;     acc_foreach(tid, acc, [&](int row, int col, float v) {
;       int t = m0 + row;
;       float o = v;
;       if (mode == 1) o = (t >= NPADR) ? v : 0.f;
;       if (mode == 2) o = sigmf(v);
;       sT[row * 136 + col] = f2bf(o);
;     });
.LBB0_2172:
	v_bfe_u32 v63, v62, 16, 1
	v_add_u32_e32 v55, 0x110, v55
	v_add3_u32 v63, v62, v63, s78
	v_lshl_add_u32 v62, v106, 1, v55
	ds_write_b16_d16_hi v62, v63
	v_add3_u32 v63, s84, v96, 58
	s_and_b64 vcc, exec, s[6:7]
	v_cmp_lt_i32_e64 s[38:39], s76, v63
	s_cbranch_vccz .Lsg_303

; __device__ __forceinline__ bf16r f2bf(float f) {
;   unsigned u = __float_as_uint(f);
;   u += 0x7fffu + ((u >> 16) & 1u);
;   return (bf16r)(u >> 16);
; }
; __device__ __forceinline__ unsigned pack2(float a, float b) { return (unsigned)f2bf(a) | ((unsigned)f2bf(b) << 16); }
; __device__ __forceinline__ float lo16(unsigned v) { return __uint_as_float(v << 16); }
; __device__ __forceinline__ float hi16(unsigned v) { return __uint_as_float(v & 0xffff0000u); }
; __device__ __forceinline__ float siluf(float x) { return x / (1.f + __expf(-x)); }
; __device__ __forceinline__ float sigmf(float x) { return 1.f / (1.f + __expf(-x)); }
; __device__ __forceinline__ void inproj_epilogue(const Params& p, int layer, int mt, int ntile, int tid,
;                                                 f32x16 (&acc)[2][2], unsigned char* smem) {
;     ...
;     acc_foreach(tid, acc, [&](int row, int col, float v) {
;       int t = m0 + row;
;       float o = v;
;       if (mode == 1) o = (t >= NPADR) ? v : 0.f;
;       if (mode == 2) o = sigmf(v);
;       sT[row * 136 + col] = f2bf(o);
;     });
.LBB0_2175:
	v_bfe_u32 v107, v63, 16, 1
	v_add_u32_e32 v55, 0x110, v55
	v_add3_u32 v63, v63, v107, s78
	v_lshl_add_u32 v55, v106, 1, v55
	ds_write_b16_d16_hi v55, v63
	v_add3_u32 v63, s84, v96, 59
	s_and_b64 vcc, exec, s[6:7]
	v_cmp_lt_i32_e64 s[40:41], s76, v63
	s_cbranch_vccz .Lsg_304

; __device__ __forceinline__ float softplusf(float x) { return fmaxf(x, 0.f) + __logf(1.f + __expf(-fabsf(x))); }
; __device__ __forceinline__ bf16r f2bf(float f) {
;   unsigned u = __float_as_uint(f);
;   u += 0x7fffu + ((u >> 16) & 1u);
;   return (bf16r)(u >> 16);
; }
; __device__ __forceinline__ unsigned pack2(float a, float b) { return (unsigned)f2bf(a) | ((unsigned)f2bf(b) << 16); }
; __device__ __forceinline__ float lo16(unsigned v) { return __uint_as_float(v << 16); }
; __device__ __forceinline__ float hi16(unsigned v) { return __uint_as_float(v & 0xffff0000u); }
; __device__ __forceinline__ float siluf(float x) { return x / (1.f + __expf(-x)); }
; __device__ __forceinline__ float sigmf(float x) { return 1.f / (1.f + __expf(-x)); }
; __device__ __forceinline__ void inproj_epilogue(const Params& p, int layer, int mt, int ntile, int tid,
;                                                 f32x16 (&acc)[2][2], unsigned char* smem) {
;     ...
;   const int m0 = mt * 128;
;   if (mode == 3) {
;     float* dt = (float*)(p.ws + OFF_DT) + (size_t)m0 * 16;
;     const float* bias = p.ssd_dt_bias + layer * 16;
;     acc_foreach(tid, acc, [&](int row, int col, float v) {
;       if (col < 16) *(dt + row * 16 + col) = softplusf(v + bias[col]);
;     });
;   } else {
;     bf16r* dstb = dst + (size_t)m0 * ld + c0;
;     bf16r* sT = (bf16r*)smem;
;     acc_foreach(tid, acc, [&](int row, int col, float v) {
;       int t = m0 + row;
;       float o = v;
;       if (mode == 1) o = (t >= NPADR) ? v : 0.f;
;       if (mode == 2) o = sigmf(v);
;       sT[row * 136 + col] = f2bf(o);
;     });
.LBB0_2713:
	s_lshl_b32 s96, s6, 7
	s_ashr_i32 s97, s96, 31
	s_cmp_lg_u32 s7, 3
	s_mov_b64 s[4:5], -1
	s_cbranch_scc0 .LBB0_2907
	v_mov_b32_e32 v106, v108
	s_movk_i32 s4, 0xffc0
	v_lshrrev_b32_e32 v107, 3, v106
	v_ashrrev_i32_e32 v96, 1, v106
	v_and_b32_e32 v107, 4, v107
	v_and_or_b32 v96, v96, s4, v107
	s_cmp_eq_u32 s7, 1
	s_cselect_b64 s[4:5], -1, 0
	v_add_u32_e32 v107, s96, v96
	s_cmp_eq_u32 s7, 2
	s_cselect_b64 s[10:11], -1, 0
	s_cmp_lg_u32 s7, 2
	v_cmp_lt_i32_e64 s[8:9], s79, v107
	s_cbranch_scc0 .Lsg_321

; __device__ __forceinline__ bf16r f2bf(float f) {
;   unsigned u = __float_as_uint(f);
;   u += 0x7fffu + ((u >> 16) & 1u);
;   return (bf16r)(u >> 16);
; }
; __device__ __forceinline__ unsigned pack2(float a, float b) { return (unsigned)f2bf(a) | ((unsigned)f2bf(b) << 16); }
; __device__ __forceinline__ float lo16(unsigned v) { return __uint_as_float(v << 16); }
; __device__ __forceinline__ float hi16(unsigned v) { return __uint_as_float(v & 0xffff0000u); }
; __device__ __forceinline__ float siluf(float x) { return x / (1.f + __expf(-x)); }
; __device__ __forceinline__ float sigmf(float x) { return 1.f / (1.f + __expf(-x)); }
; __device__ __forceinline__ void inproj_epilogue(const Params& p, int layer, int mt, int ntile, int tid,
;                                                 f32x16 (&acc)[2][2], unsigned char* smem) {
;     ...
;     acc_foreach(tid, acc, [&](int row, int col, float v) {
;       int t = m0 + row;
;       float o = v;
;       if (mode == 1) o = (t >= NPADR) ? v : 0.f;
;       if (mode == 2) o = sigmf(v);
;       sT[row * 136 + col] = f2bf(o);
;     });
.LBB0_2717:
	v_bfe_u32 v110, v107, 16, 1
	v_and_b32_e32 v106, 0x5f, v106
	v_add3_u32 v111, v107, v110, s81
	v_mul_lo_u32 v110, v96, s82
	v_lshl_add_u32 v107, v106, 1, v110
	ds_write_b16_d16_hi v107, v111
	v_add3_u32 v111, s96, v96, 1
	v_cndmask_b32_e64 v112, 0, 1, s[10:11]
	v_cmp_ne_u32_e64 s[6:7], 1, v112
	s_andn2_b64 vcc, exec, s[10:11]
	v_cmp_lt_i32_e64 s[10:11], s79, v111
	s_cbranch_vccz .Lsg_322

; __device__ __forceinline__ bf16r f2bf(float f) {
;   unsigned u = __float_as_uint(f);
;   u += 0x7fffu + ((u >> 16) & 1u);
;   return (bf16r)(u >> 16);
; }
; __device__ __forceinline__ unsigned pack2(float a, float b) { return (unsigned)f2bf(a) | ((unsigned)f2bf(b) << 16); }
; __device__ __forceinline__ float lo16(unsigned v) { return __uint_as_float(v << 16); }
; __device__ __forceinline__ float hi16(unsigned v) { return __uint_as_float(v & 0xffff0000u); }
; __device__ __forceinline__ float siluf(float x) { return x / (1.f + __expf(-x)); }
; __device__ __forceinline__ float sigmf(float x) { return 1.f / (1.f + __expf(-x)); }
; __device__ __forceinline__ void inproj_epilogue(const Params& p, int layer, int mt, int ntile, int tid,
;                                                 f32x16 (&acc)[2][2], unsigned char* smem) {
;     ...
;     acc_foreach(tid, acc, [&](int row, int col, float v) {
;       int t = m0 + row;
;       float o = v;
;       if (mode == 1) o = (t >= NPADR) ? v : 0.f;
;       if (mode == 2) o = sigmf(v);
;       sT[row * 136 + col] = f2bf(o);
;     });
.LBB0_2720:
	v_bfe_u32 v112, v111, 16, 1
	v_add3_u32 v112, v111, v112, s81
	v_add_u32_e32 v111, 0x110, v110
	v_lshl_add_u32 v110, v106, 1, v111
	ds_write_b16_d16_hi v110, v112
	v_add3_u32 v112, s96, v96, 2
	s_and_b64 vcc, exec, s[6:7]
	v_cmp_lt_i32_e64 s[12:13], s79, v112
	s_cbranch_vccz .Lsg_323

; __device__ __forceinline__ bf16r f2bf(float f) {
;   unsigned u = __float_as_uint(f);
;   u += 0x7fffu + ((u >> 16) & 1u);
;   return (bf16r)(u >> 16);
; }
; __device__ __forceinline__ unsigned pack2(float a, float b) { return (unsigned)f2bf(a) | ((unsigned)f2bf(b) << 16); }
; __device__ __forceinline__ float lo16(unsigned v) { return __uint_as_float(v << 16); }
; __device__ __forceinline__ float hi16(unsigned v) { return __uint_as_float(v & 0xffff0000u); }
; __device__ __forceinline__ float siluf(float x) { return x / (1.f + __expf(-x)); }
; __device__ __forceinline__ float sigmf(float x) { return 1.f / (1.f + __expf(-x)); }
; __device__ __forceinline__ void inproj_epilogue(const Params& p, int layer, int mt, int ntile, int tid,
;                                                 f32x16 (&acc)[2][2], unsigned char* smem) {
;     ...
;     acc_foreach(tid, acc, [&](int row, int col, float v) {
;       int t = m0 + row;
;       float o = v;
;       if (mode == 1) o = (t >= NPADR) ? v : 0.f;
;       if (mode == 2) o = sigmf(v);
;       sT[row * 136 + col] = f2bf(o);
;     });
.LBB0_2723:
	v_bfe_u32 v113, v112, 16, 1
	v_add3_u32 v113, v112, v113, s81
	v_add_u32_e32 v112, 0x110, v111
	v_lshl_add_u32 v111, v106, 1, v112
	ds_write_b16_d16_hi v111, v113
	v_add3_u32 v113, s96, v96, 3
	s_and_b64 vcc, exec, s[6:7]
	v_cmp_lt_i32_e64 s[14:15], s79, v113
	s_cbranch_vccz .Lsg_324

; __device__ __forceinline__ bf16r f2bf(float f) {
;   unsigned u = __float_as_uint(f);
;   u += 0x7fffu + ((u >> 16) & 1u);
;   return (bf16r)(u >> 16);
; }
; __device__ __forceinline__ unsigned pack2(float a, float b) { return (unsigned)f2bf(a) | ((unsigned)f2bf(b) << 16); }
; __device__ __forceinline__ float lo16(unsigned v) { return __uint_as_float(v << 16); }
; __device__ __forceinline__ float hi16(unsigned v) { return __uint_as_float(v & 0xffff0000u); }
; __device__ __forceinline__ float siluf(float x) { return x / (1.f + __expf(-x)); }
; __device__ __forceinline__ float sigmf(float x) { return 1.f / (1.f + __expf(-x)); }
; __device__ __forceinline__ void inproj_epilogue(const Params& p, int layer, int mt, int ntile, int tid,
;                                                 f32x16 (&acc)[2][2], unsigned char* smem) {
;     ...
;     acc_foreach(tid, acc, [&](int row, int col, float v) {
;       int t = m0 + row;
;       float o = v;
;       if (mode == 1) o = (t >= NPADR) ? v : 0.f;
;       if (mode == 2) o = sigmf(v);
;       sT[row * 136 + col] = f2bf(o);
;     });
.LBB0_2726:
	v_bfe_u32 v114, v113, 16, 1
	v_add3_u32 v114, v113, v114, s81
	v_add_u32_e32 v113, 0x110, v112
	v_lshl_add_u32 v112, v106, 1, v113
	ds_write_b16_d16_hi v112, v114
	v_add3_u32 v114, s96, v96, 8
	s_and_b64 vcc, exec, s[6:7]
	v_cmp_lt_i32_e64 s[16:17], s79, v114
	s_cbranch_vccz .Lsg_325

; __device__ __forceinline__ bf16r f2bf(float f) {
;   unsigned u = __float_as_uint(f);
;   u += 0x7fffu + ((u >> 16) & 1u);
;   return (bf16r)(u >> 16);
; }
; __device__ __forceinline__ unsigned pack2(float a, float b) { return (unsigned)f2bf(a) | ((unsigned)f2bf(b) << 16); }
; __device__ __forceinline__ float lo16(unsigned v) { return __uint_as_float(v << 16); }
; __device__ __forceinline__ float hi16(unsigned v) { return __uint_as_float(v & 0xffff0000u); }
; __device__ __forceinline__ float siluf(float x) { return x / (1.f + __expf(-x)); }
; __device__ __forceinline__ float sigmf(float x) { return 1.f / (1.f + __expf(-x)); }
; __device__ __forceinline__ void inproj_epilogue(const Params& p, int layer, int mt, int ntile, int tid,
;                                                 f32x16 (&acc)[2][2], unsigned char* smem) {
;     ...
;     acc_foreach(tid, acc, [&](int row, int col, float v) {
;       int t = m0 + row;
;       float o = v;
;       if (mode == 1) o = (t >= NPADR) ? v : 0.f;
;       if (mode == 2) o = sigmf(v);
;       sT[row * 136 + col] = f2bf(o);
;     });
.LBB0_2729:
	v_bfe_u32 v115, v114, 16, 1
	v_add3_u32 v115, v114, v115, s81
	v_add_u32_e32 v114, 0x550, v113
	v_lshl_add_u32 v113, v106, 1, v114
	ds_write_b16_d16_hi v113, v115
	v_add3_u32 v115, s96, v96, 9
	s_and_b64 vcc, exec, s[6:7]
	v_cmp_lt_i32_e64 s[18:19], s79, v115
	s_cbranch_vccz .Lsg_326

; __device__ __forceinline__ bf16r f2bf(float f) {
;   unsigned u = __float_as_uint(f);
;   u += 0x7fffu + ((u >> 16) & 1u);
;   return (bf16r)(u >> 16);
; }
; __device__ __forceinline__ unsigned pack2(float a, float b) { return (unsigned)f2bf(a) | ((unsigned)f2bf(b) << 16); }
; __device__ __forceinline__ float lo16(unsigned v) { return __uint_as_float(v << 16); }
; __device__ __forceinline__ float hi16(unsigned v) { return __uint_as_float(v & 0xffff0000u); }
; __device__ __forceinline__ float siluf(float x) { return x / (1.f + __expf(-x)); }
; __device__ __forceinline__ float sigmf(float x) { return 1.f / (1.f + __expf(-x)); }
; __device__ __forceinline__ void inproj_epilogue(const Params& p, int layer, int mt, int ntile, int tid,
;                                                 f32x16 (&acc)[2][2], unsigned char* smem) {
;     ...
;     acc_foreach(tid, acc, [&](int row, int col, float v) {
;       int t = m0 + row;
;       float o = v;
;       if (mode == 1) o = (t >= NPADR) ? v : 0.f;
;       if (mode == 2) o = sigmf(v);
;       sT[row * 136 + col] = f2bf(o);
;     });
.LBB0_2732:
	v_bfe_u32 v116, v115, 16, 1
	v_add3_u32 v116, v115, v116, s81
	v_add_u32_e32 v115, 0x110, v114
	v_lshl_add_u32 v114, v106, 1, v115
	ds_write_b16_d16_hi v114, v116
	v_add3_u32 v116, s96, v96, 10
	s_and_b64 vcc, exec, s[6:7]
	v_cmp_lt_i32_e64 s[20:21], s79, v116
	s_cbranch_vccz .Lsg_327

; __device__ __forceinline__ bf16r f2bf(float f) {
;   unsigned u = __float_as_uint(f);
;   u += 0x7fffu + ((u >> 16) & 1u);
;   return (bf16r)(u >> 16);
; }
; __device__ __forceinline__ unsigned pack2(float a, float b) { return (unsigned)f2bf(a) | ((unsigned)f2bf(b) << 16); }
; __device__ __forceinline__ float lo16(unsigned v) { return __uint_as_float(v << 16); }
; __device__ __forceinline__ float hi16(unsigned v) { return __uint_as_float(v & 0xffff0000u); }
; __device__ __forceinline__ float siluf(float x) { return x / (1.f + __expf(-x)); }
; __device__ __forceinline__ float sigmf(float x) { return 1.f / (1.f + __expf(-x)); }
; __device__ __forceinline__ void inproj_epilogue(const Params& p, int layer, int mt, int ntile, int tid,
;                                                 f32x16 (&acc)[2][2], unsigned char* smem) {
;     ...
;     acc_foreach(tid, acc, [&](int row, int col, float v) {
;       int t = m0 + row;
;       float o = v;
;       if (mode == 1) o = (t >= NPADR) ? v : 0.f;
;       if (mode == 2) o = sigmf(v);
;       sT[row * 136 + col] = f2bf(o);
;     });
.LBB0_2735:
	v_bfe_u32 v117, v116, 16, 1
	v_add3_u32 v117, v116, v117, s81
	v_add_u32_e32 v116, 0x110, v115
	v_lshl_add_u32 v115, v106, 1, v116
	ds_write_b16_d16_hi v115, v117
	v_add3_u32 v117, s96, v96, 11
	s_and_b64 vcc, exec, s[6:7]
	v_cmp_lt_i32_e64 s[22:23], s79, v117
	s_cbranch_vccz .Lsg_328

; __device__ __forceinline__ bf16r f2bf(float f) {
;   unsigned u = __float_as_uint(f);
;   u += 0x7fffu + ((u >> 16) & 1u);
;   return (bf16r)(u >> 16);
; }
; __device__ __forceinline__ unsigned pack2(float a, float b) { return (unsigned)f2bf(a) | ((unsigned)f2bf(b) << 16); }
; __device__ __forceinline__ float lo16(unsigned v) { return __uint_as_float(v << 16); }
; __device__ __forceinline__ float hi16(unsigned v) { return __uint_as_float(v & 0xffff0000u); }
; __device__ __forceinline__ float siluf(float x) { return x / (1.f + __expf(-x)); }
; __device__ __forceinline__ float sigmf(float x) { return 1.f / (1.f + __expf(-x)); }
; __device__ __forceinline__ void inproj_epilogue(const Params& p, int layer, int mt, int ntile, int tid,
;                                                 f32x16 (&acc)[2][2], unsigned char* smem) {
;     ...
;     acc_foreach(tid, acc, [&](int row, int col, float v) {
;       int t = m0 + row;
;       float o = v;
;       if (mode == 1) o = (t >= NPADR) ? v : 0.f;
;       if (mode == 2) o = sigmf(v);
;       sT[row * 136 + col] = f2bf(o);
;     });
.LBB0_2738:
	v_bfe_u32 v118, v117, 16, 1
	v_add_u32_e32 v116, 0x110, v116
	v_add3_u32 v118, v117, v118, s81
	v_lshl_add_u32 v117, v106, 1, v116
	ds_write_b16_d16_hi v117, v118
	v_add3_u32 v118, s96, v96, 16
	s_and_b64 vcc, exec, s[6:7]
	v_cmp_lt_i32_e64 s[24:25], s79, v118
	s_cbranch_vccz .Lsg_329

; __device__ __forceinline__ bf16r f2bf(float f) {
;   unsigned u = __float_as_uint(f);
;   u += 0x7fffu + ((u >> 16) & 1u);
;   return (bf16r)(u >> 16);
; }
; __device__ __forceinline__ unsigned pack2(float a, float b) { return (unsigned)f2bf(a) | ((unsigned)f2bf(b) << 16); }
; __device__ __forceinline__ float lo16(unsigned v) { return __uint_as_float(v << 16); }
; __device__ __forceinline__ float hi16(unsigned v) { return __uint_as_float(v & 0xffff0000u); }
; __device__ __forceinline__ float siluf(float x) { return x / (1.f + __expf(-x)); }
; __device__ __forceinline__ float sigmf(float x) { return 1.f / (1.f + __expf(-x)); }
; __device__ __forceinline__ void inproj_epilogue(const Params& p, int layer, int mt, int ntile, int tid,
;                                                 f32x16 (&acc)[2][2], unsigned char* smem) {
;     ...
;     acc_foreach(tid, acc, [&](int row, int col, float v) {
;       int t = m0 + row;
;       float o = v;
;       if (mode == 1) o = (t >= NPADR) ? v : 0.f;
;       if (mode == 2) o = sigmf(v);
;       sT[row * 136 + col] = f2bf(o);
;     });
.LBB0_2741:
	v_bfe_u32 v119, v118, 16, 1
	v_add_u32_e32 v116, 0x550, v116
	v_add3_u32 v119, v118, v119, s81
	v_lshl_add_u32 v118, v106, 1, v116
	ds_write_b16_d16_hi v118, v119
	v_add3_u32 v119, s96, v96, 17
	s_and_b64 vcc, exec, s[6:7]
	v_cmp_lt_i32_e64 s[26:27], s79, v119
	s_cbranch_vccz .Lsg_330

; __device__ __forceinline__ bf16r f2bf(float f) {
;   unsigned u = __float_as_uint(f);
;   u += 0x7fffu + ((u >> 16) & 1u);
;   return (bf16r)(u >> 16);
; }
; __device__ __forceinline__ unsigned pack2(float a, float b) { return (unsigned)f2bf(a) | ((unsigned)f2bf(b) << 16); }
; __device__ __forceinline__ float lo16(unsigned v) { return __uint_as_float(v << 16); }
; __device__ __forceinline__ float hi16(unsigned v) { return __uint_as_float(v & 0xffff0000u); }
; __device__ __forceinline__ float siluf(float x) { return x / (1.f + __expf(-x)); }
; __device__ __forceinline__ float sigmf(float x) { return 1.f / (1.f + __expf(-x)); }
; __device__ __forceinline__ void inproj_epilogue(const Params& p, int layer, int mt, int ntile, int tid,
;                                                 f32x16 (&acc)[2][2], unsigned char* smem) {
;     ...
;     acc_foreach(tid, acc, [&](int row, int col, float v) {
;       int t = m0 + row;
;       float o = v;
;       if (mode == 1) o = (t >= NPADR) ? v : 0.f;
;       if (mode == 2) o = sigmf(v);
;       sT[row * 136 + col] = f2bf(o);
;     });
.LBB0_2744:
	v_bfe_u32 v120, v119, 16, 1
	v_add_u32_e32 v116, 0x110, v116
	v_add3_u32 v120, v119, v120, s81
	v_lshl_add_u32 v119, v106, 1, v116
	ds_write_b16_d16_hi v119, v120
	v_add3_u32 v120, s96, v96, 18
	s_and_b64 vcc, exec, s[6:7]
	v_cmp_lt_i32_e64 s[28:29], s79, v120
	s_cbranch_vccz .Lsg_331

; __device__ __forceinline__ bf16r f2bf(float f) {
;   unsigned u = __float_as_uint(f);
;   u += 0x7fffu + ((u >> 16) & 1u);
;   return (bf16r)(u >> 16);
; }
; __device__ __forceinline__ unsigned pack2(float a, float b) { return (unsigned)f2bf(a) | ((unsigned)f2bf(b) << 16); }
; __device__ __forceinline__ float lo16(unsigned v) { return __uint_as_float(v << 16); }
; __device__ __forceinline__ float hi16(unsigned v) { return __uint_as_float(v & 0xffff0000u); }
; __device__ __forceinline__ float siluf(float x) { return x / (1.f + __expf(-x)); }
; __device__ __forceinline__ float sigmf(float x) { return 1.f / (1.f + __expf(-x)); }
; __device__ __forceinline__ void inproj_epilogue(const Params& p, int layer, int mt, int ntile, int tid,
;                                                 f32x16 (&acc)[2][2], unsigned char* smem) {
;     ...
;     acc_foreach(tid, acc, [&](int row, int col, float v) {
;       int t = m0 + row;
;       float o = v;
;       if (mode == 1) o = (t >= NPADR) ? v : 0.f;
;       if (mode == 2) o = sigmf(v);
;       sT[row * 136 + col] = f2bf(o);
;     });
.LBB0_2747:
	v_bfe_u32 v121, v120, 16, 1
	v_add_u32_e32 v116, 0x110, v116
	v_add3_u32 v121, v120, v121, s81
	v_lshl_add_u32 v120, v106, 1, v116
	ds_write_b16_d16_hi v120, v121
	v_add3_u32 v121, s96, v96, 19
	s_and_b64 vcc, exec, s[6:7]
	v_cmp_lt_i32_e64 s[30:31], s79, v121
	s_cbranch_vccz .Lsg_332

; __device__ __forceinline__ bf16r f2bf(float f) {
;   unsigned u = __float_as_uint(f);
;   u += 0x7fffu + ((u >> 16) & 1u);
;   return (bf16r)(u >> 16);
; }
; __device__ __forceinline__ unsigned pack2(float a, float b) { return (unsigned)f2bf(a) | ((unsigned)f2bf(b) << 16); }
; __device__ __forceinline__ float lo16(unsigned v) { return __uint_as_float(v << 16); }
; __device__ __forceinline__ float hi16(unsigned v) { return __uint_as_float(v & 0xffff0000u); }
; __device__ __forceinline__ float siluf(float x) { return x / (1.f + __expf(-x)); }
; __device__ __forceinline__ float sigmf(float x) { return 1.f / (1.f + __expf(-x)); }
; __device__ __forceinline__ void inproj_epilogue(const Params& p, int layer, int mt, int ntile, int tid,
;                                                 f32x16 (&acc)[2][2], unsigned char* smem) {
;     ...
;     acc_foreach(tid, acc, [&](int row, int col, float v) {
;       int t = m0 + row;
;       float o = v;
;       if (mode == 1) o = (t >= NPADR) ? v : 0.f;
;       if (mode == 2) o = sigmf(v);
;       sT[row * 136 + col] = f2bf(o);
;     });
.LBB0_2750:
	v_bfe_u32 v122, v121, 16, 1
	v_add_u32_e32 v116, 0x110, v116
	v_add3_u32 v122, v121, v122, s81
	v_lshl_add_u32 v121, v106, 1, v116
	ds_write_b16_d16_hi v121, v122
	v_add3_u32 v122, s96, v96, 24
	s_and_b64 vcc, exec, s[6:7]
	v_cmp_lt_i32_e64 s[34:35], s79, v122
	s_cbranch_vccz .Lsg_333

; __device__ __forceinline__ bf16r f2bf(float f) {
;   unsigned u = __float_as_uint(f);
;   u += 0x7fffu + ((u >> 16) & 1u);
;   return (bf16r)(u >> 16);
; }
; __device__ __forceinline__ unsigned pack2(float a, float b) { return (unsigned)f2bf(a) | ((unsigned)f2bf(b) << 16); }
; __device__ __forceinline__ float lo16(unsigned v) { return __uint_as_float(v << 16); }
; __device__ __forceinline__ float hi16(unsigned v) { return __uint_as_float(v & 0xffff0000u); }
; __device__ __forceinline__ float siluf(float x) { return x / (1.f + __expf(-x)); }
; __device__ __forceinline__ float sigmf(float x) { return 1.f / (1.f + __expf(-x)); }
; __device__ __forceinline__ void inproj_epilogue(const Params& p, int layer, int mt, int ntile, int tid,
;                                                 f32x16 (&acc)[2][2], unsigned char* smem) {
;     ...
;     acc_foreach(tid, acc, [&](int row, int col, float v) {
;       int t = m0 + row;
;       float o = v;
;       if (mode == 1) o = (t >= NPADR) ? v : 0.f;
;       if (mode == 2) o = sigmf(v);
;       sT[row * 136 + col] = f2bf(o);
;     });
.LBB0_2753:
	v_bfe_u32 v123, v122, 16, 1
	v_add_u32_e32 v116, 0x550, v116
	v_add3_u32 v123, v122, v123, s81
	v_lshl_add_u32 v122, v106, 1, v116
	ds_write_b16_d16_hi v122, v123
	v_add3_u32 v123, s96, v96, 25
	s_and_b64 vcc, exec, s[6:7]
	v_cmp_lt_i32_e64 s[36:37], s79, v123
	s_cbranch_vccz .Lsg_334

; __device__ __forceinline__ bf16r f2bf(float f) {
;   unsigned u = __float_as_uint(f);
;   u += 0x7fffu + ((u >> 16) & 1u);
;   return (bf16r)(u >> 16);
; }
; __device__ __forceinline__ unsigned pack2(float a, float b) { return (unsigned)f2bf(a) | ((unsigned)f2bf(b) << 16); }
; __device__ __forceinline__ float lo16(unsigned v) { return __uint_as_float(v << 16); }
; __device__ __forceinline__ float hi16(unsigned v) { return __uint_as_float(v & 0xffff0000u); }
; __device__ __forceinline__ float siluf(float x) { return x / (1.f + __expf(-x)); }
; __device__ __forceinline__ float sigmf(float x) { return 1.f / (1.f + __expf(-x)); }
; __device__ __forceinline__ void inproj_epilogue(const Params& p, int layer, int mt, int ntile, int tid,
;                                                 f32x16 (&acc)[2][2], unsigned char* smem) {
;     ...
;     acc_foreach(tid, acc, [&](int row, int col, float v) {
;       int t = m0 + row;
;       float o = v;
;       if (mode == 1) o = (t >= NPADR) ? v : 0.f;
;       if (mode == 2) o = sigmf(v);
;       sT[row * 136 + col] = f2bf(o);
;     });
.LBB0_2756:
	v_bfe_u32 v124, v123, 16, 1
	v_add_u32_e32 v116, 0x110, v116
	v_add3_u32 v124, v123, v124, s81
	v_lshl_add_u32 v123, v106, 1, v116
	ds_write_b16_d16_hi v123, v124
	v_add3_u32 v124, s96, v96, 26
	s_and_b64 vcc, exec, s[6:7]
	v_cmp_lt_i32_e64 s[38:39], s79, v124
	s_cbranch_vccz .Lsg_335

; __device__ __forceinline__ bf16r f2bf(float f) {
;   unsigned u = __float_as_uint(f);
;   u += 0x7fffu + ((u >> 16) & 1u);
;   return (bf16r)(u >> 16);
; }
; __device__ __forceinline__ unsigned pack2(float a, float b) { return (unsigned)f2bf(a) | ((unsigned)f2bf(b) << 16); }
; __device__ __forceinline__ float lo16(unsigned v) { return __uint_as_float(v << 16); }
; __device__ __forceinline__ float hi16(unsigned v) { return __uint_as_float(v & 0xffff0000u); }
; __device__ __forceinline__ float siluf(float x) { return x / (1.f + __expf(-x)); }
; __device__ __forceinline__ float sigmf(float x) { return 1.f / (1.f + __expf(-x)); }
; __device__ __forceinline__ void inproj_epilogue(const Params& p, int layer, int mt, int ntile, int tid,
;                                                 f32x16 (&acc)[2][2], unsigned char* smem) {
;     ...
;     acc_foreach(tid, acc, [&](int row, int col, float v) {
;       int t = m0 + row;
;       float o = v;
;       if (mode == 1) o = (t >= NPADR) ? v : 0.f;
;       if (mode == 2) o = sigmf(v);
;       sT[row * 136 + col] = f2bf(o);
;     });
.LBB0_2759:
	v_bfe_u32 v125, v124, 16, 1
	v_add_u32_e32 v116, 0x110, v116
	v_add3_u32 v124, v124, v125, s81
	v_lshl_add_u32 v116, v106, 1, v116
	ds_write_b16_d16_hi v116, v124
	v_add3_u32 v124, s96, v96, 27
	s_and_b64 vcc, exec, s[6:7]
	v_cmp_lt_i32_e64 s[40:41], s79, v124
	s_cbranch_vccz .Lsg_336

; __device__ __forceinline__ bf16r f2bf(float f) {
;   unsigned u = __float_as_uint(f);
;   u += 0x7fffu + ((u >> 16) & 1u);
;   return (bf16r)(u >> 16);
; }
; __device__ __forceinline__ unsigned pack2(float a, float b) { return (unsigned)f2bf(a) | ((unsigned)f2bf(b) << 16); }
; __device__ __forceinline__ float lo16(unsigned v) { return __uint_as_float(v << 16); }
; __device__ __forceinline__ float hi16(unsigned v) { return __uint_as_float(v & 0xffff0000u); }
; __device__ __forceinline__ float siluf(float x) { return x / (1.f + __expf(-x)); }
; __device__ __forceinline__ float sigmf(float x) { return 1.f / (1.f + __expf(-x)); }
; __device__ __forceinline__ void inproj_epilogue(const Params& p, int layer, int mt, int ntile, int tid,
;                                                 f32x16 (&acc)[2][2], unsigned char* smem) {
;     ...
;     acc_foreach(tid, acc, [&](int row, int col, float v) {
;       int t = m0 + row;
;       float o = v;
;       if (mode == 1) o = (t >= NPADR) ? v : 0.f;
;       if (mode == 2) o = sigmf(v);
;       sT[row * 136 + col] = f2bf(o);
;     });
.LBB0_2762:
	v_bfe_u32 v125, v124, 16, 1
	v_add3_u32 v124, v124, v125, s81
	ds_write_b16_d16_hi v116, v124 offset:272
	s_and_b64 vcc, exec, s[6:7]
	s_cbranch_vccz .Lsg_337

; __device__ __forceinline__ bf16r f2bf(float f) {
;   unsigned u = __float_as_uint(f);
;   u += 0x7fffu + ((u >> 16) & 1u);
;   return (bf16r)(u >> 16);
; }
; __device__ __forceinline__ unsigned pack2(float a, float b) { return (unsigned)f2bf(a) | ((unsigned)f2bf(b) << 16); }
; __device__ __forceinline__ float lo16(unsigned v) { return __uint_as_float(v << 16); }
; __device__ __forceinline__ float hi16(unsigned v) { return __uint_as_float(v & 0xffff0000u); }
; __device__ __forceinline__ float siluf(float x) { return x / (1.f + __expf(-x)); }
; __device__ __forceinline__ float sigmf(float x) { return 1.f / (1.f + __expf(-x)); }
; __device__ __forceinline__ void inproj_epilogue(const Params& p, int layer, int mt, int ntile, int tid,
;                                                 f32x16 (&acc)[2][2], unsigned char* smem) {
;     ...
;     acc_foreach(tid, acc, [&](int row, int col, float v) {
;       int t = m0 + row;
;       float o = v;
;       if (mode == 1) o = (t >= NPADR) ? v : 0.f;
;       if (mode == 2) o = sigmf(v);
;       sT[row * 136 + col] = f2bf(o);
;     });
.LBB0_2765:
	v_bfe_u32 v124, v48, 16, 1
	v_add3_u32 v48, v48, v124, s81
	s_and_b64 vcc, exec, s[6:7]
	ds_write_b16_d16_hi v107, v48 offset:64
	s_cbranch_vccz .Lsg_338

; __device__ __forceinline__ bf16r f2bf(float f) {
;   unsigned u = __float_as_uint(f);
;   u += 0x7fffu + ((u >> 16) & 1u);
;   return (bf16r)(u >> 16);
; }
; __device__ __forceinline__ unsigned pack2(float a, float b) { return (unsigned)f2bf(a) | ((unsigned)f2bf(b) << 16); }
; __device__ __forceinline__ float lo16(unsigned v) { return __uint_as_float(v << 16); }
; __device__ __forceinline__ float hi16(unsigned v) { return __uint_as_float(v & 0xffff0000u); }
; __device__ __forceinline__ float siluf(float x) { return x / (1.f + __expf(-x)); }
; __device__ __forceinline__ float sigmf(float x) { return 1.f / (1.f + __expf(-x)); }
; __device__ __forceinline__ void inproj_epilogue(const Params& p, int layer, int mt, int ntile, int tid,
;                                                 f32x16 (&acc)[2][2], unsigned char* smem) {
;     ...
;     acc_foreach(tid, acc, [&](int row, int col, float v) {
;       int t = m0 + row;
;       float o = v;
;       if (mode == 1) o = (t >= NPADR) ? v : 0.f;
;       if (mode == 2) o = sigmf(v);
;       sT[row * 136 + col] = f2bf(o);
;     });
.LBB0_2768:
	v_bfe_u32 v49, v48, 16, 1
	v_add3_u32 v48, v48, v49, s81
	s_and_b64 vcc, exec, s[6:7]
	ds_write_b16_d16_hi v110, v48 offset:64
	s_cbranch_vccz .Lsg_339

; __device__ __forceinline__ bf16r f2bf(float f) {
;   unsigned u = __float_as_uint(f);
;   u += 0x7fffu + ((u >> 16) & 1u);
;   return (bf16r)(u >> 16);
; }
; __device__ __forceinline__ unsigned pack2(float a, float b) { return (unsigned)f2bf(a) | ((unsigned)f2bf(b) << 16); }
; __device__ __forceinline__ float lo16(unsigned v) { return __uint_as_float(v << 16); }
; __device__ __forceinline__ float hi16(unsigned v) { return __uint_as_float(v & 0xffff0000u); }
; __device__ __forceinline__ float siluf(float x) { return x / (1.f + __expf(-x)); }
; __device__ __forceinline__ float sigmf(float x) { return 1.f / (1.f + __expf(-x)); }
; __device__ __forceinline__ void inproj_epilogue(const Params& p, int layer, int mt, int ntile, int tid,
;                                                 f32x16 (&acc)[2][2], unsigned char* smem) {
;     ...
;     acc_foreach(tid, acc, [&](int row, int col, float v) {
;       int t = m0 + row;
;       float o = v;
;       if (mode == 1) o = (t >= NPADR) ? v : 0.f;
;       if (mode == 2) o = sigmf(v);
;       sT[row * 136 + col] = f2bf(o);
;     });
.LBB0_2771:
	v_bfe_u32 v49, v48, 16, 1
	v_add3_u32 v48, v48, v49, s81
	s_and_b64 vcc, exec, s[6:7]
	ds_write_b16_d16_hi v111, v48 offset:64
	s_cbranch_vccz .Lsg_340

; __device__ __forceinline__ bf16r f2bf(float f) {
;   unsigned u = __float_as_uint(f);
;   u += 0x7fffu + ((u >> 16) & 1u);
;   return (bf16r)(u >> 16);
; }
; __device__ __forceinline__ unsigned pack2(float a, float b) { return (unsigned)f2bf(a) | ((unsigned)f2bf(b) << 16); }
; __device__ __forceinline__ float lo16(unsigned v) { return __uint_as_float(v << 16); }
; __device__ __forceinline__ float hi16(unsigned v) { return __uint_as_float(v & 0xffff0000u); }
; __device__ __forceinline__ float siluf(float x) { return x / (1.f + __expf(-x)); }
; __device__ __forceinline__ float sigmf(float x) { return 1.f / (1.f + __expf(-x)); }
; __device__ __forceinline__ void inproj_epilogue(const Params& p, int layer, int mt, int ntile, int tid,
;                                                 f32x16 (&acc)[2][2], unsigned char* smem) {
;     ...
;     acc_foreach(tid, acc, [&](int row, int col, float v) {
;       int t = m0 + row;
;       float o = v;
;       if (mode == 1) o = (t >= NPADR) ? v : 0.f;
;       if (mode == 2) o = sigmf(v);
;       sT[row * 136 + col] = f2bf(o);
;     });
.LBB0_2774:
	v_bfe_u32 v49, v48, 16, 1
	v_add3_u32 v48, v48, v49, s81
	s_and_b64 vcc, exec, s[6:7]
	ds_write_b16_d16_hi v112, v48 offset:64
	s_cbranch_vccz .Lsg_341

; __device__ __forceinline__ bf16r f2bf(float f) {
;   unsigned u = __float_as_uint(f);
;   u += 0x7fffu + ((u >> 16) & 1u);
;   return (bf16r)(u >> 16);
; }
; __device__ __forceinline__ unsigned pack2(float a, float b) { return (unsigned)f2bf(a) | ((unsigned)f2bf(b) << 16); }
; __device__ __forceinline__ float lo16(unsigned v) { return __uint_as_float(v << 16); }
; __device__ __forceinline__ float hi16(unsigned v) { return __uint_as_float(v & 0xffff0000u); }
; __device__ __forceinline__ float siluf(float x) { return x / (1.f + __expf(-x)); }
; __device__ __forceinline__ float sigmf(float x) { return 1.f / (1.f + __expf(-x)); }
; __device__ __forceinline__ void inproj_epilogue(const Params& p, int layer, int mt, int ntile, int tid,
;                                                 f32x16 (&acc)[2][2], unsigned char* smem) {
;     ...
;     acc_foreach(tid, acc, [&](int row, int col, float v) {
;       int t = m0 + row;
;       float o = v;
;       if (mode == 1) o = (t >= NPADR) ? v : 0.f;
;       if (mode == 2) o = sigmf(v);
;       sT[row * 136 + col] = f2bf(o);
;     });
.LBB0_2777:
	v_bfe_u32 v49, v48, 16, 1
	v_add3_u32 v48, v48, v49, s81
	s_and_b64 vcc, exec, s[6:7]
	ds_write_b16_d16_hi v113, v48 offset:64
	s_cbranch_vccz .Lsg_342

; __device__ __forceinline__ bf16r f2bf(float f) {
;   unsigned u = __float_as_uint(f);
;   u += 0x7fffu + ((u >> 16) & 1u);
;   return (bf16r)(u >> 16);
; }
; __device__ __forceinline__ unsigned pack2(float a, float b) { return (unsigned)f2bf(a) | ((unsigned)f2bf(b) << 16); }
; __device__ __forceinline__ float lo16(unsigned v) { return __uint_as_float(v << 16); }
; __device__ __forceinline__ float hi16(unsigned v) { return __uint_as_float(v & 0xffff0000u); }
; __device__ __forceinline__ float siluf(float x) { return x / (1.f + __expf(-x)); }
; __device__ __forceinline__ float sigmf(float x) { return 1.f / (1.f + __expf(-x)); }
; __device__ __forceinline__ void inproj_epilogue(const Params& p, int layer, int mt, int ntile, int tid,
;                                                 f32x16 (&acc)[2][2], unsigned char* smem) {
;     ...
;     acc_foreach(tid, acc, [&](int row, int col, float v) {
;       int t = m0 + row;
;       float o = v;
;       if (mode == 1) o = (t >= NPADR) ? v : 0.f;
;       if (mode == 2) o = sigmf(v);
;       sT[row * 136 + col] = f2bf(o);
;     });
.LBB0_2780:
	v_bfe_u32 v49, v48, 16, 1
	v_add3_u32 v48, v48, v49, s81
	s_and_b64 vcc, exec, s[6:7]
	ds_write_b16_d16_hi v114, v48 offset:64
	s_cbranch_vccz .Lsg_343

; __device__ __forceinline__ bf16r f2bf(float f) {
;   unsigned u = __float_as_uint(f);
;   u += 0x7fffu + ((u >> 16) & 1u);
;   return (bf16r)(u >> 16);
; }
; __device__ __forceinline__ unsigned pack2(float a, float b) { return (unsigned)f2bf(a) | ((unsigned)f2bf(b) << 16); }
; __device__ __forceinline__ float lo16(unsigned v) { return __uint_as_float(v << 16); }
; __device__ __forceinline__ float hi16(unsigned v) { return __uint_as_float(v & 0xffff0000u); }
; __device__ __forceinline__ float siluf(float x) { return x / (1.f + __expf(-x)); }
; __device__ __forceinline__ float sigmf(float x) { return 1.f / (1.f + __expf(-x)); }
; __device__ __forceinline__ void inproj_epilogue(const Params& p, int layer, int mt, int ntile, int tid,
;                                                 f32x16 (&acc)[2][2], unsigned char* smem) {
;     ...
;     acc_foreach(tid, acc, [&](int row, int col, float v) {
;       int t = m0 + row;
;       float o = v;
;       if (mode == 1) o = (t >= NPADR) ? v : 0.f;
;       if (mode == 2) o = sigmf(v);
;       sT[row * 136 + col] = f2bf(o);
;     });
.LBB0_2783:
	v_bfe_u32 v49, v48, 16, 1
	v_add3_u32 v48, v48, v49, s81
	s_and_b64 vcc, exec, s[6:7]
	ds_write_b16_d16_hi v115, v48 offset:64
	s_cbranch_vccz .Lsg_344

; __device__ __forceinline__ bf16r f2bf(float f) {
;   unsigned u = __float_as_uint(f);
;   u += 0x7fffu + ((u >> 16) & 1u);
;   return (bf16r)(u >> 16);
; }
; __device__ __forceinline__ unsigned pack2(float a, float b) { return (unsigned)f2bf(a) | ((unsigned)f2bf(b) << 16); }
; __device__ __forceinline__ float lo16(unsigned v) { return __uint_as_float(v << 16); }
; __device__ __forceinline__ float hi16(unsigned v) { return __uint_as_float(v & 0xffff0000u); }
; __device__ __forceinline__ float siluf(float x) { return x / (1.f + __expf(-x)); }
; __device__ __forceinline__ float sigmf(float x) { return 1.f / (1.f + __expf(-x)); }
; __device__ __forceinline__ void inproj_epilogue(const Params& p, int layer, int mt, int ntile, int tid,
;                                                 f32x16 (&acc)[2][2], unsigned char* smem) {
;     ...
;     acc_foreach(tid, acc, [&](int row, int col, float v) {
;       int t = m0 + row;
;       float o = v;
;       if (mode == 1) o = (t >= NPADR) ? v : 0.f;
;       if (mode == 2) o = sigmf(v);
;       sT[row * 136 + col] = f2bf(o);
;     });
.LBB0_2786:
	v_bfe_u32 v49, v48, 16, 1
	v_add3_u32 v48, v48, v49, s81
	s_and_b64 vcc, exec, s[6:7]
	ds_write_b16_d16_hi v117, v48 offset:64
	s_cbranch_vccz .Lsg_345

; __device__ __forceinline__ bf16r f2bf(float f) {
;   unsigned u = __float_as_uint(f);
;   u += 0x7fffu + ((u >> 16) & 1u);
;   return (bf16r)(u >> 16);
; }
; __device__ __forceinline__ unsigned pack2(float a, float b) { return (unsigned)f2bf(a) | ((unsigned)f2bf(b) << 16); }
; __device__ __forceinline__ float lo16(unsigned v) { return __uint_as_float(v << 16); }
; __device__ __forceinline__ float hi16(unsigned v) { return __uint_as_float(v & 0xffff0000u); }
; __device__ __forceinline__ float siluf(float x) { return x / (1.f + __expf(-x)); }
; __device__ __forceinline__ float sigmf(float x) { return 1.f / (1.f + __expf(-x)); }
; __device__ __forceinline__ void inproj_epilogue(const Params& p, int layer, int mt, int ntile, int tid,
;                                                 f32x16 (&acc)[2][2], unsigned char* smem) {
;     ...
;     acc_foreach(tid, acc, [&](int row, int col, float v) {
;       int t = m0 + row;
;       float o = v;
;       if (mode == 1) o = (t >= NPADR) ? v : 0.f;
;       if (mode == 2) o = sigmf(v);
;       sT[row * 136 + col] = f2bf(o);
;     });
.LBB0_2789:
	v_bfe_u32 v49, v48, 16, 1
	v_add3_u32 v48, v48, v49, s81
	s_and_b64 vcc, exec, s[6:7]
	ds_write_b16_d16_hi v118, v48 offset:64
	s_cbranch_vccz .Lsg_346

; __device__ __forceinline__ bf16r f2bf(float f) {
;   unsigned u = __float_as_uint(f);
;   u += 0x7fffu + ((u >> 16) & 1u);
;   return (bf16r)(u >> 16);
; }
; __device__ __forceinline__ unsigned pack2(float a, float b) { return (unsigned)f2bf(a) | ((unsigned)f2bf(b) << 16); }
; __device__ __forceinline__ float lo16(unsigned v) { return __uint_as_float(v << 16); }
; __device__ __forceinline__ float hi16(unsigned v) { return __uint_as_float(v & 0xffff0000u); }
; __device__ __forceinline__ float siluf(float x) { return x / (1.f + __expf(-x)); }
; __device__ __forceinline__ float sigmf(float x) { return 1.f / (1.f + __expf(-x)); }
; __device__ __forceinline__ void inproj_epilogue(const Params& p, int layer, int mt, int ntile, int tid,
;                                                 f32x16 (&acc)[2][2], unsigned char* smem) {
;     ...
;     acc_foreach(tid, acc, [&](int row, int col, float v) {
;       int t = m0 + row;
;       float o = v;
;       if (mode == 1) o = (t >= NPADR) ? v : 0.f;
;       if (mode == 2) o = sigmf(v);
;       sT[row * 136 + col] = f2bf(o);
;     });
.LBB0_2792:
	v_bfe_u32 v49, v48, 16, 1
	v_add3_u32 v48, v48, v49, s81
	s_and_b64 vcc, exec, s[6:7]
	ds_write_b16_d16_hi v119, v48 offset:64
	s_cbranch_vccz .Lsg_347

; __device__ __forceinline__ bf16r f2bf(float f) {
;   unsigned u = __float_as_uint(f);
;   u += 0x7fffu + ((u >> 16) & 1u);
;   return (bf16r)(u >> 16);
; }
; __device__ __forceinline__ unsigned pack2(float a, float b) { return (unsigned)f2bf(a) | ((unsigned)f2bf(b) << 16); }
; __device__ __forceinline__ float lo16(unsigned v) { return __uint_as_float(v << 16); }
; __device__ __forceinline__ float hi16(unsigned v) { return __uint_as_float(v & 0xffff0000u); }
; __device__ __forceinline__ float siluf(float x) { return x / (1.f + __expf(-x)); }
; __device__ __forceinline__ float sigmf(float x) { return 1.f / (1.f + __expf(-x)); }
; __device__ __forceinline__ void inproj_epilogue(const Params& p, int layer, int mt, int ntile, int tid,
;                                                 f32x16 (&acc)[2][2], unsigned char* smem) {
;     ...
;     acc_foreach(tid, acc, [&](int row, int col, float v) {
;       int t = m0 + row;
;       float o = v;
;       if (mode == 1) o = (t >= NPADR) ? v : 0.f;
;       if (mode == 2) o = sigmf(v);
;       sT[row * 136 + col] = f2bf(o);
;     });
.LBB0_2795:
	v_bfe_u32 v49, v48, 16, 1
	v_add3_u32 v48, v48, v49, s81
	s_and_b64 vcc, exec, s[6:7]
	ds_write_b16_d16_hi v120, v48 offset:64
	s_cbranch_vccz .Lsg_348

; __device__ __forceinline__ bf16r f2bf(float f) {
;   unsigned u = __float_as_uint(f);
;   u += 0x7fffu + ((u >> 16) & 1u);
;   return (bf16r)(u >> 16);
; }
; __device__ __forceinline__ unsigned pack2(float a, float b) { return (unsigned)f2bf(a) | ((unsigned)f2bf(b) << 16); }
; __device__ __forceinline__ float lo16(unsigned v) { return __uint_as_float(v << 16); }
; __device__ __forceinline__ float hi16(unsigned v) { return __uint_as_float(v & 0xffff0000u); }
; __device__ __forceinline__ float siluf(float x) { return x / (1.f + __expf(-x)); }
; __device__ __forceinline__ float sigmf(float x) { return 1.f / (1.f + __expf(-x)); }
; __device__ __forceinline__ void inproj_epilogue(const Params& p, int layer, int mt, int ntile, int tid,
;                                                 f32x16 (&acc)[2][2], unsigned char* smem) {
;     ...
;     acc_foreach(tid, acc, [&](int row, int col, float v) {
;       int t = m0 + row;
;       float o = v;
;       if (mode == 1) o = (t >= NPADR) ? v : 0.f;
;       if (mode == 2) o = sigmf(v);
;       sT[row * 136 + col] = f2bf(o);
;     });
.LBB0_2798:
	v_bfe_u32 v49, v48, 16, 1
	v_add3_u32 v48, v48, v49, s81
	s_and_b64 vcc, exec, s[6:7]
	ds_write_b16_d16_hi v121, v48 offset:64
	s_cbranch_vccz .Lsg_349

; __device__ __forceinline__ bf16r f2bf(float f) {
;   unsigned u = __float_as_uint(f);
;   u += 0x7fffu + ((u >> 16) & 1u);
;   return (bf16r)(u >> 16);
; }
; __device__ __forceinline__ unsigned pack2(float a, float b) { return (unsigned)f2bf(a) | ((unsigned)f2bf(b) << 16); }
; __device__ __forceinline__ float lo16(unsigned v) { return __uint_as_float(v << 16); }
; __device__ __forceinline__ float hi16(unsigned v) { return __uint_as_float(v & 0xffff0000u); }
; __device__ __forceinline__ float siluf(float x) { return x / (1.f + __expf(-x)); }
; __device__ __forceinline__ float sigmf(float x) { return 1.f / (1.f + __expf(-x)); }
; __device__ __forceinline__ void inproj_epilogue(const Params& p, int layer, int mt, int ntile, int tid,
;                                                 f32x16 (&acc)[2][2], unsigned char* smem) {
;     ...
;     acc_foreach(tid, acc, [&](int row, int col, float v) {
;       int t = m0 + row;
;       float o = v;
;       if (mode == 1) o = (t >= NPADR) ? v : 0.f;
;       if (mode == 2) o = sigmf(v);
;       sT[row * 136 + col] = f2bf(o);
;     });
.LBB0_2801:
	v_bfe_u32 v49, v48, 16, 1
	v_add3_u32 v48, v48, v49, s81
	s_and_b64 vcc, exec, s[6:7]
	ds_write_b16_d16_hi v122, v48 offset:64
	s_cbranch_vccz .Lsg_350

; __device__ __forceinline__ bf16r f2bf(float f) {
;   unsigned u = __float_as_uint(f);
;   u += 0x7fffu + ((u >> 16) & 1u);
;   return (bf16r)(u >> 16);
; }
; __device__ __forceinline__ unsigned pack2(float a, float b) { return (unsigned)f2bf(a) | ((unsigned)f2bf(b) << 16); }
; __device__ __forceinline__ float lo16(unsigned v) { return __uint_as_float(v << 16); }
; __device__ __forceinline__ float hi16(unsigned v) { return __uint_as_float(v & 0xffff0000u); }
; __device__ __forceinline__ float siluf(float x) { return x / (1.f + __expf(-x)); }
; __device__ __forceinline__ float sigmf(float x) { return 1.f / (1.f + __expf(-x)); }
; __device__ __forceinline__ void inproj_epilogue(const Params& p, int layer, int mt, int ntile, int tid,
;                                                 f32x16 (&acc)[2][2], unsigned char* smem) {
;     ...
;     acc_foreach(tid, acc, [&](int row, int col, float v) {
;       int t = m0 + row;
;       float o = v;
;       if (mode == 1) o = (t >= NPADR) ? v : 0.f;
;       if (mode == 2) o = sigmf(v);
;       sT[row * 136 + col] = f2bf(o);
;     });
.LBB0_2804:
	v_bfe_u32 v49, v48, 16, 1
	v_add3_u32 v48, v48, v49, s81
	s_and_b64 vcc, exec, s[6:7]
	ds_write_b16_d16_hi v123, v48 offset:64
	s_cbranch_vccz .Lsg_351

; __device__ __forceinline__ bf16r f2bf(float f) {
;   unsigned u = __float_as_uint(f);
;   u += 0x7fffu + ((u >> 16) & 1u);
;   return (bf16r)(u >> 16);
; }
; __device__ __forceinline__ unsigned pack2(float a, float b) { return (unsigned)f2bf(a) | ((unsigned)f2bf(b) << 16); }
; __device__ __forceinline__ float lo16(unsigned v) { return __uint_as_float(v << 16); }
; __device__ __forceinline__ float hi16(unsigned v) { return __uint_as_float(v & 0xffff0000u); }
; __device__ __forceinline__ float siluf(float x) { return x / (1.f + __expf(-x)); }
; __device__ __forceinline__ float sigmf(float x) { return 1.f / (1.f + __expf(-x)); }
; __device__ __forceinline__ void inproj_epilogue(const Params& p, int layer, int mt, int ntile, int tid,
;                                                 f32x16 (&acc)[2][2], unsigned char* smem) {
;     ...
;     acc_foreach(tid, acc, [&](int row, int col, float v) {
;       int t = m0 + row;
;       float o = v;
;       if (mode == 1) o = (t >= NPADR) ? v : 0.f;
;       if (mode == 2) o = sigmf(v);
;       sT[row * 136 + col] = f2bf(o);
;     });
.LBB0_2807:
	v_bfe_u32 v49, v48, 16, 1
	v_add3_u32 v48, v48, v49, s81
	s_and_b64 vcc, exec, s[6:7]
	ds_write_b16_d16_hi v116, v48 offset:64
	s_cbranch_vccz .Lsg_352

; __device__ __forceinline__ bf16r f2bf(float f) {
;   unsigned u = __float_as_uint(f);
;   u += 0x7fffu + ((u >> 16) & 1u);
;   return (bf16r)(u >> 16);
; }
; __device__ __forceinline__ unsigned pack2(float a, float b) { return (unsigned)f2bf(a) | ((unsigned)f2bf(b) << 16); }
; __device__ __forceinline__ float lo16(unsigned v) { return __uint_as_float(v << 16); }
; __device__ __forceinline__ float hi16(unsigned v) { return __uint_as_float(v & 0xffff0000u); }
; __device__ __forceinline__ float siluf(float x) { return x / (1.f + __expf(-x)); }
; __device__ __forceinline__ float sigmf(float x) { return 1.f / (1.f + __expf(-x)); }
; __device__ __forceinline__ void inproj_epilogue(const Params& p, int layer, int mt, int ntile, int tid,
;                                                 f32x16 (&acc)[2][2], unsigned char* smem) {
;     ...
;     acc_foreach(tid, acc, [&](int row, int col, float v) {
;       int t = m0 + row;
;       float o = v;
;       if (mode == 1) o = (t >= NPADR) ? v : 0.f;
;       if (mode == 2) o = sigmf(v);
;       sT[row * 136 + col] = f2bf(o);
;     });
.LBB0_2810:
	v_bfe_u32 v50, v48, 16, 1
	v_add_u32_e32 v49, 0x110, v116
	v_add3_u32 v48, v48, v50, s81
	ds_write_b16_d16_hi v49, v48 offset:64
	v_or_b32_e32 v48, 32, v96
	v_add_u32_e32 v49, s96, v48
	s_and_b64 vcc, exec, s[6:7]
	v_cmp_lt_i32_e64 s[8:9], s79, v49
	s_cbranch_vccz .Lsg_353

; __device__ __forceinline__ bf16r f2bf(float f) {
;   unsigned u = __float_as_uint(f);
;   u += 0x7fffu + ((u >> 16) & 1u);
;   return (bf16r)(u >> 16);
; }
; __device__ __forceinline__ unsigned pack2(float a, float b) { return (unsigned)f2bf(a) | ((unsigned)f2bf(b) << 16); }
; __device__ __forceinline__ float lo16(unsigned v) { return __uint_as_float(v << 16); }
; __device__ __forceinline__ float hi16(unsigned v) { return __uint_as_float(v & 0xffff0000u); }
; __device__ __forceinline__ float siluf(float x) { return x / (1.f + __expf(-x)); }
; __device__ __forceinline__ float sigmf(float x) { return 1.f / (1.f + __expf(-x)); }
; __device__ __forceinline__ void inproj_epilogue(const Params& p, int layer, int mt, int ntile, int tid,
;                                                 f32x16 (&acc)[2][2], unsigned char* smem) {
;     ...
;     acc_foreach(tid, acc, [&](int row, int col, float v) {
;       int t = m0 + row;
;       float o = v;
;       if (mode == 1) o = (t >= NPADR) ? v : 0.f;
;       if (mode == 2) o = sigmf(v);
;       sT[row * 136 + col] = f2bf(o);
;     });
.LBB0_2813:
	v_bfe_u32 v50, v49, 16, 1
	v_add3_u32 v50, v49, v50, s81
	v_mul_lo_u32 v49, v48, s82
	v_lshl_add_u32 v48, v106, 1, v49
	ds_write_b16_d16_hi v48, v50
	v_add3_u32 v50, s96, v96, 33
	s_and_b64 vcc, exec, s[6:7]
	v_cmp_lt_i32_e64 s[10:11], s79, v50
	s_cbranch_vccz .Lsg_354

; __device__ __forceinline__ bf16r f2bf(float f) {
;   unsigned u = __float_as_uint(f);
;   u += 0x7fffu + ((u >> 16) & 1u);
;   return (bf16r)(u >> 16);
; }
; __device__ __forceinline__ unsigned pack2(float a, float b) { return (unsigned)f2bf(a) | ((unsigned)f2bf(b) << 16); }
; __device__ __forceinline__ float lo16(unsigned v) { return __uint_as_float(v << 16); }
; __device__ __forceinline__ float hi16(unsigned v) { return __uint_as_float(v & 0xffff0000u); }
; __device__ __forceinline__ float siluf(float x) { return x / (1.f + __expf(-x)); }
; __device__ __forceinline__ float sigmf(float x) { return 1.f / (1.f + __expf(-x)); }
; __device__ __forceinline__ void inproj_epilogue(const Params& p, int layer, int mt, int ntile, int tid,
;                                                 f32x16 (&acc)[2][2], unsigned char* smem) {
;     ...
;     acc_foreach(tid, acc, [&](int row, int col, float v) {
;       int t = m0 + row;
;       float o = v;
;       if (mode == 1) o = (t >= NPADR) ? v : 0.f;
;       if (mode == 2) o = sigmf(v);
;       sT[row * 136 + col] = f2bf(o);
;     });
.LBB0_2816:
	v_bfe_u32 v51, v50, 16, 1
	v_add3_u32 v51, v50, v51, s81
	v_add_u32_e32 v50, 0x110, v49
	v_lshl_add_u32 v49, v106, 1, v50
	ds_write_b16_d16_hi v49, v51
	v_add3_u32 v51, s96, v96, 34
	s_and_b64 vcc, exec, s[6:7]
	v_cmp_lt_i32_e64 s[12:13], s79, v51
	s_cbranch_vccz .Lsg_355

; __device__ __forceinline__ bf16r f2bf(float f) {
;   unsigned u = __float_as_uint(f);
;   u += 0x7fffu + ((u >> 16) & 1u);
;   return (bf16r)(u >> 16);
; }
; __device__ __forceinline__ unsigned pack2(float a, float b) { return (unsigned)f2bf(a) | ((unsigned)f2bf(b) << 16); }
; __device__ __forceinline__ float lo16(unsigned v) { return __uint_as_float(v << 16); }
; __device__ __forceinline__ float hi16(unsigned v) { return __uint_as_float(v & 0xffff0000u); }
; __device__ __forceinline__ float siluf(float x) { return x / (1.f + __expf(-x)); }
; __device__ __forceinline__ float sigmf(float x) { return 1.f / (1.f + __expf(-x)); }
; __device__ __forceinline__ void inproj_epilogue(const Params& p, int layer, int mt, int ntile, int tid,
;                                                 f32x16 (&acc)[2][2], unsigned char* smem) {
;     ...
;     acc_foreach(tid, acc, [&](int row, int col, float v) {
;       int t = m0 + row;
;       float o = v;
;       if (mode == 1) o = (t >= NPADR) ? v : 0.f;
;       if (mode == 2) o = sigmf(v);
;       sT[row * 136 + col] = f2bf(o);
;     });
.LBB0_2819:
	v_bfe_u32 v52, v51, 16, 1
	v_add3_u32 v52, v51, v52, s81
	v_add_u32_e32 v51, 0x110, v50
	v_lshl_add_u32 v50, v106, 1, v51
	ds_write_b16_d16_hi v50, v52
	v_add3_u32 v52, s96, v96, 35
	s_and_b64 vcc, exec, s[6:7]
	v_cmp_lt_i32_e64 s[14:15], s79, v52
	s_cbranch_vccz .Lsg_356

; __device__ __forceinline__ bf16r f2bf(float f) {
;   unsigned u = __float_as_uint(f);
;   u += 0x7fffu + ((u >> 16) & 1u);
;   return (bf16r)(u >> 16);
; }
; __device__ __forceinline__ unsigned pack2(float a, float b) { return (unsigned)f2bf(a) | ((unsigned)f2bf(b) << 16); }
; __device__ __forceinline__ float lo16(unsigned v) { return __uint_as_float(v << 16); }
; __device__ __forceinline__ float hi16(unsigned v) { return __uint_as_float(v & 0xffff0000u); }
; __device__ __forceinline__ float siluf(float x) { return x / (1.f + __expf(-x)); }
; __device__ __forceinline__ float sigmf(float x) { return 1.f / (1.f + __expf(-x)); }
; __device__ __forceinline__ void inproj_epilogue(const Params& p, int layer, int mt, int ntile, int tid,
;                                                 f32x16 (&acc)[2][2], unsigned char* smem) {
;     ...
;     acc_foreach(tid, acc, [&](int row, int col, float v) {
;       int t = m0 + row;
;       float o = v;
;       if (mode == 1) o = (t >= NPADR) ? v : 0.f;
;       if (mode == 2) o = sigmf(v);
;       sT[row * 136 + col] = f2bf(o);
;     });
.LBB0_2822:
	v_bfe_u32 v53, v52, 16, 1
	v_add3_u32 v53, v52, v53, s81
	v_add_u32_e32 v52, 0x110, v51
	v_lshl_add_u32 v51, v106, 1, v52
	ds_write_b16_d16_hi v51, v53
	v_add3_u32 v53, s96, v96, 40
	s_and_b64 vcc, exec, s[6:7]
	v_cmp_lt_i32_e64 s[16:17], s79, v53
	s_cbranch_vccz .Lsg_357

; __device__ __forceinline__ float sigmf(float x) { return 1.f / (1.f + __expf(-x)); }
; __device__ __forceinline__ bf16r f2bf(float f) {
;   unsigned u = __float_as_uint(f);
;   u += 0x7fffu + ((u >> 16) & 1u);
;   return (bf16r)(u >> 16);
; __device__ __forceinline__ void inproj_epilogue(const Params& p, int layer, int mt, int ntile, int tid,
;                                                 f32x16 (&acc)[2][2], unsigned char* smem) {
;     ...
;     acc_foreach(tid, acc, [&](int row, int col, float v) {
;       int t = m0 + row;
;       float o = v;
;       if (mode == 1) o = (t >= NPADR) ? v : 0.f;
;       if (mode == 2) o = sigmf(v);
;       sT[row * 136 + col] = f2bf(o);
;     });
.LBB0_2825:
	v_bfe_u32 v54, v53, 16, 1
	v_add3_u32 v54, v53, v54, s81
	v_add_u32_e32 v53, 0x550, v52
	v_lshl_add_u32 v52, v106, 1, v53
	ds_write_b16_d16_hi v52, v54
	v_add3_u32 v54, s96, v96, 41
	s_and_b64 vcc, exec, s[6:7]
	v_cmp_lt_i32_e64 s[18:19], s79, v54
	s_cbranch_vccz .Lsg_358

; __device__ __forceinline__ float sigmf(float x) { return 1.f / (1.f + __expf(-x)); }
; __device__ __forceinline__ bf16r f2bf(float f) {
;   unsigned u = __float_as_uint(f);
;   u += 0x7fffu + ((u >> 16) & 1u);
;   return (bf16r)(u >> 16);
; __device__ __forceinline__ void inproj_epilogue(const Params& p, int layer, int mt, int ntile, int tid,
;                                                 f32x16 (&acc)[2][2], unsigned char* smem) {
;     ...
;     acc_foreach(tid, acc, [&](int row, int col, float v) {
;       int t = m0 + row;
;       float o = v;
;       if (mode == 1) o = (t >= NPADR) ? v : 0.f;
;       if (mode == 2) o = sigmf(v);
;       sT[row * 136 + col] = f2bf(o);
;     });
.LBB0_2828:
	v_bfe_u32 v55, v54, 16, 1
	v_add3_u32 v55, v54, v55, s81
	v_add_u32_e32 v54, 0x110, v53
	v_lshl_add_u32 v53, v106, 1, v54
	ds_write_b16_d16_hi v53, v55
	v_add3_u32 v55, s96, v96, 42
	s_and_b64 vcc, exec, s[6:7]
	v_cmp_lt_i32_e64 s[20:21], s79, v55
	s_cbranch_vccz .Lsg_359

; __device__ __forceinline__ float sigmf(float x) { return 1.f / (1.f + __expf(-x)); }
; __device__ __forceinline__ bf16r f2bf(float f) {
;   unsigned u = __float_as_uint(f);
;   u += 0x7fffu + ((u >> 16) & 1u);
;   return (bf16r)(u >> 16);
; __device__ __forceinline__ void inproj_epilogue(const Params& p, int layer, int mt, int ntile, int tid,
;                                                 f32x16 (&acc)[2][2], unsigned char* smem) {
;     ...
;     acc_foreach(tid, acc, [&](int row, int col, float v) {
;       int t = m0 + row;
;       float o = v;
;       if (mode == 1) o = (t >= NPADR) ? v : 0.f;
;       if (mode == 2) o = sigmf(v);
;       sT[row * 136 + col] = f2bf(o);
;     });
.LBB0_2831:
	v_bfe_u32 v56, v55, 16, 1
	v_add3_u32 v56, v55, v56, s81
	v_add_u32_e32 v55, 0x110, v54
	v_lshl_add_u32 v54, v106, 1, v55
	ds_write_b16_d16_hi v54, v56
	v_add3_u32 v56, s96, v96, 43
	s_and_b64 vcc, exec, s[6:7]
	v_cmp_lt_i32_e64 s[22:23], s79, v56
	s_cbranch_vccz .Lsg_360

; __device__ __forceinline__ float sigmf(float x) { return 1.f / (1.f + __expf(-x)); }
; __device__ __forceinline__ bf16r f2bf(float f) {
;   unsigned u = __float_as_uint(f);
;   u += 0x7fffu + ((u >> 16) & 1u);
;   return (bf16r)(u >> 16);
; __device__ __forceinline__ void inproj_epilogue(const Params& p, int layer, int mt, int ntile, int tid,
;                                                 f32x16 (&acc)[2][2], unsigned char* smem) {
;     ...
;     acc_foreach(tid, acc, [&](int row, int col, float v) {
;       int t = m0 + row;
;       float o = v;
;       if (mode == 1) o = (t >= NPADR) ? v : 0.f;
;       if (mode == 2) o = sigmf(v);
;       sT[row * 136 + col] = f2bf(o);
;     });
.LBB0_2834:
	v_bfe_u32 v57, v56, 16, 1
	v_add_u32_e32 v55, 0x110, v55
	v_add3_u32 v57, v56, v57, s81
	v_lshl_add_u32 v56, v106, 1, v55
	ds_write_b16_d16_hi v56, v57
	v_add3_u32 v57, s96, v96, 48
	s_and_b64 vcc, exec, s[6:7]
	v_cmp_lt_i32_e64 s[24:25], s79, v57
	s_cbranch_vccz .Lsg_361

; __device__ __forceinline__ float sigmf(float x) { return 1.f / (1.f + __expf(-x)); }
; __device__ __forceinline__ bf16r f2bf(float f) {
;   unsigned u = __float_as_uint(f);
;   u += 0x7fffu + ((u >> 16) & 1u);
;   return (bf16r)(u >> 16);
; __device__ __forceinline__ void inproj_epilogue(const Params& p, int layer, int mt, int ntile, int tid,
;                                                 f32x16 (&acc)[2][2], unsigned char* smem) {
;     ...
;     acc_foreach(tid, acc, [&](int row, int col, float v) {
;       int t = m0 + row;
;       float o = v;
;       if (mode == 1) o = (t >= NPADR) ? v : 0.f;
;       if (mode == 2) o = sigmf(v);
;       sT[row * 136 + col] = f2bf(o);
;     });
.LBB0_2837:
	v_bfe_u32 v58, v57, 16, 1
	v_add_u32_e32 v55, 0x550, v55
	v_add3_u32 v58, v57, v58, s81
	v_lshl_add_u32 v57, v106, 1, v55
	ds_write_b16_d16_hi v57, v58
	v_add3_u32 v58, s96, v96, 49
	s_and_b64 vcc, exec, s[6:7]
	v_cmp_lt_i32_e64 s[26:27], s79, v58
	s_cbranch_vccz .Lsg_362

; __device__ __forceinline__ float sigmf(float x) { return 1.f / (1.f + __expf(-x)); }
; __device__ __forceinline__ bf16r f2bf(float f) {
;   unsigned u = __float_as_uint(f);
;   u += 0x7fffu + ((u >> 16) & 1u);
;   return (bf16r)(u >> 16);
; __device__ __forceinline__ void inproj_epilogue(const Params& p, int layer, int mt, int ntile, int tid,
;                                                 f32x16 (&acc)[2][2], unsigned char* smem) {
;     ...
;     acc_foreach(tid, acc, [&](int row, int col, float v) {
;       int t = m0 + row;
;       float o = v;
;       if (mode == 1) o = (t >= NPADR) ? v : 0.f;
;       if (mode == 2) o = sigmf(v);
;       sT[row * 136 + col] = f2bf(o);
;     });
.LBB0_2840:
	v_bfe_u32 v59, v58, 16, 1
	v_add_u32_e32 v55, 0x110, v55
	v_add3_u32 v59, v58, v59, s81
	v_lshl_add_u32 v58, v106, 1, v55
	ds_write_b16_d16_hi v58, v59
	v_add3_u32 v59, s96, v96, 50
	s_and_b64 vcc, exec, s[6:7]
	v_cmp_lt_i32_e64 s[28:29], s79, v59
	s_cbranch_vccz .Lsg_363

; __device__ __forceinline__ float sigmf(float x) { return 1.f / (1.f + __expf(-x)); }
; __device__ __forceinline__ bf16r f2bf(float f) {
;   unsigned u = __float_as_uint(f);
;   u += 0x7fffu + ((u >> 16) & 1u);
;   return (bf16r)(u >> 16);
; __device__ __forceinline__ void inproj_epilogue(const Params& p, int layer, int mt, int ntile, int tid,
;                                                 f32x16 (&acc)[2][2], unsigned char* smem) {
;     ...
;     acc_foreach(tid, acc, [&](int row, int col, float v) {
;       int t = m0 + row;
;       float o = v;
;       if (mode == 1) o = (t >= NPADR) ? v : 0.f;
;       if (mode == 2) o = sigmf(v);
;       sT[row * 136 + col] = f2bf(o);
;     });
.LBB0_2843:
	v_bfe_u32 v60, v59, 16, 1
	v_add_u32_e32 v55, 0x110, v55
	v_add3_u32 v60, v59, v60, s81
	v_lshl_add_u32 v59, v106, 1, v55
	ds_write_b16_d16_hi v59, v60
	v_add3_u32 v60, s96, v96, 51
	s_and_b64 vcc, exec, s[6:7]
	v_cmp_lt_i32_e64 s[30:31], s79, v60
	s_cbranch_vccz .Lsg_364

; __device__ __forceinline__ float sigmf(float x) { return 1.f / (1.f + __expf(-x)); }
; __device__ __forceinline__ bf16r f2bf(float f) {
;   unsigned u = __float_as_uint(f);
;   u += 0x7fffu + ((u >> 16) & 1u);
;   return (bf16r)(u >> 16);
; __device__ __forceinline__ void inproj_epilogue(const Params& p, int layer, int mt, int ntile, int tid,
;                                                 f32x16 (&acc)[2][2], unsigned char* smem) {
;     ...
;     acc_foreach(tid, acc, [&](int row, int col, float v) {
;       int t = m0 + row;
;       float o = v;
;       if (mode == 1) o = (t >= NPADR) ? v : 0.f;
;       if (mode == 2) o = sigmf(v);
;       sT[row * 136 + col] = f2bf(o);
;     });
.LBB0_2846:
	v_bfe_u32 v61, v60, 16, 1
	v_add_u32_e32 v55, 0x110, v55
	v_add3_u32 v61, v60, v61, s81
	v_lshl_add_u32 v60, v106, 1, v55
	ds_write_b16_d16_hi v60, v61
	v_add3_u32 v61, s96, v96, 56
	s_and_b64 vcc, exec, s[6:7]
	v_cmp_lt_i32_e64 s[34:35], s79, v61
	s_cbranch_vccz .Lsg_365

; __device__ __forceinline__ float sigmf(float x) { return 1.f / (1.f + __expf(-x)); }
; __device__ __forceinline__ bf16r f2bf(float f) {
;   unsigned u = __float_as_uint(f);
;   u += 0x7fffu + ((u >> 16) & 1u);
;   return (bf16r)(u >> 16);
; __device__ __forceinline__ void inproj_epilogue(const Params& p, int layer, int mt, int ntile, int tid,
;                                                 f32x16 (&acc)[2][2], unsigned char* smem) {
;     ...
;     acc_foreach(tid, acc, [&](int row, int col, float v) {
;       int t = m0 + row;
;       float o = v;
;       if (mode == 1) o = (t >= NPADR) ? v : 0.f;
;       if (mode == 2) o = sigmf(v);
;       sT[row * 136 + col] = f2bf(o);
;     });
.LBB0_2849:
	v_bfe_u32 v62, v61, 16, 1
	v_add_u32_e32 v55, 0x550, v55
	v_add3_u32 v62, v61, v62, s81
	v_lshl_add_u32 v61, v106, 1, v55
	ds_write_b16_d16_hi v61, v62
	v_add3_u32 v62, s96, v96, 57
	s_and_b64 vcc, exec, s[6:7]
	v_cmp_lt_i32_e64 s[36:37], s79, v62
	s_cbranch_vccz .Lsg_366

; __device__ __forceinline__ float sigmf(float x) { return 1.f / (1.f + __expf(-x)); }
; __device__ __forceinline__ bf16r f2bf(float f) {
;   unsigned u = __float_as_uint(f);
;   u += 0x7fffu + ((u >> 16) & 1u);
;   return (bf16r)(u >> 16);
; __device__ __forceinline__ void inproj_epilogue(const Params& p, int layer, int mt, int ntile, int tid,
;                                                 f32x16 (&acc)[2][2], unsigned char* smem) {
;     ...
;     acc_foreach(tid, acc, [&](int row, int col, float v) {
;       int t = m0 + row;
;       float o = v;
;       if (mode == 1) o = (t >= NPADR) ? v : 0.f;
;       if (mode == 2) o = sigmf(v);
;       sT[row * 136 + col] = f2bf(o);
;     });
.LBB0_2852:
	v_bfe_u32 v63, v62, 16, 1
	v_add_u32_e32 v55, 0x110, v55
	v_add3_u32 v63, v62, v63, s81
	v_lshl_add_u32 v62, v106, 1, v55
	ds_write_b16_d16_hi v62, v63
	v_add3_u32 v63, s96, v96, 58
	s_and_b64 vcc, exec, s[6:7]
	v_cmp_lt_i32_e64 s[38:39], s79, v63
	s_cbranch_vccz .Lsg_367

; __device__ __forceinline__ float sigmf(float x) { return 1.f / (1.f + __expf(-x)); }
; __device__ __forceinline__ bf16r f2bf(float f) {
;   unsigned u = __float_as_uint(f);
;   u += 0x7fffu + ((u >> 16) & 1u);
;   return (bf16r)(u >> 16);
; __device__ __forceinline__ void inproj_epilogue(const Params& p, int layer, int mt, int ntile, int tid,
;                                                 f32x16 (&acc)[2][2], unsigned char* smem) {
;     ...
;     acc_foreach(tid, acc, [&](int row, int col, float v) {
;       int t = m0 + row;
;       float o = v;
;       if (mode == 1) o = (t >= NPADR) ? v : 0.f;
;       if (mode == 2) o = sigmf(v);
;       sT[row * 136 + col] = f2bf(o);
;     });
.LBB0_2855:
	v_bfe_u32 v107, v63, 16, 1
	v_add_u32_e32 v55, 0x110, v55
	v_add3_u32 v63, v63, v107, s81
	v_lshl_add_u32 v55, v106, 1, v55
	ds_write_b16_d16_hi v55, v63
	v_add3_u32 v63, s96, v96, 59
	s_and_b64 vcc, exec, s[6:7]
	v_cmp_lt_i32_e64 s[40:41], s79, v63
	s_cbranch_vccz .Lsg_368

; __device__ __forceinline__ float sigmf(float x) { return 1.f / (1.f + __expf(-x)); }
; __device__ __forceinline__ bf16r f2bf(float f) {
;   unsigned u = __float_as_uint(f);
;   u += 0x7fffu + ((u >> 16) & 1u);
;   return (bf16r)(u >> 16);
; __device__ __forceinline__ void inproj_epilogue(const Params& p, int layer, int mt, int ntile, int tid,
;                                                 f32x16 (&acc)[2][2], unsigned char* smem) {
;     ...
;     acc_foreach(tid, acc, [&](int row, int col, float v) {
;       int t = m0 + row;
;       float o = v;
;       if (mode == 1) o = (t >= NPADR) ? v : 0.f;
;       if (mode == 2) o = sigmf(v);
;       sT[row * 136 + col] = f2bf(o);
;     });
.LBB0_2858:
	v_bfe_u32 v96, v63, 16, 1
	v_add3_u32 v63, v63, v96, s81
	ds_write_b16_d16_hi v55, v63 offset:272
	s_and_b64 vcc, exec, s[6:7]
	s_cbranch_vccz .Lsg_369

; __device__ __forceinline__ float sigmf(float x) { return 1.f / (1.f + __expf(-x)); }
; __device__ __forceinline__ bf16r f2bf(float f) {
;   unsigned u = __float_as_uint(f);
;   u += 0x7fffu + ((u >> 16) & 1u);
;   return (bf16r)(u >> 16);
; __device__ __forceinline__ void inproj_epilogue(const Params& p, int layer, int mt, int ntile, int tid,
;                                                 f32x16 (&acc)[2][2], unsigned char* smem) {
;     ...
;     acc_foreach(tid, acc, [&](int row, int col, float v) {
;       int t = m0 + row;
;       float o = v;
;       if (mode == 1) o = (t >= NPADR) ? v : 0.f;
;       if (mode == 2) o = sigmf(v);
;       sT[row * 136 + col] = f2bf(o);
;     });
.LBB0_2861:
	v_bfe_u32 v63, v32, 16, 1
	v_add3_u32 v32, v32, v63, s81
	s_and_b64 vcc, exec, s[6:7]
	ds_write_b16_d16_hi v48, v32 offset:64
	s_cbranch_vccz .Lsg_370

; __device__ __forceinline__ float sigmf(float x) { return 1.f / (1.f + __expf(-x)); }
; __device__ __forceinline__ bf16r f2bf(float f) {
;   unsigned u = __float_as_uint(f);
;   u += 0x7fffu + ((u >> 16) & 1u);
;   return (bf16r)(u >> 16);
; __device__ __forceinline__ void inproj_epilogue(const Params& p, int layer, int mt, int ntile, int tid,
;                                                 f32x16 (&acc)[2][2], unsigned char* smem) {
;     ...
;     acc_foreach(tid, acc, [&](int row, int col, float v) {
;       int t = m0 + row;
;       float o = v;
;       if (mode == 1) o = (t >= NPADR) ? v : 0.f;
;       if (mode == 2) o = sigmf(v);
;       sT[row * 136 + col] = f2bf(o);
;     });
.LBB0_2864:
	v_bfe_u32 v33, v32, 16, 1
	v_add3_u32 v32, v32, v33, s81
	s_and_b64 vcc, exec, s[6:7]
	ds_write_b16_d16_hi v49, v32 offset:64
	s_cbranch_vccz .Lsg_371

; __device__ __forceinline__ float sigmf(float x) { return 1.f / (1.f + __expf(-x)); }
; __device__ __forceinline__ bf16r f2bf(float f) {
;   unsigned u = __float_as_uint(f);
;   u += 0x7fffu + ((u >> 16) & 1u);
;   return (bf16r)(u >> 16);
; __device__ __forceinline__ void inproj_epilogue(const Params& p, int layer, int mt, int ntile, int tid,
;                                                 f32x16 (&acc)[2][2], unsigned char* smem) {
;     ...
;     acc_foreach(tid, acc, [&](int row, int col, float v) {
;       int t = m0 + row;
;       float o = v;
;       if (mode == 1) o = (t >= NPADR) ? v : 0.f;
;       if (mode == 2) o = sigmf(v);
;       sT[row * 136 + col] = f2bf(o);
;     });
.LBB0_2867:
	v_bfe_u32 v33, v32, 16, 1
	v_add3_u32 v32, v32, v33, s81
	s_and_b64 vcc, exec, s[6:7]
	ds_write_b16_d16_hi v50, v32 offset:64
	s_cbranch_vccz .Lsg_372

; __device__ __forceinline__ float sigmf(float x) { return 1.f / (1.f + __expf(-x)); }
; __device__ __forceinline__ bf16r f2bf(float f) {
;   unsigned u = __float_as_uint(f);
;   u += 0x7fffu + ((u >> 16) & 1u);
;   return (bf16r)(u >> 16);
; __device__ __forceinline__ void inproj_epilogue(const Params& p, int layer, int mt, int ntile, int tid,
;                                                 f32x16 (&acc)[2][2], unsigned char* smem) {
;     ...
;     acc_foreach(tid, acc, [&](int row, int col, float v) {
;       int t = m0 + row;
;       float o = v;
;       if (mode == 1) o = (t >= NPADR) ? v : 0.f;
;       if (mode == 2) o = sigmf(v);
;       sT[row * 136 + col] = f2bf(o);
;     });
.LBB0_2870:
	v_bfe_u32 v33, v32, 16, 1
	v_add3_u32 v32, v32, v33, s81
	s_and_b64 vcc, exec, s[6:7]
	ds_write_b16_d16_hi v51, v32 offset:64
	s_cbranch_vccz .Lsg_373

; __device__ __forceinline__ float sigmf(float x) { return 1.f / (1.f + __expf(-x)); }
; __device__ __forceinline__ bf16r f2bf(float f) {
;   unsigned u = __float_as_uint(f);
;   u += 0x7fffu + ((u >> 16) & 1u);
;   return (bf16r)(u >> 16);
; __device__ __forceinline__ void inproj_epilogue(const Params& p, int layer, int mt, int ntile, int tid,
;                                                 f32x16 (&acc)[2][2], unsigned char* smem) {
;     ...
;     acc_foreach(tid, acc, [&](int row, int col, float v) {
;       int t = m0 + row;
;       float o = v;
;       if (mode == 1) o = (t >= NPADR) ? v : 0.f;
;       if (mode == 2) o = sigmf(v);
;       sT[row * 136 + col] = f2bf(o);
;     });
.LBB0_2873:
	v_bfe_u32 v33, v32, 16, 1
	v_add3_u32 v32, v32, v33, s81
	s_and_b64 vcc, exec, s[6:7]
	ds_write_b16_d16_hi v52, v32 offset:64
	s_cbranch_vccz .Lsg_374

; __device__ __forceinline__ float sigmf(float x) { return 1.f / (1.f + __expf(-x)); }
; __device__ __forceinline__ bf16r f2bf(float f) {
;   unsigned u = __float_as_uint(f);
;   u += 0x7fffu + ((u >> 16) & 1u);
;   return (bf16r)(u >> 16);
; __device__ __forceinline__ void inproj_epilogue(const Params& p, int layer, int mt, int ntile, int tid,
;                                                 f32x16 (&acc)[2][2], unsigned char* smem) {
;     ...
;     acc_foreach(tid, acc, [&](int row, int col, float v) {
;       int t = m0 + row;
;       float o = v;
;       if (mode == 1) o = (t >= NPADR) ? v : 0.f;
;       if (mode == 2) o = sigmf(v);
;       sT[row * 136 + col] = f2bf(o);
;     });
.LBB0_2876:
	v_bfe_u32 v33, v32, 16, 1
	v_add3_u32 v32, v32, v33, s81
	s_and_b64 vcc, exec, s[6:7]
	ds_write_b16_d16_hi v53, v32 offset:64
	s_cbranch_vccz .Lsg_375

; __device__ __forceinline__ float sigmf(float x) { return 1.f / (1.f + __expf(-x)); }
; __device__ __forceinline__ bf16r f2bf(float f) {
;   unsigned u = __float_as_uint(f);
;   u += 0x7fffu + ((u >> 16) & 1u);
;   return (bf16r)(u >> 16);
; __device__ __forceinline__ void inproj_epilogue(const Params& p, int layer, int mt, int ntile, int tid,
;                                                 f32x16 (&acc)[2][2], unsigned char* smem) {
;     ...
;     acc_foreach(tid, acc, [&](int row, int col, float v) {
;       int t = m0 + row;
;       float o = v;
;       if (mode == 1) o = (t >= NPADR) ? v : 0.f;
;       if (mode == 2) o = sigmf(v);
;       sT[row * 136 + col] = f2bf(o);
;     });
.LBB0_2879:
	v_bfe_u32 v33, v32, 16, 1
	v_add3_u32 v32, v32, v33, s81
	s_and_b64 vcc, exec, s[6:7]
	ds_write_b16_d16_hi v54, v32 offset:64
	s_cbranch_vccz .Lsg_376

; __device__ __forceinline__ float sigmf(float x) { return 1.f / (1.f + __expf(-x)); }
; __device__ __forceinline__ bf16r f2bf(float f) {
;   unsigned u = __float_as_uint(f);
;   u += 0x7fffu + ((u >> 16) & 1u);
;   return (bf16r)(u >> 16);
; __device__ __forceinline__ void inproj_epilogue(const Params& p, int layer, int mt, int ntile, int tid,
;                                                 f32x16 (&acc)[2][2], unsigned char* smem) {
;     ...
;     acc_foreach(tid, acc, [&](int row, int col, float v) {
;       int t = m0 + row;
;       float o = v;
;       if (mode == 1) o = (t >= NPADR) ? v : 0.f;
;       if (mode == 2) o = sigmf(v);
;       sT[row * 136 + col] = f2bf(o);
;     });
.LBB0_2882:
	v_bfe_u32 v33, v32, 16, 1
	v_add3_u32 v32, v32, v33, s81
	s_and_b64 vcc, exec, s[6:7]
	ds_write_b16_d16_hi v56, v32 offset:64
	s_cbranch_vccz .Lsg_377

; __device__ __forceinline__ float sigmf(float x) { return 1.f / (1.f + __expf(-x)); }
; __device__ __forceinline__ bf16r f2bf(float f) {
;   unsigned u = __float_as_uint(f);
;   u += 0x7fffu + ((u >> 16) & 1u);
;   return (bf16r)(u >> 16);
; __device__ __forceinline__ void inproj_epilogue(const Params& p, int layer, int mt, int ntile, int tid,
;                                                 f32x16 (&acc)[2][2], unsigned char* smem) {
;     ...
;     acc_foreach(tid, acc, [&](int row, int col, float v) {
;       int t = m0 + row;
;       float o = v;
;       if (mode == 1) o = (t >= NPADR) ? v : 0.f;
;       if (mode == 2) o = sigmf(v);
;       sT[row * 136 + col] = f2bf(o);
;     });
.LBB0_2885:
	v_bfe_u32 v33, v32, 16, 1
	v_add3_u32 v32, v32, v33, s81
	s_and_b64 vcc, exec, s[6:7]
	ds_write_b16_d16_hi v57, v32 offset:64
	s_cbranch_vccz .Lsg_378

; __device__ __forceinline__ float sigmf(float x) { return 1.f / (1.f + __expf(-x)); }
; __device__ __forceinline__ bf16r f2bf(float f) {
;   unsigned u = __float_as_uint(f);
;   u += 0x7fffu + ((u >> 16) & 1u);
;   return (bf16r)(u >> 16);
; __device__ __forceinline__ void inproj_epilogue(const Params& p, int layer, int mt, int ntile, int tid,
;                                                 f32x16 (&acc)[2][2], unsigned char* smem) {
;     ...
;     acc_foreach(tid, acc, [&](int row, int col, float v) {
;       int t = m0 + row;
;       float o = v;
;       if (mode == 1) o = (t >= NPADR) ? v : 0.f;
;       if (mode == 2) o = sigmf(v);
;       sT[row * 136 + col] = f2bf(o);
;     });
.LBB0_2888:
	v_bfe_u32 v33, v32, 16, 1
	v_add3_u32 v32, v32, v33, s81
	s_and_b64 vcc, exec, s[6:7]
	ds_write_b16_d16_hi v58, v32 offset:64
	s_cbranch_vccz .Lsg_379

; __device__ __forceinline__ float sigmf(float x) { return 1.f / (1.f + __expf(-x)); }
; __device__ __forceinline__ bf16r f2bf(float f) {
;   unsigned u = __float_as_uint(f);
;   u += 0x7fffu + ((u >> 16) & 1u);
;   return (bf16r)(u >> 16);
; __device__ __forceinline__ void inproj_epilogue(const Params& p, int layer, int mt, int ntile, int tid,
;                                                 f32x16 (&acc)[2][2], unsigned char* smem) {
;     ...
;     acc_foreach(tid, acc, [&](int row, int col, float v) {
;       int t = m0 + row;
;       float o = v;
;       if (mode == 1) o = (t >= NPADR) ? v : 0.f;
;       if (mode == 2) o = sigmf(v);
;       sT[row * 136 + col] = f2bf(o);
;     });
.LBB0_2891:
	v_bfe_u32 v33, v32, 16, 1
	v_add3_u32 v32, v32, v33, s81
	s_and_b64 vcc, exec, s[6:7]
	ds_write_b16_d16_hi v59, v32 offset:64
	s_cbranch_vccz .Lsg_380

; __device__ __forceinline__ float sigmf(float x) { return 1.f / (1.f + __expf(-x)); }
; __device__ __forceinline__ bf16r f2bf(float f) {
;   unsigned u = __float_as_uint(f);
;   u += 0x7fffu + ((u >> 16) & 1u);
;   return (bf16r)(u >> 16);
; __device__ __forceinline__ void inproj_epilogue(const Params& p, int layer, int mt, int ntile, int tid,
;                                                 f32x16 (&acc)[2][2], unsigned char* smem) {
;     ...
;     acc_foreach(tid, acc, [&](int row, int col, float v) {
;       int t = m0 + row;
;       float o = v;
;       if (mode == 1) o = (t >= NPADR) ? v : 0.f;
;       if (mode == 2) o = sigmf(v);
;       sT[row * 136 + col] = f2bf(o);
;     });
.LBB0_2894:
	v_bfe_u32 v33, v32, 16, 1
	v_add3_u32 v32, v32, v33, s81
	s_and_b64 vcc, exec, s[6:7]
	ds_write_b16_d16_hi v60, v32 offset:64
	s_cbranch_vccz .Lsg_381

; __device__ __forceinline__ float sigmf(float x) { return 1.f / (1.f + __expf(-x)); }
; __device__ __forceinline__ bf16r f2bf(float f) {
;   unsigned u = __float_as_uint(f);
;   u += 0x7fffu + ((u >> 16) & 1u);
;   return (bf16r)(u >> 16);
; __device__ __forceinline__ void inproj_epilogue(const Params& p, int layer, int mt, int ntile, int tid,
;                                                 f32x16 (&acc)[2][2], unsigned char* smem) {
;     ...
;     acc_foreach(tid, acc, [&](int row, int col, float v) {
;       int t = m0 + row;
;       float o = v;
;       if (mode == 1) o = (t >= NPADR) ? v : 0.f;
;       if (mode == 2) o = sigmf(v);
;       sT[row * 136 + col] = f2bf(o);
;     });
.LBB0_2897:
	v_bfe_u32 v33, v32, 16, 1
	v_add3_u32 v32, v32, v33, s81
	s_and_b64 vcc, exec, s[6:7]
	ds_write_b16_d16_hi v61, v32 offset:64
	s_cbranch_vccz .Lsg_382

; __device__ __forceinline__ float sigmf(float x) { return 1.f / (1.f + __expf(-x)); }
; __device__ __forceinline__ bf16r f2bf(float f) {
;   unsigned u = __float_as_uint(f);
;   u += 0x7fffu + ((u >> 16) & 1u);
;   return (bf16r)(u >> 16);
; __device__ __forceinline__ void inproj_epilogue(const Params& p, int layer, int mt, int ntile, int tid,
;                                                 f32x16 (&acc)[2][2], unsigned char* smem) {
;     ...
;     acc_foreach(tid, acc, [&](int row, int col, float v) {
;       int t = m0 + row;
;       float o = v;
;       if (mode == 1) o = (t >= NPADR) ? v : 0.f;
;       if (mode == 2) o = sigmf(v);
;       sT[row * 136 + col] = f2bf(o);
;     });
.LBB0_2900:
	v_bfe_u32 v33, v32, 16, 1
	v_add3_u32 v32, v32, v33, s81
	s_and_b64 vcc, exec, s[6:7]
	ds_write_b16_d16_hi v62, v32 offset:64
	s_cbranch_vccz .Lsg_383

; __device__ __forceinline__ float sigmf(float x) { return 1.f / (1.f + __expf(-x)); }
; __device__ __forceinline__ bf16r f2bf(float f) {
;   unsigned u = __float_as_uint(f);
;   u += 0x7fffu + ((u >> 16) & 1u);
;   return (bf16r)(u >> 16);
; __device__ __forceinline__ void inproj_epilogue(const Params& p, int layer, int mt, int ntile, int tid,
;                                                 f32x16 (&acc)[2][2], unsigned char* smem) {
;     ...
;     acc_foreach(tid, acc, [&](int row, int col, float v) {
;       int t = m0 + row;
;       float o = v;
;       if (mode == 1) o = (t >= NPADR) ? v : 0.f;
;       if (mode == 2) o = sigmf(v);
;       sT[row * 136 + col] = f2bf(o);
;     });
.LBB0_2903:
	v_bfe_u32 v33, v32, 16, 1
	v_add3_u32 v32, v32, v33, s81
	s_and_b64 vcc, exec, s[6:7]
	ds_write_b16_d16_hi v55, v32 offset:64
	s_cbranch_vccz .Lsg_384

; __device__ __forceinline__ float sigmf(float x) { return 1.f / (1.f + __expf(-x)); }
; __device__ __forceinline__ float softplusf(float x) { return fmaxf(x, 0.f) + __logf(1.f + __expf(-fabsf(x))); }
; template <int MT, int NT, class F>
; __device__ __forceinline__ void acc_foreach(int tid, f32x16 (&acc)[MT][NT], F f) {
;     ...
;         int row = wm * (MT * 32) + mt * 32 + (i & 3) + 8 * (i >> 2) + 4 * hi;
;         int col = wn * (NT * 32) + nt * 32 + c;
; __device__ __forceinline__ void inproj_epilogue(const Params& p, int layer, int mt, int ntile, int tid,
;                                                 f32x16 (&acc)[2][2], unsigned char* smem) {
;     ...
;   const int m0 = mt * 128;
;   if (mode == 3) {
;     float* dt = (float*)(p.ws + OFF_DT) + (size_t)m0 * 16;
;     const float* bias = p.ssd_dt_bias + layer * 16;
;     acc_foreach(tid, acc, [&](int row, int col, float v) {
;       if (col < 16) *(dt + row * 16 + col) = softplusf(v + bias[col]);
;     });
;   } else {
;     bf16r* dstb = dst + (size_t)m0 * ld + c0;
;     bf16r* sT = (bf16r*)smem;
;     acc_foreach(tid, acc, [&](int row, int col, float v) {
;       int t = m0 + row;
;       float o = v;
;       if (mode == 1) o = (t >= NPADR) ? v : 0.f;
;       if (mode == 2) o = sigmf(v);
;       sT[row * 136 + col] = f2bf(o);
;     });
.LBB0_3032:
	s_lshl_b32 s94, s6, 7
	s_ashr_i32 s95, s94, 31
	s_cmp_lg_u32 s7, 3
	s_mov_b64 s[4:5], -1
	s_cbranch_scc0 .LBB0_3226
	v_mov_b32_e32 v106, v108
	s_movk_i32 s4, 0xffc0
	v_lshrrev_b32_e32 v107, 3, v106
	v_ashrrev_i32_e32 v96, 1, v106
	v_and_b32_e32 v107, 4, v107
	v_and_or_b32 v96, v96, s4, v107
	s_cmp_eq_u32 s7, 1
	s_cselect_b64 s[4:5], -1, 0
	v_add_u32_e32 v107, s94, v96
	s_cmp_eq_u32 s7, 2
	s_cselect_b64 s[10:11], -1, 0
	s_cmp_lg_u32 s7, 2
	v_cmp_lt_i32_e64 s[8:9], s77, v107
	s_cbranch_scc0 .Lsg_385

; __device__ __forceinline__ float sigmf(float x) { return 1.f / (1.f + __expf(-x)); }
; __device__ __forceinline__ bf16r f2bf(float f) {
;   unsigned u = __float_as_uint(f);
;   u += 0x7fffu + ((u >> 16) & 1u);
;   return (bf16r)(u >> 16);
; __device__ __forceinline__ void inproj_epilogue(const Params& p, int layer, int mt, int ntile, int tid,
;                                                 f32x16 (&acc)[2][2], unsigned char* smem) {
;     ...
;     acc_foreach(tid, acc, [&](int row, int col, float v) {
;       int t = m0 + row;
;       float o = v;
;       if (mode == 1) o = (t >= NPADR) ? v : 0.f;
;       if (mode == 2) o = sigmf(v);
;       sT[row * 136 + col] = f2bf(o);
;     });
.LBB0_3036:
	v_bfe_u32 v110, v107, 16, 1
	v_and_b32_e32 v106, 0x5f, v106
	v_add3_u32 v111, v107, v110, s79
	v_mul_lo_u32 v110, v96, s80
	v_lshl_add_u32 v107, v106, 1, v110
	ds_write_b16_d16_hi v107, v111
	v_add3_u32 v111, s94, v96, 1
	v_cndmask_b32_e64 v112, 0, 1, s[10:11]
	v_cmp_ne_u32_e64 s[6:7], 1, v112
	s_andn2_b64 vcc, exec, s[10:11]
	v_cmp_lt_i32_e64 s[10:11], s77, v111
	s_cbranch_vccz .Lsg_386

; __device__ __forceinline__ float sigmf(float x) { return 1.f / (1.f + __expf(-x)); }
; __device__ __forceinline__ bf16r f2bf(float f) {
;   unsigned u = __float_as_uint(f);
;   u += 0x7fffu + ((u >> 16) & 1u);
;   return (bf16r)(u >> 16);
; __device__ __forceinline__ void inproj_epilogue(const Params& p, int layer, int mt, int ntile, int tid,
;                                                 f32x16 (&acc)[2][2], unsigned char* smem) {
;     ...
;     acc_foreach(tid, acc, [&](int row, int col, float v) {
;       int t = m0 + row;
;       float o = v;
;       if (mode == 1) o = (t >= NPADR) ? v : 0.f;
;       if (mode == 2) o = sigmf(v);
;       sT[row * 136 + col] = f2bf(o);
;     });
.LBB0_3039:
	v_bfe_u32 v112, v111, 16, 1
	v_add3_u32 v112, v111, v112, s79
	v_add_u32_e32 v111, 0x110, v110
	v_lshl_add_u32 v110, v106, 1, v111
	ds_write_b16_d16_hi v110, v112
	v_add3_u32 v112, s94, v96, 2
	s_and_b64 vcc, exec, s[6:7]
	v_cmp_lt_i32_e64 s[12:13], s77, v112
	s_cbranch_vccz .Lsg_387

; __device__ __forceinline__ float sigmf(float x) { return 1.f / (1.f + __expf(-x)); }
; __device__ __forceinline__ bf16r f2bf(float f) {
;   unsigned u = __float_as_uint(f);
;   u += 0x7fffu + ((u >> 16) & 1u);
;   return (bf16r)(u >> 16);
; __device__ __forceinline__ void inproj_epilogue(const Params& p, int layer, int mt, int ntile, int tid,
;                                                 f32x16 (&acc)[2][2], unsigned char* smem) {
;     ...
;     acc_foreach(tid, acc, [&](int row, int col, float v) {
;       int t = m0 + row;
;       float o = v;
;       if (mode == 1) o = (t >= NPADR) ? v : 0.f;
;       if (mode == 2) o = sigmf(v);
;       sT[row * 136 + col] = f2bf(o);
;     });
.LBB0_3042:
	v_bfe_u32 v113, v112, 16, 1
	v_add3_u32 v113, v112, v113, s79
	v_add_u32_e32 v112, 0x110, v111
	v_lshl_add_u32 v111, v106, 1, v112
	ds_write_b16_d16_hi v111, v113
	v_add3_u32 v113, s94, v96, 3
	s_and_b64 vcc, exec, s[6:7]
	v_cmp_lt_i32_e64 s[14:15], s77, v113
	s_cbranch_vccz .Lsg_388

; __device__ __forceinline__ float sigmf(float x) { return 1.f / (1.f + __expf(-x)); }
; __device__ __forceinline__ bf16r f2bf(float f) {
;   unsigned u = __float_as_uint(f);
;   u += 0x7fffu + ((u >> 16) & 1u);
;   return (bf16r)(u >> 16);
; __device__ __forceinline__ void inproj_epilogue(const Params& p, int layer, int mt, int ntile, int tid,
;                                                 f32x16 (&acc)[2][2], unsigned char* smem) {
;     ...
;     acc_foreach(tid, acc, [&](int row, int col, float v) {
;       int t = m0 + row;
;       float o = v;
;       if (mode == 1) o = (t >= NPADR) ? v : 0.f;
;       if (mode == 2) o = sigmf(v);
;       sT[row * 136 + col] = f2bf(o);
;     });
.LBB0_3045:
	v_bfe_u32 v114, v113, 16, 1
	v_add3_u32 v114, v113, v114, s79
	v_add_u32_e32 v113, 0x110, v112
	v_lshl_add_u32 v112, v106, 1, v113
	ds_write_b16_d16_hi v112, v114
	v_add3_u32 v114, s94, v96, 8
	s_and_b64 vcc, exec, s[6:7]
	v_cmp_lt_i32_e64 s[16:17], s77, v114
	s_cbranch_vccz .Lsg_389

; __device__ __forceinline__ float sigmf(float x) { return 1.f / (1.f + __expf(-x)); }
; __device__ __forceinline__ bf16r f2bf(float f) {
;   unsigned u = __float_as_uint(f);
;   u += 0x7fffu + ((u >> 16) & 1u);
;   return (bf16r)(u >> 16);
; __device__ __forceinline__ void inproj_epilogue(const Params& p, int layer, int mt, int ntile, int tid,
;                                                 f32x16 (&acc)[2][2], unsigned char* smem) {
;     ...
;     acc_foreach(tid, acc, [&](int row, int col, float v) {
;       int t = m0 + row;
;       float o = v;
;       if (mode == 1) o = (t >= NPADR) ? v : 0.f;
;       if (mode == 2) o = sigmf(v);
;       sT[row * 136 + col] = f2bf(o);
;     });
.LBB0_3048:
	v_bfe_u32 v115, v114, 16, 1
	v_add3_u32 v115, v114, v115, s79
	v_add_u32_e32 v114, 0x550, v113
	v_lshl_add_u32 v113, v106, 1, v114
	ds_write_b16_d16_hi v113, v115
	v_add3_u32 v115, s94, v96, 9
	s_and_b64 vcc, exec, s[6:7]
	v_cmp_lt_i32_e64 s[18:19], s77, v115
	s_cbranch_vccz .Lsg_390

; __device__ __forceinline__ float sigmf(float x) { return 1.f / (1.f + __expf(-x)); }
; __device__ __forceinline__ bf16r f2bf(float f) {
;   unsigned u = __float_as_uint(f);
;   u += 0x7fffu + ((u >> 16) & 1u);
;   return (bf16r)(u >> 16);
; __device__ __forceinline__ void inproj_epilogue(const Params& p, int layer, int mt, int ntile, int tid,
;                                                 f32x16 (&acc)[2][2], unsigned char* smem) {
;     ...
;     acc_foreach(tid, acc, [&](int row, int col, float v) {
;       int t = m0 + row;
;       float o = v;
;       if (mode == 1) o = (t >= NPADR) ? v : 0.f;
;       if (mode == 2) o = sigmf(v);
;       sT[row * 136 + col] = f2bf(o);
;     });
.LBB0_3051:
	v_bfe_u32 v116, v115, 16, 1
	v_add3_u32 v116, v115, v116, s79
	v_add_u32_e32 v115, 0x110, v114
	v_lshl_add_u32 v114, v106, 1, v115
	ds_write_b16_d16_hi v114, v116
	v_add3_u32 v116, s94, v96, 10
	s_and_b64 vcc, exec, s[6:7]
	v_cmp_lt_i32_e64 s[20:21], s77, v116
	s_cbranch_vccz .Lsg_391

; __device__ __forceinline__ float sigmf(float x) { return 1.f / (1.f + __expf(-x)); }
; __device__ __forceinline__ bf16r f2bf(float f) {
;   unsigned u = __float_as_uint(f);
;   u += 0x7fffu + ((u >> 16) & 1u);
;   return (bf16r)(u >> 16);
; __device__ __forceinline__ void inproj_epilogue(const Params& p, int layer, int mt, int ntile, int tid,
;                                                 f32x16 (&acc)[2][2], unsigned char* smem) {
;     ...
;     acc_foreach(tid, acc, [&](int row, int col, float v) {
;       int t = m0 + row;
;       float o = v;
;       if (mode == 1) o = (t >= NPADR) ? v : 0.f;
;       if (mode == 2) o = sigmf(v);
;       sT[row * 136 + col] = f2bf(o);
;     });
.LBB0_3054:
	v_bfe_u32 v117, v116, 16, 1
	v_add3_u32 v117, v116, v117, s79
	v_add_u32_e32 v116, 0x110, v115
	v_lshl_add_u32 v115, v106, 1, v116
	ds_write_b16_d16_hi v115, v117
	v_add3_u32 v117, s94, v96, 11
	s_and_b64 vcc, exec, s[6:7]
	v_cmp_lt_i32_e64 s[22:23], s77, v117
	s_cbranch_vccz .Lsg_392

; __device__ __forceinline__ float sigmf(float x) { return 1.f / (1.f + __expf(-x)); }
; __device__ __forceinline__ bf16r f2bf(float f) {
;   unsigned u = __float_as_uint(f);
;   u += 0x7fffu + ((u >> 16) & 1u);
;   return (bf16r)(u >> 16);
; __device__ __forceinline__ void inproj_epilogue(const Params& p, int layer, int mt, int ntile, int tid,
;                                                 f32x16 (&acc)[2][2], unsigned char* smem) {
;     ...
;     acc_foreach(tid, acc, [&](int row, int col, float v) {
;       int t = m0 + row;
;       float o = v;
;       if (mode == 1) o = (t >= NPADR) ? v : 0.f;
;       if (mode == 2) o = sigmf(v);
;       sT[row * 136 + col] = f2bf(o);
;     });
.LBB0_3057:
	v_bfe_u32 v118, v117, 16, 1
	v_add_u32_e32 v116, 0x110, v116
	v_add3_u32 v118, v117, v118, s79
	v_lshl_add_u32 v117, v106, 1, v116
	ds_write_b16_d16_hi v117, v118
	v_add3_u32 v118, s94, v96, 16
	s_and_b64 vcc, exec, s[6:7]
	v_cmp_lt_i32_e64 s[24:25], s77, v118
	s_cbranch_vccz .Lsg_393

; __device__ __forceinline__ float sigmf(float x) { return 1.f / (1.f + __expf(-x)); }
; __device__ __forceinline__ bf16r f2bf(float f) {
;   unsigned u = __float_as_uint(f);
;   u += 0x7fffu + ((u >> 16) & 1u);
;   return (bf16r)(u >> 16);
; __device__ __forceinline__ void inproj_epilogue(const Params& p, int layer, int mt, int ntile, int tid,
;                                                 f32x16 (&acc)[2][2], unsigned char* smem) {
;     ...
;     acc_foreach(tid, acc, [&](int row, int col, float v) {
;       int t = m0 + row;
;       float o = v;
;       if (mode == 1) o = (t >= NPADR) ? v : 0.f;
;       if (mode == 2) o = sigmf(v);
;       sT[row * 136 + col] = f2bf(o);
;     });
.LBB0_3060:
	v_bfe_u32 v119, v118, 16, 1
	v_add_u32_e32 v116, 0x550, v116
	v_add3_u32 v119, v118, v119, s79
	v_lshl_add_u32 v118, v106, 1, v116
	ds_write_b16_d16_hi v118, v119
	v_add3_u32 v119, s94, v96, 17
	s_and_b64 vcc, exec, s[6:7]
	v_cmp_lt_i32_e64 s[26:27], s77, v119
	s_cbranch_vccz .Lsg_394

; __device__ __forceinline__ float sigmf(float x) { return 1.f / (1.f + __expf(-x)); }
; __device__ __forceinline__ bf16r f2bf(float f) {
;   unsigned u = __float_as_uint(f);
;   u += 0x7fffu + ((u >> 16) & 1u);
;   return (bf16r)(u >> 16);
; __device__ __forceinline__ void inproj_epilogue(const Params& p, int layer, int mt, int ntile, int tid,
;                                                 f32x16 (&acc)[2][2], unsigned char* smem) {
;     ...
;     acc_foreach(tid, acc, [&](int row, int col, float v) {
;       int t = m0 + row;
;       float o = v;
;       if (mode == 1) o = (t >= NPADR) ? v : 0.f;
;       if (mode == 2) o = sigmf(v);
;       sT[row * 136 + col] = f2bf(o);
;     });
.LBB0_3063:
	v_bfe_u32 v120, v119, 16, 1
	v_add_u32_e32 v116, 0x110, v116
	v_add3_u32 v120, v119, v120, s79
	v_lshl_add_u32 v119, v106, 1, v116
	ds_write_b16_d16_hi v119, v120
	v_add3_u32 v120, s94, v96, 18
	s_and_b64 vcc, exec, s[6:7]
	v_cmp_lt_i32_e64 s[28:29], s77, v120
	s_cbranch_vccz .Lsg_395

; __device__ __forceinline__ float sigmf(float x) { return 1.f / (1.f + __expf(-x)); }
; __device__ __forceinline__ bf16r f2bf(float f) {
;   unsigned u = __float_as_uint(f);
;   u += 0x7fffu + ((u >> 16) & 1u);
;   return (bf16r)(u >> 16);
; __device__ __forceinline__ void inproj_epilogue(const Params& p, int layer, int mt, int ntile, int tid,
;                                                 f32x16 (&acc)[2][2], unsigned char* smem) {
;     ...
;     acc_foreach(tid, acc, [&](int row, int col, float v) {
;       int t = m0 + row;
;       float o = v;
;       if (mode == 1) o = (t >= NPADR) ? v : 0.f;
;       if (mode == 2) o = sigmf(v);
;       sT[row * 136 + col] = f2bf(o);
;     });
.LBB0_3066:
	v_bfe_u32 v121, v120, 16, 1
	v_add_u32_e32 v116, 0x110, v116
	v_add3_u32 v121, v120, v121, s79
	v_lshl_add_u32 v120, v106, 1, v116
	ds_write_b16_d16_hi v120, v121
	v_add3_u32 v121, s94, v96, 19
	s_and_b64 vcc, exec, s[6:7]
	v_cmp_lt_i32_e64 s[30:31], s77, v121
	s_cbranch_vccz .Lsg_396

; __device__ __forceinline__ float sigmf(float x) { return 1.f / (1.f + __expf(-x)); }
; __device__ __forceinline__ bf16r f2bf(float f) {
;   unsigned u = __float_as_uint(f);
;   u += 0x7fffu + ((u >> 16) & 1u);
;   return (bf16r)(u >> 16);
; __device__ __forceinline__ void inproj_epilogue(const Params& p, int layer, int mt, int ntile, int tid,
;                                                 f32x16 (&acc)[2][2], unsigned char* smem) {
;     ...
;     acc_foreach(tid, acc, [&](int row, int col, float v) {
;       int t = m0 + row;
;       float o = v;
;       if (mode == 1) o = (t >= NPADR) ? v : 0.f;
;       if (mode == 2) o = sigmf(v);
;       sT[row * 136 + col] = f2bf(o);
;     });
.LBB0_3069:
	v_bfe_u32 v122, v121, 16, 1
	v_add_u32_e32 v116, 0x110, v116
	v_add3_u32 v122, v121, v122, s79
	v_lshl_add_u32 v121, v106, 1, v116
	ds_write_b16_d16_hi v121, v122
	v_add3_u32 v122, s94, v96, 24
	s_and_b64 vcc, exec, s[6:7]
	v_cmp_lt_i32_e64 s[34:35], s77, v122
	s_cbranch_vccz .Lsg_397

; __device__ __forceinline__ float sigmf(float x) { return 1.f / (1.f + __expf(-x)); }
; __device__ __forceinline__ bf16r f2bf(float f) {
;   unsigned u = __float_as_uint(f);
;   u += 0x7fffu + ((u >> 16) & 1u);
;   return (bf16r)(u >> 16);
; __device__ __forceinline__ void inproj_epilogue(const Params& p, int layer, int mt, int ntile, int tid,
;                                                 f32x16 (&acc)[2][2], unsigned char* smem) {
;     ...
;     acc_foreach(tid, acc, [&](int row, int col, float v) {
;       int t = m0 + row;
;       float o = v;
;       if (mode == 1) o = (t >= NPADR) ? v : 0.f;
;       if (mode == 2) o = sigmf(v);
;       sT[row * 136 + col] = f2bf(o);
;     });
.LBB0_3072:
	v_bfe_u32 v123, v122, 16, 1
	v_add_u32_e32 v116, 0x550, v116
	v_add3_u32 v123, v122, v123, s79
	v_lshl_add_u32 v122, v106, 1, v116
	ds_write_b16_d16_hi v122, v123
	v_add3_u32 v123, s94, v96, 25
	s_and_b64 vcc, exec, s[6:7]
	v_cmp_lt_i32_e64 s[36:37], s77, v123
	s_cbranch_vccz .Lsg_398

; __device__ __forceinline__ float sigmf(float x) { return 1.f / (1.f + __expf(-x)); }
; __device__ __forceinline__ bf16r f2bf(float f) {
;   unsigned u = __float_as_uint(f);
;   u += 0x7fffu + ((u >> 16) & 1u);
;   return (bf16r)(u >> 16);
; __device__ __forceinline__ void inproj_epilogue(const Params& p, int layer, int mt, int ntile, int tid,
;                                                 f32x16 (&acc)[2][2], unsigned char* smem) {
;     ...
;     acc_foreach(tid, acc, [&](int row, int col, float v) {
;       int t = m0 + row;
;       float o = v;
;       if (mode == 1) o = (t >= NPADR) ? v : 0.f;
;       if (mode == 2) o = sigmf(v);
;       sT[row * 136 + col] = f2bf(o);
;     });
.LBB0_3075:
	v_bfe_u32 v124, v123, 16, 1
	v_add_u32_e32 v116, 0x110, v116
	v_add3_u32 v124, v123, v124, s79
	v_lshl_add_u32 v123, v106, 1, v116
	ds_write_b16_d16_hi v123, v124
	v_add3_u32 v124, s94, v96, 26
	s_and_b64 vcc, exec, s[6:7]
	v_cmp_lt_i32_e64 s[38:39], s77, v124
	s_cbranch_vccz .Lsg_399

; __device__ __forceinline__ float sigmf(float x) { return 1.f / (1.f + __expf(-x)); }
; __device__ __forceinline__ bf16r f2bf(float f) {
;   unsigned u = __float_as_uint(f);
;   u += 0x7fffu + ((u >> 16) & 1u);
;   return (bf16r)(u >> 16);
; __device__ __forceinline__ void inproj_epilogue(const Params& p, int layer, int mt, int ntile, int tid,
;                                                 f32x16 (&acc)[2][2], unsigned char* smem) {
;     ...
;     acc_foreach(tid, acc, [&](int row, int col, float v) {
;       int t = m0 + row;
;       float o = v;
;       if (mode == 1) o = (t >= NPADR) ? v : 0.f;
;       if (mode == 2) o = sigmf(v);
;       sT[row * 136 + col] = f2bf(o);
;     });
.LBB0_3078:
	v_bfe_u32 v125, v124, 16, 1
	v_add_u32_e32 v116, 0x110, v116
	v_add3_u32 v124, v124, v125, s79
	v_lshl_add_u32 v116, v106, 1, v116
	ds_write_b16_d16_hi v116, v124
	v_add3_u32 v124, s94, v96, 27
	s_and_b64 vcc, exec, s[6:7]
	v_cmp_lt_i32_e64 s[40:41], s77, v124
	s_cbranch_vccz .Lsg_400

; __device__ __forceinline__ float sigmf(float x) { return 1.f / (1.f + __expf(-x)); }
; template <int MT, int NT, class F>
; __device__ __forceinline__ void acc_foreach(int tid, f32x16 (&acc)[MT][NT], F f) {
;     ...
;         int row = wm * (MT * 32) + mt * 32 + (i & 3) + 8 * (i >> 2) + 4 * hi;
;         int col = wn * (NT * 32) + nt * 32 + c;
; __device__ __forceinline__ void inproj_epilogue(const Params& p, int layer, int mt, int ntile, int tid,
;                                                 f32x16 (&acc)[2][2], unsigned char* smem) {
;     ...
;     acc_foreach(tid, acc, [&](int row, int col, float v) {
;       int t = m0 + row;
;       float o = v;
;       if (mode == 1) o = (t >= NPADR) ? v : 0.f;
;       if (mode == 2) o = sigmf(v);
;       sT[row * 136 + col] = f2bf(o);
;     });
.LBB0_3129:
	v_bfe_u32 v50, v48, 16, 1
	v_add_u32_e32 v49, 0x110, v116
	v_add3_u32 v48, v48, v50, s79
	ds_write_b16_d16_hi v49, v48 offset:64
	v_or_b32_e32 v48, 32, v96
	v_add_u32_e32 v49, s94, v48
	s_and_b64 vcc, exec, s[6:7]
	v_cmp_lt_i32_e64 s[8:9], s77, v49
	s_cbranch_vccz .Lsg_417

; __device__ __forceinline__ float sigmf(float x) { return 1.f / (1.f + __expf(-x)); }
; __device__ __forceinline__ bf16r f2bf(float f) {
;   unsigned u = __float_as_uint(f);
;   u += 0x7fffu + ((u >> 16) & 1u);
;   return (bf16r)(u >> 16);
; __device__ __forceinline__ void inproj_epilogue(const Params& p, int layer, int mt, int ntile, int tid,
;                                                 f32x16 (&acc)[2][2], unsigned char* smem) {
;     ...
;     acc_foreach(tid, acc, [&](int row, int col, float v) {
;       int t = m0 + row;
;       float o = v;
;       if (mode == 1) o = (t >= NPADR) ? v : 0.f;
;       if (mode == 2) o = sigmf(v);
;       sT[row * 136 + col] = f2bf(o);
;     });
.LBB0_3132:
	v_bfe_u32 v50, v49, 16, 1
	v_add3_u32 v50, v49, v50, s79
	v_mul_lo_u32 v49, v48, s80
	v_lshl_add_u32 v48, v106, 1, v49
	ds_write_b16_d16_hi v48, v50
	v_add3_u32 v50, s94, v96, 33
	s_and_b64 vcc, exec, s[6:7]
	v_cmp_lt_i32_e64 s[10:11], s77, v50
	s_cbranch_vccz .Lsg_418

; __device__ __forceinline__ float sigmf(float x) { return 1.f / (1.f + __expf(-x)); }
; __device__ __forceinline__ bf16r f2bf(float f) {
;   unsigned u = __float_as_uint(f);
;   u += 0x7fffu + ((u >> 16) & 1u);
;   return (bf16r)(u >> 16);
; __device__ __forceinline__ void inproj_epilogue(const Params& p, int layer, int mt, int ntile, int tid,
;                                                 f32x16 (&acc)[2][2], unsigned char* smem) {
;     ...
;     acc_foreach(tid, acc, [&](int row, int col, float v) {
;       int t = m0 + row;
;       float o = v;
;       if (mode == 1) o = (t >= NPADR) ? v : 0.f;
;       if (mode == 2) o = sigmf(v);
;       sT[row * 136 + col] = f2bf(o);
;     });
.LBB0_3135:
	v_bfe_u32 v51, v50, 16, 1
	v_add3_u32 v51, v50, v51, s79
	v_add_u32_e32 v50, 0x110, v49
	v_lshl_add_u32 v49, v106, 1, v50
	ds_write_b16_d16_hi v49, v51
	v_add3_u32 v51, s94, v96, 34
	s_and_b64 vcc, exec, s[6:7]
	v_cmp_lt_i32_e64 s[12:13], s77, v51
	s_cbranch_vccz .Lsg_419

; __device__ __forceinline__ float sigmf(float x) { return 1.f / (1.f + __expf(-x)); }
; __device__ __forceinline__ bf16r f2bf(float f) {
;   unsigned u = __float_as_uint(f);
;   u += 0x7fffu + ((u >> 16) & 1u);
;   return (bf16r)(u >> 16);
; __device__ __forceinline__ void inproj_epilogue(const Params& p, int layer, int mt, int ntile, int tid,
;                                                 f32x16 (&acc)[2][2], unsigned char* smem) {
;     ...
;     acc_foreach(tid, acc, [&](int row, int col, float v) {
;       int t = m0 + row;
;       float o = v;
;       if (mode == 1) o = (t >= NPADR) ? v : 0.f;
;       if (mode == 2) o = sigmf(v);
;       sT[row * 136 + col] = f2bf(o);
;     });
.LBB0_3138:
	v_bfe_u32 v52, v51, 16, 1
	v_add3_u32 v52, v51, v52, s79
	v_add_u32_e32 v51, 0x110, v50
	v_lshl_add_u32 v50, v106, 1, v51
	ds_write_b16_d16_hi v50, v52
	v_add3_u32 v52, s94, v96, 35
	s_and_b64 vcc, exec, s[6:7]
	v_cmp_lt_i32_e64 s[14:15], s77, v52
	s_cbranch_vccz .Lsg_420

; __device__ __forceinline__ float sigmf(float x) { return 1.f / (1.f + __expf(-x)); }
; __device__ __forceinline__ bf16r f2bf(float f) {
;   unsigned u = __float_as_uint(f);
;   u += 0x7fffu + ((u >> 16) & 1u);
;   return (bf16r)(u >> 16);
; __device__ __forceinline__ void inproj_epilogue(const Params& p, int layer, int mt, int ntile, int tid,
;                                                 f32x16 (&acc)[2][2], unsigned char* smem) {
;     ...
;     acc_foreach(tid, acc, [&](int row, int col, float v) {
;       int t = m0 + row;
;       float o = v;
;       if (mode == 1) o = (t >= NPADR) ? v : 0.f;
;       if (mode == 2) o = sigmf(v);
;       sT[row * 136 + col] = f2bf(o);
;     });
.LBB0_3141:
	v_bfe_u32 v53, v52, 16, 1
	v_add3_u32 v53, v52, v53, s79
	v_add_u32_e32 v52, 0x110, v51
	v_lshl_add_u32 v51, v106, 1, v52
	ds_write_b16_d16_hi v51, v53
	v_add3_u32 v53, s94, v96, 40
	s_and_b64 vcc, exec, s[6:7]
	v_cmp_lt_i32_e64 s[16:17], s77, v53
	s_cbranch_vccz .Lsg_421

; __device__ __forceinline__ float sigmf(float x) { return 1.f / (1.f + __expf(-x)); }
; __device__ __forceinline__ bf16r f2bf(float f) {
;   unsigned u = __float_as_uint(f);
;   u += 0x7fffu + ((u >> 16) & 1u);
;   return (bf16r)(u >> 16);
; __device__ __forceinline__ void inproj_epilogue(const Params& p, int layer, int mt, int ntile, int tid,
;                                                 f32x16 (&acc)[2][2], unsigned char* smem) {
;     ...
;     acc_foreach(tid, acc, [&](int row, int col, float v) {
;       int t = m0 + row;
;       float o = v;
;       if (mode == 1) o = (t >= NPADR) ? v : 0.f;
;       if (mode == 2) o = sigmf(v);
;       sT[row * 136 + col] = f2bf(o);
;     });
.LBB0_3144:
	v_bfe_u32 v54, v53, 16, 1
	v_add3_u32 v54, v53, v54, s79
	v_add_u32_e32 v53, 0x550, v52
	v_lshl_add_u32 v52, v106, 1, v53
	ds_write_b16_d16_hi v52, v54
	v_add3_u32 v54, s94, v96, 41
	s_and_b64 vcc, exec, s[6:7]
	v_cmp_lt_i32_e64 s[18:19], s77, v54
	s_cbranch_vccz .Lsg_422

; __device__ __forceinline__ float sigmf(float x) { return 1.f / (1.f + __expf(-x)); }
; __device__ __forceinline__ bf16r f2bf(float f) {
;   unsigned u = __float_as_uint(f);
;   u += 0x7fffu + ((u >> 16) & 1u);
;   return (bf16r)(u >> 16);
; __device__ __forceinline__ void inproj_epilogue(const Params& p, int layer, int mt, int ntile, int tid,
;                                                 f32x16 (&acc)[2][2], unsigned char* smem) {
;     ...
;     acc_foreach(tid, acc, [&](int row, int col, float v) {
;       int t = m0 + row;
;       float o = v;
;       if (mode == 1) o = (t >= NPADR) ? v : 0.f;
;       if (mode == 2) o = sigmf(v);
;       sT[row * 136 + col] = f2bf(o);
;     });
.LBB0_3147:
	v_bfe_u32 v55, v54, 16, 1
	v_add3_u32 v55, v54, v55, s79
	v_add_u32_e32 v54, 0x110, v53
	v_lshl_add_u32 v53, v106, 1, v54
	ds_write_b16_d16_hi v53, v55
	v_add3_u32 v55, s94, v96, 42
	s_and_b64 vcc, exec, s[6:7]
	v_cmp_lt_i32_e64 s[20:21], s77, v55
	s_cbranch_vccz .Lsg_423

; __device__ __forceinline__ float sigmf(float x) { return 1.f / (1.f + __expf(-x)); }
; __device__ __forceinline__ bf16r f2bf(float f) {
;   unsigned u = __float_as_uint(f);
;   u += 0x7fffu + ((u >> 16) & 1u);
;   return (bf16r)(u >> 16);
; __device__ __forceinline__ void inproj_epilogue(const Params& p, int layer, int mt, int ntile, int tid,
;                                                 f32x16 (&acc)[2][2], unsigned char* smem) {
;     ...
;     acc_foreach(tid, acc, [&](int row, int col, float v) {
;       int t = m0 + row;
;       float o = v;
;       if (mode == 1) o = (t >= NPADR) ? v : 0.f;
;       if (mode == 2) o = sigmf(v);
;       sT[row * 136 + col] = f2bf(o);
;     });
.LBB0_3150:
	v_bfe_u32 v56, v55, 16, 1
	v_add3_u32 v56, v55, v56, s79
	v_add_u32_e32 v55, 0x110, v54
	v_lshl_add_u32 v54, v106, 1, v55
	ds_write_b16_d16_hi v54, v56
	v_add3_u32 v56, s94, v96, 43
	s_and_b64 vcc, exec, s[6:7]
	v_cmp_lt_i32_e64 s[22:23], s77, v56
	s_cbranch_vccz .Lsg_424

; __device__ __forceinline__ float sigmf(float x) { return 1.f / (1.f + __expf(-x)); }
; __device__ __forceinline__ bf16r f2bf(float f) {
;   unsigned u = __float_as_uint(f);
;   u += 0x7fffu + ((u >> 16) & 1u);
;   return (bf16r)(u >> 16);
; __device__ __forceinline__ void inproj_epilogue(const Params& p, int layer, int mt, int ntile, int tid,
;                                                 f32x16 (&acc)[2][2], unsigned char* smem) {
;     ...
;     acc_foreach(tid, acc, [&](int row, int col, float v) {
;       int t = m0 + row;
;       float o = v;
;       if (mode == 1) o = (t >= NPADR) ? v : 0.f;
;       if (mode == 2) o = sigmf(v);
;       sT[row * 136 + col] = f2bf(o);
;     });
.LBB0_3153:
	v_bfe_u32 v57, v56, 16, 1
	v_add_u32_e32 v55, 0x110, v55
	v_add3_u32 v57, v56, v57, s79
	v_lshl_add_u32 v56, v106, 1, v55
	ds_write_b16_d16_hi v56, v57
	v_add3_u32 v57, s94, v96, 48
	s_and_b64 vcc, exec, s[6:7]
	v_cmp_lt_i32_e64 s[24:25], s77, v57
	s_cbranch_vccz .Lsg_425

; __device__ __forceinline__ float sigmf(float x) { return 1.f / (1.f + __expf(-x)); }
; __device__ __forceinline__ bf16r f2bf(float f) {
;   unsigned u = __float_as_uint(f);
;   u += 0x7fffu + ((u >> 16) & 1u);
;   return (bf16r)(u >> 16);
; __device__ __forceinline__ void inproj_epilogue(const Params& p, int layer, int mt, int ntile, int tid,
;                                                 f32x16 (&acc)[2][2], unsigned char* smem) {
;     ...
;     acc_foreach(tid, acc, [&](int row, int col, float v) {
;       int t = m0 + row;
;       float o = v;
;       if (mode == 1) o = (t >= NPADR) ? v : 0.f;
;       if (mode == 2) o = sigmf(v);
;       sT[row * 136 + col] = f2bf(o);
;     });
.LBB0_3156:
	v_bfe_u32 v58, v57, 16, 1
	v_add_u32_e32 v55, 0x550, v55
	v_add3_u32 v58, v57, v58, s79
	v_lshl_add_u32 v57, v106, 1, v55
	ds_write_b16_d16_hi v57, v58
	v_add3_u32 v58, s94, v96, 49
	s_and_b64 vcc, exec, s[6:7]
	v_cmp_lt_i32_e64 s[26:27], s77, v58
	s_cbranch_vccz .Lsg_426

; __device__ __forceinline__ float sigmf(float x) { return 1.f / (1.f + __expf(-x)); }
; __device__ __forceinline__ bf16r f2bf(float f) {
;   unsigned u = __float_as_uint(f);
;   u += 0x7fffu + ((u >> 16) & 1u);
;   return (bf16r)(u >> 16);
; __device__ __forceinline__ void inproj_epilogue(const Params& p, int layer, int mt, int ntile, int tid,
;                                                 f32x16 (&acc)[2][2], unsigned char* smem) {
;     ...
;     acc_foreach(tid, acc, [&](int row, int col, float v) {
;       int t = m0 + row;
;       float o = v;
;       if (mode == 1) o = (t >= NPADR) ? v : 0.f;
;       if (mode == 2) o = sigmf(v);
;       sT[row * 136 + col] = f2bf(o);
;     });
.LBB0_3159:
	v_bfe_u32 v59, v58, 16, 1
	v_add_u32_e32 v55, 0x110, v55
	v_add3_u32 v59, v58, v59, s79
	v_lshl_add_u32 v58, v106, 1, v55
	ds_write_b16_d16_hi v58, v59
	v_add3_u32 v59, s94, v96, 50
	s_and_b64 vcc, exec, s[6:7]
	v_cmp_lt_i32_e64 s[28:29], s77, v59
	s_cbranch_vccz .Lsg_427

; __device__ __forceinline__ float sigmf(float x) { return 1.f / (1.f + __expf(-x)); }
; __device__ __forceinline__ bf16r f2bf(float f) {
;   unsigned u = __float_as_uint(f);
;   u += 0x7fffu + ((u >> 16) & 1u);
;   return (bf16r)(u >> 16);
; __device__ __forceinline__ void inproj_epilogue(const Params& p, int layer, int mt, int ntile, int tid,
;                                                 f32x16 (&acc)[2][2], unsigned char* smem) {
;     ...
;     acc_foreach(tid, acc, [&](int row, int col, float v) {
;       int t = m0 + row;
;       float o = v;
;       if (mode == 1) o = (t >= NPADR) ? v : 0.f;
;       if (mode == 2) o = sigmf(v);
;       sT[row * 136 + col] = f2bf(o);
;     });
.LBB0_3162:
	v_bfe_u32 v60, v59, 16, 1
	v_add_u32_e32 v55, 0x110, v55
	v_add3_u32 v60, v59, v60, s79
	v_lshl_add_u32 v59, v106, 1, v55
	ds_write_b16_d16_hi v59, v60
	v_add3_u32 v60, s94, v96, 51
	s_and_b64 vcc, exec, s[6:7]
	v_cmp_lt_i32_e64 s[30:31], s77, v60
	s_cbranch_vccz .Lsg_428

; __device__ __forceinline__ float sigmf(float x) { return 1.f / (1.f + __expf(-x)); }
; __device__ __forceinline__ bf16r f2bf(float f) {
;   unsigned u = __float_as_uint(f);
;   u += 0x7fffu + ((u >> 16) & 1u);
;   return (bf16r)(u >> 16);
; __device__ __forceinline__ void inproj_epilogue(const Params& p, int layer, int mt, int ntile, int tid,
;                                                 f32x16 (&acc)[2][2], unsigned char* smem) {
;     ...
;     acc_foreach(tid, acc, [&](int row, int col, float v) {
;       int t = m0 + row;
;       float o = v;
;       if (mode == 1) o = (t >= NPADR) ? v : 0.f;
;       if (mode == 2) o = sigmf(v);
;       sT[row * 136 + col] = f2bf(o);
;     });
.LBB0_3165:
	v_bfe_u32 v61, v60, 16, 1
	v_add_u32_e32 v55, 0x110, v55
	v_add3_u32 v61, v60, v61, s79
	v_lshl_add_u32 v60, v106, 1, v55
	ds_write_b16_d16_hi v60, v61
	v_add3_u32 v61, s94, v96, 56
	s_and_b64 vcc, exec, s[6:7]
	v_cmp_lt_i32_e64 s[34:35], s77, v61
	s_cbranch_vccz .Lsg_429

; __device__ __forceinline__ float sigmf(float x) { return 1.f / (1.f + __expf(-x)); }
; __device__ __forceinline__ bf16r f2bf(float f) {
;   unsigned u = __float_as_uint(f);
;   u += 0x7fffu + ((u >> 16) & 1u);
;   return (bf16r)(u >> 16);
; __device__ __forceinline__ void inproj_epilogue(const Params& p, int layer, int mt, int ntile, int tid,
;                                                 f32x16 (&acc)[2][2], unsigned char* smem) {
;     ...
;     acc_foreach(tid, acc, [&](int row, int col, float v) {
;       int t = m0 + row;
;       float o = v;
;       if (mode == 1) o = (t >= NPADR) ? v : 0.f;
;       if (mode == 2) o = sigmf(v);
;       sT[row * 136 + col] = f2bf(o);
;     });
.LBB0_3168:
	v_bfe_u32 v62, v61, 16, 1
	v_add_u32_e32 v55, 0x550, v55
	v_add3_u32 v62, v61, v62, s79
	v_lshl_add_u32 v61, v106, 1, v55
	ds_write_b16_d16_hi v61, v62
	v_add3_u32 v62, s94, v96, 57
	s_and_b64 vcc, exec, s[6:7]
	v_cmp_lt_i32_e64 s[36:37], s77, v62
	s_cbranch_vccz .Lsg_430

; __device__ __forceinline__ float sigmf(float x) { return 1.f / (1.f + __expf(-x)); }
; __device__ __forceinline__ bf16r f2bf(float f) {
;   unsigned u = __float_as_uint(f);
;   u += 0x7fffu + ((u >> 16) & 1u);
;   return (bf16r)(u >> 16);
; __device__ __forceinline__ void inproj_epilogue(const Params& p, int layer, int mt, int ntile, int tid,
;                                                 f32x16 (&acc)[2][2], unsigned char* smem) {
;     ...
;     acc_foreach(tid, acc, [&](int row, int col, float v) {
;       int t = m0 + row;
;       float o = v;
;       if (mode == 1) o = (t >= NPADR) ? v : 0.f;
;       if (mode == 2) o = sigmf(v);
;       sT[row * 136 + col] = f2bf(o);
;     });
.LBB0_3171:
	v_bfe_u32 v63, v62, 16, 1
	v_add_u32_e32 v55, 0x110, v55
	v_add3_u32 v63, v62, v63, s79
	v_lshl_add_u32 v62, v106, 1, v55
	ds_write_b16_d16_hi v62, v63
	v_add3_u32 v63, s94, v96, 58
	s_and_b64 vcc, exec, s[6:7]
	v_cmp_lt_i32_e64 s[38:39], s77, v63
	s_cbranch_vccz .Lsg_431

; __device__ __forceinline__ float sigmf(float x) { return 1.f / (1.f + __expf(-x)); }
; __device__ __forceinline__ bf16r f2bf(float f) {
;   unsigned u = __float_as_uint(f);
;   u += 0x7fffu + ((u >> 16) & 1u);
;   return (bf16r)(u >> 16);
; __device__ __forceinline__ void inproj_epilogue(const Params& p, int layer, int mt, int ntile, int tid,
;                                                 f32x16 (&acc)[2][2], unsigned char* smem) {
;     ...
;     acc_foreach(tid, acc, [&](int row, int col, float v) {
;       int t = m0 + row;
;       float o = v;
;       if (mode == 1) o = (t >= NPADR) ? v : 0.f;
;       if (mode == 2) o = sigmf(v);
;       sT[row * 136 + col] = f2bf(o);
;     });
.LBB0_3174:
	v_bfe_u32 v107, v63, 16, 1
	v_add_u32_e32 v55, 0x110, v55
	v_add3_u32 v63, v63, v107, s79
	v_lshl_add_u32 v55, v106, 1, v55
	ds_write_b16_d16_hi v55, v63
	v_add3_u32 v63, s94, v96, 59
	s_and_b64 vcc, exec, s[6:7]
	v_cmp_lt_i32_e64 s[40:41], s77, v63
	s_cbranch_vccz .Lsg_432

; __device__ __forceinline__ float sigmf(float x) { return 1.f / (1.f + __expf(-x)); }
; __device__ __forceinline__ float softplusf(float x) { return fmaxf(x, 0.f) + __logf(1.f + __expf(-fabsf(x))); }
; template <int MT, int NT, class F>
; __device__ __forceinline__ void acc_foreach(int tid, f32x16 (&acc)[MT][NT], F f) {
;     ...
;         int row = wm * (MT * 32) + mt * 32 + (i & 3) + 8 * (i >> 2) + 4 * hi;
;         int col = wn * (NT * 32) + nt * 32 + c;
; __device__ __forceinline__ void inproj_epilogue(const Params& p, int layer, int mt, int ntile, int tid,
;                                                 f32x16 (&acc)[2][2], unsigned char* smem) {
;     ...
;   const int m0 = mt * 128;
;   if (mode == 3) {
;     float* dt = (float*)(p.ws + OFF_DT) + (size_t)m0 * 16;
;     const float* bias = p.ssd_dt_bias + layer * 16;
;     acc_foreach(tid, acc, [&](int row, int col, float v) {
;       if (col < 16) *(dt + row * 16 + col) = softplusf(v + bias[col]);
;     });
;   } else {
;     bf16r* dstb = dst + (size_t)m0 * ld + c0;
;     bf16r* sT = (bf16r*)smem;
;     acc_foreach(tid, acc, [&](int row, int col, float v) {
;       int t = m0 + row;
;       float o = v;
;       if (mode == 1) o = (t >= NPADR) ? v : 0.f;
;       if (mode == 2) o = sigmf(v);
;       sT[row * 136 + col] = f2bf(o);
;     });
.LBB0_3366:
	s_lshl_b32 s88, s6, 7
	s_ashr_i32 s89, s88, 31
	s_cmp_lg_u32 s7, 3
	s_mov_b64 s[4:5], -1
	s_cbranch_scc0 .LBB0_3560
	v_mov_b32_e32 v106, v108
	s_movk_i32 s4, 0xffc0
	v_lshrrev_b32_e32 v107, 3, v106
	v_ashrrev_i32_e32 v96, 1, v106
	v_and_b32_e32 v107, 4, v107
	v_and_or_b32 v96, v96, s4, v107
	s_cmp_eq_u32 s7, 1
	s_cselect_b64 s[4:5], -1, 0
	v_add_u32_e32 v107, s88, v96
	s_cmp_eq_u32 s7, 2
	s_cselect_b64 s[10:11], -1, 0
	s_cmp_lg_u32 s7, 2
	v_cmp_lt_i32_e64 s[8:9], s81, v107
	s_cbranch_scc0 .Lsg_449

; __device__ __forceinline__ float sigmf(float x) { return 1.f / (1.f + __expf(-x)); }
; __device__ __forceinline__ void inproj_epilogue(const Params& p, int layer, int mt, int ntile, int tid,
;                                                 f32x16 (&acc)[2][2], unsigned char* smem) {
;     ...
;     acc_foreach(tid, acc, [&](int row, int col, float v) {
;       int t = m0 + row;
;       float o = v;
;       if (mode == 1) o = (t >= NPADR) ? v : 0.f;
;       if (mode == 2) o = sigmf(v);
;       sT[row * 136 + col] = f2bf(o);
;     });
.LBB0_3370:
	v_bfe_u32 v110, v107, 16, 1
	v_and_b32_e32 v106, 0x5f, v106
	v_add3_u32 v111, v107, v110, s83
	v_mul_lo_u32 v110, v96, s90
	v_lshl_add_u32 v107, v106, 1, v110
	ds_write_b16_d16_hi v107, v111
	v_add3_u32 v111, s88, v96, 1
	v_cndmask_b32_e64 v112, 0, 1, s[10:11]
	v_cmp_ne_u32_e64 s[6:7], 1, v112
	s_andn2_b64 vcc, exec, s[10:11]
	v_cmp_lt_i32_e64 s[10:11], s81, v111
	s_cbranch_vccz .Lsg_450

; __device__ __forceinline__ float sigmf(float x) { return 1.f / (1.f + __expf(-x)); }
; __device__ __forceinline__ void inproj_epilogue(const Params& p, int layer, int mt, int ntile, int tid,
;                                                 f32x16 (&acc)[2][2], unsigned char* smem) {
;     ...
;     acc_foreach(tid, acc, [&](int row, int col, float v) {
;       int t = m0 + row;
;       float o = v;
;       if (mode == 1) o = (t >= NPADR) ? v : 0.f;
;       if (mode == 2) o = sigmf(v);
;       sT[row * 136 + col] = f2bf(o);
;     });
.LBB0_3373:
	v_bfe_u32 v112, v111, 16, 1
	v_add3_u32 v112, v111, v112, s83
	v_add_u32_e32 v111, 0x110, v110
	v_lshl_add_u32 v110, v106, 1, v111
	ds_write_b16_d16_hi v110, v112
	v_add3_u32 v112, s88, v96, 2
	s_and_b64 vcc, exec, s[6:7]
	v_cmp_lt_i32_e64 s[12:13], s81, v112
	s_cbranch_vccz .Lsg_451

; __device__ __forceinline__ float sigmf(float x) { return 1.f / (1.f + __expf(-x)); }
; __device__ __forceinline__ void inproj_epilogue(const Params& p, int layer, int mt, int ntile, int tid,
;                                                 f32x16 (&acc)[2][2], unsigned char* smem) {
;     ...
;     acc_foreach(tid, acc, [&](int row, int col, float v) {
;       int t = m0 + row;
;       float o = v;
;       if (mode == 1) o = (t >= NPADR) ? v : 0.f;
;       if (mode == 2) o = sigmf(v);
;       sT[row * 136 + col] = f2bf(o);
;     });
.LBB0_3376:
	v_bfe_u32 v113, v112, 16, 1
	v_add3_u32 v113, v112, v113, s83
	v_add_u32_e32 v112, 0x110, v111
	v_lshl_add_u32 v111, v106, 1, v112
	ds_write_b16_d16_hi v111, v113
	v_add3_u32 v113, s88, v96, 3
	s_and_b64 vcc, exec, s[6:7]
	v_cmp_lt_i32_e64 s[14:15], s81, v113
	s_cbranch_vccz .Lsg_452

; __device__ __forceinline__ float sigmf(float x) { return 1.f / (1.f + __expf(-x)); }
; __device__ __forceinline__ void inproj_epilogue(const Params& p, int layer, int mt, int ntile, int tid,
;                                                 f32x16 (&acc)[2][2], unsigned char* smem) {
;     ...
;     acc_foreach(tid, acc, [&](int row, int col, float v) {
;       int t = m0 + row;
;       float o = v;
;       if (mode == 1) o = (t >= NPADR) ? v : 0.f;
;       if (mode == 2) o = sigmf(v);
;       sT[row * 136 + col] = f2bf(o);
;     });
.LBB0_3379:
	v_bfe_u32 v114, v113, 16, 1
	v_add3_u32 v114, v113, v114, s83
	v_add_u32_e32 v113, 0x110, v112
	v_lshl_add_u32 v112, v106, 1, v113
	ds_write_b16_d16_hi v112, v114
	v_add3_u32 v114, s88, v96, 8
	s_and_b64 vcc, exec, s[6:7]
	v_cmp_lt_i32_e64 s[16:17], s81, v114
	s_cbranch_vccz .Lsg_453

; __device__ __forceinline__ float sigmf(float x) { return 1.f / (1.f + __expf(-x)); }
; __device__ __forceinline__ void inproj_epilogue(const Params& p, int layer, int mt, int ntile, int tid,
;                                                 f32x16 (&acc)[2][2], unsigned char* smem) {
;     ...
;     acc_foreach(tid, acc, [&](int row, int col, float v) {
;       int t = m0 + row;
;       float o = v;
;       if (mode == 1) o = (t >= NPADR) ? v : 0.f;
;       if (mode == 2) o = sigmf(v);
;       sT[row * 136 + col] = f2bf(o);
;     });
.LBB0_3382:
	v_bfe_u32 v115, v114, 16, 1
	v_add3_u32 v115, v114, v115, s83
	v_add_u32_e32 v114, 0x550, v113
	v_lshl_add_u32 v113, v106, 1, v114
	ds_write_b16_d16_hi v113, v115
	v_add3_u32 v115, s88, v96, 9
	s_and_b64 vcc, exec, s[6:7]
	v_cmp_lt_i32_e64 s[18:19], s81, v115
	s_cbranch_vccz .Lsg_454

; __device__ __forceinline__ float sigmf(float x) { return 1.f / (1.f + __expf(-x)); }
; __device__ __forceinline__ void inproj_epilogue(const Params& p, int layer, int mt, int ntile, int tid,
;                                                 f32x16 (&acc)[2][2], unsigned char* smem) {
;     ...
;     acc_foreach(tid, acc, [&](int row, int col, float v) {
;       int t = m0 + row;
;       float o = v;
;       if (mode == 1) o = (t >= NPADR) ? v : 0.f;
;       if (mode == 2) o = sigmf(v);
;       sT[row * 136 + col] = f2bf(o);
;     });
.LBB0_3385:
	v_bfe_u32 v116, v115, 16, 1
	v_add3_u32 v116, v115, v116, s83
	v_add_u32_e32 v115, 0x110, v114
	v_lshl_add_u32 v114, v106, 1, v115
	ds_write_b16_d16_hi v114, v116
	v_add3_u32 v116, s88, v96, 10
	s_and_b64 vcc, exec, s[6:7]
	v_cmp_lt_i32_e64 s[20:21], s81, v116
	s_cbranch_vccz .Lsg_455

; __device__ __forceinline__ float sigmf(float x) { return 1.f / (1.f + __expf(-x)); }
; __device__ __forceinline__ void inproj_epilogue(const Params& p, int layer, int mt, int ntile, int tid,
;                                                 f32x16 (&acc)[2][2], unsigned char* smem) {
;     ...
;     acc_foreach(tid, acc, [&](int row, int col, float v) {
;       int t = m0 + row;
;       float o = v;
;       if (mode == 1) o = (t >= NPADR) ? v : 0.f;
;       if (mode == 2) o = sigmf(v);
;       sT[row * 136 + col] = f2bf(o);
;     });
.LBB0_3388:
	v_bfe_u32 v117, v116, 16, 1
	v_add3_u32 v117, v116, v117, s83
	v_add_u32_e32 v116, 0x110, v115
	v_lshl_add_u32 v115, v106, 1, v116
	ds_write_b16_d16_hi v115, v117
	v_add3_u32 v117, s88, v96, 11
	s_and_b64 vcc, exec, s[6:7]
	v_cmp_lt_i32_e64 s[22:23], s81, v117
	s_cbranch_vccz .Lsg_456

; __device__ __forceinline__ float sigmf(float x) { return 1.f / (1.f + __expf(-x)); }
; __device__ __forceinline__ void inproj_epilogue(const Params& p, int layer, int mt, int ntile, int tid,
;                                                 f32x16 (&acc)[2][2], unsigned char* smem) {
;     ...
;     acc_foreach(tid, acc, [&](int row, int col, float v) {
;       int t = m0 + row;
;       float o = v;
;       if (mode == 1) o = (t >= NPADR) ? v : 0.f;
;       if (mode == 2) o = sigmf(v);
;       sT[row * 136 + col] = f2bf(o);
;     });
.LBB0_3391:
	v_bfe_u32 v118, v117, 16, 1
	v_add_u32_e32 v116, 0x110, v116
	v_add3_u32 v118, v117, v118, s83
	v_lshl_add_u32 v117, v106, 1, v116
	ds_write_b16_d16_hi v117, v118
	v_add3_u32 v118, s88, v96, 16
	s_and_b64 vcc, exec, s[6:7]
	v_cmp_lt_i32_e64 s[24:25], s81, v118
	s_cbranch_vccz .Lsg_457

; __device__ __forceinline__ float sigmf(float x) { return 1.f / (1.f + __expf(-x)); }
; __device__ __forceinline__ void inproj_epilogue(const Params& p, int layer, int mt, int ntile, int tid,
;                                                 f32x16 (&acc)[2][2], unsigned char* smem) {
;     ...
;     acc_foreach(tid, acc, [&](int row, int col, float v) {
;       int t = m0 + row;
;       float o = v;
;       if (mode == 1) o = (t >= NPADR) ? v : 0.f;
;       if (mode == 2) o = sigmf(v);
;       sT[row * 136 + col] = f2bf(o);
;     });
.LBB0_3394:
	v_bfe_u32 v119, v118, 16, 1
	v_add_u32_e32 v116, 0x550, v116
	v_add3_u32 v119, v118, v119, s83
	v_lshl_add_u32 v118, v106, 1, v116
	ds_write_b16_d16_hi v118, v119
	v_add3_u32 v119, s88, v96, 17
	s_and_b64 vcc, exec, s[6:7]
	v_cmp_lt_i32_e64 s[26:27], s81, v119
	s_cbranch_vccz .Lsg_458

; __device__ __forceinline__ float sigmf(float x) { return 1.f / (1.f + __expf(-x)); }
; __device__ __forceinline__ void inproj_epilogue(const Params& p, int layer, int mt, int ntile, int tid,
;                                                 f32x16 (&acc)[2][2], unsigned char* smem) {
;     ...
;     acc_foreach(tid, acc, [&](int row, int col, float v) {
;       int t = m0 + row;
;       float o = v;
;       if (mode == 1) o = (t >= NPADR) ? v : 0.f;
;       if (mode == 2) o = sigmf(v);
;       sT[row * 136 + col] = f2bf(o);
;     });
.LBB0_3397:
	v_bfe_u32 v120, v119, 16, 1
	v_add_u32_e32 v116, 0x110, v116
	v_add3_u32 v120, v119, v120, s83
	v_lshl_add_u32 v119, v106, 1, v116
	ds_write_b16_d16_hi v119, v120
	v_add3_u32 v120, s88, v96, 18
	s_and_b64 vcc, exec, s[6:7]
	v_cmp_lt_i32_e64 s[28:29], s81, v120
	s_cbranch_vccz .Lsg_459

; __device__ __forceinline__ float sigmf(float x) { return 1.f / (1.f + __expf(-x)); }
; __device__ __forceinline__ void inproj_epilogue(const Params& p, int layer, int mt, int ntile, int tid,
;                                                 f32x16 (&acc)[2][2], unsigned char* smem) {
;     ...
;     acc_foreach(tid, acc, [&](int row, int col, float v) {
;       int t = m0 + row;
;       float o = v;
;       if (mode == 1) o = (t >= NPADR) ? v : 0.f;
;       if (mode == 2) o = sigmf(v);
;       sT[row * 136 + col] = f2bf(o);
;     });
.LBB0_3400:
	v_bfe_u32 v121, v120, 16, 1
	v_add_u32_e32 v116, 0x110, v116
	v_add3_u32 v121, v120, v121, s83
	v_lshl_add_u32 v120, v106, 1, v116
	ds_write_b16_d16_hi v120, v121
	v_add3_u32 v121, s88, v96, 19
	s_and_b64 vcc, exec, s[6:7]
	v_cmp_lt_i32_e64 s[30:31], s81, v121
	s_cbranch_vccz .Lsg_460

; __device__ __forceinline__ float sigmf(float x) { return 1.f / (1.f + __expf(-x)); }
; __device__ __forceinline__ void inproj_epilogue(const Params& p, int layer, int mt, int ntile, int tid,
;                                                 f32x16 (&acc)[2][2], unsigned char* smem) {
;     ...
;     acc_foreach(tid, acc, [&](int row, int col, float v) {
;       int t = m0 + row;
;       float o = v;
;       if (mode == 1) o = (t >= NPADR) ? v : 0.f;
;       if (mode == 2) o = sigmf(v);
;       sT[row * 136 + col] = f2bf(o);
;     });
.LBB0_3403:
	v_bfe_u32 v122, v121, 16, 1
	v_add_u32_e32 v116, 0x110, v116
	v_add3_u32 v122, v121, v122, s83
	v_lshl_add_u32 v121, v106, 1, v116
	ds_write_b16_d16_hi v121, v122
	v_add3_u32 v122, s88, v96, 24
	s_and_b64 vcc, exec, s[6:7]
	v_cmp_lt_i32_e64 s[34:35], s81, v122
	s_cbranch_vccz .Lsg_461

; __device__ __forceinline__ float sigmf(float x) { return 1.f / (1.f + __expf(-x)); }
; __device__ __forceinline__ void inproj_epilogue(const Params& p, int layer, int mt, int ntile, int tid,
;                                                 f32x16 (&acc)[2][2], unsigned char* smem) {
;     ...
;     acc_foreach(tid, acc, [&](int row, int col, float v) {
;       int t = m0 + row;
;       float o = v;
;       if (mode == 1) o = (t >= NPADR) ? v : 0.f;
;       if (mode == 2) o = sigmf(v);
;       sT[row * 136 + col] = f2bf(o);
;     });
.LBB0_3406:
	v_bfe_u32 v123, v122, 16, 1
	v_add_u32_e32 v116, 0x550, v116
	v_add3_u32 v123, v122, v123, s83
	v_lshl_add_u32 v122, v106, 1, v116
	ds_write_b16_d16_hi v122, v123
	v_add3_u32 v123, s88, v96, 25
	s_and_b64 vcc, exec, s[6:7]
	v_cmp_lt_i32_e64 s[36:37], s81, v123
	s_cbranch_vccz .Lsg_462

; __device__ __forceinline__ float sigmf(float x) { return 1.f / (1.f + __expf(-x)); }
; __device__ __forceinline__ void inproj_epilogue(const Params& p, int layer, int mt, int ntile, int tid,
;                                                 f32x16 (&acc)[2][2], unsigned char* smem) {
;     ...
;     acc_foreach(tid, acc, [&](int row, int col, float v) {
;       int t = m0 + row;
;       float o = v;
;       if (mode == 1) o = (t >= NPADR) ? v : 0.f;
;       if (mode == 2) o = sigmf(v);
;       sT[row * 136 + col] = f2bf(o);
;     });
.LBB0_3409:
	v_bfe_u32 v124, v123, 16, 1
	v_add_u32_e32 v116, 0x110, v116
	v_add3_u32 v124, v123, v124, s83
	v_lshl_add_u32 v123, v106, 1, v116
	ds_write_b16_d16_hi v123, v124
	v_add3_u32 v124, s88, v96, 26
	s_and_b64 vcc, exec, s[6:7]
	v_cmp_lt_i32_e64 s[38:39], s81, v124
	s_cbranch_vccz .Lsg_463

; __device__ __forceinline__ float sigmf(float x) { return 1.f / (1.f + __expf(-x)); }
; __device__ __forceinline__ void inproj_epilogue(const Params& p, int layer, int mt, int ntile, int tid,
;                                                 f32x16 (&acc)[2][2], unsigned char* smem) {
;     ...
;     acc_foreach(tid, acc, [&](int row, int col, float v) {
;       int t = m0 + row;
;       float o = v;
;       if (mode == 1) o = (t >= NPADR) ? v : 0.f;
;       if (mode == 2) o = sigmf(v);
;       sT[row * 136 + col] = f2bf(o);
;     });
.LBB0_3412:
	v_bfe_u32 v125, v124, 16, 1
	v_add_u32_e32 v116, 0x110, v116
	v_add3_u32 v124, v124, v125, s83
	v_lshl_add_u32 v116, v106, 1, v116
	ds_write_b16_d16_hi v116, v124
	v_add3_u32 v124, s88, v96, 27
	s_and_b64 vcc, exec, s[6:7]
	v_cmp_lt_i32_e64 s[40:41], s81, v124
	s_cbranch_vccz .Lsg_464

; __device__ __forceinline__ float sigmf(float x) { return 1.f / (1.f + __expf(-x)); }
; __device__ __forceinline__ void inproj_epilogue(const Params& p, int layer, int mt, int ntile, int tid,
;                                                 f32x16 (&acc)[2][2], unsigned char* smem) {
;     ...
;     acc_foreach(tid, acc, [&](int row, int col, float v) {
;       int t = m0 + row;
;       float o = v;
;       if (mode == 1) o = (t >= NPADR) ? v : 0.f;
;       if (mode == 2) o = sigmf(v);
;       sT[row * 136 + col] = f2bf(o);
;     });
.LBB0_3415:
	v_bfe_u32 v125, v124, 16, 1
	v_add3_u32 v124, v124, v125, s83
	ds_write_b16_d16_hi v116, v124 offset:272
	s_and_b64 vcc, exec, s[6:7]
	s_cbranch_vccz .Lsg_465

; __device__ __forceinline__ float sigmf(float x) { return 1.f / (1.f + __expf(-x)); }
; __device__ __forceinline__ void inproj_epilogue(const Params& p, int layer, int mt, int ntile, int tid,
;                                                 f32x16 (&acc)[2][2], unsigned char* smem) {
;     ...
;     acc_foreach(tid, acc, [&](int row, int col, float v) {
;       int t = m0 + row;
;       float o = v;
;       if (mode == 1) o = (t >= NPADR) ? v : 0.f;
;       if (mode == 2) o = sigmf(v);
;       sT[row * 136 + col] = f2bf(o);
;     });
.LBB0_3418:
	v_bfe_u32 v124, v48, 16, 1
	v_add3_u32 v48, v48, v124, s83
	s_and_b64 vcc, exec, s[6:7]
	ds_write_b16_d16_hi v107, v48 offset:64
	s_cbranch_vccz .Lsg_466

; __device__ __forceinline__ float sigmf(float x) { return 1.f / (1.f + __expf(-x)); }
; __device__ __forceinline__ void inproj_epilogue(const Params& p, int layer, int mt, int ntile, int tid,
;                                                 f32x16 (&acc)[2][2], unsigned char* smem) {
;     ...
;     acc_foreach(tid, acc, [&](int row, int col, float v) {
;       int t = m0 + row;
;       float o = v;
;       if (mode == 1) o = (t >= NPADR) ? v : 0.f;
;       if (mode == 2) o = sigmf(v);
;       sT[row * 136 + col] = f2bf(o);
;     });
.LBB0_3421:
	v_bfe_u32 v49, v48, 16, 1
	v_add3_u32 v48, v48, v49, s83
	s_and_b64 vcc, exec, s[6:7]
	ds_write_b16_d16_hi v110, v48 offset:64
	s_cbranch_vccz .Lsg_467

; __device__ __forceinline__ float sigmf(float x) { return 1.f / (1.f + __expf(-x)); }
; __device__ __forceinline__ void inproj_epilogue(const Params& p, int layer, int mt, int ntile, int tid,
;                                                 f32x16 (&acc)[2][2], unsigned char* smem) {
;     ...
;     acc_foreach(tid, acc, [&](int row, int col, float v) {
;       int t = m0 + row;
;       float o = v;
;       if (mode == 1) o = (t >= NPADR) ? v : 0.f;
;       if (mode == 2) o = sigmf(v);
;       sT[row * 136 + col] = f2bf(o);
;     });
.LBB0_3424:
	v_bfe_u32 v49, v48, 16, 1
	v_add3_u32 v48, v48, v49, s83
	s_and_b64 vcc, exec, s[6:7]
	ds_write_b16_d16_hi v111, v48 offset:64
	s_cbranch_vccz .Lsg_468

; __device__ __forceinline__ float sigmf(float x) { return 1.f / (1.f + __expf(-x)); }
; __device__ __forceinline__ void inproj_epilogue(const Params& p, int layer, int mt, int ntile, int tid,
;                                                 f32x16 (&acc)[2][2], unsigned char* smem) {
;     ...
;     acc_foreach(tid, acc, [&](int row, int col, float v) {
;       int t = m0 + row;
;       float o = v;
;       if (mode == 1) o = (t >= NPADR) ? v : 0.f;
;       if (mode == 2) o = sigmf(v);
;       sT[row * 136 + col] = f2bf(o);
;     });
.LBB0_3427:
	v_bfe_u32 v49, v48, 16, 1
	v_add3_u32 v48, v48, v49, s83
	s_and_b64 vcc, exec, s[6:7]
	ds_write_b16_d16_hi v112, v48 offset:64
	s_cbranch_vccz .Lsg_469

; __device__ __forceinline__ float sigmf(float x) { return 1.f / (1.f + __expf(-x)); }
; __device__ __forceinline__ void inproj_epilogue(const Params& p, int layer, int mt, int ntile, int tid,
;                                                 f32x16 (&acc)[2][2], unsigned char* smem) {
;     ...
;     acc_foreach(tid, acc, [&](int row, int col, float v) {
;       int t = m0 + row;
;       float o = v;
;       if (mode == 1) o = (t >= NPADR) ? v : 0.f;
;       if (mode == 2) o = sigmf(v);
;       sT[row * 136 + col] = f2bf(o);
;     });
.LBB0_3430:
	v_bfe_u32 v49, v48, 16, 1
	v_add3_u32 v48, v48, v49, s83
	s_and_b64 vcc, exec, s[6:7]
	ds_write_b16_d16_hi v113, v48 offset:64
	s_cbranch_vccz .Lsg_470

; __device__ __forceinline__ float sigmf(float x) { return 1.f / (1.f + __expf(-x)); }
; __device__ __forceinline__ void inproj_epilogue(const Params& p, int layer, int mt, int ntile, int tid,
;                                                 f32x16 (&acc)[2][2], unsigned char* smem) {
;     ...
;     acc_foreach(tid, acc, [&](int row, int col, float v) {
;       int t = m0 + row;
;       float o = v;
;       if (mode == 1) o = (t >= NPADR) ? v : 0.f;
;       if (mode == 2) o = sigmf(v);
;       sT[row * 136 + col] = f2bf(o);
;     });
.LBB0_3433:
	v_bfe_u32 v49, v48, 16, 1
	v_add3_u32 v48, v48, v49, s83
	s_and_b64 vcc, exec, s[6:7]
	ds_write_b16_d16_hi v114, v48 offset:64
	s_cbranch_vccz .Lsg_471

; __device__ __forceinline__ float sigmf(float x) { return 1.f / (1.f + __expf(-x)); }
; __device__ __forceinline__ void inproj_epilogue(const Params& p, int layer, int mt, int ntile, int tid,
;                                                 f32x16 (&acc)[2][2], unsigned char* smem) {
;     ...
;     acc_foreach(tid, acc, [&](int row, int col, float v) {
;       int t = m0 + row;
;       float o = v;
;       if (mode == 1) o = (t >= NPADR) ? v : 0.f;
;       if (mode == 2) o = sigmf(v);
;       sT[row * 136 + col] = f2bf(o);
;     });
.LBB0_3436:
	v_bfe_u32 v49, v48, 16, 1
	v_add3_u32 v48, v48, v49, s83
	s_and_b64 vcc, exec, s[6:7]
	ds_write_b16_d16_hi v115, v48 offset:64
	s_cbranch_vccz .Lsg_472

; __device__ __forceinline__ float sigmf(float x) { return 1.f / (1.f + __expf(-x)); }
; __device__ __forceinline__ void inproj_epilogue(const Params& p, int layer, int mt, int ntile, int tid,
;                                                 f32x16 (&acc)[2][2], unsigned char* smem) {
;     ...
;     acc_foreach(tid, acc, [&](int row, int col, float v) {
;       int t = m0 + row;
;       float o = v;
;       if (mode == 1) o = (t >= NPADR) ? v : 0.f;
;       if (mode == 2) o = sigmf(v);
;       sT[row * 136 + col] = f2bf(o);
;     });
.LBB0_3439:
	v_bfe_u32 v49, v48, 16, 1
	v_add3_u32 v48, v48, v49, s83
	s_and_b64 vcc, exec, s[6:7]
	ds_write_b16_d16_hi v117, v48 offset:64
	s_cbranch_vccz .Lsg_473

; __device__ __forceinline__ float sigmf(float x) { return 1.f / (1.f + __expf(-x)); }
; __device__ __forceinline__ void inproj_epilogue(const Params& p, int layer, int mt, int ntile, int tid,
;                                                 f32x16 (&acc)[2][2], unsigned char* smem) {
;     ...
;     acc_foreach(tid, acc, [&](int row, int col, float v) {
;       int t = m0 + row;
;       float o = v;
;       if (mode == 1) o = (t >= NPADR) ? v : 0.f;
;       if (mode == 2) o = sigmf(v);
;       sT[row * 136 + col] = f2bf(o);
;     });
.LBB0_3442:
	v_bfe_u32 v49, v48, 16, 1
	v_add3_u32 v48, v48, v49, s83
	s_and_b64 vcc, exec, s[6:7]
	ds_write_b16_d16_hi v118, v48 offset:64
	s_cbranch_vccz .Lsg_474

; __device__ __forceinline__ float sigmf(float x) { return 1.f / (1.f + __expf(-x)); }
; __device__ __forceinline__ void inproj_epilogue(const Params& p, int layer, int mt, int ntile, int tid,
;                                                 f32x16 (&acc)[2][2], unsigned char* smem) {
;     ...
;     acc_foreach(tid, acc, [&](int row, int col, float v) {
;       int t = m0 + row;
;       float o = v;
;       if (mode == 1) o = (t >= NPADR) ? v : 0.f;
;       if (mode == 2) o = sigmf(v);
;       sT[row * 136 + col] = f2bf(o);
;     });
.LBB0_3445:
	v_bfe_u32 v49, v48, 16, 1
	v_add3_u32 v48, v48, v49, s83
	s_and_b64 vcc, exec, s[6:7]
	ds_write_b16_d16_hi v119, v48 offset:64
	s_cbranch_vccz .Lsg_475

; __device__ __forceinline__ float sigmf(float x) { return 1.f / (1.f + __expf(-x)); }
; __device__ __forceinline__ void inproj_epilogue(const Params& p, int layer, int mt, int ntile, int tid,
;                                                 f32x16 (&acc)[2][2], unsigned char* smem) {
;     ...
;     acc_foreach(tid, acc, [&](int row, int col, float v) {
;       int t = m0 + row;
;       float o = v;
;       if (mode == 1) o = (t >= NPADR) ? v : 0.f;
;       if (mode == 2) o = sigmf(v);
;       sT[row * 136 + col] = f2bf(o);
;     });
.LBB0_3448:
	v_bfe_u32 v49, v48, 16, 1
	v_add3_u32 v48, v48, v49, s83
	s_and_b64 vcc, exec, s[6:7]
	ds_write_b16_d16_hi v120, v48 offset:64
	s_cbranch_vccz .Lsg_476

; __device__ __forceinline__ float sigmf(float x) { return 1.f / (1.f + __expf(-x)); }
; __device__ __forceinline__ void inproj_epilogue(const Params& p, int layer, int mt, int ntile, int tid,
;                                                 f32x16 (&acc)[2][2], unsigned char* smem) {
;     ...
;     acc_foreach(tid, acc, [&](int row, int col, float v) {
;       int t = m0 + row;
;       float o = v;
;       if (mode == 1) o = (t >= NPADR) ? v : 0.f;
;       if (mode == 2) o = sigmf(v);
;       sT[row * 136 + col] = f2bf(o);
;     });
.LBB0_3451:
	v_bfe_u32 v49, v48, 16, 1
	v_add3_u32 v48, v48, v49, s83
	s_and_b64 vcc, exec, s[6:7]
	ds_write_b16_d16_hi v121, v48 offset:64
	s_cbranch_vccz .Lsg_477

; __device__ __forceinline__ float sigmf(float x) { return 1.f / (1.f + __expf(-x)); }
; __device__ __forceinline__ void inproj_epilogue(const Params& p, int layer, int mt, int ntile, int tid,
;                                                 f32x16 (&acc)[2][2], unsigned char* smem) {
;     ...
;     acc_foreach(tid, acc, [&](int row, int col, float v) {
;       int t = m0 + row;
;       float o = v;
;       if (mode == 1) o = (t >= NPADR) ? v : 0.f;
;       if (mode == 2) o = sigmf(v);
;       sT[row * 136 + col] = f2bf(o);
;     });
.LBB0_3454:
	v_bfe_u32 v49, v48, 16, 1
	v_add3_u32 v48, v48, v49, s83
	s_and_b64 vcc, exec, s[6:7]
	ds_write_b16_d16_hi v122, v48 offset:64
	s_cbranch_vccz .Lsg_478

; __device__ __forceinline__ float sigmf(float x) { return 1.f / (1.f + __expf(-x)); }
; __device__ __forceinline__ void inproj_epilogue(const Params& p, int layer, int mt, int ntile, int tid,
;                                                 f32x16 (&acc)[2][2], unsigned char* smem) {
;     ...
;     acc_foreach(tid, acc, [&](int row, int col, float v) {
;       int t = m0 + row;
;       float o = v;
;       if (mode == 1) o = (t >= NPADR) ? v : 0.f;
;       if (mode == 2) o = sigmf(v);
;       sT[row * 136 + col] = f2bf(o);
;     });
.LBB0_3457:
	v_bfe_u32 v49, v48, 16, 1
	v_add3_u32 v48, v48, v49, s83
	s_and_b64 vcc, exec, s[6:7]
	ds_write_b16_d16_hi v123, v48 offset:64
	s_cbranch_vccz .Lsg_479

; __device__ __forceinline__ float sigmf(float x) { return 1.f / (1.f + __expf(-x)); }
; __device__ __forceinline__ void inproj_epilogue(const Params& p, int layer, int mt, int ntile, int tid,
;                                                 f32x16 (&acc)[2][2], unsigned char* smem) {
;     ...
;     acc_foreach(tid, acc, [&](int row, int col, float v) {
;       int t = m0 + row;
;       float o = v;
;       if (mode == 1) o = (t >= NPADR) ? v : 0.f;
;       if (mode == 2) o = sigmf(v);
;       sT[row * 136 + col] = f2bf(o);
;     });
.LBB0_3460:
	v_bfe_u32 v49, v48, 16, 1
	v_add3_u32 v48, v48, v49, s83
	s_and_b64 vcc, exec, s[6:7]
	ds_write_b16_d16_hi v116, v48 offset:64
	s_cbranch_vccz .Lsg_480

; __device__ __forceinline__ float sigmf(float x) { return 1.f / (1.f + __expf(-x)); }
; __device__ __forceinline__ void inproj_epilogue(const Params& p, int layer, int mt, int ntile, int tid,
;                                                 f32x16 (&acc)[2][2], unsigned char* smem) {
;     ...
;     acc_foreach(tid, acc, [&](int row, int col, float v) {
;       int t = m0 + row;
;       float o = v;
;       if (mode == 1) o = (t >= NPADR) ? v : 0.f;
;       if (mode == 2) o = sigmf(v);
;       sT[row * 136 + col] = f2bf(o);
;     });
.LBB0_3463:
	v_bfe_u32 v50, v48, 16, 1
	v_add_u32_e32 v49, 0x110, v116
	v_add3_u32 v48, v48, v50, s83
	ds_write_b16_d16_hi v49, v48 offset:64
	v_or_b32_e32 v48, 32, v96
	v_add_u32_e32 v49, s88, v48
	s_and_b64 vcc, exec, s[6:7]
	v_cmp_lt_i32_e64 s[8:9], s81, v49
	s_cbranch_vccz .Lsg_481

; __device__ __forceinline__ float sigmf(float x) { return 1.f / (1.f + __expf(-x)); }
; __device__ __forceinline__ void inproj_epilogue(const Params& p, int layer, int mt, int ntile, int tid,
;                                                 f32x16 (&acc)[2][2], unsigned char* smem) {
;     ...
;     acc_foreach(tid, acc, [&](int row, int col, float v) {
;       int t = m0 + row;
;       float o = v;
;       if (mode == 1) o = (t >= NPADR) ? v : 0.f;
;       if (mode == 2) o = sigmf(v);
;       sT[row * 136 + col] = f2bf(o);
;     });
.LBB0_3466:
	v_bfe_u32 v50, v49, 16, 1
	v_add3_u32 v50, v49, v50, s83
	v_mul_lo_u32 v49, v48, s90
	v_lshl_add_u32 v48, v106, 1, v49
	ds_write_b16_d16_hi v48, v50
	v_add3_u32 v50, s88, v96, 33
	s_and_b64 vcc, exec, s[6:7]
	v_cmp_lt_i32_e64 s[10:11], s81, v50
	s_cbranch_vccz .Lsg_482

; __device__ __forceinline__ float sigmf(float x) { return 1.f / (1.f + __expf(-x)); }
; __device__ __forceinline__ void inproj_epilogue(const Params& p, int layer, int mt, int ntile, int tid,
;                                                 f32x16 (&acc)[2][2], unsigned char* smem) {
;     ...
;     acc_foreach(tid, acc, [&](int row, int col, float v) {
;       int t = m0 + row;
;       float o = v;
;       if (mode == 1) o = (t >= NPADR) ? v : 0.f;
;       if (mode == 2) o = sigmf(v);
;       sT[row * 136 + col] = f2bf(o);
;     });
.LBB0_3469:
	v_bfe_u32 v51, v50, 16, 1
	v_add3_u32 v51, v50, v51, s83
	v_add_u32_e32 v50, 0x110, v49
	v_lshl_add_u32 v49, v106, 1, v50
	ds_write_b16_d16_hi v49, v51
	v_add3_u32 v51, s88, v96, 34
	s_and_b64 vcc, exec, s[6:7]
	v_cmp_lt_i32_e64 s[12:13], s81, v51
	s_cbranch_vccz .Lsg_483

; __device__ __forceinline__ float sigmf(float x) { return 1.f / (1.f + __expf(-x)); }
; __device__ __forceinline__ void inproj_epilogue(const Params& p, int layer, int mt, int ntile, int tid,
;                                                 f32x16 (&acc)[2][2], unsigned char* smem) {
;     ...
;     acc_foreach(tid, acc, [&](int row, int col, float v) {
;       int t = m0 + row;
;       float o = v;
;       if (mode == 1) o = (t >= NPADR) ? v : 0.f;
;       if (mode == 2) o = sigmf(v);
;       sT[row * 136 + col] = f2bf(o);
;     });
.LBB0_3472:
	v_bfe_u32 v52, v51, 16, 1
	v_add3_u32 v52, v51, v52, s83
	v_add_u32_e32 v51, 0x110, v50
	v_lshl_add_u32 v50, v106, 1, v51
	ds_write_b16_d16_hi v50, v52
	v_add3_u32 v52, s88, v96, 35
	s_and_b64 vcc, exec, s[6:7]
	v_cmp_lt_i32_e64 s[14:15], s81, v52
	s_cbranch_vccz .Lsg_484

; __device__ __forceinline__ float sigmf(float x) { return 1.f / (1.f + __expf(-x)); }
; __device__ __forceinline__ void inproj_epilogue(const Params& p, int layer, int mt, int ntile, int tid,
;                                                 f32x16 (&acc)[2][2], unsigned char* smem) {
;     ...
;     acc_foreach(tid, acc, [&](int row, int col, float v) {
;       int t = m0 + row;
;       float o = v;
;       if (mode == 1) o = (t >= NPADR) ? v : 0.f;
;       if (mode == 2) o = sigmf(v);
;       sT[row * 136 + col] = f2bf(o);
;     });
.LBB0_3475:
	v_bfe_u32 v53, v52, 16, 1
	v_add3_u32 v53, v52, v53, s83
	v_add_u32_e32 v52, 0x110, v51
	v_lshl_add_u32 v51, v106, 1, v52
	ds_write_b16_d16_hi v51, v53
	v_add3_u32 v53, s88, v96, 40
	s_and_b64 vcc, exec, s[6:7]
	v_cmp_lt_i32_e64 s[16:17], s81, v53
	s_cbranch_vccz .Lsg_485

; __device__ __forceinline__ float sigmf(float x) { return 1.f / (1.f + __expf(-x)); }
; __device__ __forceinline__ void inproj_epilogue(const Params& p, int layer, int mt, int ntile, int tid,
;                                                 f32x16 (&acc)[2][2], unsigned char* smem) {
;     ...
;     acc_foreach(tid, acc, [&](int row, int col, float v) {
;       int t = m0 + row;
;       float o = v;
;       if (mode == 1) o = (t >= NPADR) ? v : 0.f;
;       if (mode == 2) o = sigmf(v);
;       sT[row * 136 + col] = f2bf(o);
;     });
.LBB0_3478:
	v_bfe_u32 v54, v53, 16, 1
	v_add3_u32 v54, v53, v54, s83
	v_add_u32_e32 v53, 0x550, v52
	v_lshl_add_u32 v52, v106, 1, v53
	ds_write_b16_d16_hi v52, v54
	v_add3_u32 v54, s88, v96, 41
	s_and_b64 vcc, exec, s[6:7]
	v_cmp_lt_i32_e64 s[18:19], s81, v54
	s_cbranch_vccz .Lsg_486

; __device__ __forceinline__ float sigmf(float x) { return 1.f / (1.f + __expf(-x)); }
; __device__ __forceinline__ void inproj_epilogue(const Params& p, int layer, int mt, int ntile, int tid,
;                                                 f32x16 (&acc)[2][2], unsigned char* smem) {
;     ...
;     acc_foreach(tid, acc, [&](int row, int col, float v) {
;       int t = m0 + row;
;       float o = v;
;       if (mode == 1) o = (t >= NPADR) ? v : 0.f;
;       if (mode == 2) o = sigmf(v);
;       sT[row * 136 + col] = f2bf(o);
;     });
.LBB0_3481:
	v_bfe_u32 v55, v54, 16, 1
	v_add3_u32 v55, v54, v55, s83
	v_add_u32_e32 v54, 0x110, v53
	v_lshl_add_u32 v53, v106, 1, v54
	ds_write_b16_d16_hi v53, v55
	v_add3_u32 v55, s88, v96, 42
	s_and_b64 vcc, exec, s[6:7]
	v_cmp_lt_i32_e64 s[20:21], s81, v55
	s_cbranch_vccz .Lsg_487

; __device__ __forceinline__ float sigmf(float x) { return 1.f / (1.f + __expf(-x)); }
; __device__ __forceinline__ void inproj_epilogue(const Params& p, int layer, int mt, int ntile, int tid,
;                                                 f32x16 (&acc)[2][2], unsigned char* smem) {
;     ...
;     acc_foreach(tid, acc, [&](int row, int col, float v) {
;       int t = m0 + row;
;       float o = v;
;       if (mode == 1) o = (t >= NPADR) ? v : 0.f;
;       if (mode == 2) o = sigmf(v);
;       sT[row * 136 + col] = f2bf(o);
;     });
.LBB0_3484:
	v_bfe_u32 v56, v55, 16, 1
	v_add3_u32 v56, v55, v56, s83
	v_add_u32_e32 v55, 0x110, v54
	v_lshl_add_u32 v54, v106, 1, v55
	ds_write_b16_d16_hi v54, v56
	v_add3_u32 v56, s88, v96, 43
	s_and_b64 vcc, exec, s[6:7]
	v_cmp_lt_i32_e64 s[22:23], s81, v56
	s_cbranch_vccz .Lsg_488

; __device__ __forceinline__ float sigmf(float x) { return 1.f / (1.f + __expf(-x)); }
; __device__ __forceinline__ void inproj_epilogue(const Params& p, int layer, int mt, int ntile, int tid,
;                                                 f32x16 (&acc)[2][2], unsigned char* smem) {
;     ...
;     acc_foreach(tid, acc, [&](int row, int col, float v) {
;       int t = m0 + row;
;       float o = v;
;       if (mode == 1) o = (t >= NPADR) ? v : 0.f;
;       if (mode == 2) o = sigmf(v);
;       sT[row * 136 + col] = f2bf(o);
;     });
.LBB0_3487:
	v_bfe_u32 v57, v56, 16, 1
	v_add_u32_e32 v55, 0x110, v55
	v_add3_u32 v57, v56, v57, s83
	v_lshl_add_u32 v56, v106, 1, v55
	ds_write_b16_d16_hi v56, v57
	v_add3_u32 v57, s88, v96, 48
	s_and_b64 vcc, exec, s[6:7]
	v_cmp_lt_i32_e64 s[24:25], s81, v57
	s_cbranch_vccz .Lsg_489

; __device__ __forceinline__ float sigmf(float x) { return 1.f / (1.f + __expf(-x)); }
; __device__ __forceinline__ void inproj_epilogue(const Params& p, int layer, int mt, int ntile, int tid,
;                                                 f32x16 (&acc)[2][2], unsigned char* smem) {
;     ...
;     acc_foreach(tid, acc, [&](int row, int col, float v) {
;       int t = m0 + row;
;       float o = v;
;       if (mode == 1) o = (t >= NPADR) ? v : 0.f;
;       if (mode == 2) o = sigmf(v);
;       sT[row * 136 + col] = f2bf(o);
;     });
.LBB0_3490:
	v_bfe_u32 v58, v57, 16, 1
	v_add_u32_e32 v55, 0x550, v55
	v_add3_u32 v58, v57, v58, s83
	v_lshl_add_u32 v57, v106, 1, v55
	ds_write_b16_d16_hi v57, v58
	v_add3_u32 v58, s88, v96, 49
	s_and_b64 vcc, exec, s[6:7]
	v_cmp_lt_i32_e64 s[26:27], s81, v58
	s_cbranch_vccz .Lsg_490

; __device__ __forceinline__ float sigmf(float x) { return 1.f / (1.f + __expf(-x)); }
; __device__ __forceinline__ void inproj_epilogue(const Params& p, int layer, int mt, int ntile, int tid,
;                                                 f32x16 (&acc)[2][2], unsigned char* smem) {
;     ...
;     acc_foreach(tid, acc, [&](int row, int col, float v) {
;       int t = m0 + row;
;       float o = v;
;       if (mode == 1) o = (t >= NPADR) ? v : 0.f;
;       if (mode == 2) o = sigmf(v);
;       sT[row * 136 + col] = f2bf(o);
;     });
.LBB0_3493:
	v_bfe_u32 v59, v58, 16, 1
	v_add_u32_e32 v55, 0x110, v55
	v_add3_u32 v59, v58, v59, s83
	v_lshl_add_u32 v58, v106, 1, v55
	ds_write_b16_d16_hi v58, v59
	v_add3_u32 v59, s88, v96, 50
	s_and_b64 vcc, exec, s[6:7]
	v_cmp_lt_i32_e64 s[28:29], s81, v59
	s_cbranch_vccz .Lsg_491

; __device__ __forceinline__ float sigmf(float x) { return 1.f / (1.f + __expf(-x)); }
; __device__ __forceinline__ void inproj_epilogue(const Params& p, int layer, int mt, int ntile, int tid,
;                                                 f32x16 (&acc)[2][2], unsigned char* smem) {
;     ...
;     acc_foreach(tid, acc, [&](int row, int col, float v) {
;       int t = m0 + row;
;       float o = v;
;       if (mode == 1) o = (t >= NPADR) ? v : 0.f;
;       if (mode == 2) o = sigmf(v);
;       sT[row * 136 + col] = f2bf(o);
;     });
.LBB0_3496:
	v_bfe_u32 v60, v59, 16, 1
	v_add_u32_e32 v55, 0x110, v55
	v_add3_u32 v60, v59, v60, s83
	v_lshl_add_u32 v59, v106, 1, v55
	ds_write_b16_d16_hi v59, v60
	v_add3_u32 v60, s88, v96, 51
	s_and_b64 vcc, exec, s[6:7]
	v_cmp_lt_i32_e64 s[30:31], s81, v60
	s_cbranch_vccz .Lsg_492

; __device__ __forceinline__ float sigmf(float x) { return 1.f / (1.f + __expf(-x)); }
; __device__ __forceinline__ void inproj_epilogue(const Params& p, int layer, int mt, int ntile, int tid,
;                                                 f32x16 (&acc)[2][2], unsigned char* smem) {
;     ...
;     acc_foreach(tid, acc, [&](int row, int col, float v) {
;       int t = m0 + row;
;       float o = v;
;       if (mode == 1) o = (t >= NPADR) ? v : 0.f;
;       if (mode == 2) o = sigmf(v);
;       sT[row * 136 + col] = f2bf(o);
;     });
.LBB0_3499:
	v_bfe_u32 v61, v60, 16, 1
	v_add_u32_e32 v55, 0x110, v55
	v_add3_u32 v61, v60, v61, s83
	v_lshl_add_u32 v60, v106, 1, v55
	ds_write_b16_d16_hi v60, v61
	v_add3_u32 v61, s88, v96, 56
	s_and_b64 vcc, exec, s[6:7]
	v_cmp_lt_i32_e64 s[34:35], s81, v61
	s_cbranch_vccz .Lsg_493

; __device__ __forceinline__ float sigmf(float x) { return 1.f / (1.f + __expf(-x)); }
; __device__ __forceinline__ void inproj_epilogue(const Params& p, int layer, int mt, int ntile, int tid,
;                                                 f32x16 (&acc)[2][2], unsigned char* smem) {
;     ...
;     acc_foreach(tid, acc, [&](int row, int col, float v) {
;       int t = m0 + row;
;       float o = v;
;       if (mode == 1) o = (t >= NPADR) ? v : 0.f;
;       if (mode == 2) o = sigmf(v);
;       sT[row * 136 + col] = f2bf(o);
;     });
.LBB0_3502:
	v_bfe_u32 v62, v61, 16, 1
	v_add_u32_e32 v55, 0x550, v55
	v_add3_u32 v62, v61, v62, s83
	v_lshl_add_u32 v61, v106, 1, v55
	ds_write_b16_d16_hi v61, v62
	v_add3_u32 v62, s88, v96, 57
	s_and_b64 vcc, exec, s[6:7]
	v_cmp_lt_i32_e64 s[36:37], s81, v62
	s_cbranch_vccz .Lsg_494

; __device__ __forceinline__ float sigmf(float x) { return 1.f / (1.f + __expf(-x)); }
; __device__ __forceinline__ void inproj_epilogue(const Params& p, int layer, int mt, int ntile, int tid,
;                                                 f32x16 (&acc)[2][2], unsigned char* smem) {
;     ...
;     acc_foreach(tid, acc, [&](int row, int col, float v) {
;       int t = m0 + row;
;       float o = v;
;       if (mode == 1) o = (t >= NPADR) ? v : 0.f;
;       if (mode == 2) o = sigmf(v);
;       sT[row * 136 + col] = f2bf(o);
;     });
.LBB0_3505:
	v_bfe_u32 v63, v62, 16, 1
	v_add_u32_e32 v55, 0x110, v55
	v_add3_u32 v63, v62, v63, s83
	v_lshl_add_u32 v62, v106, 1, v55
	ds_write_b16_d16_hi v62, v63
	v_add3_u32 v63, s88, v96, 58
	s_and_b64 vcc, exec, s[6:7]
	v_cmp_lt_i32_e64 s[38:39], s81, v63
	s_cbranch_vccz .Lsg_495

; __device__ __forceinline__ float sigmf(float x) { return 1.f / (1.f + __expf(-x)); }
; __device__ __forceinline__ void inproj_epilogue(const Params& p, int layer, int mt, int ntile, int tid,
;                                                 f32x16 (&acc)[2][2], unsigned char* smem) {
;     ...
;     acc_foreach(tid, acc, [&](int row, int col, float v) {
;       int t = m0 + row;
;       float o = v;
;       if (mode == 1) o = (t >= NPADR) ? v : 0.f;
;       if (mode == 2) o = sigmf(v);
;       sT[row * 136 + col] = f2bf(o);
;     });
.LBB0_3508:
	v_bfe_u32 v107, v63, 16, 1
	v_add_u32_e32 v55, 0x110, v55
	v_add3_u32 v63, v63, v107, s83
	v_lshl_add_u32 v55, v106, 1, v55
	ds_write_b16_d16_hi v55, v63
	v_add3_u32 v63, s88, v96, 59
	s_and_b64 vcc, exec, s[6:7]
	v_cmp_lt_i32_e64 s[40:41], s81, v63
	s_cbranch_vccz .Lsg_496

; __device__ __forceinline__ float sigmf(float x) { return 1.f / (1.f + __expf(-x)); }
; __device__ __forceinline__ void inproj_epilogue(const Params& p, int layer, int mt, int ntile, int tid,
;                                                 f32x16 (&acc)[2][2], unsigned char* smem) {
;     ...
;     acc_foreach(tid, acc, [&](int row, int col, float v) {
;       int t = m0 + row;
;       float o = v;
;       if (mode == 1) o = (t >= NPADR) ? v : 0.f;
;       if (mode == 2) o = sigmf(v);
;       sT[row * 136 + col] = f2bf(o);
;     });
.LBB0_3511:
	v_bfe_u32 v96, v63, 16, 1
	v_add3_u32 v63, v63, v96, s83
	ds_write_b16_d16_hi v55, v63 offset:272
	s_and_b64 vcc, exec, s[6:7]
	s_cbranch_vccz .Lsg_497

; __device__ __forceinline__ float sigmf(float x) { return 1.f / (1.f + __expf(-x)); }
; __device__ __forceinline__ void inproj_epilogue(const Params& p, int layer, int mt, int ntile, int tid,
;                                                 f32x16 (&acc)[2][2], unsigned char* smem) {
;     ...
;     acc_foreach(tid, acc, [&](int row, int col, float v) {
;       int t = m0 + row;
;       float o = v;
;       if (mode == 1) o = (t >= NPADR) ? v : 0.f;
;       if (mode == 2) o = sigmf(v);
;       sT[row * 136 + col] = f2bf(o);
;     });
.LBB0_3514:
	v_bfe_u32 v63, v32, 16, 1
	v_add3_u32 v32, v32, v63, s83
	s_and_b64 vcc, exec, s[6:7]
	ds_write_b16_d16_hi v48, v32 offset:64
	s_cbranch_vccz .Lsg_498

; __device__ __forceinline__ float sigmf(float x) { return 1.f / (1.f + __expf(-x)); }
; __device__ __forceinline__ void inproj_epilogue(const Params& p, int layer, int mt, int ntile, int tid,
;                                                 f32x16 (&acc)[2][2], unsigned char* smem) {
;     ...
;     acc_foreach(tid, acc, [&](int row, int col, float v) {
;       int t = m0 + row;
;       float o = v;
;       if (mode == 1) o = (t >= NPADR) ? v : 0.f;
;       if (mode == 2) o = sigmf(v);
;       sT[row * 136 + col] = f2bf(o);
;     });
.LBB0_3517:
	v_bfe_u32 v33, v32, 16, 1
	v_add3_u32 v32, v32, v33, s83
	s_and_b64 vcc, exec, s[6:7]
	ds_write_b16_d16_hi v49, v32 offset:64
	s_cbranch_vccz .Lsg_499

; __device__ __forceinline__ float sigmf(float x) { return 1.f / (1.f + __expf(-x)); }
; __device__ __forceinline__ void inproj_epilogue(const Params& p, int layer, int mt, int ntile, int tid,
;                                                 f32x16 (&acc)[2][2], unsigned char* smem) {
;     ...
;     acc_foreach(tid, acc, [&](int row, int col, float v) {
;       int t = m0 + row;
;       float o = v;
;       if (mode == 1) o = (t >= NPADR) ? v : 0.f;
;       if (mode == 2) o = sigmf(v);
;       sT[row * 136 + col] = f2bf(o);
;     });
.LBB0_3520:
	v_bfe_u32 v33, v32, 16, 1
	v_add3_u32 v32, v32, v33, s83
	s_and_b64 vcc, exec, s[6:7]
	ds_write_b16_d16_hi v50, v32 offset:64
	s_cbranch_vccz .Lsg_500

; __device__ __forceinline__ float sigmf(float x) { return 1.f / (1.f + __expf(-x)); }
; __device__ __forceinline__ void inproj_epilogue(const Params& p, int layer, int mt, int ntile, int tid,
;                                                 f32x16 (&acc)[2][2], unsigned char* smem) {
;     ...
;     acc_foreach(tid, acc, [&](int row, int col, float v) {
;       int t = m0 + row;
;       float o = v;
;       if (mode == 1) o = (t >= NPADR) ? v : 0.f;
;       if (mode == 2) o = sigmf(v);
;       sT[row * 136 + col] = f2bf(o);
;     });
.LBB0_3523:
	v_bfe_u32 v33, v32, 16, 1
	v_add3_u32 v32, v32, v33, s83
	s_and_b64 vcc, exec, s[6:7]
	ds_write_b16_d16_hi v51, v32 offset:64
	s_cbranch_vccz .Lsg_501

; __device__ __forceinline__ float sigmf(float x) { return 1.f / (1.f + __expf(-x)); }
; __device__ __forceinline__ void inproj_epilogue(const Params& p, int layer, int mt, int ntile, int tid,
;                                                 f32x16 (&acc)[2][2], unsigned char* smem) {
;     ...
;     acc_foreach(tid, acc, [&](int row, int col, float v) {
;       int t = m0 + row;
;       float o = v;
;       if (mode == 1) o = (t >= NPADR) ? v : 0.f;
;       if (mode == 2) o = sigmf(v);
;       sT[row * 136 + col] = f2bf(o);
;     });
.LBB0_3526:
	v_bfe_u32 v33, v32, 16, 1
	v_add3_u32 v32, v32, v33, s83
	s_and_b64 vcc, exec, s[6:7]
	ds_write_b16_d16_hi v52, v32 offset:64
	s_cbranch_vccz .Lsg_502

; __device__ __forceinline__ float sigmf(float x) { return 1.f / (1.f + __expf(-x)); }
; __device__ __forceinline__ void inproj_epilogue(const Params& p, int layer, int mt, int ntile, int tid,
;                                                 f32x16 (&acc)[2][2], unsigned char* smem) {
;     ...
;     acc_foreach(tid, acc, [&](int row, int col, float v) {
;       int t = m0 + row;
;       float o = v;
;       if (mode == 1) o = (t >= NPADR) ? v : 0.f;
;       if (mode == 2) o = sigmf(v);
;       sT[row * 136 + col] = f2bf(o);
;     });
.LBB0_3529:
	v_bfe_u32 v33, v32, 16, 1
	v_add3_u32 v32, v32, v33, s83
	s_and_b64 vcc, exec, s[6:7]
	ds_write_b16_d16_hi v53, v32 offset:64
	s_cbranch_vccz .Lsg_503

; __device__ __forceinline__ float sigmf(float x) { return 1.f / (1.f + __expf(-x)); }
; __device__ __forceinline__ void inproj_epilogue(const Params& p, int layer, int mt, int ntile, int tid,
;                                                 f32x16 (&acc)[2][2], unsigned char* smem) {
;     ...
;     acc_foreach(tid, acc, [&](int row, int col, float v) {
;       int t = m0 + row;
;       float o = v;
;       if (mode == 1) o = (t >= NPADR) ? v : 0.f;
;       if (mode == 2) o = sigmf(v);
;       sT[row * 136 + col] = f2bf(o);
;     });
.LBB0_3532:
	v_bfe_u32 v33, v32, 16, 1
	v_add3_u32 v32, v32, v33, s83
	s_and_b64 vcc, exec, s[6:7]
	ds_write_b16_d16_hi v54, v32 offset:64
	s_cbranch_vccz .Lsg_504

; __device__ __forceinline__ float sigmf(float x) { return 1.f / (1.f + __expf(-x)); }
; __device__ __forceinline__ void inproj_epilogue(const Params& p, int layer, int mt, int ntile, int tid,
;                                                 f32x16 (&acc)[2][2], unsigned char* smem) {
;     ...
;     acc_foreach(tid, acc, [&](int row, int col, float v) {
;       int t = m0 + row;
;       float o = v;
;       if (mode == 1) o = (t >= NPADR) ? v : 0.f;
;       if (mode == 2) o = sigmf(v);
;       sT[row * 136 + col] = f2bf(o);
;     });
.LBB0_3535:
	v_bfe_u32 v33, v32, 16, 1
	v_add3_u32 v32, v32, v33, s83
	s_and_b64 vcc, exec, s[6:7]
	ds_write_b16_d16_hi v56, v32 offset:64
	s_cbranch_vccz .Lsg_505

; __device__ __forceinline__ float sigmf(float x) { return 1.f / (1.f + __expf(-x)); }
; __device__ __forceinline__ void inproj_epilogue(const Params& p, int layer, int mt, int ntile, int tid,
;                                                 f32x16 (&acc)[2][2], unsigned char* smem) {
;     ...
;     acc_foreach(tid, acc, [&](int row, int col, float v) {
;       int t = m0 + row;
;       float o = v;
;       if (mode == 1) o = (t >= NPADR) ? v : 0.f;
;       if (mode == 2) o = sigmf(v);
;       sT[row * 136 + col] = f2bf(o);
;     });
.LBB0_3538:
	v_bfe_u32 v33, v32, 16, 1
	v_add3_u32 v32, v32, v33, s83
	s_and_b64 vcc, exec, s[6:7]
	ds_write_b16_d16_hi v57, v32 offset:64
	s_cbranch_vccz .Lsg_506

; __device__ __forceinline__ float sigmf(float x) { return 1.f / (1.f + __expf(-x)); }
; __device__ __forceinline__ void inproj_epilogue(const Params& p, int layer, int mt, int ntile, int tid,
;                                                 f32x16 (&acc)[2][2], unsigned char* smem) {
;     ...
;     acc_foreach(tid, acc, [&](int row, int col, float v) {
;       int t = m0 + row;
;       float o = v;
;       if (mode == 1) o = (t >= NPADR) ? v : 0.f;
;       if (mode == 2) o = sigmf(v);
;       sT[row * 136 + col] = f2bf(o);
;     });
.LBB0_3541:
	v_bfe_u32 v33, v32, 16, 1
	v_add3_u32 v32, v32, v33, s83
	s_and_b64 vcc, exec, s[6:7]
	ds_write_b16_d16_hi v58, v32 offset:64
	s_cbranch_vccz .Lsg_507

; __device__ __forceinline__ float sigmf(float x) { return 1.f / (1.f + __expf(-x)); }
; __device__ __forceinline__ void inproj_epilogue(const Params& p, int layer, int mt, int ntile, int tid,
;                                                 f32x16 (&acc)[2][2], unsigned char* smem) {
;     ...
;     acc_foreach(tid, acc, [&](int row, int col, float v) {
;       int t = m0 + row;
;       float o = v;
;       if (mode == 1) o = (t >= NPADR) ? v : 0.f;
;       if (mode == 2) o = sigmf(v);
;       sT[row * 136 + col] = f2bf(o);
;     });
.LBB0_3544:
	v_bfe_u32 v33, v32, 16, 1
	v_add3_u32 v32, v32, v33, s83
	s_and_b64 vcc, exec, s[6:7]
	ds_write_b16_d16_hi v59, v32 offset:64
	s_cbranch_vccz .Lsg_508

; __device__ __forceinline__ float sigmf(float x) { return 1.f / (1.f + __expf(-x)); }
; __device__ __forceinline__ void inproj_epilogue(const Params& p, int layer, int mt, int ntile, int tid,
;                                                 f32x16 (&acc)[2][2], unsigned char* smem) {
;     ...
;     acc_foreach(tid, acc, [&](int row, int col, float v) {
;       int t = m0 + row;
;       float o = v;
;       if (mode == 1) o = (t >= NPADR) ? v : 0.f;
;       if (mode == 2) o = sigmf(v);
;       sT[row * 136 + col] = f2bf(o);
;     });
.LBB0_3547:
	v_bfe_u32 v33, v32, 16, 1
	v_add3_u32 v32, v32, v33, s83
	s_and_b64 vcc, exec, s[6:7]
	ds_write_b16_d16_hi v60, v32 offset:64
	s_cbranch_vccz .Lsg_509

; __device__ __forceinline__ float sigmf(float x) { return 1.f / (1.f + __expf(-x)); }
; __device__ __forceinline__ void inproj_epilogue(const Params& p, int layer, int mt, int ntile, int tid,
;                                                 f32x16 (&acc)[2][2], unsigned char* smem) {
;     ...
;     acc_foreach(tid, acc, [&](int row, int col, float v) {
;       int t = m0 + row;
;       float o = v;
;       if (mode == 1) o = (t >= NPADR) ? v : 0.f;
;       if (mode == 2) o = sigmf(v);
;       sT[row * 136 + col] = f2bf(o);
;     });
.LBB0_3550:
	v_bfe_u32 v33, v32, 16, 1
	v_add3_u32 v32, v32, v33, s83
	s_and_b64 vcc, exec, s[6:7]
	ds_write_b16_d16_hi v61, v32 offset:64
	s_cbranch_vccz .Lsg_510

; __device__ __forceinline__ float sigmf(float x) { return 1.f / (1.f + __expf(-x)); }
; __device__ __forceinline__ void inproj_epilogue(const Params& p, int layer, int mt, int ntile, int tid,
;                                                 f32x16 (&acc)[2][2], unsigned char* smem) {
;     ...
;     acc_foreach(tid, acc, [&](int row, int col, float v) {
;       int t = m0 + row;
;       float o = v;
;       if (mode == 1) o = (t >= NPADR) ? v : 0.f;
;       if (mode == 2) o = sigmf(v);
;       sT[row * 136 + col] = f2bf(o);
;     });
.LBB0_3553:
	v_bfe_u32 v33, v32, 16, 1
	v_add3_u32 v32, v32, v33, s83
	s_and_b64 vcc, exec, s[6:7]
	ds_write_b16_d16_hi v62, v32 offset:64
	s_cbranch_vccz .Lsg_511

; __device__ __forceinline__ float sigmf(float x) { return 1.f / (1.f + __expf(-x)); }
; __device__ __forceinline__ void inproj_epilogue(const Params& p, int layer, int mt, int ntile, int tid,
;                                                 f32x16 (&acc)[2][2], unsigned char* smem) {
;     ...
;     acc_foreach(tid, acc, [&](int row, int col, float v) {
;       int t = m0 + row;
;       float o = v;
;       if (mode == 1) o = (t >= NPADR) ? v : 0.f;
;       if (mode == 2) o = sigmf(v);
;       sT[row * 136 + col] = f2bf(o);
;     });
.LBB0_3556:
	v_bfe_u32 v33, v32, 16, 1
	v_add3_u32 v32, v32, v33, s83
	s_and_b64 vcc, exec, s[6:7]
	ds_write_b16_d16_hi v55, v32 offset:64
	s_cbranch_vccz .Lsg_512

; __device__ __forceinline__ float sigmf(float x) { return 1.f / (1.f + __expf(-x)); }
; __device__ __forceinline__ void inproj_epilogue(const Params& p, int layer, int mt, int ntile, int tid,
;                                                 f32x16 (&acc)[2][2], unsigned char* smem) {
;     ...
;       if (mode == 2) o = sigmf(v);
.Lsg_464:
	v_mul_f32_e32 v124, 0xbfb8aa3b, v31
	v_exp_f32_e32 v124, v124
	s_nop 0
	v_add_f32_e32 v124, 1.0, v124
	v_div_scale_f32 v125, s[96:97], v124, v124, 1.0
	v_rcp_f32_e32 v126, v125
	v_div_scale_f32 v127, vcc, 1.0, v124, 1.0
	v_fma_f32 v128, -v125, v126, 1.0
	v_fmac_f32_e32 v126, v128, v126
	v_mul_f32_e32 v128, v127, v126
	v_fma_f32 v129, -v125, v128, v127
	v_fmac_f32_e32 v128, v129, v126
	v_fma_f32 v125, -v125, v128, v127
	v_div_fmas_f32 v125, v125, v126, v128
	v_div_fixup_f32 v124, v125, v124, 1.0
	s_branch .LBB0_3415

; __device__ __forceinline__ float sigmf(float x) { return 1.f / (1.f + __expf(-x)); }
; __device__ __forceinline__ void inproj_epilogue(const Params& p, int layer, int mt, int ntile, int tid,
;                                                 f32x16 (&acc)[2][2], unsigned char* smem) {
;     ...
;       if (mode == 2) o = sigmf(v);
.Lsg_496:
	v_mul_f32_e32 v63, 0xbfb8aa3b, v15
	v_exp_f32_e32 v63, v63
	s_nop 0
	v_add_f32_e32 v63, 1.0, v63
	v_div_scale_f32 v96, s[96:97], v63, v63, 1.0
	v_rcp_f32_e32 v106, v96
	v_div_scale_f32 v107, vcc, 1.0, v63, 1.0
	v_fma_f32 v110, -v96, v106, 1.0
	v_fmac_f32_e32 v106, v110, v106
	v_mul_f32_e32 v110, v107, v106
	v_fma_f32 v111, -v96, v110, v107
	v_fmac_f32_e32 v110, v111, v106
	v_fma_f32 v96, -v96, v110, v107
	v_div_fmas_f32 v96, v96, v106, v110
	v_div_fixup_f32 v63, v96, v63, 1.0
	s_branch .LBB0_3511

; __device__ __forceinline__ float sigmf(float x) { return 1.f / (1.f + __expf(-x)); }
; __device__ __forceinline__ float softplusf(float x) { return fmaxf(x, 0.f) + __logf(1.f + __expf(-fabsf(x))); }
; template <int MT, int NT, class F>
; __device__ __forceinline__ void acc_foreach(int tid, f32x16 (&acc)[MT][NT], F f) {
;   tid = relaunder(tid);
;   const int lane = tid & 63, w = tid >> 6;
;   const int wm = w >> 1, wn = w & 1, hi = lane >> 5, c = lane & 31;
; #pragma unroll
;   for (int mt = 0; mt < MT; mt++)
; #pragma unroll
;     for (int nt = 0; nt < NT; nt++)
; #pragma unroll
;       for (int i = 0; i < 16; i++) {
;         int row = wm * (MT * 32) + mt * 32 + (i & 3) + 8 * (i >> 2) + 4 * hi;
;         int col = wn * (NT * 32) + nt * 32 + c;
; __device__ __forceinline__ void inproj_epilogue(const Params& p, int layer, int mt, int ntile, int tid,
;                                                 f32x16 (&acc)[2][2], unsigned char* smem) {
;     ...
;   const int m0 = mt * 128;
;   if (mode == 3) {
;     float* dt = (float*)(p.ws + OFF_DT) + (size_t)m0 * 16;
;     const float* bias = p.ssd_dt_bias + layer * 16;
;     acc_foreach(tid, acc, [&](int row, int col, float v) {
;       if (col < 16) *(dt + row * 16 + col) = softplusf(v + bias[col]);
;     });
;   } else {
;     bf16r* dstb = dst + (size_t)m0 * ld + c0;
;     bf16r* sT = (bf16r*)smem;
;     acc_foreach(tid, acc, [&](int row, int col, float v) {
;       int t = m0 + row;
;       float o = v;
;       if (mode == 1) o = (t >= NPADR) ? v : 0.f;
;       if (mode == 2) o = sigmf(v);
;       sT[row * 136 + col] = f2bf(o);
.LBB0_4150:
	s_lshl_b32 s74, s6, 7
	s_ashr_i32 s75, s74, 31
	s_cmp_lg_u32 s7, 3
	s_mov_b64 s[4:5], -1
	s_cbranch_scc0 .LBB0_4344
	v_mov_b32_e32 v106, v108
	s_movk_i32 s4, 0xffc0
	v_lshrrev_b32_e32 v107, 3, v106
	v_ashrrev_i32_e32 v96, 1, v106
	v_and_b32_e32 v107, 4, v107
	v_and_or_b32 v96, v96, s4, v107
	s_cmp_eq_u32 s7, 1
	s_cselect_b64 s[4:5], -1, 0
	v_add_u32_e32 v107, s74, v96
	s_cmp_eq_u32 s7, 2
	s_cselect_b64 s[10:11], -1, 0
	s_cmp_lg_u32 s7, 2
	v_cmp_lt_i32_e64 s[8:9], s78, v107
	s_cbranch_scc0 .Lsg_513

; __device__ __forceinline__ float sigmf(float x) { return 1.f / (1.f + __expf(-x)); }
; __device__ __forceinline__ void inproj_epilogue(const Params& p, int layer, int mt, int ntile, int tid,
;                                                 f32x16 (&acc)[2][2], unsigned char* smem) {
;     ...
;     acc_foreach(tid, acc, [&](int row, int col, float v) {
;       int t = m0 + row;
;       float o = v;
;       if (mode == 1) o = (t >= NPADR) ? v : 0.f;
;       if (mode == 2) o = sigmf(v);
;       sT[row * 136 + col] = f2bf(o);
;     });
.LBB0_4154:
	v_bfe_u32 v110, v107, 16, 1
	v_and_b32_e32 v106, 0x5f, v106
	v_add3_u32 v111, v107, v110, s80
	v_mul_lo_u32 v110, v96, s81
	v_lshl_add_u32 v107, v106, 1, v110
	ds_write_b16_d16_hi v107, v111
	v_add3_u32 v111, s74, v96, 1
	v_cndmask_b32_e64 v112, 0, 1, s[10:11]
	v_cmp_ne_u32_e64 s[6:7], 1, v112
	s_andn2_b64 vcc, exec, s[10:11]
	v_cmp_lt_i32_e64 s[10:11], s78, v111
	s_cbranch_vccz .Lsg_514

; __device__ __forceinline__ float sigmf(float x) { return 1.f / (1.f + __expf(-x)); }
; __device__ __forceinline__ void inproj_epilogue(const Params& p, int layer, int mt, int ntile, int tid,
;                                                 f32x16 (&acc)[2][2], unsigned char* smem) {
;     ...
;     acc_foreach(tid, acc, [&](int row, int col, float v) {
;       int t = m0 + row;
;       float o = v;
;       if (mode == 1) o = (t >= NPADR) ? v : 0.f;
;       if (mode == 2) o = sigmf(v);
;       sT[row * 136 + col] = f2bf(o);
;     });
.LBB0_4157:
	v_bfe_u32 v112, v111, 16, 1
	v_add3_u32 v112, v111, v112, s80
	v_add_u32_e32 v111, 0x110, v110
	v_lshl_add_u32 v110, v106, 1, v111
	ds_write_b16_d16_hi v110, v112
	v_add3_u32 v112, s74, v96, 2
	s_and_b64 vcc, exec, s[6:7]
	v_cmp_lt_i32_e64 s[12:13], s78, v112
	s_cbranch_vccz .Lsg_515

; __device__ __forceinline__ float sigmf(float x) { return 1.f / (1.f + __expf(-x)); }
; __device__ __forceinline__ void inproj_epilogue(const Params& p, int layer, int mt, int ntile, int tid,
;                                                 f32x16 (&acc)[2][2], unsigned char* smem) {
;     ...
;     acc_foreach(tid, acc, [&](int row, int col, float v) {
;       int t = m0 + row;
;       float o = v;
;       if (mode == 1) o = (t >= NPADR) ? v : 0.f;
;       if (mode == 2) o = sigmf(v);
;       sT[row * 136 + col] = f2bf(o);
;     });
.LBB0_4160:
	v_bfe_u32 v113, v112, 16, 1
	v_add3_u32 v113, v112, v113, s80
	v_add_u32_e32 v112, 0x110, v111
	v_lshl_add_u32 v111, v106, 1, v112
	ds_write_b16_d16_hi v111, v113
	v_add3_u32 v113, s74, v96, 3
	s_and_b64 vcc, exec, s[6:7]
	v_cmp_lt_i32_e64 s[14:15], s78, v113
	s_cbranch_vccz .Lsg_516

; __device__ __forceinline__ float sigmf(float x) { return 1.f / (1.f + __expf(-x)); }
; __device__ __forceinline__ void inproj_epilogue(const Params& p, int layer, int mt, int ntile, int tid,
;                                                 f32x16 (&acc)[2][2], unsigned char* smem) {
;     ...
;     acc_foreach(tid, acc, [&](int row, int col, float v) {
;       int t = m0 + row;
;       float o = v;
;       if (mode == 1) o = (t >= NPADR) ? v : 0.f;
;       if (mode == 2) o = sigmf(v);
;       sT[row * 136 + col] = f2bf(o);
;     });
.LBB0_4163:
	v_bfe_u32 v114, v113, 16, 1
	v_add3_u32 v114, v113, v114, s80
	v_add_u32_e32 v113, 0x110, v112
	v_lshl_add_u32 v112, v106, 1, v113
	ds_write_b16_d16_hi v112, v114
	v_add3_u32 v114, s74, v96, 8
	s_and_b64 vcc, exec, s[6:7]
	v_cmp_lt_i32_e64 s[16:17], s78, v114
	s_cbranch_vccz .Lsg_517

; __device__ __forceinline__ float sigmf(float x) { return 1.f / (1.f + __expf(-x)); }
; __device__ __forceinline__ void inproj_epilogue(const Params& p, int layer, int mt, int ntile, int tid,
;                                                 f32x16 (&acc)[2][2], unsigned char* smem) {
;     ...
;     acc_foreach(tid, acc, [&](int row, int col, float v) {
;       int t = m0 + row;
;       float o = v;
;       if (mode == 1) o = (t >= NPADR) ? v : 0.f;
;       if (mode == 2) o = sigmf(v);
;       sT[row * 136 + col] = f2bf(o);
;     });
.LBB0_4166:
	v_bfe_u32 v115, v114, 16, 1
	v_add3_u32 v115, v114, v115, s80
	v_add_u32_e32 v114, 0x550, v113
	v_lshl_add_u32 v113, v106, 1, v114
	ds_write_b16_d16_hi v113, v115
	v_add3_u32 v115, s74, v96, 9
	s_and_b64 vcc, exec, s[6:7]
	v_cmp_lt_i32_e64 s[18:19], s78, v115
	s_cbranch_vccz .Lsg_518

; __device__ __forceinline__ float sigmf(float x) { return 1.f / (1.f + __expf(-x)); }
; __device__ __forceinline__ void inproj_epilogue(const Params& p, int layer, int mt, int ntile, int tid,
;                                                 f32x16 (&acc)[2][2], unsigned char* smem) {
;     ...
;     acc_foreach(tid, acc, [&](int row, int col, float v) {
;       int t = m0 + row;
;       float o = v;
;       if (mode == 1) o = (t >= NPADR) ? v : 0.f;
;       if (mode == 2) o = sigmf(v);
;       sT[row * 136 + col] = f2bf(o);
;     });
.LBB0_4169:
	v_bfe_u32 v116, v115, 16, 1
	v_add3_u32 v116, v115, v116, s80
	v_add_u32_e32 v115, 0x110, v114
	v_lshl_add_u32 v114, v106, 1, v115
	ds_write_b16_d16_hi v114, v116
	v_add3_u32 v116, s74, v96, 10
	s_and_b64 vcc, exec, s[6:7]
	v_cmp_lt_i32_e64 s[20:21], s78, v116
	s_cbranch_vccz .Lsg_519

; __device__ __forceinline__ float sigmf(float x) { return 1.f / (1.f + __expf(-x)); }
; __device__ __forceinline__ void inproj_epilogue(const Params& p, int layer, int mt, int ntile, int tid,
;                                                 f32x16 (&acc)[2][2], unsigned char* smem) {
;     ...
;     acc_foreach(tid, acc, [&](int row, int col, float v) {
;       int t = m0 + row;
;       float o = v;
;       if (mode == 1) o = (t >= NPADR) ? v : 0.f;
;       if (mode == 2) o = sigmf(v);
;       sT[row * 136 + col] = f2bf(o);
;     });
.LBB0_4172:
	v_bfe_u32 v117, v116, 16, 1
	v_add3_u32 v117, v116, v117, s80
	v_add_u32_e32 v116, 0x110, v115
	v_lshl_add_u32 v115, v106, 1, v116
	ds_write_b16_d16_hi v115, v117
	v_add3_u32 v117, s74, v96, 11
	s_and_b64 vcc, exec, s[6:7]
	v_cmp_lt_i32_e64 s[22:23], s78, v117
	s_cbranch_vccz .Lsg_520

; __device__ __forceinline__ float sigmf(float x) { return 1.f / (1.f + __expf(-x)); }
; __device__ __forceinline__ void inproj_epilogue(const Params& p, int layer, int mt, int ntile, int tid,
;                                                 f32x16 (&acc)[2][2], unsigned char* smem) {
;     ...
;     acc_foreach(tid, acc, [&](int row, int col, float v) {
;       int t = m0 + row;
;       float o = v;
;       if (mode == 1) o = (t >= NPADR) ? v : 0.f;
;       if (mode == 2) o = sigmf(v);
;       sT[row * 136 + col] = f2bf(o);
;     });
.LBB0_4175:
	v_bfe_u32 v118, v117, 16, 1
	v_add_u32_e32 v116, 0x110, v116
	v_add3_u32 v118, v117, v118, s80
	v_lshl_add_u32 v117, v106, 1, v116
	ds_write_b16_d16_hi v117, v118
	v_add3_u32 v118, s74, v96, 16
	s_and_b64 vcc, exec, s[6:7]
	v_cmp_lt_i32_e64 s[24:25], s78, v118
	s_cbranch_vccz .Lsg_521

; __device__ __forceinline__ float sigmf(float x) { return 1.f / (1.f + __expf(-x)); }
; __device__ __forceinline__ void inproj_epilogue(const Params& p, int layer, int mt, int ntile, int tid,
;                                                 f32x16 (&acc)[2][2], unsigned char* smem) {
;     ...
;     acc_foreach(tid, acc, [&](int row, int col, float v) {
;       int t = m0 + row;
;       float o = v;
;       if (mode == 1) o = (t >= NPADR) ? v : 0.f;
;       if (mode == 2) o = sigmf(v);
;       sT[row * 136 + col] = f2bf(o);
;     });
.LBB0_4178:
	v_bfe_u32 v119, v118, 16, 1
	v_add_u32_e32 v116, 0x550, v116
	v_add3_u32 v119, v118, v119, s80
	v_lshl_add_u32 v118, v106, 1, v116
	ds_write_b16_d16_hi v118, v119
	v_add3_u32 v119, s74, v96, 17
	s_and_b64 vcc, exec, s[6:7]
	v_cmp_lt_i32_e64 s[26:27], s78, v119
	s_cbranch_vccz .Lsg_522

; __device__ __forceinline__ float sigmf(float x) { return 1.f / (1.f + __expf(-x)); }
; __device__ __forceinline__ void inproj_epilogue(const Params& p, int layer, int mt, int ntile, int tid,
;                                                 f32x16 (&acc)[2][2], unsigned char* smem) {
;     ...
;     acc_foreach(tid, acc, [&](int row, int col, float v) {
;       int t = m0 + row;
;       float o = v;
;       if (mode == 1) o = (t >= NPADR) ? v : 0.f;
;       if (mode == 2) o = sigmf(v);
;       sT[row * 136 + col] = f2bf(o);
;     });
.LBB0_4181:
	v_bfe_u32 v120, v119, 16, 1
	v_add_u32_e32 v116, 0x110, v116
	v_add3_u32 v120, v119, v120, s80
	v_lshl_add_u32 v119, v106, 1, v116
	ds_write_b16_d16_hi v119, v120
	v_add3_u32 v120, s74, v96, 18
	s_and_b64 vcc, exec, s[6:7]
	v_cmp_lt_i32_e64 s[28:29], s78, v120
	s_cbranch_vccz .Lsg_523

; __device__ __forceinline__ float sigmf(float x) { return 1.f / (1.f + __expf(-x)); }
; __device__ __forceinline__ void inproj_epilogue(const Params& p, int layer, int mt, int ntile, int tid,
;                                                 f32x16 (&acc)[2][2], unsigned char* smem) {
;     ...
;     acc_foreach(tid, acc, [&](int row, int col, float v) {
;       int t = m0 + row;
;       float o = v;
;       if (mode == 1) o = (t >= NPADR) ? v : 0.f;
;       if (mode == 2) o = sigmf(v);
;       sT[row * 136 + col] = f2bf(o);
;     });
.LBB0_4184:
	v_bfe_u32 v121, v120, 16, 1
	v_add_u32_e32 v116, 0x110, v116
	v_add3_u32 v121, v120, v121, s80
	v_lshl_add_u32 v120, v106, 1, v116
	ds_write_b16_d16_hi v120, v121
	v_add3_u32 v121, s74, v96, 19
	s_and_b64 vcc, exec, s[6:7]
	v_cmp_lt_i32_e64 s[30:31], s78, v121
	s_cbranch_vccz .Lsg_524

; __device__ __forceinline__ float sigmf(float x) { return 1.f / (1.f + __expf(-x)); }
; __device__ __forceinline__ void inproj_epilogue(const Params& p, int layer, int mt, int ntile, int tid,
;                                                 f32x16 (&acc)[2][2], unsigned char* smem) {
;     ...
;     acc_foreach(tid, acc, [&](int row, int col, float v) {
;       int t = m0 + row;
;       float o = v;
;       if (mode == 1) o = (t >= NPADR) ? v : 0.f;
;       if (mode == 2) o = sigmf(v);
;       sT[row * 136 + col] = f2bf(o);
;     });
.LBB0_4187:
	v_bfe_u32 v122, v121, 16, 1
	v_add_u32_e32 v116, 0x110, v116
	v_add3_u32 v122, v121, v122, s80
	v_lshl_add_u32 v121, v106, 1, v116
	ds_write_b16_d16_hi v121, v122
	v_add3_u32 v122, s74, v96, 24
	s_and_b64 vcc, exec, s[6:7]
	v_cmp_lt_i32_e64 s[34:35], s78, v122
	s_cbranch_vccz .Lsg_525

; __device__ __forceinline__ float sigmf(float x) { return 1.f / (1.f + __expf(-x)); }
; __device__ __forceinline__ void inproj_epilogue(const Params& p, int layer, int mt, int ntile, int tid,
;                                                 f32x16 (&acc)[2][2], unsigned char* smem) {
;     ...
;     acc_foreach(tid, acc, [&](int row, int col, float v) {
;       int t = m0 + row;
;       float o = v;
;       if (mode == 1) o = (t >= NPADR) ? v : 0.f;
;       if (mode == 2) o = sigmf(v);
;       sT[row * 136 + col] = f2bf(o);
;     });
.LBB0_4190:
	v_bfe_u32 v123, v122, 16, 1
	v_add_u32_e32 v116, 0x550, v116
	v_add3_u32 v123, v122, v123, s80
	v_lshl_add_u32 v122, v106, 1, v116
	ds_write_b16_d16_hi v122, v123
	v_add3_u32 v123, s74, v96, 25
	s_and_b64 vcc, exec, s[6:7]
	v_cmp_lt_i32_e64 s[36:37], s78, v123
	s_cbranch_vccz .Lsg_526

; __device__ __forceinline__ float sigmf(float x) { return 1.f / (1.f + __expf(-x)); }
; __device__ __forceinline__ void inproj_epilogue(const Params& p, int layer, int mt, int ntile, int tid,
;                                                 f32x16 (&acc)[2][2], unsigned char* smem) {
;     ...
;     acc_foreach(tid, acc, [&](int row, int col, float v) {
;       int t = m0 + row;
;       float o = v;
;       if (mode == 1) o = (t >= NPADR) ? v : 0.f;
;       if (mode == 2) o = sigmf(v);
;       sT[row * 136 + col] = f2bf(o);
;     });
.LBB0_4193:
	v_bfe_u32 v124, v123, 16, 1
	v_add_u32_e32 v116, 0x110, v116
	v_add3_u32 v124, v123, v124, s80
	v_lshl_add_u32 v123, v106, 1, v116
	ds_write_b16_d16_hi v123, v124
	v_add3_u32 v124, s74, v96, 26
	s_and_b64 vcc, exec, s[6:7]
	v_cmp_lt_i32_e64 s[38:39], s78, v124
	s_cbranch_vccz .Lsg_527

; __device__ __forceinline__ float sigmf(float x) { return 1.f / (1.f + __expf(-x)); }
; __device__ __forceinline__ void inproj_epilogue(const Params& p, int layer, int mt, int ntile, int tid,
;                                                 f32x16 (&acc)[2][2], unsigned char* smem) {
;     ...
;     acc_foreach(tid, acc, [&](int row, int col, float v) {
;       int t = m0 + row;
;       float o = v;
;       if (mode == 1) o = (t >= NPADR) ? v : 0.f;
;       if (mode == 2) o = sigmf(v);
;       sT[row * 136 + col] = f2bf(o);
;     });
.LBB0_4196:
	v_bfe_u32 v125, v124, 16, 1
	v_add_u32_e32 v116, 0x110, v116
	v_add3_u32 v124, v124, v125, s80
	v_lshl_add_u32 v116, v106, 1, v116
	ds_write_b16_d16_hi v116, v124
	v_add3_u32 v124, s74, v96, 27
	s_and_b64 vcc, exec, s[6:7]
	v_cmp_lt_i32_e64 s[40:41], s78, v124
	s_cbranch_vccz .Lsg_528

; __device__ __forceinline__ float sigmf(float x) { return 1.f / (1.f + __expf(-x)); }
; __device__ __forceinline__ void inproj_epilogue(const Params& p, int layer, int mt, int ntile, int tid,
;                                                 f32x16 (&acc)[2][2], unsigned char* smem) {
;     ...
;     acc_foreach(tid, acc, [&](int row, int col, float v) {
;       int t = m0 + row;
;       float o = v;
;       if (mode == 1) o = (t >= NPADR) ? v : 0.f;
;       if (mode == 2) o = sigmf(v);
;       sT[row * 136 + col] = f2bf(o);
;     });
.LBB0_4199:
	v_bfe_u32 v125, v124, 16, 1
	v_add3_u32 v124, v124, v125, s80
	ds_write_b16_d16_hi v116, v124 offset:272
	s_and_b64 vcc, exec, s[6:7]
	s_cbranch_vccz .Lsg_529

; __device__ __forceinline__ float sigmf(float x) { return 1.f / (1.f + __expf(-x)); }
; __device__ __forceinline__ void inproj_epilogue(const Params& p, int layer, int mt, int ntile, int tid,
;                                                 f32x16 (&acc)[2][2], unsigned char* smem) {
;     ...
;     acc_foreach(tid, acc, [&](int row, int col, float v) {
;       int t = m0 + row;
;       float o = v;
;       if (mode == 1) o = (t >= NPADR) ? v : 0.f;
;       if (mode == 2) o = sigmf(v);
;       sT[row * 136 + col] = f2bf(o);
;     });
.LBB0_4202:
	v_bfe_u32 v124, v48, 16, 1
	v_add3_u32 v48, v48, v124, s80
	s_and_b64 vcc, exec, s[6:7]
	ds_write_b16_d16_hi v107, v48 offset:64
	s_cbranch_vccz .Lsg_530

; __device__ __forceinline__ float sigmf(float x) { return 1.f / (1.f + __expf(-x)); }
; __device__ __forceinline__ void inproj_epilogue(const Params& p, int layer, int mt, int ntile, int tid,
;                                                 f32x16 (&acc)[2][2], unsigned char* smem) {
;     ...
;     acc_foreach(tid, acc, [&](int row, int col, float v) {
;       int t = m0 + row;
;       float o = v;
;       if (mode == 1) o = (t >= NPADR) ? v : 0.f;
;       if (mode == 2) o = sigmf(v);
;       sT[row * 136 + col] = f2bf(o);
;     });
.LBB0_4205:
	v_bfe_u32 v49, v48, 16, 1
	v_add3_u32 v48, v48, v49, s80
	s_and_b64 vcc, exec, s[6:7]
	ds_write_b16_d16_hi v110, v48 offset:64
	s_cbranch_vccz .Lsg_531

; __device__ __forceinline__ float sigmf(float x) { return 1.f / (1.f + __expf(-x)); }
; __device__ __forceinline__ void inproj_epilogue(const Params& p, int layer, int mt, int ntile, int tid,
;                                                 f32x16 (&acc)[2][2], unsigned char* smem) {
;     ...
;     acc_foreach(tid, acc, [&](int row, int col, float v) {
;       int t = m0 + row;
;       float o = v;
;       if (mode == 1) o = (t >= NPADR) ? v : 0.f;
;       if (mode == 2) o = sigmf(v);
;       sT[row * 136 + col] = f2bf(o);
;     });
.LBB0_4208:
	v_bfe_u32 v49, v48, 16, 1
	v_add3_u32 v48, v48, v49, s80
	s_and_b64 vcc, exec, s[6:7]
	ds_write_b16_d16_hi v111, v48 offset:64
	s_cbranch_vccz .Lsg_532

; __device__ __forceinline__ float sigmf(float x) { return 1.f / (1.f + __expf(-x)); }
; __device__ __forceinline__ void inproj_epilogue(const Params& p, int layer, int mt, int ntile, int tid,
;                                                 f32x16 (&acc)[2][2], unsigned char* smem) {
;     ...
;     acc_foreach(tid, acc, [&](int row, int col, float v) {
;       int t = m0 + row;
;       float o = v;
;       if (mode == 1) o = (t >= NPADR) ? v : 0.f;
;       if (mode == 2) o = sigmf(v);
;       sT[row * 136 + col] = f2bf(o);
;     });
.LBB0_4211:
	v_bfe_u32 v49, v48, 16, 1
	v_add3_u32 v48, v48, v49, s80
	s_and_b64 vcc, exec, s[6:7]
	ds_write_b16_d16_hi v112, v48 offset:64
	s_cbranch_vccz .Lsg_533

; __device__ __forceinline__ float sigmf(float x) { return 1.f / (1.f + __expf(-x)); }
; __device__ __forceinline__ void inproj_epilogue(const Params& p, int layer, int mt, int ntile, int tid,
;                                                 f32x16 (&acc)[2][2], unsigned char* smem) {
;     ...
;     acc_foreach(tid, acc, [&](int row, int col, float v) {
;       int t = m0 + row;
;       float o = v;
;       if (mode == 1) o = (t >= NPADR) ? v : 0.f;
;       if (mode == 2) o = sigmf(v);
;       sT[row * 136 + col] = f2bf(o);
;     });
.LBB0_4214:
	v_bfe_u32 v49, v48, 16, 1
	v_add3_u32 v48, v48, v49, s80
	s_and_b64 vcc, exec, s[6:7]
	ds_write_b16_d16_hi v113, v48 offset:64
	s_cbranch_vccz .Lsg_534

; __device__ __forceinline__ float sigmf(float x) { return 1.f / (1.f + __expf(-x)); }
; __device__ __forceinline__ void inproj_epilogue(const Params& p, int layer, int mt, int ntile, int tid,
;                                                 f32x16 (&acc)[2][2], unsigned char* smem) {
;     ...
;     acc_foreach(tid, acc, [&](int row, int col, float v) {
;       int t = m0 + row;
;       float o = v;
;       if (mode == 1) o = (t >= NPADR) ? v : 0.f;
;       if (mode == 2) o = sigmf(v);
;       sT[row * 136 + col] = f2bf(o);
;     });
.LBB0_4217:
	v_bfe_u32 v49, v48, 16, 1
	v_add3_u32 v48, v48, v49, s80
	s_and_b64 vcc, exec, s[6:7]
	ds_write_b16_d16_hi v114, v48 offset:64
	s_cbranch_vccz .Lsg_535

; __device__ __forceinline__ float sigmf(float x) { return 1.f / (1.f + __expf(-x)); }
; __device__ __forceinline__ void inproj_epilogue(const Params& p, int layer, int mt, int ntile, int tid,
;                                                 f32x16 (&acc)[2][2], unsigned char* smem) {
;     ...
;     acc_foreach(tid, acc, [&](int row, int col, float v) {
;       int t = m0 + row;
;       float o = v;
;       if (mode == 1) o = (t >= NPADR) ? v : 0.f;
;       if (mode == 2) o = sigmf(v);
;       sT[row * 136 + col] = f2bf(o);
;     });
.LBB0_4220:
	v_bfe_u32 v49, v48, 16, 1
	v_add3_u32 v48, v48, v49, s80
	s_and_b64 vcc, exec, s[6:7]
	ds_write_b16_d16_hi v115, v48 offset:64
	s_cbranch_vccz .Lsg_536

; __device__ __forceinline__ float sigmf(float x) { return 1.f / (1.f + __expf(-x)); }
; __device__ __forceinline__ void inproj_epilogue(const Params& p, int layer, int mt, int ntile, int tid,
;                                                 f32x16 (&acc)[2][2], unsigned char* smem) {
;     ...
;     acc_foreach(tid, acc, [&](int row, int col, float v) {
;       int t = m0 + row;
;       float o = v;
;       if (mode == 1) o = (t >= NPADR) ? v : 0.f;
;       if (mode == 2) o = sigmf(v);
;       sT[row * 136 + col] = f2bf(o);
;     });
.LBB0_4223:
	v_bfe_u32 v49, v48, 16, 1
	v_add3_u32 v48, v48, v49, s80
	s_and_b64 vcc, exec, s[6:7]
	ds_write_b16_d16_hi v117, v48 offset:64
	s_cbranch_vccz .Lsg_537

; __device__ __forceinline__ float sigmf(float x) { return 1.f / (1.f + __expf(-x)); }
; __device__ __forceinline__ void inproj_epilogue(const Params& p, int layer, int mt, int ntile, int tid,
;                                                 f32x16 (&acc)[2][2], unsigned char* smem) {
;     ...
;     acc_foreach(tid, acc, [&](int row, int col, float v) {
;       int t = m0 + row;
;       float o = v;
;       if (mode == 1) o = (t >= NPADR) ? v : 0.f;
;       if (mode == 2) o = sigmf(v);
;       sT[row * 136 + col] = f2bf(o);
;     });
.LBB0_4226:
	v_bfe_u32 v49, v48, 16, 1
	v_add3_u32 v48, v48, v49, s80
	s_and_b64 vcc, exec, s[6:7]
	ds_write_b16_d16_hi v118, v48 offset:64
	s_cbranch_vccz .Lsg_538

; __device__ __forceinline__ float sigmf(float x) { return 1.f / (1.f + __expf(-x)); }
; __device__ __forceinline__ void inproj_epilogue(const Params& p, int layer, int mt, int ntile, int tid,
;                                                 f32x16 (&acc)[2][2], unsigned char* smem) {
;     ...
;     acc_foreach(tid, acc, [&](int row, int col, float v) {
;       int t = m0 + row;
;       float o = v;
;       if (mode == 1) o = (t >= NPADR) ? v : 0.f;
;       if (mode == 2) o = sigmf(v);
;       sT[row * 136 + col] = f2bf(o);
;     });
.LBB0_4229:
	v_bfe_u32 v49, v48, 16, 1
	v_add3_u32 v48, v48, v49, s80
	s_and_b64 vcc, exec, s[6:7]
	ds_write_b16_d16_hi v119, v48 offset:64
	s_cbranch_vccz .Lsg_539

; __device__ __forceinline__ float sigmf(float x) { return 1.f / (1.f + __expf(-x)); }
; __device__ __forceinline__ void inproj_epilogue(const Params& p, int layer, int mt, int ntile, int tid,
;                                                 f32x16 (&acc)[2][2], unsigned char* smem) {
;     ...
;     acc_foreach(tid, acc, [&](int row, int col, float v) {
;       int t = m0 + row;
;       float o = v;
;       if (mode == 1) o = (t >= NPADR) ? v : 0.f;
;       if (mode == 2) o = sigmf(v);
;       sT[row * 136 + col] = f2bf(o);
;     });
.LBB0_4232:
	v_bfe_u32 v49, v48, 16, 1
	v_add3_u32 v48, v48, v49, s80
	s_and_b64 vcc, exec, s[6:7]
	ds_write_b16_d16_hi v120, v48 offset:64
	s_cbranch_vccz .Lsg_540

; __device__ __forceinline__ float sigmf(float x) { return 1.f / (1.f + __expf(-x)); }
; __device__ __forceinline__ void inproj_epilogue(const Params& p, int layer, int mt, int ntile, int tid,
;                                                 f32x16 (&acc)[2][2], unsigned char* smem) {
;     ...
;     acc_foreach(tid, acc, [&](int row, int col, float v) {
;       int t = m0 + row;
;       float o = v;
;       if (mode == 1) o = (t >= NPADR) ? v : 0.f;
;       if (mode == 2) o = sigmf(v);
;       sT[row * 136 + col] = f2bf(o);
;     });
.LBB0_4235:
	v_bfe_u32 v49, v48, 16, 1
	v_add3_u32 v48, v48, v49, s80
	s_and_b64 vcc, exec, s[6:7]
	ds_write_b16_d16_hi v121, v48 offset:64
	s_cbranch_vccz .Lsg_541

; __device__ __forceinline__ float sigmf(float x) { return 1.f / (1.f + __expf(-x)); }
; __device__ __forceinline__ void inproj_epilogue(const Params& p, int layer, int mt, int ntile, int tid,
;                                                 f32x16 (&acc)[2][2], unsigned char* smem) {
;     ...
;     acc_foreach(tid, acc, [&](int row, int col, float v) {
;       int t = m0 + row;
;       float o = v;
;       if (mode == 1) o = (t >= NPADR) ? v : 0.f;
;       if (mode == 2) o = sigmf(v);
;       sT[row * 136 + col] = f2bf(o);
;     });
.LBB0_4238:
	v_bfe_u32 v49, v48, 16, 1
	v_add3_u32 v48, v48, v49, s80
	s_and_b64 vcc, exec, s[6:7]
	ds_write_b16_d16_hi v122, v48 offset:64
	s_cbranch_vccz .Lsg_542

; __device__ __forceinline__ float sigmf(float x) { return 1.f / (1.f + __expf(-x)); }
; __device__ __forceinline__ void inproj_epilogue(const Params& p, int layer, int mt, int ntile, int tid,
;                                                 f32x16 (&acc)[2][2], unsigned char* smem) {
;     ...
;     acc_foreach(tid, acc, [&](int row, int col, float v) {
;       int t = m0 + row;
;       float o = v;
;       if (mode == 1) o = (t >= NPADR) ? v : 0.f;
;       if (mode == 2) o = sigmf(v);
;       sT[row * 136 + col] = f2bf(o);
;     });
.LBB0_4241:
	v_bfe_u32 v49, v48, 16, 1
	v_add3_u32 v48, v48, v49, s80
	s_and_b64 vcc, exec, s[6:7]
	ds_write_b16_d16_hi v123, v48 offset:64
	s_cbranch_vccz .Lsg_543

; __device__ __forceinline__ float sigmf(float x) { return 1.f / (1.f + __expf(-x)); }
; __device__ __forceinline__ void inproj_epilogue(const Params& p, int layer, int mt, int ntile, int tid,
;                                                 f32x16 (&acc)[2][2], unsigned char* smem) {
;     ...
;     acc_foreach(tid, acc, [&](int row, int col, float v) {
;       int t = m0 + row;
;       float o = v;
;       if (mode == 1) o = (t >= NPADR) ? v : 0.f;
;       if (mode == 2) o = sigmf(v);
;       sT[row * 136 + col] = f2bf(o);
;     });
.LBB0_4244:
	v_bfe_u32 v49, v48, 16, 1
	v_add3_u32 v48, v48, v49, s80
	s_and_b64 vcc, exec, s[6:7]
	ds_write_b16_d16_hi v116, v48 offset:64
	s_cbranch_vccz .Lsg_544

; __device__ __forceinline__ float sigmf(float x) { return 1.f / (1.f + __expf(-x)); }
; __device__ __forceinline__ void inproj_epilogue(const Params& p, int layer, int mt, int ntile, int tid,
;                                                 f32x16 (&acc)[2][2], unsigned char* smem) {
;     ...
;     acc_foreach(tid, acc, [&](int row, int col, float v) {
;       int t = m0 + row;
;       float o = v;
;       if (mode == 1) o = (t >= NPADR) ? v : 0.f;
;       if (mode == 2) o = sigmf(v);
;       sT[row * 136 + col] = f2bf(o);
;     });
.LBB0_4247:
	v_bfe_u32 v50, v48, 16, 1
	v_add_u32_e32 v49, 0x110, v116
	v_add3_u32 v48, v48, v50, s80
	ds_write_b16_d16_hi v49, v48 offset:64
	v_or_b32_e32 v48, 32, v96
	v_add_u32_e32 v49, s74, v48
	s_and_b64 vcc, exec, s[6:7]
	v_cmp_lt_i32_e64 s[8:9], s78, v49
	s_cbranch_vccz .Lsg_545

; __device__ __forceinline__ float sigmf(float x) { return 1.f / (1.f + __expf(-x)); }
; __device__ __forceinline__ void inproj_epilogue(const Params& p, int layer, int mt, int ntile, int tid,
;                                                 f32x16 (&acc)[2][2], unsigned char* smem) {
;     ...
;     acc_foreach(tid, acc, [&](int row, int col, float v) {
;       int t = m0 + row;
;       float o = v;
;       if (mode == 1) o = (t >= NPADR) ? v : 0.f;
;       if (mode == 2) o = sigmf(v);
;       sT[row * 136 + col] = f2bf(o);
;     });
.LBB0_4250:
	v_bfe_u32 v50, v49, 16, 1
	v_add3_u32 v50, v49, v50, s80
	v_mul_lo_u32 v49, v48, s81
	v_lshl_add_u32 v48, v106, 1, v49
	ds_write_b16_d16_hi v48, v50
	v_add3_u32 v50, s74, v96, 33
	s_and_b64 vcc, exec, s[6:7]
	v_cmp_lt_i32_e64 s[10:11], s78, v50
	s_cbranch_vccz .Lsg_546

; __device__ __forceinline__ float sigmf(float x) { return 1.f / (1.f + __expf(-x)); }
; __device__ __forceinline__ void inproj_epilogue(const Params& p, int layer, int mt, int ntile, int tid,
;                                                 f32x16 (&acc)[2][2], unsigned char* smem) {
;     ...
;     acc_foreach(tid, acc, [&](int row, int col, float v) {
;       int t = m0 + row;
;       float o = v;
;       if (mode == 1) o = (t >= NPADR) ? v : 0.f;
;       if (mode == 2) o = sigmf(v);
;       sT[row * 136 + col] = f2bf(o);
;     });
.LBB0_4253:
	v_bfe_u32 v51, v50, 16, 1
	v_add3_u32 v51, v50, v51, s80
	v_add_u32_e32 v50, 0x110, v49
	v_lshl_add_u32 v49, v106, 1, v50
	ds_write_b16_d16_hi v49, v51
	v_add3_u32 v51, s74, v96, 34
	s_and_b64 vcc, exec, s[6:7]
	v_cmp_lt_i32_e64 s[12:13], s78, v51
	s_cbranch_vccz .Lsg_547

; __device__ __forceinline__ float sigmf(float x) { return 1.f / (1.f + __expf(-x)); }
; __device__ __forceinline__ void inproj_epilogue(const Params& p, int layer, int mt, int ntile, int tid,
;                                                 f32x16 (&acc)[2][2], unsigned char* smem) {
;     ...
;     acc_foreach(tid, acc, [&](int row, int col, float v) {
;       int t = m0 + row;
;       float o = v;
;       if (mode == 1) o = (t >= NPADR) ? v : 0.f;
;       if (mode == 2) o = sigmf(v);
;       sT[row * 136 + col] = f2bf(o);
;     });
.LBB0_4256:
	v_bfe_u32 v52, v51, 16, 1
	v_add3_u32 v52, v51, v52, s80
	v_add_u32_e32 v51, 0x110, v50
	v_lshl_add_u32 v50, v106, 1, v51
	ds_write_b16_d16_hi v50, v52
	v_add3_u32 v52, s74, v96, 35
	s_and_b64 vcc, exec, s[6:7]
	v_cmp_lt_i32_e64 s[14:15], s78, v52
	s_cbranch_vccz .Lsg_548

; __device__ __forceinline__ float sigmf(float x) { return 1.f / (1.f + __expf(-x)); }
; __device__ __forceinline__ void inproj_epilogue(const Params& p, int layer, int mt, int ntile, int tid,
;                                                 f32x16 (&acc)[2][2], unsigned char* smem) {
;     ...
;     acc_foreach(tid, acc, [&](int row, int col, float v) {
;       int t = m0 + row;
;       float o = v;
;       if (mode == 1) o = (t >= NPADR) ? v : 0.f;
;       if (mode == 2) o = sigmf(v);
;       sT[row * 136 + col] = f2bf(o);
;     });
.LBB0_4259:
	v_bfe_u32 v53, v52, 16, 1
	v_add3_u32 v53, v52, v53, s80
	v_add_u32_e32 v52, 0x110, v51
	v_lshl_add_u32 v51, v106, 1, v52
	ds_write_b16_d16_hi v51, v53
	v_add3_u32 v53, s74, v96, 40
	s_and_b64 vcc, exec, s[6:7]
	v_cmp_lt_i32_e64 s[16:17], s78, v53
	s_cbranch_vccz .Lsg_549

; __device__ __forceinline__ float sigmf(float x) { return 1.f / (1.f + __expf(-x)); }
; __device__ __forceinline__ void inproj_epilogue(const Params& p, int layer, int mt, int ntile, int tid,
;                                                 f32x16 (&acc)[2][2], unsigned char* smem) {
;     ...
;     acc_foreach(tid, acc, [&](int row, int col, float v) {
;       int t = m0 + row;
;       float o = v;
;       if (mode == 1) o = (t >= NPADR) ? v : 0.f;
;       if (mode == 2) o = sigmf(v);
;       sT[row * 136 + col] = f2bf(o);
;     });
.LBB0_4262:
	v_bfe_u32 v54, v53, 16, 1
	v_add3_u32 v54, v53, v54, s80
	v_add_u32_e32 v53, 0x550, v52
	v_lshl_add_u32 v52, v106, 1, v53
	ds_write_b16_d16_hi v52, v54
	v_add3_u32 v54, s74, v96, 41
	s_and_b64 vcc, exec, s[6:7]
	v_cmp_lt_i32_e64 s[18:19], s78, v54
	s_cbranch_vccz .Lsg_550

; __device__ __forceinline__ float sigmf(float x) { return 1.f / (1.f + __expf(-x)); }
; __device__ __forceinline__ void inproj_epilogue(const Params& p, int layer, int mt, int ntile, int tid,
;                                                 f32x16 (&acc)[2][2], unsigned char* smem) {
;     ...
;     acc_foreach(tid, acc, [&](int row, int col, float v) {
;       int t = m0 + row;
;       float o = v;
;       if (mode == 1) o = (t >= NPADR) ? v : 0.f;
;       if (mode == 2) o = sigmf(v);
;       sT[row * 136 + col] = f2bf(o);
;     });
.LBB0_4265:
	v_bfe_u32 v55, v54, 16, 1
	v_add3_u32 v55, v54, v55, s80
	v_add_u32_e32 v54, 0x110, v53
	v_lshl_add_u32 v53, v106, 1, v54
	ds_write_b16_d16_hi v53, v55
	v_add3_u32 v55, s74, v96, 42
	s_and_b64 vcc, exec, s[6:7]
	v_cmp_lt_i32_e64 s[20:21], s78, v55
	s_cbranch_vccz .Lsg_551

; __device__ __forceinline__ float sigmf(float x) { return 1.f / (1.f + __expf(-x)); }
; __device__ __forceinline__ void inproj_epilogue(const Params& p, int layer, int mt, int ntile, int tid,
;                                                 f32x16 (&acc)[2][2], unsigned char* smem) {
;     ...
;     acc_foreach(tid, acc, [&](int row, int col, float v) {
;       int t = m0 + row;
;       float o = v;
;       if (mode == 1) o = (t >= NPADR) ? v : 0.f;
;       if (mode == 2) o = sigmf(v);
;       sT[row * 136 + col] = f2bf(o);
;     });
.LBB0_4268:
	v_bfe_u32 v56, v55, 16, 1
	v_add3_u32 v56, v55, v56, s80
	v_add_u32_e32 v55, 0x110, v54
	v_lshl_add_u32 v54, v106, 1, v55
	ds_write_b16_d16_hi v54, v56
	v_add3_u32 v56, s74, v96, 43
	s_and_b64 vcc, exec, s[6:7]
	v_cmp_lt_i32_e64 s[22:23], s78, v56
	s_cbranch_vccz .Lsg_552

; __device__ __forceinline__ float sigmf(float x) { return 1.f / (1.f + __expf(-x)); }
; __device__ __forceinline__ void inproj_epilogue(const Params& p, int layer, int mt, int ntile, int tid,
;                                                 f32x16 (&acc)[2][2], unsigned char* smem) {
;     ...
;     acc_foreach(tid, acc, [&](int row, int col, float v) {
;       int t = m0 + row;
;       float o = v;
;       if (mode == 1) o = (t >= NPADR) ? v : 0.f;
;       if (mode == 2) o = sigmf(v);
;       sT[row * 136 + col] = f2bf(o);
;     });
.LBB0_4271:
	v_bfe_u32 v57, v56, 16, 1
	v_add_u32_e32 v55, 0x110, v55
	v_add3_u32 v57, v56, v57, s80
	v_lshl_add_u32 v56, v106, 1, v55
	ds_write_b16_d16_hi v56, v57
	v_add3_u32 v57, s74, v96, 48
	s_and_b64 vcc, exec, s[6:7]
	v_cmp_lt_i32_e64 s[24:25], s78, v57
	s_cbranch_vccz .Lsg_553

; __device__ __forceinline__ float sigmf(float x) { return 1.f / (1.f + __expf(-x)); }
; __device__ __forceinline__ void inproj_epilogue(const Params& p, int layer, int mt, int ntile, int tid,
;                                                 f32x16 (&acc)[2][2], unsigned char* smem) {
;     ...
;     acc_foreach(tid, acc, [&](int row, int col, float v) {
;       int t = m0 + row;
;       float o = v;
;       if (mode == 1) o = (t >= NPADR) ? v : 0.f;
;       if (mode == 2) o = sigmf(v);
;       sT[row * 136 + col] = f2bf(o);
;     });
.LBB0_4274:
	v_bfe_u32 v58, v57, 16, 1
	v_add_u32_e32 v55, 0x550, v55
	v_add3_u32 v58, v57, v58, s80
	v_lshl_add_u32 v57, v106, 1, v55
	ds_write_b16_d16_hi v57, v58
	v_add3_u32 v58, s74, v96, 49
	s_and_b64 vcc, exec, s[6:7]
	v_cmp_lt_i32_e64 s[26:27], s78, v58
	s_cbranch_vccz .Lsg_554

; __device__ __forceinline__ float sigmf(float x) { return 1.f / (1.f + __expf(-x)); }
; __device__ __forceinline__ void inproj_epilogue(const Params& p, int layer, int mt, int ntile, int tid,
;                                                 f32x16 (&acc)[2][2], unsigned char* smem) {
;     ...
;     acc_foreach(tid, acc, [&](int row, int col, float v) {
;       int t = m0 + row;
;       float o = v;
;       if (mode == 1) o = (t >= NPADR) ? v : 0.f;
;       if (mode == 2) o = sigmf(v);
;       sT[row * 136 + col] = f2bf(o);
;     });
.LBB0_4277:
	v_bfe_u32 v59, v58, 16, 1
	v_add_u32_e32 v55, 0x110, v55
	v_add3_u32 v59, v58, v59, s80
	v_lshl_add_u32 v58, v106, 1, v55
	ds_write_b16_d16_hi v58, v59
	v_add3_u32 v59, s74, v96, 50
	s_and_b64 vcc, exec, s[6:7]
	v_cmp_lt_i32_e64 s[28:29], s78, v59
	s_cbranch_vccz .Lsg_555

; __device__ __forceinline__ float sigmf(float x) { return 1.f / (1.f + __expf(-x)); }
; __device__ __forceinline__ void inproj_epilogue(const Params& p, int layer, int mt, int ntile, int tid,
;                                                 f32x16 (&acc)[2][2], unsigned char* smem) {
;     ...
;     acc_foreach(tid, acc, [&](int row, int col, float v) {
;       int t = m0 + row;
;       float o = v;
;       if (mode == 1) o = (t >= NPADR) ? v : 0.f;
;       if (mode == 2) o = sigmf(v);
;       sT[row * 136 + col] = f2bf(o);
;     });
.LBB0_4280:
	v_bfe_u32 v60, v59, 16, 1
	v_add_u32_e32 v55, 0x110, v55
	v_add3_u32 v60, v59, v60, s80
	v_lshl_add_u32 v59, v106, 1, v55
	ds_write_b16_d16_hi v59, v60
	v_add3_u32 v60, s74, v96, 51
	s_and_b64 vcc, exec, s[6:7]
	v_cmp_lt_i32_e64 s[30:31], s78, v60
	s_cbranch_vccz .Lsg_556

; __device__ __forceinline__ float sigmf(float x) { return 1.f / (1.f + __expf(-x)); }
; __device__ __forceinline__ void inproj_epilogue(const Params& p, int layer, int mt, int ntile, int tid,
;                                                 f32x16 (&acc)[2][2], unsigned char* smem) {
;     ...
;     acc_foreach(tid, acc, [&](int row, int col, float v) {
;       int t = m0 + row;
;       float o = v;
;       if (mode == 1) o = (t >= NPADR) ? v : 0.f;
;       if (mode == 2) o = sigmf(v);
;       sT[row * 136 + col] = f2bf(o);
;     });
.LBB0_4283:
	v_bfe_u32 v61, v60, 16, 1
	v_add_u32_e32 v55, 0x110, v55
	v_add3_u32 v61, v60, v61, s80
	v_lshl_add_u32 v60, v106, 1, v55
	ds_write_b16_d16_hi v60, v61
	v_add3_u32 v61, s74, v96, 56
	s_and_b64 vcc, exec, s[6:7]
	v_cmp_lt_i32_e64 s[34:35], s78, v61
	s_cbranch_vccz .Lsg_557

; __device__ __forceinline__ float sigmf(float x) { return 1.f / (1.f + __expf(-x)); }
; __device__ __forceinline__ void inproj_epilogue(const Params& p, int layer, int mt, int ntile, int tid,
;                                                 f32x16 (&acc)[2][2], unsigned char* smem) {
;     ...
;     acc_foreach(tid, acc, [&](int row, int col, float v) {
;       int t = m0 + row;
;       float o = v;
;       if (mode == 1) o = (t >= NPADR) ? v : 0.f;
;       if (mode == 2) o = sigmf(v);
;       sT[row * 136 + col] = f2bf(o);
;     });
.LBB0_4286:
	v_bfe_u32 v62, v61, 16, 1
	v_add_u32_e32 v55, 0x550, v55
	v_add3_u32 v62, v61, v62, s80
	v_lshl_add_u32 v61, v106, 1, v55
	ds_write_b16_d16_hi v61, v62
	v_add3_u32 v62, s74, v96, 57
	s_and_b64 vcc, exec, s[6:7]
	v_cmp_lt_i32_e64 s[36:37], s78, v62
	s_cbranch_vccz .Lsg_558

; __device__ __forceinline__ float sigmf(float x) { return 1.f / (1.f + __expf(-x)); }
; __device__ __forceinline__ void inproj_epilogue(const Params& p, int layer, int mt, int ntile, int tid,
;                                                 f32x16 (&acc)[2][2], unsigned char* smem) {
;     ...
;     acc_foreach(tid, acc, [&](int row, int col, float v) {
;       int t = m0 + row;
;       float o = v;
;       if (mode == 1) o = (t >= NPADR) ? v : 0.f;
;       if (mode == 2) o = sigmf(v);
;       sT[row * 136 + col] = f2bf(o);
;     });
.LBB0_4289:
	v_bfe_u32 v63, v62, 16, 1
	v_add_u32_e32 v55, 0x110, v55
	v_add3_u32 v63, v62, v63, s80
	v_lshl_add_u32 v62, v106, 1, v55
	ds_write_b16_d16_hi v62, v63
	v_add3_u32 v63, s74, v96, 58
	s_and_b64 vcc, exec, s[6:7]
	v_cmp_lt_i32_e64 s[38:39], s78, v63
	s_cbranch_vccz .Lsg_559

; __device__ __forceinline__ float sigmf(float x) { return 1.f / (1.f + __expf(-x)); }
; __device__ __forceinline__ void inproj_epilogue(const Params& p, int layer, int mt, int ntile, int tid,
;                                                 f32x16 (&acc)[2][2], unsigned char* smem) {
;     ...
;     acc_foreach(tid, acc, [&](int row, int col, float v) {
;       int t = m0 + row;
;       float o = v;
;       if (mode == 1) o = (t >= NPADR) ? v : 0.f;
;       if (mode == 2) o = sigmf(v);
;       sT[row * 136 + col] = f2bf(o);
;     });
.LBB0_4292:
	v_bfe_u32 v107, v63, 16, 1
	v_add_u32_e32 v55, 0x110, v55
	v_add3_u32 v63, v63, v107, s80
	v_lshl_add_u32 v55, v106, 1, v55
	ds_write_b16_d16_hi v55, v63
	v_add3_u32 v63, s74, v96, 59
	s_and_b64 vcc, exec, s[6:7]
	v_cmp_lt_i32_e64 s[40:41], s78, v63
	s_cbranch_vccz .Lsg_560

; __device__ __forceinline__ float sigmf(float x) { return 1.f / (1.f + __expf(-x)); }
; __device__ __forceinline__ void inproj_epilogue(const Params& p, int layer, int mt, int ntile, int tid,
;                                                 f32x16 (&acc)[2][2], unsigned char* smem) {
;     ...
;     acc_foreach(tid, acc, [&](int row, int col, float v) {
;       int t = m0 + row;
;       float o = v;
;       if (mode == 1) o = (t >= NPADR) ? v : 0.f;
;       if (mode == 2) o = sigmf(v);
;       sT[row * 136 + col] = f2bf(o);
;     });
.LBB0_4295:
	v_bfe_u32 v96, v63, 16, 1
	v_add3_u32 v63, v63, v96, s80
	ds_write_b16_d16_hi v55, v63 offset:272
	s_and_b64 vcc, exec, s[6:7]
	s_cbranch_vccz .Lsg_561

; __device__ __forceinline__ float sigmf(float x) { return 1.f / (1.f + __expf(-x)); }
; __device__ __forceinline__ void inproj_epilogue(const Params& p, int layer, int mt, int ntile, int tid,
;                                                 f32x16 (&acc)[2][2], unsigned char* smem) {
;     ...
;     acc_foreach(tid, acc, [&](int row, int col, float v) {
;       int t = m0 + row;
;       float o = v;
;       if (mode == 1) o = (t >= NPADR) ? v : 0.f;
;       if (mode == 2) o = sigmf(v);
;       sT[row * 136 + col] = f2bf(o);
;     });
.LBB0_4298:
	v_bfe_u32 v63, v32, 16, 1
	v_add3_u32 v32, v32, v63, s80
	s_and_b64 vcc, exec, s[6:7]
	ds_write_b16_d16_hi v48, v32 offset:64
	s_cbranch_vccz .Lsg_562

; __device__ __forceinline__ float sigmf(float x) { return 1.f / (1.f + __expf(-x)); }
; __device__ __forceinline__ void inproj_epilogue(const Params& p, int layer, int mt, int ntile, int tid,
;                                                 f32x16 (&acc)[2][2], unsigned char* smem) {
;     ...
;     acc_foreach(tid, acc, [&](int row, int col, float v) {
;       int t = m0 + row;
;       float o = v;
;       if (mode == 1) o = (t >= NPADR) ? v : 0.f;
;       if (mode == 2) o = sigmf(v);
;       sT[row * 136 + col] = f2bf(o);
;     });
.LBB0_4301:
	v_bfe_u32 v33, v32, 16, 1
	v_add3_u32 v32, v32, v33, s80
	s_and_b64 vcc, exec, s[6:7]
	ds_write_b16_d16_hi v49, v32 offset:64
	s_cbranch_vccz .Lsg_563

; __device__ __forceinline__ float sigmf(float x) { return 1.f / (1.f + __expf(-x)); }
; __device__ __forceinline__ void inproj_epilogue(const Params& p, int layer, int mt, int ntile, int tid,
;                                                 f32x16 (&acc)[2][2], unsigned char* smem) {
;     ...
;     acc_foreach(tid, acc, [&](int row, int col, float v) {
;       int t = m0 + row;
;       float o = v;
;       if (mode == 1) o = (t >= NPADR) ? v : 0.f;
;       if (mode == 2) o = sigmf(v);
;       sT[row * 136 + col] = f2bf(o);
;     });
.LBB0_4304:
	v_bfe_u32 v33, v32, 16, 1
	v_add3_u32 v32, v32, v33, s80
	s_and_b64 vcc, exec, s[6:7]
	ds_write_b16_d16_hi v50, v32 offset:64
	s_cbranch_vccz .Lsg_564

; __device__ __forceinline__ float sigmf(float x) { return 1.f / (1.f + __expf(-x)); }
; __device__ __forceinline__ void inproj_epilogue(const Params& p, int layer, int mt, int ntile, int tid,
;                                                 f32x16 (&acc)[2][2], unsigned char* smem) {
;     ...
;     acc_foreach(tid, acc, [&](int row, int col, float v) {
;       int t = m0 + row;
;       float o = v;
;       if (mode == 1) o = (t >= NPADR) ? v : 0.f;
;       if (mode == 2) o = sigmf(v);
;       sT[row * 136 + col] = f2bf(o);
;     });
.LBB0_4307:
	v_bfe_u32 v33, v32, 16, 1
	v_add3_u32 v32, v32, v33, s80
	s_and_b64 vcc, exec, s[6:7]
	ds_write_b16_d16_hi v51, v32 offset:64
	s_cbranch_vccz .Lsg_565

; __device__ __forceinline__ float sigmf(float x) { return 1.f / (1.f + __expf(-x)); }
; __device__ __forceinline__ void inproj_epilogue(const Params& p, int layer, int mt, int ntile, int tid,
;                                                 f32x16 (&acc)[2][2], unsigned char* smem) {
;     ...
;     acc_foreach(tid, acc, [&](int row, int col, float v) {
;       int t = m0 + row;
;       float o = v;
;       if (mode == 1) o = (t >= NPADR) ? v : 0.f;
;       if (mode == 2) o = sigmf(v);
;       sT[row * 136 + col] = f2bf(o);
;     });
.LBB0_4310:
	v_bfe_u32 v33, v32, 16, 1
	v_add3_u32 v32, v32, v33, s80
	s_and_b64 vcc, exec, s[6:7]
	ds_write_b16_d16_hi v52, v32 offset:64
	s_cbranch_vccz .Lsg_566

; __device__ __forceinline__ float sigmf(float x) { return 1.f / (1.f + __expf(-x)); }
; __device__ __forceinline__ void inproj_epilogue(const Params& p, int layer, int mt, int ntile, int tid,
;                                                 f32x16 (&acc)[2][2], unsigned char* smem) {
;     ...
;     acc_foreach(tid, acc, [&](int row, int col, float v) {
;       int t = m0 + row;
;       float o = v;
;       if (mode == 1) o = (t >= NPADR) ? v : 0.f;
;       if (mode == 2) o = sigmf(v);
;       sT[row * 136 + col] = f2bf(o);
;     });
.LBB0_4313:
	v_bfe_u32 v33, v32, 16, 1
	v_add3_u32 v32, v32, v33, s80
	s_and_b64 vcc, exec, s[6:7]
	ds_write_b16_d16_hi v53, v32 offset:64
	s_cbranch_vccz .Lsg_567

; __device__ __forceinline__ float sigmf(float x) { return 1.f / (1.f + __expf(-x)); }
; __device__ __forceinline__ void inproj_epilogue(const Params& p, int layer, int mt, int ntile, int tid,
;                                                 f32x16 (&acc)[2][2], unsigned char* smem) {
;     ...
;     acc_foreach(tid, acc, [&](int row, int col, float v) {
;       int t = m0 + row;
;       float o = v;
;       if (mode == 1) o = (t >= NPADR) ? v : 0.f;
;       if (mode == 2) o = sigmf(v);
;       sT[row * 136 + col] = f2bf(o);
;     });
.LBB0_4316:
	v_bfe_u32 v33, v32, 16, 1
	v_add3_u32 v32, v32, v33, s80
	s_and_b64 vcc, exec, s[6:7]
	ds_write_b16_d16_hi v54, v32 offset:64
	s_cbranch_vccz .Lsg_568

; __device__ __forceinline__ float sigmf(float x) { return 1.f / (1.f + __expf(-x)); }
; __device__ __forceinline__ void inproj_epilogue(const Params& p, int layer, int mt, int ntile, int tid,
;                                                 f32x16 (&acc)[2][2], unsigned char* smem) {
;     ...
;     acc_foreach(tid, acc, [&](int row, int col, float v) {
;       int t = m0 + row;
;       float o = v;
;       if (mode == 1) o = (t >= NPADR) ? v : 0.f;
;       if (mode == 2) o = sigmf(v);
;       sT[row * 136 + col] = f2bf(o);
;     });
.LBB0_4319:
	v_bfe_u32 v33, v32, 16, 1
	v_add3_u32 v32, v32, v33, s80
	s_and_b64 vcc, exec, s[6:7]
	ds_write_b16_d16_hi v56, v32 offset:64
	s_cbranch_vccz .Lsg_569

; __device__ __forceinline__ float sigmf(float x) { return 1.f / (1.f + __expf(-x)); }
; __device__ __forceinline__ void inproj_epilogue(const Params& p, int layer, int mt, int ntile, int tid,
;                                                 f32x16 (&acc)[2][2], unsigned char* smem) {
;     ...
;     acc_foreach(tid, acc, [&](int row, int col, float v) {
;       int t = m0 + row;
;       float o = v;
;       if (mode == 1) o = (t >= NPADR) ? v : 0.f;
;       if (mode == 2) o = sigmf(v);
;       sT[row * 136 + col] = f2bf(o);
;     });
.LBB0_4322:
	v_bfe_u32 v33, v32, 16, 1
	v_add3_u32 v32, v32, v33, s80
	s_and_b64 vcc, exec, s[6:7]
	ds_write_b16_d16_hi v57, v32 offset:64
	s_cbranch_vccz .Lsg_570

; __device__ __forceinline__ float sigmf(float x) { return 1.f / (1.f + __expf(-x)); }
; __device__ __forceinline__ void inproj_epilogue(const Params& p, int layer, int mt, int ntile, int tid,
;                                                 f32x16 (&acc)[2][2], unsigned char* smem) {
;     ...
;     acc_foreach(tid, acc, [&](int row, int col, float v) {
;       int t = m0 + row;
;       float o = v;
;       if (mode == 1) o = (t >= NPADR) ? v : 0.f;
;       if (mode == 2) o = sigmf(v);
;       sT[row * 136 + col] = f2bf(o);
;     });
.LBB0_4325:
	v_bfe_u32 v33, v32, 16, 1
	v_add3_u32 v32, v32, v33, s80
	s_and_b64 vcc, exec, s[6:7]
	ds_write_b16_d16_hi v58, v32 offset:64
	s_cbranch_vccz .Lsg_571

; __device__ __forceinline__ float sigmf(float x) { return 1.f / (1.f + __expf(-x)); }
; __device__ __forceinline__ void inproj_epilogue(const Params& p, int layer, int mt, int ntile, int tid,
;                                                 f32x16 (&acc)[2][2], unsigned char* smem) {
;     ...
;     acc_foreach(tid, acc, [&](int row, int col, float v) {
;       int t = m0 + row;
;       float o = v;
;       if (mode == 1) o = (t >= NPADR) ? v : 0.f;
;       if (mode == 2) o = sigmf(v);
;       sT[row * 136 + col] = f2bf(o);
;     });
.LBB0_4328:
	v_bfe_u32 v33, v32, 16, 1
	v_add3_u32 v32, v32, v33, s80
	s_and_b64 vcc, exec, s[6:7]
	ds_write_b16_d16_hi v59, v32 offset:64
	s_cbranch_vccz .Lsg_572

; __device__ __forceinline__ float sigmf(float x) { return 1.f / (1.f + __expf(-x)); }
; __device__ __forceinline__ void inproj_epilogue(const Params& p, int layer, int mt, int ntile, int tid,
;                                                 f32x16 (&acc)[2][2], unsigned char* smem) {
;     ...
;     acc_foreach(tid, acc, [&](int row, int col, float v) {
;       int t = m0 + row;
;       float o = v;
;       if (mode == 1) o = (t >= NPADR) ? v : 0.f;
;       if (mode == 2) o = sigmf(v);
;       sT[row * 136 + col] = f2bf(o);
;     });
.LBB0_4331:
	v_bfe_u32 v33, v32, 16, 1
	v_add3_u32 v32, v32, v33, s80
	s_and_b64 vcc, exec, s[6:7]
	ds_write_b16_d16_hi v60, v32 offset:64
	s_cbranch_vccz .Lsg_573

; __device__ __forceinline__ float sigmf(float x) { return 1.f / (1.f + __expf(-x)); }
; __device__ __forceinline__ void inproj_epilogue(const Params& p, int layer, int mt, int ntile, int tid,
;                                                 f32x16 (&acc)[2][2], unsigned char* smem) {
;     ...
;     acc_foreach(tid, acc, [&](int row, int col, float v) {
;       int t = m0 + row;
;       float o = v;
;       if (mode == 1) o = (t >= NPADR) ? v : 0.f;
;       if (mode == 2) o = sigmf(v);
;       sT[row * 136 + col] = f2bf(o);
;     });
.LBB0_4334:
	v_bfe_u32 v33, v32, 16, 1
	v_add3_u32 v32, v32, v33, s80
	s_and_b64 vcc, exec, s[6:7]
	ds_write_b16_d16_hi v61, v32 offset:64
	s_cbranch_vccz .Lsg_574

; __device__ __forceinline__ float sigmf(float x) { return 1.f / (1.f + __expf(-x)); }
; __device__ __forceinline__ void inproj_epilogue(const Params& p, int layer, int mt, int ntile, int tid,
;                                                 f32x16 (&acc)[2][2], unsigned char* smem) {
;     ...
;     acc_foreach(tid, acc, [&](int row, int col, float v) {
;       int t = m0 + row;
;       float o = v;
;       if (mode == 1) o = (t >= NPADR) ? v : 0.f;
;       if (mode == 2) o = sigmf(v);
;       sT[row * 136 + col] = f2bf(o);
;     });
.LBB0_4337:
	v_bfe_u32 v33, v32, 16, 1
	v_add3_u32 v32, v32, v33, s80
	s_and_b64 vcc, exec, s[6:7]
	ds_write_b16_d16_hi v62, v32 offset:64
	s_cbranch_vccz .Lsg_575

; __device__ __forceinline__ float sigmf(float x) { return 1.f / (1.f + __expf(-x)); }
; __device__ __forceinline__ void inproj_epilogue(const Params& p, int layer, int mt, int ntile, int tid,
;                                                 f32x16 (&acc)[2][2], unsigned char* smem) {
;     ...
;     acc_foreach(tid, acc, [&](int row, int col, float v) {
;       int t = m0 + row;
;       float o = v;
;       if (mode == 1) o = (t >= NPADR) ? v : 0.f;
;       if (mode == 2) o = sigmf(v);
;       sT[row * 136 + col] = f2bf(o);
;     });
.LBB0_4340:
	v_bfe_u32 v33, v32, 16, 1
	v_add3_u32 v32, v32, v33, s80
	s_and_b64 vcc, exec, s[6:7]
	ds_write_b16_d16_hi v55, v32 offset:64
	s_cbranch_vccz .Lsg_576

; __device__ __forceinline__ float sigmf(float x) { return 1.f / (1.f + __expf(-x)); }
; __device__ __forceinline__ void inproj_epilogue(const Params& p, int layer, int mt, int ntile, int tid,
;                                                 f32x16 (&acc)[2][2], unsigned char* smem) {
;     ...
;       if (mode == 2) o = sigmf(v);
.Lsg_528:
	v_mul_f32_e32 v124, 0xbfb8aa3b, v31
	v_exp_f32_e32 v124, v124
	s_nop 0
	v_add_f32_e32 v124, 1.0, v124
	v_div_scale_f32 v125, s[92:93], v124, v124, 1.0
	v_rcp_f32_e32 v126, v125
	v_div_scale_f32 v127, vcc, 1.0, v124, 1.0
	v_fma_f32 v128, -v125, v126, 1.0
	v_fmac_f32_e32 v126, v128, v126
	v_mul_f32_e32 v128, v127, v126
	v_fma_f32 v129, -v125, v128, v127
	v_fmac_f32_e32 v128, v129, v126
	v_fma_f32 v125, -v125, v128, v127
	v_div_fmas_f32 v125, v125, v126, v128
	v_div_fixup_f32 v124, v125, v124, 1.0
	s_branch .LBB0_4199

; __device__ __forceinline__ float sigmf(float x) { return 1.f / (1.f + __expf(-x)); }
; __device__ __forceinline__ void inproj_epilogue(const Params& p, int layer, int mt, int ntile, int tid,
;                                                 f32x16 (&acc)[2][2], unsigned char* smem) {
;     ...
;       if (mode == 2) o = sigmf(v);
.Lsg_560:
	v_mul_f32_e32 v63, 0xbfb8aa3b, v15
	v_exp_f32_e32 v63, v63
	s_nop 0
	v_add_f32_e32 v63, 1.0, v63
	v_div_scale_f32 v96, s[92:93], v63, v63, 1.0
	v_rcp_f32_e32 v106, v96
	v_div_scale_f32 v107, vcc, 1.0, v63, 1.0
	v_fma_f32 v110, -v96, v106, 1.0
	v_fmac_f32_e32 v106, v110, v106
	v_mul_f32_e32 v110, v107, v106
	v_fma_f32 v111, -v96, v110, v107
	v_fmac_f32_e32 v110, v111, v106
	v_fma_f32 v96, -v96, v110, v107
	v_div_fmas_f32 v96, v96, v106, v110
	v_div_fixup_f32 v63, v96, v63, 1.0
	s_branch .LBB0_4295

; __device__ __forceinline__ float sigmf(float x) { return 1.f / (1.f + __expf(-x)); }
; __device__ __forceinline__ float softplusf(float x) { return fmaxf(x, 0.f) + __logf(1.f + __expf(-fabsf(x))); }
; template <int MT, int NT, class F>
; __device__ __forceinline__ void acc_foreach(int tid, f32x16 (&acc)[MT][NT], F f) {
;     ...
;         int row = wm * (MT * 32) + mt * 32 + (i & 3) + 8 * (i >> 2) + 4 * hi;
; __device__ __forceinline__ void inproj_epilogue(const Params& p, int layer, int mt, int ntile, int tid,
;                                                 f32x16 (&acc)[2][2], unsigned char* smem) {
;     ...
;   const int m0 = mt * 128;
;   if (mode == 3) {
;     float* dt = (float*)(p.ws + OFF_DT) + (size_t)m0 * 16;
;     const float* bias = p.ssd_dt_bias + layer * 16;
;     acc_foreach(tid, acc, [&](int row, int col, float v) {
;       if (col < 16) *(dt + row * 16 + col) = softplusf(v + bias[col]);
;     });
;   } else {
;     bf16r* dstb = dst + (size_t)m0 * ld + c0;
;     bf16r* sT = (bf16r*)smem;
;     acc_foreach(tid, acc, [&](int row, int col, float v) {
;       int t = m0 + row;
;       float o = v;
;       if (mode == 1) o = (t >= NPADR) ? v : 0.f;
;       if (mode == 2) o = sigmf(v);
;       sT[row * 136 + col] = f2bf(o);
;     });
.LBB0_4541:
	s_lshl_b32 s74, s6, 7
	s_ashr_i32 s75, s74, 31
	s_cmp_lg_u32 s7, 3
	s_mov_b64 s[4:5], -1
	s_cbranch_scc0 .LBB0_4735
	v_mov_b32_e32 v106, v108
	s_movk_i32 s4, 0xffc0
	v_lshrrev_b32_e32 v107, 3, v106
	v_ashrrev_i32_e32 v96, 1, v106
	v_and_b32_e32 v107, 4, v107
	v_and_or_b32 v96, v96, s4, v107
	s_cmp_eq_u32 s7, 1
	s_cselect_b64 s[4:5], -1, 0
	v_add_u32_e32 v107, s74, v96
	s_cmp_eq_u32 s7, 2
	s_cselect_b64 s[10:11], -1, 0
	s_cmp_lg_u32 s7, 2
	v_cmp_lt_i32_e64 s[8:9], s81, v107
	s_cbranch_scc0 .Lsg_577

; __device__ __forceinline__ float sigmf(float x) { return 1.f / (1.f + __expf(-x)); }
; __device__ __forceinline__ void inproj_epilogue(const Params& p, int layer, int mt, int ntile, int tid,
;                                                 f32x16 (&acc)[2][2], unsigned char* smem) {
;     ...
;     acc_foreach(tid, acc, [&](int row, int col, float v) {
;       int t = m0 + row;
;       float o = v;
;       if (mode == 1) o = (t >= NPADR) ? v : 0.f;
;       if (mode == 2) o = sigmf(v);
;       sT[row * 136 + col] = f2bf(o);
;     });
.LBB0_4545:
	v_bfe_u32 v110, v107, 16, 1
	v_and_b32_e32 v106, 0x5f, v106
	v_add3_u32 v111, v107, v110, s83
	v_mul_lo_u32 v110, v96, s86
	v_lshl_add_u32 v107, v106, 1, v110
	ds_write_b16_d16_hi v107, v111
	v_add3_u32 v111, s74, v96, 1
	v_cndmask_b32_e64 v112, 0, 1, s[10:11]
	v_cmp_ne_u32_e64 s[6:7], 1, v112
	s_andn2_b64 vcc, exec, s[10:11]
	v_cmp_lt_i32_e64 s[10:11], s81, v111
	s_cbranch_vccz .Lsg_578

; __device__ __forceinline__ float sigmf(float x) { return 1.f / (1.f + __expf(-x)); }
; __device__ __forceinline__ void inproj_epilogue(const Params& p, int layer, int mt, int ntile, int tid,
;                                                 f32x16 (&acc)[2][2], unsigned char* smem) {
;     ...
;     acc_foreach(tid, acc, [&](int row, int col, float v) {
;       int t = m0 + row;
;       float o = v;
;       if (mode == 1) o = (t >= NPADR) ? v : 0.f;
;       if (mode == 2) o = sigmf(v);
;       sT[row * 136 + col] = f2bf(o);
;     });
.LBB0_4548:
	v_bfe_u32 v112, v111, 16, 1
	v_add3_u32 v112, v111, v112, s83
	v_add_u32_e32 v111, 0x110, v110
	v_lshl_add_u32 v110, v106, 1, v111
	ds_write_b16_d16_hi v110, v112
	v_add3_u32 v112, s74, v96, 2
	s_and_b64 vcc, exec, s[6:7]
	v_cmp_lt_i32_e64 s[12:13], s81, v112
	s_cbranch_vccz .Lsg_579

; __device__ __forceinline__ float sigmf(float x) { return 1.f / (1.f + __expf(-x)); }
; __device__ __forceinline__ void inproj_epilogue(const Params& p, int layer, int mt, int ntile, int tid,
;                                                 f32x16 (&acc)[2][2], unsigned char* smem) {
;     ...
;     acc_foreach(tid, acc, [&](int row, int col, float v) {
;       int t = m0 + row;
;       float o = v;
;       if (mode == 1) o = (t >= NPADR) ? v : 0.f;
;       if (mode == 2) o = sigmf(v);
;       sT[row * 136 + col] = f2bf(o);
;     });
.LBB0_4551:
	v_bfe_u32 v113, v112, 16, 1
	v_add3_u32 v113, v112, v113, s83
	v_add_u32_e32 v112, 0x110, v111
	v_lshl_add_u32 v111, v106, 1, v112
	ds_write_b16_d16_hi v111, v113
	v_add3_u32 v113, s74, v96, 3
	s_and_b64 vcc, exec, s[6:7]
	v_cmp_lt_i32_e64 s[14:15], s81, v113
	s_cbranch_vccz .Lsg_580

; __device__ __forceinline__ float sigmf(float x) { return 1.f / (1.f + __expf(-x)); }
; __device__ __forceinline__ void inproj_epilogue(const Params& p, int layer, int mt, int ntile, int tid,
;                                                 f32x16 (&acc)[2][2], unsigned char* smem) {
;     ...
;     acc_foreach(tid, acc, [&](int row, int col, float v) {
;       int t = m0 + row;
;       float o = v;
;       if (mode == 1) o = (t >= NPADR) ? v : 0.f;
;       if (mode == 2) o = sigmf(v);
;       sT[row * 136 + col] = f2bf(o);
;     });
.LBB0_4554:
	v_bfe_u32 v114, v113, 16, 1
	v_add3_u32 v114, v113, v114, s83
	v_add_u32_e32 v113, 0x110, v112
	v_lshl_add_u32 v112, v106, 1, v113
	ds_write_b16_d16_hi v112, v114
	v_add3_u32 v114, s74, v96, 8
	s_and_b64 vcc, exec, s[6:7]
	v_cmp_lt_i32_e64 s[16:17], s81, v114
	s_cbranch_vccz .Lsg_581

; __device__ __forceinline__ float sigmf(float x) { return 1.f / (1.f + __expf(-x)); }
; __device__ __forceinline__ void inproj_epilogue(const Params& p, int layer, int mt, int ntile, int tid,
;                                                 f32x16 (&acc)[2][2], unsigned char* smem) {
;     ...
;     acc_foreach(tid, acc, [&](int row, int col, float v) {
;       int t = m0 + row;
;       float o = v;
;       if (mode == 1) o = (t >= NPADR) ? v : 0.f;
;       if (mode == 2) o = sigmf(v);
;       sT[row * 136 + col] = f2bf(o);
;     });
.LBB0_4557:
	v_bfe_u32 v115, v114, 16, 1
	v_add3_u32 v115, v114, v115, s83
	v_add_u32_e32 v114, 0x550, v113
	v_lshl_add_u32 v113, v106, 1, v114
	ds_write_b16_d16_hi v113, v115
	v_add3_u32 v115, s74, v96, 9
	s_and_b64 vcc, exec, s[6:7]
	v_cmp_lt_i32_e64 s[18:19], s81, v115
	s_cbranch_vccz .Lsg_582

; __device__ __forceinline__ float sigmf(float x) { return 1.f / (1.f + __expf(-x)); }
; __device__ __forceinline__ void inproj_epilogue(const Params& p, int layer, int mt, int ntile, int tid,
;                                                 f32x16 (&acc)[2][2], unsigned char* smem) {
;     ...
;     acc_foreach(tid, acc, [&](int row, int col, float v) {
;       int t = m0 + row;
;       float o = v;
;       if (mode == 1) o = (t >= NPADR) ? v : 0.f;
;       if (mode == 2) o = sigmf(v);
;       sT[row * 136 + col] = f2bf(o);
;     });
.LBB0_4560:
	v_bfe_u32 v116, v115, 16, 1
	v_add3_u32 v116, v115, v116, s83
	v_add_u32_e32 v115, 0x110, v114
	v_lshl_add_u32 v114, v106, 1, v115
	ds_write_b16_d16_hi v114, v116
	v_add3_u32 v116, s74, v96, 10
	s_and_b64 vcc, exec, s[6:7]
	v_cmp_lt_i32_e64 s[20:21], s81, v116
	s_cbranch_vccz .Lsg_583

; __device__ __forceinline__ float sigmf(float x) { return 1.f / (1.f + __expf(-x)); }
; __device__ __forceinline__ void inproj_epilogue(const Params& p, int layer, int mt, int ntile, int tid,
;                                                 f32x16 (&acc)[2][2], unsigned char* smem) {
;     ...
;     acc_foreach(tid, acc, [&](int row, int col, float v) {
;       int t = m0 + row;
;       float o = v;
;       if (mode == 1) o = (t >= NPADR) ? v : 0.f;
;       if (mode == 2) o = sigmf(v);
;       sT[row * 136 + col] = f2bf(o);
;     });
.LBB0_4563:
	v_bfe_u32 v117, v116, 16, 1
	v_add3_u32 v117, v116, v117, s83
	v_add_u32_e32 v116, 0x110, v115
	v_lshl_add_u32 v115, v106, 1, v116
	ds_write_b16_d16_hi v115, v117
	v_add3_u32 v117, s74, v96, 11
	s_and_b64 vcc, exec, s[6:7]
	v_cmp_lt_i32_e64 s[22:23], s81, v117
	s_cbranch_vccz .Lsg_584

; __device__ __forceinline__ float sigmf(float x) { return 1.f / (1.f + __expf(-x)); }
; __device__ __forceinline__ void inproj_epilogue(const Params& p, int layer, int mt, int ntile, int tid,
;                                                 f32x16 (&acc)[2][2], unsigned char* smem) {
;     ...
;     acc_foreach(tid, acc, [&](int row, int col, float v) {
;       int t = m0 + row;
;       float o = v;
;       if (mode == 1) o = (t >= NPADR) ? v : 0.f;
;       if (mode == 2) o = sigmf(v);
;       sT[row * 136 + col] = f2bf(o);
;     });
.LBB0_4566:
	v_bfe_u32 v118, v117, 16, 1
	v_add_u32_e32 v116, 0x110, v116
	v_add3_u32 v118, v117, v118, s83
	v_lshl_add_u32 v117, v106, 1, v116
	ds_write_b16_d16_hi v117, v118
	v_add3_u32 v118, s74, v96, 16
	s_and_b64 vcc, exec, s[6:7]
	v_cmp_lt_i32_e64 s[24:25], s81, v118
	s_cbranch_vccz .Lsg_585

; __device__ __forceinline__ float sigmf(float x) { return 1.f / (1.f + __expf(-x)); }
; __device__ __forceinline__ void inproj_epilogue(const Params& p, int layer, int mt, int ntile, int tid,
;                                                 f32x16 (&acc)[2][2], unsigned char* smem) {
;     ...
;     acc_foreach(tid, acc, [&](int row, int col, float v) {
;       int t = m0 + row;
;       float o = v;
;       if (mode == 1) o = (t >= NPADR) ? v : 0.f;
;       if (mode == 2) o = sigmf(v);
;       sT[row * 136 + col] = f2bf(o);
;     });
.LBB0_4569:
	v_bfe_u32 v119, v118, 16, 1
	v_add_u32_e32 v116, 0x550, v116
	v_add3_u32 v119, v118, v119, s83
	v_lshl_add_u32 v118, v106, 1, v116
	ds_write_b16_d16_hi v118, v119
	v_add3_u32 v119, s74, v96, 17
	s_and_b64 vcc, exec, s[6:7]
	v_cmp_lt_i32_e64 s[26:27], s81, v119
	s_cbranch_vccz .Lsg_586

; __device__ __forceinline__ float sigmf(float x) { return 1.f / (1.f + __expf(-x)); }
; __device__ __forceinline__ void inproj_epilogue(const Params& p, int layer, int mt, int ntile, int tid,
;                                                 f32x16 (&acc)[2][2], unsigned char* smem) {
;     ...
;     acc_foreach(tid, acc, [&](int row, int col, float v) {
;       int t = m0 + row;
;       float o = v;
;       if (mode == 1) o = (t >= NPADR) ? v : 0.f;
;       if (mode == 2) o = sigmf(v);
;       sT[row * 136 + col] = f2bf(o);
;     });
.LBB0_4572:
	v_bfe_u32 v120, v119, 16, 1
	v_add_u32_e32 v116, 0x110, v116
	v_add3_u32 v120, v119, v120, s83
	v_lshl_add_u32 v119, v106, 1, v116
	ds_write_b16_d16_hi v119, v120
	v_add3_u32 v120, s74, v96, 18
	s_and_b64 vcc, exec, s[6:7]
	v_cmp_lt_i32_e64 s[28:29], s81, v120
	s_cbranch_vccz .Lsg_587

; __device__ __forceinline__ float sigmf(float x) { return 1.f / (1.f + __expf(-x)); }
; __device__ __forceinline__ void inproj_epilogue(const Params& p, int layer, int mt, int ntile, int tid,
;                                                 f32x16 (&acc)[2][2], unsigned char* smem) {
;     ...
;     acc_foreach(tid, acc, [&](int row, int col, float v) {
;       int t = m0 + row;
;       float o = v;
;       if (mode == 1) o = (t >= NPADR) ? v : 0.f;
;       if (mode == 2) o = sigmf(v);
;       sT[row * 136 + col] = f2bf(o);
;     });
.LBB0_4575:
	v_bfe_u32 v121, v120, 16, 1
	v_add_u32_e32 v116, 0x110, v116
	v_add3_u32 v121, v120, v121, s83
	v_lshl_add_u32 v120, v106, 1, v116
	ds_write_b16_d16_hi v120, v121
	v_add3_u32 v121, s74, v96, 19
	s_and_b64 vcc, exec, s[6:7]
	v_cmp_lt_i32_e64 s[30:31], s81, v121
	s_cbranch_vccz .Lsg_588

; __device__ __forceinline__ float sigmf(float x) { return 1.f / (1.f + __expf(-x)); }
; __device__ __forceinline__ void inproj_epilogue(const Params& p, int layer, int mt, int ntile, int tid,
;                                                 f32x16 (&acc)[2][2], unsigned char* smem) {
;     ...
;     acc_foreach(tid, acc, [&](int row, int col, float v) {
;       int t = m0 + row;
;       float o = v;
;       if (mode == 1) o = (t >= NPADR) ? v : 0.f;
;       if (mode == 2) o = sigmf(v);
;       sT[row * 136 + col] = f2bf(o);
;     });
.LBB0_4578:
	v_bfe_u32 v122, v121, 16, 1
	v_add_u32_e32 v116, 0x110, v116
	v_add3_u32 v122, v121, v122, s83
	v_lshl_add_u32 v121, v106, 1, v116
	ds_write_b16_d16_hi v121, v122
	v_add3_u32 v122, s74, v96, 24
	s_and_b64 vcc, exec, s[6:7]
	v_cmp_lt_i32_e64 s[34:35], s81, v122
	s_cbranch_vccz .Lsg_589

; __device__ __forceinline__ float sigmf(float x) { return 1.f / (1.f + __expf(-x)); }
; __device__ __forceinline__ void inproj_epilogue(const Params& p, int layer, int mt, int ntile, int tid,
;                                                 f32x16 (&acc)[2][2], unsigned char* smem) {
;     ...
;     acc_foreach(tid, acc, [&](int row, int col, float v) {
;       int t = m0 + row;
;       float o = v;
;       if (mode == 1) o = (t >= NPADR) ? v : 0.f;
;       if (mode == 2) o = sigmf(v);
;       sT[row * 136 + col] = f2bf(o);
;     });
.LBB0_4581:
	v_bfe_u32 v123, v122, 16, 1
	v_add_u32_e32 v116, 0x550, v116
	v_add3_u32 v123, v122, v123, s83
	v_lshl_add_u32 v122, v106, 1, v116
	ds_write_b16_d16_hi v122, v123
	v_add3_u32 v123, s74, v96, 25
	s_and_b64 vcc, exec, s[6:7]
	v_cmp_lt_i32_e64 s[36:37], s81, v123
	s_cbranch_vccz .Lsg_590

; __device__ __forceinline__ float sigmf(float x) { return 1.f / (1.f + __expf(-x)); }
; __device__ __forceinline__ void inproj_epilogue(const Params& p, int layer, int mt, int ntile, int tid,
;                                                 f32x16 (&acc)[2][2], unsigned char* smem) {
;     ...
;     acc_foreach(tid, acc, [&](int row, int col, float v) {
;       int t = m0 + row;
;       float o = v;
;       if (mode == 1) o = (t >= NPADR) ? v : 0.f;
;       if (mode == 2) o = sigmf(v);
;       sT[row * 136 + col] = f2bf(o);
;     });
.LBB0_4584:
	v_bfe_u32 v124, v123, 16, 1
	v_add_u32_e32 v116, 0x110, v116
	v_add3_u32 v124, v123, v124, s83
	v_lshl_add_u32 v123, v106, 1, v116
	ds_write_b16_d16_hi v123, v124
	v_add3_u32 v124, s74, v96, 26
	s_and_b64 vcc, exec, s[6:7]
	v_cmp_lt_i32_e64 s[38:39], s81, v124
	s_cbranch_vccz .Lsg_591

; __device__ __forceinline__ float sigmf(float x) { return 1.f / (1.f + __expf(-x)); }
; __device__ __forceinline__ void inproj_epilogue(const Params& p, int layer, int mt, int ntile, int tid,
;                                                 f32x16 (&acc)[2][2], unsigned char* smem) {
;     ...
;     acc_foreach(tid, acc, [&](int row, int col, float v) {
;       int t = m0 + row;
;       float o = v;
;       if (mode == 1) o = (t >= NPADR) ? v : 0.f;
;       if (mode == 2) o = sigmf(v);
;       sT[row * 136 + col] = f2bf(o);
;     });
.LBB0_4587:
	v_bfe_u32 v125, v124, 16, 1
	v_add_u32_e32 v116, 0x110, v116
	v_add3_u32 v124, v124, v125, s83
	v_lshl_add_u32 v116, v106, 1, v116
	ds_write_b16_d16_hi v116, v124
	v_add3_u32 v124, s74, v96, 27
	s_and_b64 vcc, exec, s[6:7]
	v_cmp_lt_i32_e64 s[40:41], s81, v124
	s_cbranch_vccz .Lsg_592

; __device__ __forceinline__ float sigmf(float x) { return 1.f / (1.f + __expf(-x)); }
; template <int MT, int NT, class F>
; __device__ __forceinline__ void acc_foreach(int tid, f32x16 (&acc)[MT][NT], F f) {
;     ...
;         int row = wm * (MT * 32) + mt * 32 + (i & 3) + 8 * (i >> 2) + 4 * hi;
; __device__ __forceinline__ void inproj_epilogue(const Params& p, int layer, int mt, int ntile, int tid,
;                                                 f32x16 (&acc)[2][2], unsigned char* smem) {
;     ...
;     acc_foreach(tid, acc, [&](int row, int col, float v) {
;       int t = m0 + row;
;       float o = v;
;       if (mode == 1) o = (t >= NPADR) ? v : 0.f;
;       if (mode == 2) o = sigmf(v);
;       sT[row * 136 + col] = f2bf(o);
;     });
.LBB0_4638:
	v_bfe_u32 v50, v48, 16, 1
	v_add_u32_e32 v49, 0x110, v116
	v_add3_u32 v48, v48, v50, s83
	ds_write_b16_d16_hi v49, v48 offset:64
	v_or_b32_e32 v48, 32, v96
	v_add_u32_e32 v49, s74, v48
	s_and_b64 vcc, exec, s[6:7]
	v_cmp_lt_i32_e64 s[8:9], s81, v49
	s_cbranch_vccz .Lsg_609

; __device__ __forceinline__ float sigmf(float x) { return 1.f / (1.f + __expf(-x)); }
; __device__ __forceinline__ void inproj_epilogue(const Params& p, int layer, int mt, int ntile, int tid,
;                                                 f32x16 (&acc)[2][2], unsigned char* smem) {
;     ...
;     acc_foreach(tid, acc, [&](int row, int col, float v) {
;       int t = m0 + row;
;       float o = v;
;       if (mode == 1) o = (t >= NPADR) ? v : 0.f;
;       if (mode == 2) o = sigmf(v);
;       sT[row * 136 + col] = f2bf(o);
;     });
.LBB0_4641:
	v_bfe_u32 v50, v49, 16, 1
	v_add3_u32 v50, v49, v50, s83
	v_mul_lo_u32 v49, v48, s86
	v_lshl_add_u32 v48, v106, 1, v49
	ds_write_b16_d16_hi v48, v50
	v_add3_u32 v50, s74, v96, 33
	s_and_b64 vcc, exec, s[6:7]
	v_cmp_lt_i32_e64 s[10:11], s81, v50
	s_cbranch_vccz .Lsg_610

; __device__ __forceinline__ float sigmf(float x) { return 1.f / (1.f + __expf(-x)); }
; __device__ __forceinline__ void inproj_epilogue(const Params& p, int layer, int mt, int ntile, int tid,
;                                                 f32x16 (&acc)[2][2], unsigned char* smem) {
;     ...
;     acc_foreach(tid, acc, [&](int row, int col, float v) {
;       int t = m0 + row;
;       float o = v;
;       if (mode == 1) o = (t >= NPADR) ? v : 0.f;
;       if (mode == 2) o = sigmf(v);
;       sT[row * 136 + col] = f2bf(o);
;     });
.LBB0_4644:
	v_bfe_u32 v51, v50, 16, 1
	v_add3_u32 v51, v50, v51, s83
	v_add_u32_e32 v50, 0x110, v49
	v_lshl_add_u32 v49, v106, 1, v50
	ds_write_b16_d16_hi v49, v51
	v_add3_u32 v51, s74, v96, 34
	s_and_b64 vcc, exec, s[6:7]
	v_cmp_lt_i32_e64 s[12:13], s81, v51
	s_cbranch_vccz .Lsg_611

; __device__ __forceinline__ float sigmf(float x) { return 1.f / (1.f + __expf(-x)); }
; __device__ __forceinline__ void inproj_epilogue(const Params& p, int layer, int mt, int ntile, int tid,
;                                                 f32x16 (&acc)[2][2], unsigned char* smem) {
;     ...
;     acc_foreach(tid, acc, [&](int row, int col, float v) {
;       int t = m0 + row;
;       float o = v;
;       if (mode == 1) o = (t >= NPADR) ? v : 0.f;
;       if (mode == 2) o = sigmf(v);
;       sT[row * 136 + col] = f2bf(o);
;     });
.LBB0_4647:
	v_bfe_u32 v52, v51, 16, 1
	v_add3_u32 v52, v51, v52, s83
	v_add_u32_e32 v51, 0x110, v50
	v_lshl_add_u32 v50, v106, 1, v51
	ds_write_b16_d16_hi v50, v52
	v_add3_u32 v52, s74, v96, 35
	s_and_b64 vcc, exec, s[6:7]
	v_cmp_lt_i32_e64 s[14:15], s81, v52
	s_cbranch_vccz .Lsg_612

; __device__ __forceinline__ float sigmf(float x) { return 1.f / (1.f + __expf(-x)); }
; __device__ __forceinline__ void inproj_epilogue(const Params& p, int layer, int mt, int ntile, int tid,
;                                                 f32x16 (&acc)[2][2], unsigned char* smem) {
;     ...
;     acc_foreach(tid, acc, [&](int row, int col, float v) {
;       int t = m0 + row;
;       float o = v;
;       if (mode == 1) o = (t >= NPADR) ? v : 0.f;
;       if (mode == 2) o = sigmf(v);
;       sT[row * 136 + col] = f2bf(o);
;     });
.LBB0_4650:
	v_bfe_u32 v53, v52, 16, 1
	v_add3_u32 v53, v52, v53, s83
	v_add_u32_e32 v52, 0x110, v51
	v_lshl_add_u32 v51, v106, 1, v52
	ds_write_b16_d16_hi v51, v53
	v_add3_u32 v53, s74, v96, 40
	s_and_b64 vcc, exec, s[6:7]
	v_cmp_lt_i32_e64 s[16:17], s81, v53
	s_cbranch_vccz .Lsg_613

; __device__ __forceinline__ float sigmf(float x) { return 1.f / (1.f + __expf(-x)); }
; __device__ __forceinline__ void inproj_epilogue(const Params& p, int layer, int mt, int ntile, int tid,
;                                                 f32x16 (&acc)[2][2], unsigned char* smem) {
;     ...
;     acc_foreach(tid, acc, [&](int row, int col, float v) {
;       int t = m0 + row;
;       float o = v;
;       if (mode == 1) o = (t >= NPADR) ? v : 0.f;
;       if (mode == 2) o = sigmf(v);
;       sT[row * 136 + col] = f2bf(o);
;     });
.LBB0_4653:
	v_bfe_u32 v54, v53, 16, 1
	v_add3_u32 v54, v53, v54, s83
	v_add_u32_e32 v53, 0x550, v52
	v_lshl_add_u32 v52, v106, 1, v53
	ds_write_b16_d16_hi v52, v54
	v_add3_u32 v54, s74, v96, 41
	s_and_b64 vcc, exec, s[6:7]
	v_cmp_lt_i32_e64 s[18:19], s81, v54
	s_cbranch_vccz .Lsg_614

; __device__ __forceinline__ float sigmf(float x) { return 1.f / (1.f + __expf(-x)); }
; __device__ __forceinline__ void inproj_epilogue(const Params& p, int layer, int mt, int ntile, int tid,
;                                                 f32x16 (&acc)[2][2], unsigned char* smem) {
;     ...
;     acc_foreach(tid, acc, [&](int row, int col, float v) {
;       int t = m0 + row;
;       float o = v;
;       if (mode == 1) o = (t >= NPADR) ? v : 0.f;
;       if (mode == 2) o = sigmf(v);
;       sT[row * 136 + col] = f2bf(o);
;     });
.LBB0_4656:
	v_bfe_u32 v55, v54, 16, 1
	v_add3_u32 v55, v54, v55, s83
	v_add_u32_e32 v54, 0x110, v53
	v_lshl_add_u32 v53, v106, 1, v54
	ds_write_b16_d16_hi v53, v55
	v_add3_u32 v55, s74, v96, 42
	s_and_b64 vcc, exec, s[6:7]
	v_cmp_lt_i32_e64 s[20:21], s81, v55
	s_cbranch_vccz .Lsg_615

; __device__ __forceinline__ float sigmf(float x) { return 1.f / (1.f + __expf(-x)); }
; __device__ __forceinline__ void inproj_epilogue(const Params& p, int layer, int mt, int ntile, int tid,
;                                                 f32x16 (&acc)[2][2], unsigned char* smem) {
;     ...
;     acc_foreach(tid, acc, [&](int row, int col, float v) {
;       int t = m0 + row;
;       float o = v;
;       if (mode == 1) o = (t >= NPADR) ? v : 0.f;
;       if (mode == 2) o = sigmf(v);
;       sT[row * 136 + col] = f2bf(o);
;     });
.LBB0_4659:
	v_bfe_u32 v56, v55, 16, 1
	v_add3_u32 v56, v55, v56, s83
	v_add_u32_e32 v55, 0x110, v54
	v_lshl_add_u32 v54, v106, 1, v55
	ds_write_b16_d16_hi v54, v56
	v_add3_u32 v56, s74, v96, 43
	s_and_b64 vcc, exec, s[6:7]
	v_cmp_lt_i32_e64 s[22:23], s81, v56
	s_cbranch_vccz .Lsg_616

; __device__ __forceinline__ float sigmf(float x) { return 1.f / (1.f + __expf(-x)); }
; __device__ __forceinline__ void inproj_epilogue(const Params& p, int layer, int mt, int ntile, int tid,
;                                                 f32x16 (&acc)[2][2], unsigned char* smem) {
;     ...
;     acc_foreach(tid, acc, [&](int row, int col, float v) {
;       int t = m0 + row;
;       float o = v;
;       if (mode == 1) o = (t >= NPADR) ? v : 0.f;
;       if (mode == 2) o = sigmf(v);
;       sT[row * 136 + col] = f2bf(o);
;     });
.LBB0_4662:
	v_bfe_u32 v57, v56, 16, 1
	v_add_u32_e32 v55, 0x110, v55
	v_add3_u32 v57, v56, v57, s83
	v_lshl_add_u32 v56, v106, 1, v55
	ds_write_b16_d16_hi v56, v57
	v_add3_u32 v57, s74, v96, 48
	s_and_b64 vcc, exec, s[6:7]
	v_cmp_lt_i32_e64 s[24:25], s81, v57
	s_cbranch_vccz .Lsg_617

; __device__ __forceinline__ float sigmf(float x) { return 1.f / (1.f + __expf(-x)); }
; __device__ __forceinline__ void inproj_epilogue(const Params& p, int layer, int mt, int ntile, int tid,
;                                                 f32x16 (&acc)[2][2], unsigned char* smem) {
;     ...
;     acc_foreach(tid, acc, [&](int row, int col, float v) {
;       int t = m0 + row;
;       float o = v;
;       if (mode == 1) o = (t >= NPADR) ? v : 0.f;
;       if (mode == 2) o = sigmf(v);
;       sT[row * 136 + col] = f2bf(o);
;     });
.LBB0_4665:
	v_bfe_u32 v58, v57, 16, 1
	v_add_u32_e32 v55, 0x550, v55
	v_add3_u32 v58, v57, v58, s83
	v_lshl_add_u32 v57, v106, 1, v55
	ds_write_b16_d16_hi v57, v58
	v_add3_u32 v58, s74, v96, 49
	s_and_b64 vcc, exec, s[6:7]
	v_cmp_lt_i32_e64 s[26:27], s81, v58
	s_cbranch_vccz .Lsg_618

; __device__ __forceinline__ float sigmf(float x) { return 1.f / (1.f + __expf(-x)); }
; __device__ __forceinline__ void inproj_epilogue(const Params& p, int layer, int mt, int ntile, int tid,
;                                                 f32x16 (&acc)[2][2], unsigned char* smem) {
;     ...
;     acc_foreach(tid, acc, [&](int row, int col, float v) {
;       int t = m0 + row;
;       float o = v;
;       if (mode == 1) o = (t >= NPADR) ? v : 0.f;
;       if (mode == 2) o = sigmf(v);
;       sT[row * 136 + col] = f2bf(o);
;     });
.LBB0_4668:
	v_bfe_u32 v59, v58, 16, 1
	v_add_u32_e32 v55, 0x110, v55
	v_add3_u32 v59, v58, v59, s83
	v_lshl_add_u32 v58, v106, 1, v55
	ds_write_b16_d16_hi v58, v59
	v_add3_u32 v59, s74, v96, 50
	s_and_b64 vcc, exec, s[6:7]
	v_cmp_lt_i32_e64 s[28:29], s81, v59
	s_cbranch_vccz .Lsg_619

; __device__ __forceinline__ float sigmf(float x) { return 1.f / (1.f + __expf(-x)); }
; __device__ __forceinline__ void inproj_epilogue(const Params& p, int layer, int mt, int ntile, int tid,
;                                                 f32x16 (&acc)[2][2], unsigned char* smem) {
;     ...
;     acc_foreach(tid, acc, [&](int row, int col, float v) {
;       int t = m0 + row;
;       float o = v;
;       if (mode == 1) o = (t >= NPADR) ? v : 0.f;
;       if (mode == 2) o = sigmf(v);
;       sT[row * 136 + col] = f2bf(o);
;     });
.LBB0_4671:
	v_bfe_u32 v60, v59, 16, 1
	v_add_u32_e32 v55, 0x110, v55
	v_add3_u32 v60, v59, v60, s83
	v_lshl_add_u32 v59, v106, 1, v55
	ds_write_b16_d16_hi v59, v60
	v_add3_u32 v60, s74, v96, 51
	s_and_b64 vcc, exec, s[6:7]
	v_cmp_lt_i32_e64 s[30:31], s81, v60
	s_cbranch_vccz .Lsg_620

; __device__ __forceinline__ float sigmf(float x) { return 1.f / (1.f + __expf(-x)); }
; __device__ __forceinline__ void inproj_epilogue(const Params& p, int layer, int mt, int ntile, int tid,
;                                                 f32x16 (&acc)[2][2], unsigned char* smem) {
;     ...
;     acc_foreach(tid, acc, [&](int row, int col, float v) {
;       int t = m0 + row;
;       float o = v;
;       if (mode == 1) o = (t >= NPADR) ? v : 0.f;
;       if (mode == 2) o = sigmf(v);
;       sT[row * 136 + col] = f2bf(o);
;     });
.LBB0_4674:
	v_bfe_u32 v61, v60, 16, 1
	v_add_u32_e32 v55, 0x110, v55
	v_add3_u32 v61, v60, v61, s83
	v_lshl_add_u32 v60, v106, 1, v55
	ds_write_b16_d16_hi v60, v61
	v_add3_u32 v61, s74, v96, 56
	s_and_b64 vcc, exec, s[6:7]
	v_cmp_lt_i32_e64 s[34:35], s81, v61
	s_cbranch_vccz .Lsg_621

; __device__ __forceinline__ float sigmf(float x) { return 1.f / (1.f + __expf(-x)); }
; __device__ __forceinline__ void inproj_epilogue(const Params& p, int layer, int mt, int ntile, int tid,
;                                                 f32x16 (&acc)[2][2], unsigned char* smem) {
;     ...
;     acc_foreach(tid, acc, [&](int row, int col, float v) {
;       int t = m0 + row;
;       float o = v;
;       if (mode == 1) o = (t >= NPADR) ? v : 0.f;
;       if (mode == 2) o = sigmf(v);
;       sT[row * 136 + col] = f2bf(o);
;     });
.LBB0_4677:
	v_bfe_u32 v62, v61, 16, 1
	v_add_u32_e32 v55, 0x550, v55
	v_add3_u32 v62, v61, v62, s83
	v_lshl_add_u32 v61, v106, 1, v55
	ds_write_b16_d16_hi v61, v62
	v_add3_u32 v62, s74, v96, 57
	s_and_b64 vcc, exec, s[6:7]
	v_cmp_lt_i32_e64 s[36:37], s81, v62
	s_cbranch_vccz .Lsg_622

; __device__ __forceinline__ float sigmf(float x) { return 1.f / (1.f + __expf(-x)); }
; __device__ __forceinline__ void inproj_epilogue(const Params& p, int layer, int mt, int ntile, int tid,
;                                                 f32x16 (&acc)[2][2], unsigned char* smem) {
;     ...
;     acc_foreach(tid, acc, [&](int row, int col, float v) {
;       int t = m0 + row;
;       float o = v;
;       if (mode == 1) o = (t >= NPADR) ? v : 0.f;
;       if (mode == 2) o = sigmf(v);
;       sT[row * 136 + col] = f2bf(o);
;     });
.LBB0_4680:
	v_bfe_u32 v63, v62, 16, 1
	v_add_u32_e32 v55, 0x110, v55
	v_add3_u32 v63, v62, v63, s83
	v_lshl_add_u32 v62, v106, 1, v55
	ds_write_b16_d16_hi v62, v63
	v_add3_u32 v63, s74, v96, 58
	s_and_b64 vcc, exec, s[6:7]
	v_cmp_lt_i32_e64 s[38:39], s81, v63
	s_cbranch_vccz .Lsg_623

; __device__ __forceinline__ float sigmf(float x) { return 1.f / (1.f + __expf(-x)); }
; __device__ __forceinline__ void inproj_epilogue(const Params& p, int layer, int mt, int ntile, int tid,
;                                                 f32x16 (&acc)[2][2], unsigned char* smem) {
;     ...
;     acc_foreach(tid, acc, [&](int row, int col, float v) {
;       int t = m0 + row;
;       float o = v;
;       if (mode == 1) o = (t >= NPADR) ? v : 0.f;
;       if (mode == 2) o = sigmf(v);
;       sT[row * 136 + col] = f2bf(o);
;     });
.LBB0_4683:
	v_bfe_u32 v107, v63, 16, 1
	v_add_u32_e32 v55, 0x110, v55
	v_add3_u32 v63, v63, v107, s83
	v_lshl_add_u32 v55, v106, 1, v55
	ds_write_b16_d16_hi v55, v63
	v_add3_u32 v63, s74, v96, 59
	s_and_b64 vcc, exec, s[6:7]
	v_cmp_lt_i32_e64 s[40:41], s81, v63
	s_cbranch_vccz .Lsg_624
